# attention units: every v_pk_{mul,add,fma}_f32 split into two scalar fp32 ops (packed fp32 between MFMAs issues slower than two singles)
# speedup vs baseline: 1.0074x; 1.0036x over previous
.LBB0_984:
	s_or_b64 exec, exec, s[6:7]
	v_mov_b32_e32 v11, v228
	s_barrier
	s_load_dwordx2 s[6:7], s[0:1], 0x100
	s_lshl_b32 s8, s86, 5
	s_and_b32 s14, s8, 0x7fffff00
	s_add_i32 s14, s14, 0xffff1600
	v_and_b32_e32 v10, 15, v11
	s_waitcnt lgkmcnt(0)
	s_add_u32 s10, s6, 0xae00000
	s_addc_u32 s11, s7, 0
	s_lshl_b32 s9, s86, 7
	s_and_b32 s9, s9, 0x80
	v_ashrrev_i32_e32 v0, 2, v11
	s_and_b32 s12, s8, 0xc0
	s_or_b32 s8, s9, s14
	v_and_b32_e32 v0, -16, v0
	v_or_b32_e32 v1, s8, v10
	v_add_u32_e32 v78, v1, v0
	v_mov_b64_e32 v[0:1], s[10:11]
	v_mad_i64_i32 v[0:1], s[8:9], v78, s93, v[0:1]
	s_lshl_b32 s8, s12, 1
	s_mov_b32 s9, s97
	v_lshl_add_u64 v[0:1], v[0:1], 0, s[8:9]
	v_and_b32_e32 v8, 48, v11
	v_mov_b32_e32 v9, v65
	v_lshl_add_u64 v[0:1], v[0:1], 0, v[8:9]
	s_mov_b64 s[12:13], 0x1000
	v_lshl_add_u64 v[4:5], v[0:1], 0, s[12:13]
	v_add_co_u32_e32 v0, vcc, 0x1000, v0
	v_and_b32_e32 v9, 63, v11
	s_nop 0
	v_addc_co_u32_e32 v1, vcc, 0, v1, vcc
	global_load_dwordx4 v[0:3], v[0:1], off
	s_nop 0
	global_load_dwordx4 v[4:7], v[4:5], off offset:64
	v_cmp_gt_u32_e32 vcc, 32, v9
	v_mov_b32_e32 v79, 0
	v_mov_b32_e32 v80, 0
	v_mov_b32_e32 v81, 0
	s_and_saveexec_b64 s[12:13], vcc
	s_cbranch_execz .LBB0_986
	s_load_dwordx2 s[16:17], s[0:1], 0xc0
	s_lshl_b32 s18, s45, 7
	s_ashr_i32 s19, s18, 31
	s_lshl_b64 s[18:19], s[18:19], 2
	v_lshlrev_b32_e32 v9, 2, v9
	s_waitcnt lgkmcnt(0)
	s_add_u32 s16, s16, s18
	s_addc_u32 s17, s17, s19
	global_load_dword v13, v9, s[16:17]
	global_load_dword v15, v9, s[16:17] offset:128
	global_load_dword v12, v9, s[16:17] offset:256
	global_load_dword v14, v9, s[16:17] offset:384
	s_waitcnt vmcnt(0)
	v_mul_f32_e32 v80, v12, v14
	v_mul_f32_e32 v81, v13, v15
.LBB0_986:
	s_or_b64 exec, exec, s[12:13]
	s_waitcnt vmcnt(0)
	v_lshlrev_b32_e32 v12, 16, v0
	v_and_b32_e32 v13, 0xffff0000, v0
	s_mov_b32 s12, 0x3e8293ee
	v_lshlrev_b32_e32 v0, 16, v1
	v_and_b32_e32 v1, 0xffff0000, v1
	v_mul_f32_e32 v14, s12, v0
	v_mul_f32_e32 v15, s12, v1
	v_lshlrev_b32_e32 v0, 16, v2
	v_and_b32_e32 v1, 0xffff0000, v2
	v_mul_f32_e32 v12, s12, v12
	v_mul_f32_e32 v13, s12, v13
	v_mul_f32_e32 v16, s12, v0
	v_mul_f32_e32 v17, s12, v1
	v_lshlrev_b32_e32 v0, 16, v3
	v_and_b32_e32 v1, 0xffff0000, v3
	v_mul_f32_e32 v18, s12, v0
	v_mul_f32_e32 v19, s12, v1
	v_cvt_pk_bf16_f32 v0, v12, v13
	v_lshlrev_b32_e32 v12, 16, v4
	v_and_b32_e32 v13, 0xffff0000, v4
	v_lshlrev_b32_e32 v4, 16, v5
	v_and_b32_e32 v5, 0xffff0000, v5
	v_cvt_pk_bf16_f32 v1, v14, v15
	v_mul_f32_e32 v14, s12, v4
	v_mul_f32_e32 v15, s12, v5
	v_lshlrev_b32_e32 v4, 16, v6
	v_and_b32_e32 v5, 0xffff0000, v6
	v_lshlrev_b32_e32 v9, 4, v11
	v_add_u32_e32 v20, 0x200, v11
	v_cvt_pk_bf16_f32 v2, v16, v17
	v_mul_f32_e32 v12, s12, v12
	v_mul_f32_e32 v13, s12, v13
	v_mul_f32_e32 v16, s12, v4
	v_mul_f32_e32 v17, s12, v5
	v_lshlrev_b32_e32 v4, 16, v7
	v_and_b32_e32 v5, 0xffff0000, v7
	v_and_b32_e32 v64, 0x70, v9
	v_ashrrev_i32_e32 v9, 3, v11
	v_ashrrev_i32_e32 v45, 3, v20
	v_cvt_pk_bf16_f32 v3, v18, v19
	v_mul_f32_e32 v18, s12, v4
	v_mul_f32_e32 v19, s12, v5
	v_cvt_pk_bf16_f32 v4, v12, v13
	v_lshl_add_u64 v[36:37], s[10:11], 0, v[64:65]
	v_add_u32_e32 v12, s14, v9
	v_add_u32_e32 v20, s14, v45
	s_bitset1_b32 s14, 7
	v_cvt_pk_bf16_f32 v6, v16, v17
	v_mad_i64_i32 v[16:17], s[10:11], v12, s93, v[36:37]
	s_or_b32 s96, s8, 0x1200
	v_add_u32_e32 v28, s14, v9
	v_lshl_add_u64 v[12:13], v[16:17], 0, s[96:97]
	s_or_b32 s10, s8, 0x1400
	s_mov_b32 s11, s97
	v_mad_i64_i32 v[24:25], s[12:13], v20, s93, v[36:37]
	v_mad_i64_i32 v[32:33], s[12:13], v28, s93, v[36:37]
	v_cvt_pk_bf16_f32 v5, v14, v15
	global_load_dwordx4 v[12:15], v[12:13], off
	v_lshl_add_u64 v[16:17], v[16:17], 0, s[10:11]
	v_lshl_add_u64 v[20:21], v[24:25], 0, s[96:97]
	v_lshl_add_u64 v[28:29], v[32:33], 0, s[96:97]
	v_add_u32_e32 v38, s14, v45
	v_cvt_pk_bf16_f32 v7, v18, v19
	global_load_dwordx4 v[16:19], v[16:17], off
	v_lshl_add_u64 v[24:25], v[24:25], 0, s[10:11]
	global_load_dwordx4 v[20:23], v[20:21], off
	v_lshl_add_u64 v[32:33], v[32:33], 0, s[10:11]
	global_load_dwordx4 v[28:31], v[28:29], off
	v_mad_i64_i32 v[40:41], s[12:13], v38, s93, v[36:37]
	global_load_dwordx4 v[24:27], v[24:25], off
	v_lshl_add_u64 v[36:37], v[40:41], 0, s[96:97]
	global_load_dwordx4 v[32:35], v[32:33], off
	v_lshl_add_u64 v[40:41], v[40:41], 0, s[10:11]
	global_load_dwordx4 v[36:39], v[36:37], off
	v_add_u32_e32 v44, 0, v64
	global_load_dwordx4 v[40:43], v[40:41], off
	v_mad_u64_u32 v[46:47], s[10:11], v9, s94, v[44:45]
	s_barrier
	v_add_u32_e32 v54, 0, v8
	v_mad_u32_u24 v8, v10, s94, v54
	v_readlane_b32 s12, v255, 21
	v_readlane_b32 s14, v255, 23
	v_readlane_b32 s15, v255, 24
	v_readlane_b32 s13, v255, 22
	s_mov_b32 s14, s12
	s_mov_b32 s15, s12
	s_mov_b32 s13, s12
	s_mov_b32 s16, s12
	v_writelane_b32 v255, s16, 21
	s_cmp_eq_u64 exec, 0
	s_waitcnt vmcnt(7)
	ds_write_b128 v46, v[12:15]
	s_waitcnt vmcnt(6)
	ds_write_b128 v46, v[16:19] offset:18432
	v_mad_u64_u32 v[12:13], s[10:11], v45, s94, v[44:45]
	s_waitcnt vmcnt(5)
	ds_write_b128 v12, v[20:23]
	s_waitcnt vmcnt(3)
	ds_write_b128 v12, v[24:27] offset:18432
	s_waitcnt lgkmcnt(0)
	s_barrier
	ds_write_b128 v46, v[28:31] offset:36864
	s_waitcnt vmcnt(2)
	ds_write_b128 v46, v[32:35] offset:55296
	s_waitcnt vmcnt(1)
	ds_write_b128 v12, v[36:39] offset:36864
	s_waitcnt vmcnt(0)
	ds_write_b128 v12, v[40:43] offset:55296
	ds_read_b128 v[12:15], v8
	ds_read_b128 v[16:19], v8 offset:64
	v_mov_b64_e32 v[30:31], s[14:15]
	v_mov_b64_e32 v[28:29], s[12:13]
	v_writelane_b32 v255, s17, 22
	v_writelane_b32 v255, s18, 23
	s_waitcnt lgkmcnt(1)
	v_mfma_f32_16x16x32_bf16 v[44:47], v[12:15], v[0:3], v[28:31]
	ds_read_b128 v[12:15], v8 offset:2304
	ds_read_b128 v[20:23], v8 offset:2368
	v_writelane_b32 v255, s19, 24
	s_waitcnt lgkmcnt(1)
	v_mfma_f32_16x16x32_bf16 v[48:51], v[12:15], v[0:3], v[28:31]
	ds_read_b128 v[12:15], v8 offset:4608
	ds_read_b128 v[24:27], v8 offset:4672
	s_waitcnt lgkmcnt(1)
	v_mfma_f32_16x16x32_bf16 v[32:35], v[12:15], v[0:3], v[28:31]
	ds_read_b128 v[12:15], v8 offset:6912
	ds_read_b128 v[40:43], v8 offset:6976
	v_mfma_f32_16x16x32_bf16 v[16:19], v[16:19], v[4:7], v[28:31]
	v_mfma_f32_16x16x32_bf16 v[20:23], v[20:23], v[4:7], v[28:31]
	s_waitcnt lgkmcnt(2)
	v_mfma_f32_16x16x32_bf16 v[24:27], v[24:27], v[4:7], v[28:31]
	s_waitcnt lgkmcnt(1)
	v_mfma_f32_16x16x32_bf16 v[36:39], v[12:15], v[0:3], v[28:31]
	v_mov_b32_e32 v12, 0
	s_waitcnt lgkmcnt(0)
	v_mfma_f32_16x16x32_bf16 v[28:31], v[40:43], v[4:7], v[28:31]
	s_cbranch_scc1 .LBB0_988
	v_max_f32_e32 v8, v45, v45
	v_max_f32_e32 v9, v44, v44
	v_max_f32_e32 v8, v9, v8
	v_max3_f32 v8, v8, v46, v47
	v_max3_f32 v8, v8, v48, v49
	v_max3_f32 v8, v8, v50, v51
	v_max3_f32 v8, v8, v32, v33
	v_max3_f32 v8, v8, v34, v35
	v_max3_f32 v8, v8, v36, v37
	v_max3_f32 v8, v8, v38, v39
	v_mov_b32_e32 v9, v8
	s_nop 1
	v_permlane16_swap_b32_e32 v8, v9
	v_max_f32_e32 v9, v9, v9
	v_max_f32_e32 v8, v8, v8
	v_max_f32_e32 v8, v8, v9
	v_mov_b32_e32 v9, v8
	s_nop 1
	v_permlane32_swap_b32_e32 v8, v9
	v_max_f32_e32 v9, v9, v9
	v_max_f32_e32 v8, v8, v8
	v_max_f32_e32 v8, v8, v9
	v_exp_f32_e64 v9, -v8
	v_add_f32_e32 v79, 0, v8
	v_mul_f32_e32 v12, 0, v9
	v_sub_f32_e32 v44, v44, v8
	v_sub_f32_e32 v45, v45, v8
	v_sub_f32_e32 v46, v46, v8
	v_sub_f32_e32 v47, v47, v8
	v_sub_f32_e32 v48, v48, v8
	v_sub_f32_e32 v49, v49, v8
	v_sub_f32_e32 v50, v50, v8
	v_sub_f32_e32 v51, v51, v8
	v_sub_f32_e32 v32, v32, v8
	v_sub_f32_e32 v33, v33, v8
	v_sub_f32_e32 v34, v34, v8
	v_sub_f32_e32 v35, v35, v8
	v_sub_f32_e32 v36, v36, v8
	v_sub_f32_e32 v37, v37, v8
	v_sub_f32_e32 v38, v38, v8
	v_sub_f32_e32 v39, v39, v8
.LBB0_988:
	s_cmp_eq_u64 exec, 0
	s_cbranch_scc1 .LBB0_990
	v_max_f32_e32 v8, v17, v17
	v_max_f32_e32 v9, v16, v16
	v_max_f32_e32 v8, v9, v8
	v_max3_f32 v8, v8, v18, v19
	v_max3_f32 v8, v8, v20, v21
	v_max3_f32 v8, v8, v22, v23
	v_max3_f32 v8, v8, v24, v25
	v_max3_f32 v8, v8, v26, v27
	v_max3_f32 v8, v8, v28, v29
	v_max3_f32 v8, v8, v30, v31
	v_mov_b32_e32 v9, v8
	s_nop 1
	v_permlane16_swap_b32_e32 v8, v9
	v_max_f32_e32 v9, v9, v9
	v_max_f32_e32 v8, v8, v8
	v_max_f32_e32 v8, v8, v9
	v_mov_b32_e32 v9, v8
	s_nop 1
	v_permlane32_swap_b32_e32 v8, v9
	v_max_f32_e32 v9, v9, v9
	v_max_f32_e32 v8, v8, v8
	v_max_f32_e32 v14, v8, v9
	v_exp_f32_e64 v8, -v14
	v_add_f32_e32 v84, 0, v14
	v_sub_f32_e32 v16, v16, v14
	v_sub_f32_e32 v17, v17, v14
	v_sub_f32_e32 v18, v18, v14
	v_sub_f32_e32 v19, v19, v14
	v_mul_f32_e32 v8, 0, v8
	v_sub_f32_e32 v20, v20, v14
	v_sub_f32_e32 v21, v21, v14
	v_sub_f32_e32 v22, v22, v14
	v_sub_f32_e32 v23, v23, v14
	v_sub_f32_e32 v24, v24, v14
	v_sub_f32_e32 v25, v25, v14
	v_sub_f32_e32 v26, v26, v14
	v_sub_f32_e32 v27, v27, v14
	v_sub_f32_e32 v28, v28, v14
	v_sub_f32_e32 v29, v29, v14
	v_sub_f32_e32 v30, v30, v14
	v_sub_f32_e32 v31, v31, v14
	v_xor_b32_e32 v42, 0x80000000, v84
	s_branch .LBB0_991

.LBB0_991:
	v_exp_f32_e32 v40, v44
	v_exp_f32_e32 v41, v45
	v_exp_f32_e32 v46, v46
	v_exp_f32_e32 v47, v47
	v_bfe_u32 v9, v11, 4, 2
	v_add_f32_e32 v11, 0, v40
	v_exp_f32_e32 v48, v48
	v_add_f32_e32 v11, v41, v11
	v_exp_f32_e32 v49, v49
	v_add_f32_e32 v11, v46, v11
	v_exp_f32_e32 v50, v50
	v_add_f32_e32 v11, v47, v11
	v_exp_f32_e32 v51, v51
	v_add_f32_e32 v11, v48, v11
	v_exp_f32_e32 v32, v32
	v_lshlrev_b32_e32 v64, 2, v9
	v_lshrrev_b32_e32 v9, 2, v10
	v_mul_u32_u24_e32 v55, 0x90, v10
	v_add_f32_e32 v11, v49, v11
	v_exp_f32_e32 v33, v33
	v_or_b32_e32 v9, v64, v9
	v_lshlrev_b32_e32 v10, 3, v10
	v_add_f32_e32 v11, v50, v11
	v_exp_f32_e32 v34, v34
	v_and_b32_e32 v10, 24, v10
	v_mul_u32_u24_e32 v9, 0x90, v9
	v_add_f32_e32 v11, v51, v11
	v_exp_f32_e32 v35, v35
	v_add3_u32 v82, 0, v10, v9
	v_add_f32_e32 v11, v32, v11
	v_exp_f32_e32 v36, v36
	v_exp_f32_e32 v92, v24
	v_exp_f32_e32 v93, v25
	v_exp_f32_e32 v94, v26
	v_exp_f32_e32 v95, v27
	v_exp_f32_e32 v96, v28
	v_exp_f32_e32 v97, v29
	v_exp_f32_e32 v98, v30
	v_exp_f32_e32 v99, v31
	ds_read_b64_tr_b16 v[26:27], v82 offset:20736
	ds_read_b64_tr_b16 v[24:25], v82 offset:18432
	ds_read_b64_tr_b16 v[28:29], v82 offset:18464
	ds_read_b64_tr_b16 v[30:31], v82 offset:20768
	v_add_f32_e32 v11, v33, v11
	v_exp_f32_e32 v37, v37
	v_add_f32_e32 v11, v34, v11
	v_exp_f32_e32 v38, v38
	v_add_f32_e32 v11, v35, v11
	v_exp_f32_e32 v39, v39
	v_add_f32_e32 v11, v36, v11
	v_exp_f32_e32 v63, v16
	v_exp_f32_e32 v85, v17
	v_exp_f32_e32 v86, v18
	v_exp_f32_e32 v87, v19
	v_exp_f32_e32 v88, v20
	v_exp_f32_e32 v89, v21
	v_exp_f32_e32 v90, v22
	v_exp_f32_e32 v91, v23
	v_add_f32_e32 v11, v37, v11
	v_add_f32_e32 v11, v38, v11
	v_add_f32_e32 v11, v39, v11
	v_mov_b32_e32 v13, v12
	v_mov_b32_e32 v14, v12
	v_mov_b32_e32 v15, v12
	v_add_f32_e32 v62, v12, v11
	v_mov_b32_e32 v9, v8
	v_mov_b32_e32 v10, v8
	v_mov_b32_e32 v11, v8
	v_cvt_pk_bf16_f32 v16, v40, v41
	v_cvt_pk_bf16_f32 v17, v46, v47
	v_cvt_pk_bf16_f32 v18, v48, v49
	v_cvt_pk_bf16_f32 v19, v50, v51
	v_cvt_pk_bf16_f32 v20, v63, v85
	v_cvt_pk_bf16_f32 v21, v86, v87
	v_cvt_pk_bf16_f32 v22, v88, v89
	v_cvt_pk_bf16_f32 v23, v90, v91
	v_cvt_pk_bf16_f32 v48, v36, v37
	v_cvt_pk_bf16_f32 v49, v38, v39
	s_waitcnt lgkmcnt(0)
	v_mfma_f32_16x16x32_bf16 v[36:39], v[28:31], v[16:19], v[12:15]
	v_cvt_pk_bf16_f32 v46, v32, v33
	v_cvt_pk_bf16_f32 v47, v34, v35
	v_cvt_pk_bf16_f32 v50, v92, v93
	v_mfma_f32_16x16x32_bf16 v[56:59], v[28:31], v[20:23], v[8:11]
	ds_read_b64_tr_b16 v[28:29], v82 offset:18496
	ds_read_b64_tr_b16 v[30:31], v82 offset:20800
	v_cvt_pk_bf16_f32 v51, v94, v95
	v_cvt_pk_bf16_f32 v52, v96, v97
	s_waitcnt lgkmcnt(0)
	v_mfma_f32_16x16x32_bf16 v[66:69], v[28:31], v[16:19], v[12:15]
	v_cvt_pk_bf16_f32 v53, v98, v99
	v_add_u32_e32 v83, v54, v55
	v_mov_b32_e32 v43, v42
	v_mfma_f32_16x16x32_bf16 v[70:73], v[28:31], v[20:23], v[8:11]
	ds_read_b64_tr_b16 v[28:29], v82 offset:18528
	ds_read_b64_tr_b16 v[30:31], v82 offset:20832
	v_mov_b32_e32 v44, v42
	v_mov_b32_e32 v45, v42
	v_mfma_f32_16x16x32_bf16 v[32:35], v[24:27], v[16:19], v[12:15]
	s_waitcnt lgkmcnt(0)
	v_mfma_f32_16x16x32_bf16 v[12:15], v[28:31], v[16:19], v[12:15]
	ds_read_b64_tr_b16 v[16:17], v82 offset:23040
	ds_read_b64_tr_b16 v[18:19], v82 offset:25344
	v_mfma_f32_16x16x32_bf16 v[24:27], v[24:27], v[20:23], v[8:11]
	v_mfma_f32_16x16x32_bf16 v[74:77], v[28:31], v[20:23], v[8:11]
	s_waitcnt lgkmcnt(0)
	v_mfma_f32_16x16x32_bf16 v[30:33], v[16:19], v[46:49], v[32:35]
	v_mfma_f32_16x16x32_bf16 v[26:29], v[16:19], v[50:53], v[24:27]
	ds_read_b64_tr_b16 v[16:17], v82 offset:23072
	ds_read_b64_tr_b16 v[18:19], v82 offset:25376
	s_waitcnt lgkmcnt(0)
	v_mfma_f32_16x16x32_bf16 v[38:41], v[16:19], v[46:49], v[36:39]
	v_mfma_f32_16x16x32_bf16 v[34:37], v[16:19], v[50:53], v[56:59]
	ds_read_b64_tr_b16 v[16:17], v82 offset:23104
	ds_read_b64_tr_b16 v[18:19], v82 offset:25408
	s_nop 0
	ds_read_b64_tr_b16 v[56:57], v82 offset:23136
	ds_read_b64_tr_b16 v[58:59], v82 offset:25440
	s_waitcnt lgkmcnt(2)
	v_mfma_f32_16x16x32_bf16 v[22:25], v[16:19], v[46:49], v[66:69]
	v_mfma_f32_16x16x32_bf16 v[18:21], v[16:19], v[50:53], v[70:73]
	s_waitcnt lgkmcnt(0)
	v_mfma_f32_16x16x32_bf16 v[14:17], v[56:59], v[46:49], v[12:15]
	v_mfma_f32_16x16x32_bf16 v[10:13], v[56:59], v[50:53], v[74:77]
	ds_read_b128 v[46:49], v83 offset:9216
	ds_read_b128 v[50:53], v83 offset:9280
	s_nop 0
	v_xor_b32_e32 v74, 0x80000000, v79
	v_mov_b32_e32 v75, v74
	v_mov_b32_e32 v76, v74
	v_mov_b32_e32 v77, v74
	s_waitcnt lgkmcnt(1)
	s_nop 0
	v_mfma_f32_16x16x32_bf16 v[58:61], v[46:49], v[0:3], v[74:77]
	s_waitcnt lgkmcnt(0)
	v_mfma_f32_16x16x32_bf16 v[46:49], v[50:53], v[4:7], v[42:45]
	ds_read_b128 v[50:53], v83 offset:11520
	ds_read_b128 v[54:57], v83 offset:11584
	s_nop 3
	v_max3_f32 v9, v60, v58, v59
	s_waitcnt lgkmcnt(1)
	v_mfma_f32_16x16x32_bf16 v[66:69], v[50:53], v[0:3], v[74:77]
	s_waitcnt lgkmcnt(0)
	v_mfma_f32_16x16x32_bf16 v[50:53], v[54:57], v[4:7], v[42:45]
	ds_read_b128 v[54:57], v83 offset:13824
	ds_read_b128 v[100:103], v83 offset:13888
	s_nop 3
	v_max3_f32 v9, v61, v9, v66
	v_max3_f32 v9, v68, v67, v9
	s_waitcnt lgkmcnt(1)
	v_mfma_f32_16x16x32_bf16 v[70:73], v[54:57], v[0:3], v[74:77]
	s_waitcnt lgkmcnt(0)
	v_mfma_f32_16x16x32_bf16 v[54:57], v[100:103], v[4:7], v[42:45]
	ds_read_b128 v[100:103], v83 offset:16128
	ds_read_b128 v[104:107], v83 offset:16192
	s_nop 3
	v_max3_f32 v9, v70, v69, v9
	v_max3_f32 v9, v72, v71, v9
	s_waitcnt lgkmcnt(1)
	v_mfma_f32_16x16x32_bf16 v[74:77], v[100:103], v[0:3], v[74:77]
	s_waitcnt lgkmcnt(0)
	v_mfma_f32_16x16x32_bf16 v[42:45], v[104:107], v[4:7], v[42:45]
	s_nop 5
	v_max3_f32 v9, v74, v73, v9
	v_max3_f32 v9, v76, v75, v9
	v_max_f32_e32 v100, v77, v77
	v_max_f32_e32 v9, v100, v9
	v_cmp_lt_f32_e32 vcc, s52, v9
	s_cbranch_vccz .LBB0_993
	v_max_f32_e32 v9, v59, v59
	v_max_f32_e32 v100, v58, v58
	v_max_f32_e32 v9, v100, v9
	v_max3_f32 v9, v9, v60, v61
	v_max3_f32 v9, v9, v66, v67
	v_max3_f32 v9, v9, v68, v69
	v_max3_f32 v9, v9, v70, v71
	v_max3_f32 v9, v9, v72, v73
	v_max3_f32 v9, v9, v74, v75
	v_max3_f32 v9, v9, v76, v77
	v_mov_b32_e32 v100, v9
	s_nop 1
	v_permlane16_swap_b32_e32 v9, v100
	v_max_f32_e32 v100, v100, v100
	v_max_f32_e32 v9, v9, v9
	v_max_f32_e32 v9, v9, v100
	v_mov_b32_e32 v100, v9
	s_nop 1
	v_permlane32_swap_b32_e32 v9, v100
	v_max_f32_e32 v100, v100, v100
	v_max_f32_e32 v9, v9, v9
	v_max_f32_e32 v9, v9, v100
	v_cmp_lt_f32_e32 vcc, s52, v9
	s_nop 1
	v_cndmask_b32_e32 v100, 0, v9, vcc
	v_exp_f32_e64 v102, -v100
	v_add_f32_e32 v79, v79, v100
	v_sub_f32_e32 v58, v58, v100
	v_sub_f32_e32 v59, v59, v100
	v_sub_f32_e32 v60, v60, v100
	v_sub_f32_e32 v61, v61, v100
	v_mul_f32_e32 v62, v62, v102
	v_sub_f32_e32 v66, v66, v100
	v_sub_f32_e32 v67, v67, v100
	v_sub_f32_e32 v68, v68, v100
	v_sub_f32_e32 v69, v69, v100
	v_sub_f32_e32 v70, v70, v100
	v_sub_f32_e32 v71, v71, v100
	v_sub_f32_e32 v72, v72, v100
	v_sub_f32_e32 v73, v73, v100
	v_sub_f32_e32 v74, v74, v100
	v_sub_f32_e32 v75, v75, v100
	v_sub_f32_e32 v76, v76, v100
	v_sub_f32_e32 v77, v77, v100
	v_mul_f32_e32 v16, v16, v102
	v_mul_f32_e32 v17, v17, v102
	v_mul_f32_e32 v14, v14, v102
	v_mul_f32_e32 v15, v15, v102
	v_mul_f32_e32 v24, v24, v102
	v_mul_f32_e32 v25, v25, v102
	v_mul_f32_e32 v22, v22, v102
	v_mul_f32_e32 v23, v23, v102
	v_mul_f32_e32 v40, v40, v102
	v_mul_f32_e32 v41, v41, v102
	v_mul_f32_e32 v38, v38, v102
	v_mul_f32_e32 v39, v39, v102
	v_mul_f32_e32 v32, v32, v102
	v_mul_f32_e32 v33, v33, v102
	v_mul_f32_e32 v30, v30, v102
	v_mul_f32_e32 v31, v31, v102
.LBB0_993:
	v_add_f32_e32 v9, 0, v63
	v_add_f32_e32 v9, v85, v9
	v_add_f32_e32 v9, v86, v9
	v_add_f32_e32 v9, v87, v9
	v_add_f32_e32 v9, v88, v9
	v_add_f32_e32 v9, v89, v9
	v_add_f32_e32 v9, v90, v9
	v_add_f32_e32 v9, v91, v9
	v_add_f32_e32 v9, v92, v9
	v_add_f32_e32 v9, v93, v9
	v_add_f32_e32 v9, v94, v9
	v_add_f32_e32 v9, v95, v9
	v_add_f32_e32 v9, v96, v9
	v_add_f32_e32 v9, v97, v9
	v_add_f32_e32 v9, v98, v9
	v_add_f32_e32 v9, v99, v9
	v_add_f32_e32 v86, v8, v9
	v_max3_f32 v8, v48, v46, v47
	v_max3_f32 v8, v49, v8, v50
	v_max3_f32 v8, v52, v51, v8
	v_max3_f32 v8, v54, v53, v8
	v_max3_f32 v8, v56, v55, v8
	v_max3_f32 v8, v42, v57, v8
	v_max3_f32 v8, v44, v43, v8
	v_max_f32_e32 v9, v45, v45
	v_max_f32_e32 v8, v9, v8
	v_cmp_lt_f32_e32 vcc, s52, v8
	s_cbranch_vccz .LBB0_995
	v_max_f32_e32 v8, v47, v47
	v_max_f32_e32 v9, v46, v46
	v_max_f32_e32 v8, v9, v8
	v_max3_f32 v8, v8, v48, v49
	v_max3_f32 v8, v8, v50, v51
	v_max3_f32 v8, v8, v52, v53
	v_max3_f32 v8, v8, v54, v55
	v_max3_f32 v8, v8, v56, v57
	v_max3_f32 v8, v8, v42, v43
	v_max3_f32 v8, v8, v44, v45
	v_mov_b32_e32 v9, v8
	s_nop 1
	v_permlane16_swap_b32_e32 v8, v9
	v_max_f32_e32 v9, v9, v9
	v_max_f32_e32 v8, v8, v8
	v_max_f32_e32 v8, v8, v9
	v_mov_b32_e32 v9, v8
	s_nop 1
	v_permlane32_swap_b32_e32 v8, v9
	v_max_f32_e32 v9, v9, v9
	v_max_f32_e32 v8, v8, v8
	v_max_f32_e32 v8, v8, v9
	v_cmp_lt_f32_e32 vcc, s52, v8
	s_nop 1
	v_cndmask_b32_e32 v8, 0, v8, vcc
	v_exp_f32_e64 v88, -v8
	v_add_f32_e32 v84, v84, v8
	v_sub_f32_e32 v46, v46, v8
	v_sub_f32_e32 v47, v47, v8
	v_sub_f32_e32 v48, v48, v8
	v_sub_f32_e32 v49, v49, v8
	v_mul_f32_e32 v86, v86, v88
	v_sub_f32_e32 v50, v50, v8
	v_sub_f32_e32 v51, v51, v8
	v_sub_f32_e32 v52, v52, v8
	v_sub_f32_e32 v53, v53, v8
	v_sub_f32_e32 v54, v54, v8
	v_sub_f32_e32 v55, v55, v8
	v_sub_f32_e32 v56, v56, v8
	v_sub_f32_e32 v57, v57, v8
	v_sub_f32_e32 v42, v42, v8
	v_sub_f32_e32 v43, v43, v8
	v_sub_f32_e32 v44, v44, v8
	v_sub_f32_e32 v45, v45, v8
	v_mul_f32_e32 v12, v12, v88
	v_mul_f32_e32 v13, v13, v88
	v_mul_f32_e32 v10, v10, v88
	v_mul_f32_e32 v11, v11, v88
	v_mul_f32_e32 v20, v20, v88
	v_mul_f32_e32 v21, v21, v88
	v_mul_f32_e32 v18, v18, v88
	v_mul_f32_e32 v19, v19, v88
	v_mul_f32_e32 v36, v36, v88
	v_mul_f32_e32 v37, v37, v88
	v_mul_f32_e32 v34, v34, v88
	v_mul_f32_e32 v35, v35, v88
	v_mul_f32_e32 v28, v28, v88
	v_mul_f32_e32 v29, v29, v88
	v_mul_f32_e32 v26, v26, v88
	v_mul_f32_e32 v27, v27, v88
.LBB0_995:
	v_exp_f32_e32 v8, v58
	v_exp_f32_e32 v58, v59
	v_exp_f32_e32 v59, v60
	v_exp_f32_e32 v60, v61
	v_add_f32_e32 v9, 0, v8
	v_exp_f32_e32 v61, v66
	v_add_f32_e32 v9, v58, v9
	v_exp_f32_e32 v63, v67
	v_add_f32_e32 v9, v59, v9
	v_exp_f32_e32 v66, v68
	v_add_f32_e32 v9, v60, v9
	v_exp_f32_e32 v67, v69
	v_add_f32_e32 v9, v61, v9
	v_exp_f32_e32 v68, v70
	v_add_f32_e32 v9, v63, v9
	v_exp_f32_e32 v69, v71
	v_add_f32_e32 v9, v66, v9
	v_exp_f32_e32 v70, v72
	v_add_f32_e32 v9, v67, v9
	v_exp_f32_e32 v71, v73
	v_add_f32_e32 v9, v68, v9
	v_exp_f32_e32 v72, v74
	v_add_f32_e32 v9, v69, v9
	v_exp_f32_e32 v73, v75
	v_add_f32_e32 v9, v70, v9
	v_exp_f32_e32 v74, v76
	v_add_f32_e32 v9, v71, v9
	v_exp_f32_e32 v75, v77
	v_add_f32_e32 v9, v72, v9
	v_add_f32_e32 v9, v73, v9
	v_add_f32_e32 v9, v74, v9
	v_add_f32_e32 v9, v75, v9
	v_add_f32_e32 v85, v62, v9
	v_exp_f32_e32 v89, v48
	v_exp_f32_e32 v94, v53
	v_exp_f32_e32 v95, v54
	v_exp_f32_e32 v96, v55
	v_cvt_pk_bf16_f32 v53, v59, v60
	v_cvt_pk_bf16_f32 v54, v61, v63
	v_cvt_pk_bf16_f32 v55, v66, v67
	v_cvt_pk_bf16_f32 v48, v68, v69
	ds_read_b64_tr_b16 v[62:63], v82 offset:29952
	ds_read_b64_tr_b16 v[60:61], v82 offset:27648
	ds_read_b64_tr_b16 v[66:67], v82 offset:27680
	ds_read_b64_tr_b16 v[68:69], v82 offset:29984
	v_exp_f32_e32 v87, v46
	v_exp_f32_e32 v88, v47
	v_exp_f32_e32 v90, v49
	v_exp_f32_e32 v91, v50
	v_exp_f32_e32 v92, v51
	v_exp_f32_e32 v93, v52
	v_exp_f32_e32 v97, v56
	v_exp_f32_e32 v98, v57
	v_cvt_pk_bf16_f32 v52, v8, v58
	v_cvt_pk_bf16_f32 v56, v87, v88
	v_cvt_pk_bf16_f32 v57, v89, v90
	v_cvt_pk_bf16_f32 v58, v91, v92
	v_cvt_pk_bf16_f32 v59, v93, v94
	s_waitcnt lgkmcnt(2)
	v_mfma_f32_16x16x32_bf16 v[30:33], v[60:63], v[52:55], v[30:33]
	v_exp_f32_e32 v99, v42
	v_exp_f32_e32 v100, v43
	v_exp_f32_e32 v101, v44
	v_mfma_f32_16x16x32_bf16 v[26:29], v[60:63], v[56:59], v[26:29]
	v_exp_f32_e32 v102, v45
	v_cvt_pk_bf16_f32 v49, v70, v71
	v_cvt_pk_bf16_f32 v50, v72, v73
	s_waitcnt lgkmcnt(0)
	v_mfma_f32_16x16x32_bf16 v[60:63], v[66:69], v[56:59], v[34:37]
	s_nop 2
	ds_read_b64_tr_b16 v[34:35], v82 offset:27712
	ds_read_b64_tr_b16 v[36:37], v82 offset:30016
	v_cvt_pk_bf16_f32 v51, v74, v75
	v_cvt_pk_bf16_f32 v44, v95, v96
	s_waitcnt lgkmcnt(0)
	v_mfma_f32_16x16x32_bf16 v[22:25], v[34:37], v[52:55], v[22:25]
	v_cvt_pk_bf16_f32 v45, v97, v98
	v_cvt_pk_bf16_f32 v46, v99, v100
	v_cvt_pk_bf16_f32 v47, v101, v102
	v_mfma_f32_16x16x32_bf16 v[18:21], v[34:37], v[56:59], v[18:21]
	ds_read_b64_tr_b16 v[34:35], v82 offset:27744
	ds_read_b64_tr_b16 v[36:37], v82 offset:30048
	v_mfma_f32_16x16x32_bf16 v[38:41], v[66:69], v[52:55], v[38:41]
	s_waitcnt lgkmcnt(0)
	v_mfma_f32_16x16x32_bf16 v[14:17], v[34:37], v[52:55], v[14:17]
	ds_read_b64_tr_b16 v[52:53], v82 offset:32256
	ds_read_b64_tr_b16 v[54:55], v82 offset:34560
	v_mfma_f32_16x16x32_bf16 v[8:11], v[34:37], v[56:59], v[10:13]
	s_waitcnt lgkmcnt(0)
	v_mfma_f32_16x16x32_bf16 v[32:35], v[52:55], v[48:51], v[30:33]
	v_mfma_f32_16x16x32_bf16 v[28:31], v[52:55], v[44:47], v[26:29]
	ds_read_b64_tr_b16 v[52:53], v82 offset:32288
	ds_read_b64_tr_b16 v[54:55], v82 offset:34592
	s_waitcnt lgkmcnt(0)
	v_mfma_f32_16x16x32_bf16 v[40:43], v[52:55], v[48:51], v[38:41]
	v_mfma_f32_16x16x32_bf16 v[36:39], v[52:55], v[44:47], v[60:63]
	ds_read_b64_tr_b16 v[52:53], v82 offset:32320
	ds_read_b64_tr_b16 v[54:55], v82 offset:34624
	s_nop 0
	v_xor_b32_e32 v60, 0x80000000, v79
	s_waitcnt lgkmcnt(0)
	v_mfma_f32_16x16x32_bf16 v[24:27], v[52:55], v[48:51], v[22:25]
	v_mov_b32_e32 v61, v60
	v_mov_b32_e32 v62, v60
	v_mov_b32_e32 v63, v60
	v_mfma_f32_16x16x32_bf16 v[20:23], v[52:55], v[44:47], v[18:21]
	ds_read_b64_tr_b16 v[52:53], v82 offset:32352
	ds_read_b64_tr_b16 v[54:55], v82 offset:34656
	s_waitcnt lgkmcnt(0)
	s_barrier
	v_mfma_f32_16x16x32_bf16 v[12:15], v[52:55], v[48:51], v[14:17]
	v_mfma_f32_16x16x32_bf16 v[16:19], v[52:55], v[44:47], v[8:11]
	ds_read_b128 v[44:47], v83 offset:36864
	ds_read_b128 v[48:51], v83 offset:36928
	s_nop 0
	v_xor_b32_e32 v8, 0x80000000, v84
	v_mov_b32_e32 v9, v8
	v_mov_b32_e32 v10, v8
	v_mov_b32_e32 v11, v8
	s_waitcnt lgkmcnt(1)
	v_mfma_f32_16x16x32_bf16 v[56:59], v[44:47], v[0:3], v[60:63]
	s_waitcnt lgkmcnt(0)
	v_mfma_f32_16x16x32_bf16 v[44:47], v[48:51], v[4:7], v[8:11]
	ds_read_b128 v[48:51], v83 offset:39168
	ds_read_b128 v[52:55], v83 offset:39232
	s_waitcnt lgkmcnt(1)
	v_mfma_f32_16x16x32_bf16 v[66:69], v[48:51], v[0:3], v[60:63]
	s_waitcnt lgkmcnt(0)
	v_mfma_f32_16x16x32_bf16 v[48:51], v[52:55], v[4:7], v[8:11]
	ds_read_b128 v[52:55], v83 offset:41472
	ds_read_b128 v[74:77], v83 offset:41536
	s_waitcnt lgkmcnt(1)
	v_mfma_f32_16x16x32_bf16 v[70:73], v[52:55], v[0:3], v[60:63]
	s_waitcnt lgkmcnt(0)
	v_mfma_f32_16x16x32_bf16 v[52:55], v[74:77], v[4:7], v[8:11]
	ds_read_b128 v[74:77], v83 offset:43776
	ds_read_b128 v[104:107], v83 offset:43840
	s_waitcnt lgkmcnt(1)
	v_mfma_f32_16x16x32_bf16 v[74:77], v[74:77], v[0:3], v[60:63]
	s_waitcnt lgkmcnt(0)
	v_mfma_f32_16x16x32_bf16 v[60:63], v[104:107], v[4:7], v[8:11]
	s_nop 2
	v_max3_f32 v9, v58, v56, v57
	v_max3_f32 v9, v59, v9, v66
	v_max3_f32 v9, v68, v67, v9
	v_max3_f32 v9, v70, v69, v9
	v_max3_f32 v9, v72, v71, v9
	v_max3_f32 v9, v74, v73, v9
	v_max3_f32 v9, v76, v75, v9
	v_max_f32_e32 v10, v77, v77
	v_max_f32_e32 v9, v10, v9
	v_cmp_lt_f32_e32 vcc, s52, v9
	s_cbranch_vccz .LBB0_997
	v_max_f32_e32 v9, v57, v57
	v_max_f32_e32 v10, v56, v56
	v_max_f32_e32 v9, v10, v9
	v_max3_f32 v9, v9, v58, v59
	v_max3_f32 v9, v9, v66, v67
	v_max3_f32 v9, v9, v68, v69
	v_max3_f32 v9, v9, v70, v71
	v_max3_f32 v9, v9, v72, v73
	v_max3_f32 v9, v9, v74, v75
	v_max3_f32 v9, v9, v76, v77
	v_mov_b32_e32 v10, v9
	s_nop 1
	v_permlane16_swap_b32_e32 v9, v10
	v_max_f32_e32 v10, v10, v10
	v_max_f32_e32 v9, v9, v9
	v_max_f32_e32 v9, v9, v10
	v_mov_b32_e32 v10, v9
	s_nop 1
	v_permlane32_swap_b32_e32 v9, v10
	v_max_f32_e32 v10, v10, v10
	v_max_f32_e32 v9, v9, v9
	v_max_f32_e32 v9, v9, v10
	v_cmp_lt_f32_e32 vcc, s52, v9
	s_nop 1
	v_cndmask_b32_e32 v10, 0, v9, vcc
	v_exp_f32_e64 v104, -v10
	v_add_f32_e32 v79, v79, v10
	v_sub_f32_e32 v56, v56, v10
	v_sub_f32_e32 v57, v57, v10
	v_sub_f32_e32 v58, v58, v10
	v_sub_f32_e32 v59, v59, v10
	v_mul_f32_e32 v85, v85, v104
	v_sub_f32_e32 v66, v66, v10
	v_sub_f32_e32 v67, v67, v10
	v_sub_f32_e32 v68, v68, v10
	v_sub_f32_e32 v69, v69, v10
	v_sub_f32_e32 v70, v70, v10
	v_sub_f32_e32 v71, v71, v10
	v_sub_f32_e32 v72, v72, v10
	v_sub_f32_e32 v73, v73, v10
	v_sub_f32_e32 v74, v74, v10
	v_sub_f32_e32 v75, v75, v10
	v_sub_f32_e32 v76, v76, v10
	v_sub_f32_e32 v77, v77, v10
	v_mul_f32_e32 v14, v14, v104
	v_mul_f32_e32 v15, v15, v104
	v_mul_f32_e32 v12, v12, v104
	v_mul_f32_e32 v13, v13, v104
	v_mul_f32_e32 v26, v26, v104
	v_mul_f32_e32 v27, v27, v104
	v_mul_f32_e32 v24, v24, v104
	v_mul_f32_e32 v25, v25, v104
	v_mul_f32_e32 v42, v42, v104
	v_mul_f32_e32 v43, v43, v104
	v_mul_f32_e32 v40, v40, v104
	v_mul_f32_e32 v41, v41, v104
	v_mul_f32_e32 v34, v34, v104
	v_mul_f32_e32 v35, v35, v104
	v_mul_f32_e32 v32, v32, v104
	v_mul_f32_e32 v33, v33, v104
.LBB0_997:
	v_add_f32_e32 v9, 0, v87
	v_add_f32_e32 v9, v88, v9
	v_add_f32_e32 v9, v89, v9
	v_add_f32_e32 v9, v90, v9
	v_add_f32_e32 v9, v91, v9
	v_add_f32_e32 v9, v92, v9
	v_add_f32_e32 v9, v93, v9
	v_add_f32_e32 v9, v94, v9
	v_add_f32_e32 v9, v95, v9
	v_add_f32_e32 v9, v96, v9
	v_add_f32_e32 v9, v97, v9
	v_add_f32_e32 v9, v98, v9
	v_add_f32_e32 v9, v99, v9
	v_add_f32_e32 v9, v100, v9
	v_add_f32_e32 v9, v101, v9
	v_add_f32_e32 v9, v102, v9
	v_add_f32_e32 v86, v86, v9
	v_max3_f32 v9, v46, v44, v45
	v_max3_f32 v9, v47, v9, v48
	v_max3_f32 v9, v50, v49, v9
	v_max3_f32 v9, v52, v51, v9
	v_max3_f32 v9, v54, v53, v9
	v_max3_f32 v9, v60, v55, v9
	v_max3_f32 v9, v62, v61, v9
	v_max_f32_e32 v10, v63, v63
	v_max_f32_e32 v9, v10, v9
	v_cmp_lt_f32_e32 vcc, s52, v9
	s_cbranch_vccz .LBB0_999
	v_max_f32_e32 v8, v45, v45
	v_max_f32_e32 v9, v44, v44
	v_max_f32_e32 v8, v9, v8
	v_max3_f32 v8, v8, v46, v47
	v_max3_f32 v8, v8, v48, v49
	v_max3_f32 v8, v8, v50, v51
	v_max3_f32 v8, v8, v52, v53
	v_max3_f32 v8, v8, v54, v55
	v_max3_f32 v8, v8, v60, v61
	v_max3_f32 v8, v8, v62, v63
	v_mov_b32_e32 v9, v8
	s_nop 1
	v_permlane16_swap_b32_e32 v8, v9
	v_max_f32_e32 v9, v9, v9
	v_max_f32_e32 v8, v8, v8
	v_max_f32_e32 v8, v8, v9
	v_mov_b32_e32 v9, v8
	s_nop 1
	v_permlane32_swap_b32_e32 v8, v9
	v_max_f32_e32 v9, v9, v9
	v_max_f32_e32 v8, v8, v8
	v_max_f32_e32 v8, v8, v9
	v_cmp_lt_f32_e32 vcc, s52, v8
	s_nop 1
	v_cndmask_b32_e32 v8, 0, v8, vcc
	v_exp_f32_e64 v10, -v8
	v_add_f32_e32 v9, v84, v8
	v_sub_f32_e32 v44, v44, v8
	v_sub_f32_e32 v45, v45, v8
	v_sub_f32_e32 v46, v46, v8
	v_sub_f32_e32 v47, v47, v8
	v_mul_f32_e32 v86, v86, v10
	v_sub_f32_e32 v48, v48, v8
	v_sub_f32_e32 v49, v49, v8
	v_sub_f32_e32 v50, v50, v8
	v_sub_f32_e32 v51, v51, v8
	v_sub_f32_e32 v52, v52, v8
	v_sub_f32_e32 v53, v53, v8
	v_sub_f32_e32 v54, v54, v8
	v_sub_f32_e32 v55, v55, v8
	v_sub_f32_e32 v60, v60, v8
	v_sub_f32_e32 v61, v61, v8
	v_sub_f32_e32 v62, v62, v8
	v_sub_f32_e32 v63, v63, v8
	v_mul_f32_e32 v18, v18, v10
	v_mul_f32_e32 v19, v19, v10
	v_mul_f32_e32 v16, v16, v10
	v_mul_f32_e32 v17, v17, v10
	v_mul_f32_e32 v22, v22, v10
	v_mul_f32_e32 v23, v23, v10
	v_mul_f32_e32 v20, v20, v10
	v_mul_f32_e32 v21, v21, v10
	v_mul_f32_e32 v38, v38, v10
	v_mul_f32_e32 v39, v39, v10
	v_mul_f32_e32 v36, v36, v10
	v_mul_f32_e32 v37, v37, v10
	v_mul_f32_e32 v30, v30, v10
	v_mul_f32_e32 v31, v31, v10
	v_mul_f32_e32 v28, v28, v10
	v_mul_f32_e32 v29, v29, v10
	v_xor_b32_e32 v8, 0x80000000, v9
.LBB0_999:
	v_exp_f32_e32 v56, v56
	v_exp_f32_e32 v57, v57
	v_exp_f32_e32 v58, v58
	v_exp_f32_e32 v59, v59
	v_add_f32_e32 v9, 0, v56
	v_exp_f32_e32 v66, v66
	v_add_f32_e32 v9, v57, v9
	v_exp_f32_e32 v67, v67
	v_add_f32_e32 v9, v58, v9
	v_exp_f32_e32 v68, v68
	v_add_f32_e32 v9, v59, v9
	v_exp_f32_e32 v69, v69
	v_add_f32_e32 v9, v66, v9
	v_exp_f32_e32 v70, v70
	v_add_f32_e32 v9, v67, v9
	v_exp_f32_e32 v71, v71
	v_add_f32_e32 v9, v68, v9
	v_exp_f32_e32 v72, v72
	v_add_f32_e32 v9, v69, v9
	v_exp_f32_e32 v73, v73
	v_add_f32_e32 v9, v70, v9
	v_exp_f32_e32 v98, v74
	v_add_f32_e32 v9, v71, v9
	v_exp_f32_e32 v99, v75
	v_add_f32_e32 v9, v72, v9
	v_exp_f32_e32 v100, v76
	v_add_f32_e32 v9, v73, v9
	v_exp_f32_e32 v101, v77
	v_add_f32_e32 v9, v98, v9
	v_add_f32_e32 v9, v99, v9
	v_add_f32_e32 v9, v100, v9
	v_add_f32_e32 v9, v101, v9
	v_add_f32_e32 v74, v85, v9
	v_exp_f32_e32 v75, v44
	v_exp_f32_e32 v76, v45
	v_exp_f32_e32 v77, v46
	v_exp_f32_e32 v84, v47
	v_exp_f32_e32 v85, v48
	v_exp_f32_e32 v87, v49
	v_exp_f32_e32 v88, v50
	v_exp_f32_e32 v89, v51
	v_exp_f32_e32 v92, v54
	v_exp_f32_e32 v94, v60
	v_exp_f32_e32 v95, v61
	v_exp_f32_e32 v96, v62
	v_exp_f32_e32 v97, v63
	v_cvt_pk_bf16_f32 v54, v66, v67
	ds_read_b64_tr_b16 v[62:63], v82 offset:57600
	ds_read_b64_tr_b16 v[60:61], v82 offset:55296
	ds_read_b64_tr_b16 v[66:67], v82 offset:55328
	v_exp_f32_e32 v90, v52
	v_exp_f32_e32 v91, v53
	v_exp_f32_e32 v93, v55
	v_cvt_pk_bf16_f32 v52, v56, v57
	v_cvt_pk_bf16_f32 v53, v58, v59
	v_cvt_pk_bf16_f32 v55, v68, v69
	v_cvt_pk_bf16_f32 v56, v75, v76
	v_cvt_pk_bf16_f32 v57, v77, v84
	v_cvt_pk_bf16_f32 v58, v85, v87
	v_cvt_pk_bf16_f32 v59, v88, v89
	s_waitcnt lgkmcnt(1)
	v_mfma_f32_16x16x32_bf16 v[32:35], v[60:63], v[52:55], v[32:35]
	ds_read_b64_tr_b16 v[68:69], v82 offset:57632
	v_cvt_pk_bf16_f32 v44, v70, v71
	v_cvt_pk_bf16_f32 v45, v72, v73
	v_mfma_f32_16x16x32_bf16 v[28:31], v[60:63], v[56:59], v[28:31]
	ds_read_b64_tr_b16 v[60:61], v82 offset:55360
	ds_read_b64_tr_b16 v[62:63], v82 offset:57664
	v_cvt_pk_bf16_f32 v46, v98, v99
	v_cvt_pk_bf16_f32 v47, v100, v101
	s_waitcnt lgkmcnt(0)
	v_mfma_f32_16x16x32_bf16 v[24:27], v[60:63], v[52:55], v[24:27]
	v_cvt_pk_bf16_f32 v48, v90, v91
	v_cvt_pk_bf16_f32 v49, v92, v93
	v_cvt_pk_bf16_f32 v50, v94, v95
	v_mfma_f32_16x16x32_bf16 v[20:23], v[60:63], v[56:59], v[20:23]
	ds_read_b64_tr_b16 v[60:61], v82 offset:55392
	ds_read_b64_tr_b16 v[62:63], v82 offset:57696
	v_cvt_pk_bf16_f32 v51, v96, v97
	v_xor_b32_e32 v70, 0x80000000, v79
	v_mfma_f32_16x16x32_bf16 v[40:43], v[66:69], v[52:55], v[40:43]
	v_mov_b32_e32 v9, v8
	v_mov_b32_e32 v10, v8
	v_mov_b32_e32 v11, v8
	s_waitcnt lgkmcnt(0)
	v_mfma_f32_16x16x32_bf16 v[12:15], v[60:63], v[52:55], v[12:15]
	v_mov_b32_e32 v71, v70
	v_mov_b32_e32 v72, v70
	v_mov_b32_e32 v73, v70
	v_mfma_f32_16x16x32_bf16 v[52:55], v[60:63], v[56:59], v[16:19]
	s_nop 2
	ds_read_b64_tr_b16 v[16:17], v82 offset:59904
	ds_read_b64_tr_b16 v[18:19], v82 offset:62208
	s_waitcnt lgkmcnt(0)
	v_mfma_f32_16x16x32_bf16 v[32:35], v[16:19], v[44:47], v[32:35]
	v_mfma_f32_16x16x32_bf16 v[28:31], v[16:19], v[48:51], v[28:31]
	ds_read_b64_tr_b16 v[16:17], v82 offset:59936
	ds_read_b64_tr_b16 v[18:19], v82 offset:62240
	v_mfma_f32_16x16x32_bf16 v[36:39], v[66:69], v[56:59], v[36:39]
	s_waitcnt lgkmcnt(0)
	v_mfma_f32_16x16x32_bf16 v[40:43], v[16:19], v[44:47], v[40:43]
	v_mfma_f32_16x16x32_bf16 v[36:39], v[16:19], v[48:51], v[36:39]
	ds_read_b64_tr_b16 v[16:17], v82 offset:59968
	ds_read_b64_tr_b16 v[18:19], v82 offset:62272
	ds_read_b64_tr_b16 v[56:57], v82 offset:60000
	ds_read_b64_tr_b16 v[58:59], v82 offset:62304
	s_waitcnt lgkmcnt(2)
	v_mfma_f32_16x16x32_bf16 v[24:27], v[16:19], v[44:47], v[24:27]
	v_mfma_f32_16x16x32_bf16 v[20:23], v[16:19], v[48:51], v[20:23]
	s_waitcnt lgkmcnt(0)
	v_mfma_f32_16x16x32_bf16 v[16:19], v[56:59], v[44:47], v[12:15]
	v_mfma_f32_16x16x32_bf16 v[12:15], v[56:59], v[48:51], v[52:55]
	ds_read_b128 v[44:47], v83 offset:46080
	ds_read_b128 v[48:51], v83 offset:46144
	s_waitcnt lgkmcnt(1)
	v_mfma_f32_16x16x32_bf16 v[56:59], v[44:47], v[0:3], v[70:73]
	s_waitcnt lgkmcnt(0)
	v_mfma_f32_16x16x32_bf16 v[44:47], v[48:51], v[4:7], v[8:11]
	ds_read_b128 v[48:51], v83 offset:48384
	ds_read_b128 v[52:55], v83 offset:48448
	s_waitcnt lgkmcnt(1)
	v_mfma_f32_16x16x32_bf16 v[60:63], v[48:51], v[0:3], v[70:73]
	s_waitcnt lgkmcnt(0)
	v_mfma_f32_16x16x32_bf16 v[48:51], v[52:55], v[4:7], v[8:11]
	ds_read_b128 v[52:55], v83 offset:50688
	ds_read_b128 v[98:101], v83 offset:50752
	s_waitcnt lgkmcnt(1)
	v_mfma_f32_16x16x32_bf16 v[66:69], v[52:55], v[0:3], v[70:73]
	s_waitcnt lgkmcnt(0)
	v_mfma_f32_16x16x32_bf16 v[52:55], v[98:101], v[4:7], v[8:11]
	ds_read_b128 v[98:101], v83 offset:52992
	ds_read_b128 v[102:105], v83 offset:53056
	s_waitcnt lgkmcnt(1)
	v_mfma_f32_16x16x32_bf16 v[70:73], v[98:101], v[0:3], v[70:73]
	s_waitcnt lgkmcnt(0)
	v_mfma_f32_16x16x32_bf16 v[0:3], v[102:105], v[4:7], v[8:11]
	v_max3_f32 v4, v58, v56, v57
	v_max3_f32 v4, v59, v4, v60
	v_max3_f32 v4, v62, v61, v4
	v_max3_f32 v4, v66, v63, v4
	v_max3_f32 v4, v68, v67, v4
	s_nop 0
	v_max3_f32 v4, v70, v69, v4
	v_max3_f32 v4, v72, v71, v4
	v_max_f32_e32 v5, v73, v73
	v_max_f32_e32 v4, v5, v4
	v_cmp_lt_f32_e32 vcc, s52, v4
	s_cbranch_vccz .LBB0_1001
	v_max_f32_e32 v4, v57, v57
	v_max_f32_e32 v5, v56, v56
	v_max_f32_e32 v4, v5, v4
	v_max3_f32 v4, v4, v58, v59
	v_max3_f32 v4, v4, v60, v61
	v_max3_f32 v4, v4, v62, v63
	v_max3_f32 v4, v4, v66, v67
	v_max3_f32 v4, v4, v68, v69
	v_max3_f32 v4, v4, v70, v71
	v_max3_f32 v4, v4, v72, v73
	v_mov_b32_e32 v5, v4
	s_nop 1
	v_permlane16_swap_b32_e32 v4, v5
	v_max_f32_e32 v5, v5, v5
	v_max_f32_e32 v4, v4, v4
	v_max_f32_e32 v4, v4, v5
	v_mov_b32_e32 v5, v4
	s_nop 1
	v_permlane32_swap_b32_e32 v4, v5
	v_max_f32_e32 v5, v5, v5
	v_max_f32_e32 v4, v4, v4
	v_max_f32_e32 v4, v4, v5
	v_cmp_lt_f32_e32 vcc, s52, v4
	s_nop 1
	v_cndmask_b32_e32 v4, 0, v4, vcc
	v_exp_f32_e64 v6, -v4
	v_sub_f32_e32 v56, v56, v4
	v_sub_f32_e32 v57, v57, v4
	v_sub_f32_e32 v58, v58, v4
	v_sub_f32_e32 v59, v59, v4
	v_sub_f32_e32 v60, v60, v4
	v_sub_f32_e32 v61, v61, v4
	v_mul_f32_e32 v74, v74, v6
	v_sub_f32_e32 v62, v62, v4
	v_sub_f32_e32 v63, v63, v4
	v_sub_f32_e32 v66, v66, v4
	v_sub_f32_e32 v67, v67, v4
	v_sub_f32_e32 v68, v68, v4
	v_sub_f32_e32 v69, v69, v4
	v_sub_f32_e32 v70, v70, v4
	v_sub_f32_e32 v71, v71, v4
	v_sub_f32_e32 v72, v72, v4
	v_sub_f32_e32 v73, v73, v4
	v_mul_f32_e32 v18, v18, v6
	v_mul_f32_e32 v19, v19, v6
	v_mul_f32_e32 v16, v16, v6
	v_mul_f32_e32 v17, v17, v6
	v_mul_f32_e32 v26, v26, v6
	v_mul_f32_e32 v27, v27, v6
	v_mul_f32_e32 v24, v24, v6
	v_mul_f32_e32 v25, v25, v6
	v_mul_f32_e32 v42, v42, v6
	v_mul_f32_e32 v43, v43, v6
	v_mul_f32_e32 v40, v40, v6
	v_mul_f32_e32 v41, v41, v6
	v_mul_f32_e32 v34, v34, v6
	v_mul_f32_e32 v35, v35, v6
	v_mul_f32_e32 v32, v32, v6
	v_mul_f32_e32 v33, v33, v6
.LBB0_1001:
	v_add_f32_e32 v4, 0, v75
	v_add_f32_e32 v4, v76, v4
	v_add_f32_e32 v4, v77, v4
	v_add_f32_e32 v4, v84, v4
	v_add_f32_e32 v4, v85, v4
	v_add_f32_e32 v4, v87, v4
	v_add_f32_e32 v4, v88, v4
	v_add_f32_e32 v4, v89, v4
	v_add_f32_e32 v4, v90, v4
	v_max3_f32 v5, v46, v44, v45
	v_add_f32_e32 v4, v91, v4
	v_max3_f32 v5, v47, v5, v48
	v_add_f32_e32 v4, v92, v4
	v_max3_f32 v5, v50, v49, v5
	v_add_f32_e32 v4, v93, v4
	v_max3_f32 v5, v52, v51, v5
	v_add_f32_e32 v4, v94, v4
	v_max3_f32 v5, v54, v53, v5
	v_add_f32_e32 v4, v95, v4
	v_max3_f32 v5, v0, v55, v5
	v_add_f32_e32 v4, v96, v4
	v_max3_f32 v5, v2, v1, v5
	v_max_f32_e32 v6, v3, v3
	v_add_f32_e32 v4, v97, v4
	v_max_f32_e32 v5, v6, v5
	v_add_f32_e32 v4, v86, v4
	v_cmp_lt_f32_e32 vcc, s52, v5
	s_cbranch_vccz .LBB0_1003
	v_max_f32_e32 v5, v45, v45
	v_max_f32_e32 v6, v44, v44
	v_max_f32_e32 v5, v6, v5
	v_max3_f32 v5, v5, v46, v47
	v_max3_f32 v5, v5, v48, v49
	v_max3_f32 v5, v5, v50, v51
	v_max3_f32 v5, v5, v52, v53
	v_max3_f32 v5, v5, v54, v55
	v_max3_f32 v5, v5, v0, v1
	v_max3_f32 v5, v5, v2, v3
	v_mov_b32_e32 v6, v5
	s_nop 1
	v_permlane16_swap_b32_e32 v5, v6
	v_max_f32_e32 v6, v6, v6
	v_max_f32_e32 v5, v5, v5
	v_max_f32_e32 v5, v5, v6
	v_mov_b32_e32 v6, v5
	s_nop 1
	v_permlane32_swap_b32_e32 v5, v6
	v_max_f32_e32 v6, v6, v6
	v_max_f32_e32 v5, v5, v5
	v_max_f32_e32 v5, v5, v6
	v_cmp_lt_f32_e32 vcc, s52, v5
	s_nop 1
	v_cndmask_b32_e32 v6, 0, v5, vcc
	v_exp_f32_e64 v8, -v6
	v_sub_f32_e32 v44, v44, v6
	v_sub_f32_e32 v45, v45, v6
	v_sub_f32_e32 v46, v46, v6
	v_sub_f32_e32 v47, v47, v6
	v_sub_f32_e32 v48, v48, v6
	v_sub_f32_e32 v49, v49, v6
	v_mul_f32_e32 v4, v4, v8
	v_sub_f32_e32 v50, v50, v6
	v_sub_f32_e32 v51, v51, v6
	v_sub_f32_e32 v52, v52, v6
	v_sub_f32_e32 v53, v53, v6
	v_sub_f32_e32 v54, v54, v6
	v_sub_f32_e32 v55, v55, v6
	v_sub_f32_e32 v0, v0, v6
	v_sub_f32_e32 v1, v1, v6
	v_sub_f32_e32 v2, v2, v6
	v_sub_f32_e32 v3, v3, v6
	v_mul_f32_e32 v14, v14, v8
	v_mul_f32_e32 v15, v15, v8
	v_mul_f32_e32 v12, v12, v8
	v_mul_f32_e32 v13, v13, v8
	v_mul_f32_e32 v22, v22, v8
	v_mul_f32_e32 v23, v23, v8
	v_mul_f32_e32 v20, v20, v8
	v_mul_f32_e32 v21, v21, v8
	v_mul_f32_e32 v38, v38, v8
	v_mul_f32_e32 v39, v39, v8
	v_mul_f32_e32 v36, v36, v8
	v_mul_f32_e32 v37, v37, v8
	v_mul_f32_e32 v30, v30, v8
	v_mul_f32_e32 v31, v31, v8
	v_mul_f32_e32 v28, v28, v8
	v_mul_f32_e32 v29, v29, v8
.LBB0_1003:
	v_exp_f32_e32 v5, v56
	v_exp_f32_e32 v7, v57
	v_exp_f32_e32 v9, v58
	v_exp_f32_e32 v10, v59
	v_add_f32_e32 v6, 0, v5
	v_exp_f32_e32 v11, v60
	v_add_f32_e32 v6, v7, v6
	v_exp_f32_e32 v58, v61
	v_add_f32_e32 v6, v9, v6
	v_exp_f32_e32 v59, v62
	v_add_f32_e32 v6, v10, v6
	v_exp_f32_e32 v60, v63
	v_add_f32_e32 v6, v11, v6
	v_exp_f32_e32 v61, v66
	v_add_f32_e32 v6, v58, v6
	v_exp_f32_e32 v62, v67
	v_add_f32_e32 v6, v59, v6
	v_exp_f32_e32 v63, v68
	v_add_f32_e32 v6, v60, v6
	v_exp_f32_e32 v66, v69
	v_add_f32_e32 v6, v61, v6
	v_exp_f32_e32 v67, v70
	v_add_f32_e32 v6, v62, v6
	v_exp_f32_e32 v68, v71
	v_add_f32_e32 v6, v63, v6
	v_exp_f32_e32 v69, v72
	v_add_f32_e32 v6, v66, v6
	v_exp_f32_e32 v70, v73
	v_add_f32_e32 v6, v67, v6
	v_add_f32_e32 v6, v68, v6
	v_add_f32_e32 v6, v69, v6
	v_add_f32_e32 v6, v70, v6
	v_add_f32_e32 v56, v74, v6
	v_exp_f32_e32 v6, v44
	v_exp_f32_e32 v44, v45
	v_exp_f32_e32 v45, v46
	v_exp_f32_e32 v46, v47
	v_add_f32_e32 v8, 0, v6
	v_exp_f32_e32 v47, v48
	v_add_f32_e32 v8, v44, v8
	v_exp_f32_e32 v49, v49
	v_add_f32_e32 v8, v45, v8
	v_exp_f32_e32 v50, v50
	v_add_f32_e32 v8, v46, v8
	v_exp_f32_e32 v51, v51
	v_add_f32_e32 v8, v47, v8
	v_exp_f32_e32 v52, v52
	v_add_f32_e32 v8, v49, v8
	v_exp_f32_e32 v53, v53
	v_add_f32_e32 v8, v50, v8
	v_exp_f32_e32 v54, v54
	v_add_f32_e32 v8, v51, v8
	v_exp_f32_e32 v55, v55
	v_add_f32_e32 v8, v52, v8
	v_exp_f32_e32 v71, v0
	v_add_f32_e32 v8, v53, v8
	v_exp_f32_e32 v72, v1
	v_add_f32_e32 v8, v54, v8
	v_exp_f32_e32 v73, v2
	v_add_f32_e32 v8, v55, v8
	v_exp_f32_e32 v3, v3
	v_add_f32_e32 v0, v71, v8
	v_add_f32_e32 v0, v72, v0
	v_add_f32_e32 v0, v73, v0
	v_add_u32_e32 v57, 0xd800, v82
	v_add_f32_e32 v0, v3, v0
	v_add_f32_e32 v48, v4, v0
	v_cvt_pk_bf16_f32 v9, v9, v10
	v_cvt_pk_bf16_f32 v10, v11, v58
	v_cvt_pk_bf16_f32 v11, v59, v60
	v_cvt_pk_bf16_f32 v45, v45, v46
	v_cvt_pk_bf16_f32 v46, v47, v49
	v_cvt_pk_bf16_f32 v47, v50, v51
	v_cvt_pk_bf16_f32 v4, v61, v62
	v_cvt_pk_bf16_f32 v0, v52, v53
	ds_read_b64_tr_b16 v[52:53], v57 offset:11520
	ds_read_b64_tr_b16 v[60:61], v57 offset:11552
	ds_read_b64_tr_b16 v[50:51], v82 offset:64512
	ds_read_b64_tr_b16 v[58:59], v82 offset:64544
	v_cvt_pk_bf16_f32 v8, v5, v7
	v_cvt_pk_bf16_f32 v44, v6, v44
	v_cvt_pk_bf16_f32 v5, v63, v66
	s_waitcnt lgkmcnt(1)
	v_mfma_f32_16x16x32_bf16 v[32:35], v[50:53], v[8:11], v[32:35]
	v_cvt_pk_bf16_f32 v6, v67, v68
	v_cvt_pk_bf16_f32 v7, v69, v70
	v_cvt_pk_bf16_f32 v1, v54, v55
	v_mfma_f32_16x16x32_bf16 v[28:31], v[50:53], v[44:47], v[28:31]
	ds_read_b64_tr_b16 v[50:51], v82 offset:64576
	ds_read_b64_tr_b16 v[52:53], v57 offset:11584
	v_cvt_pk_bf16_f32 v2, v71, v72
	v_cvt_pk_bf16_f32 v3, v73, v3
	s_waitcnt lgkmcnt(2)
	v_mfma_f32_16x16x32_bf16 v[40:43], v[58:61], v[8:11], v[40:43]
	s_lshl_b32 s12, s45, 6
	s_ashr_i32 s13, s12, 31
	s_lshl_b64 s[12:13], s[12:13], 2
	v_mfma_f32_16x16x32_bf16 v[36:39], v[58:61], v[44:47], v[36:39]
	v_ashrrev_i32_e32 v79, 31, v78
	s_mov_b32 s9, s97
	s_waitcnt lgkmcnt(0)
	v_mfma_f32_16x16x32_bf16 v[58:61], v[50:53], v[8:11], v[24:27]
	v_mfma_f32_16x16x32_bf16 v[50:53], v[50:53], v[44:47], v[20:23]
	s_nop 2
	ds_read_b64_tr_b16 v[20:21], v82 offset:64608
	ds_read_b64_tr_b16 v[22:23], v57 offset:11616
	s_waitcnt lgkmcnt(0)
	v_mfma_f32_16x16x32_bf16 v[66:69], v[20:23], v[8:11], v[16:19]
	ds_read_b64_tr_b16 v[8:9], v57 offset:13824
	ds_read_b64_tr_b16 v[10:11], v57 offset:16128
	v_mfma_f32_16x16x32_bf16 v[44:47], v[20:23], v[44:47], v[12:15]
	s_nop 2
	ds_read_b64_tr_b16 v[12:13], v57 offset:13856
	ds_read_b64_tr_b16 v[14:15], v57 offset:16160
	s_waitcnt lgkmcnt(2)
	v_mfma_f32_16x16x32_bf16 v[16:19], v[8:11], v[4:7], v[32:35]
	v_mfma_f32_16x16x32_bf16 v[24:27], v[8:11], v[0:3], v[28:31]
	s_nop 2
	ds_read_b64_tr_b16 v[28:29], v57 offset:13888
	ds_read_b64_tr_b16 v[30:31], v57 offset:16192
	ds_read_b64_tr_b16 v[32:33], v57 offset:13920
	ds_read_b64_tr_b16 v[34:35], v57 offset:16224
	s_waitcnt lgkmcnt(0)
	v_mfma_f32_16x16x32_bf16 v[8:11], v[12:15], v[4:7], v[40:43]
	s_barrier
	s_load_dwordx2 s[10:11], s[0:1], 0xc8
	v_mfma_f32_16x16x32_bf16 v[12:15], v[12:15], v[0:3], v[36:39]
	s_waitcnt lgkmcnt(0)
	s_add_u32 s10, s10, s12
	v_mfma_f32_16x16x32_bf16 v[20:23], v[28:31], v[4:7], v[58:61]
	s_addc_u32 s11, s11, s13
	v_mfma_f32_16x16x32_bf16 v[28:31], v[28:31], v[0:3], v[50:53]
	v_mfma_f32_16x16x32_bf16 v[4:7], v[32:35], v[4:7], v[66:69]
	s_nop 1
	v_lshlrev_b64 v[52:53], 11, v[78:79]
	v_lshl_add_u64 v[52:53], s[6:7], 0, v[52:53]
	v_lshl_add_u64 v[52:53], v[52:53], 0, s[8:9]
	v_mfma_f32_16x16x32_bf16 v[0:3], v[32:35], v[0:3], v[44:47]
	v_mov_b32_e32 v32, v56
	s_nop 1
	v_permlane16_swap_b32_e32 v56, v32
	v_add_f32_e32 v32, v56, v32
	v_mov_b32_e32 v33, v32
	s_nop 1
	v_permlane32_swap_b32_e32 v32, v33
	v_add_f32_e32 v34, v32, v33
	v_mov_b32_e32 v32, v48
	s_nop 1
	v_permlane16_swap_b32_e32 v48, v32
	v_add_f32_e32 v32, v48, v32
	v_mov_b32_e32 v33, v32
	s_nop 1
	v_permlane32_swap_b32_e32 v32, v33
	v_add_f32_e32 v35, v32, v33
	s_nop 0
	v_add_f32_dpp v32, v81, v81 quad_perm:[1,0,3,2] row_mask:0xf bank_mask:0xf bound_ctrl:1
	v_rcp_f32_e32 v48, v34
	v_rcp_f32_e32 v34, v35
	v_add_f32_dpp v32, v32, v32 quad_perm:[2,3,0,1] row_mask:0xf bank_mask:0xf bound_ctrl:1
	v_lshlrev_b32_e32 v44, 2, v64
	v_lshlrev_b32_e32 v64, 1, v64
	v_add_f32_dpp v32, v32, v32 row_half_mirror row_mask:0xf bank_mask:0xf bound_ctrl:1
	s_mov_b64 s[6:7], 0xf000600
	s_nop 0
	v_add_f32_dpp v32, v32, v32 row_mirror row_mask:0xf bank_mask:0xf bound_ctrl:1
	v_mov_b32_e32 v33, v32
	s_nop 1
	v_permlane16_swap_b32_e32 v32, v33
	v_add_f32_e32 v32, v32, v33
	v_mov_b32_e32 v33, v32
	s_nop 1
	v_permlane32_swap_b32_e32 v32, v33
	v_add_f32_e32 v33, v32, v33
	s_nop 0
	v_add_f32_dpp v32, v80, v80 quad_perm:[1,0,3,2] row_mask:0xf bank_mask:0xf bound_ctrl:1
	v_mul_f32_e32 v33, 0x3fb8aa3b, v33
	v_exp_f32_e32 v191, v33
	v_add_f32_dpp v32, v32, v32 quad_perm:[2,3,0,1] row_mask:0xf bank_mask:0xf bound_ctrl:1
	s_nop 1
	v_add_f32_dpp v32, v32, v32 row_half_mirror row_mask:0xf bank_mask:0xf bound_ctrl:1
	s_nop 1
	v_add_f32_dpp v32, v32, v32 row_mirror row_mask:0xf bank_mask:0xf bound_ctrl:1
	v_mov_b32_e32 v36, v32
	s_nop 1
	v_permlane16_swap_b32_e32 v32, v36
	v_add_f32_e32 v32, v32, v36
	v_mov_b32_e32 v36, v32
	s_nop 1
	v_permlane32_swap_b32_e32 v32, v36
	v_add_f32_e32 v36, v32, v36
	v_cvt_f32_i32_e32 v32, s45
	v_mul_f32_e32 v33, 0x3fb8aa3b, v36
	v_exp_f32_e32 v33, v33
	v_mul_f32_e32 v32, 0xbe99999a, v32
	v_mul_f32_e32 v32, 0x3fb8aa3b, v32
	v_exp_f32_e32 v32, v32
	s_nop 0
	v_mul_f32_e32 v32, 0x3f19999a, v32
	v_sub_f32_e32 v32, v190, v32
	v_sub_f32_e32 v33, v191, v33
	s_nop 0
	v_add_f32_e32 v33, v32, v33
	v_mul_f32_e32 v50, v34, v33
	v_sub_f32_e32 v49, 1.0, v32
	global_load_dwordx4 v[32:35], v44, s[10:11]
	global_load_dwordx4 v[36:39], v44, s[10:11] offset:64
	global_load_dwordx4 v[40:43], v44, s[10:11] offset:128
	s_nop 0
	global_load_dwordx4 v[44:47], v44, s[10:11] offset:192
	v_mul_f32_e32 v24, v24, v50
	v_mul_f32_e32 v25, v25, v50
	v_mul_f32_e32 v26, v26, v50
	v_mul_f32_e32 v27, v27, v50
	v_fma_f32 v16, v16, v48, -v24
	v_fma_f32 v17, v17, v48, -v25
	v_fma_f32 v18, v18, v48, -v26
	v_fma_f32 v19, v19, v48, -v27
	v_mul_f32_e32 v24, v17, v17
	v_fma_f32 v25, v17, v17, v24
	v_fma_f32 v24, v16, v16, v24
	v_mul_f32_e32 v26, v19, v19
	v_fma_f32 v24, v18, v18, v24
	v_fma_f32 v25, v19, v19, v25
	v_mul_f32_e32 v12, v12, v50
	v_mul_f32_e32 v13, v13, v50
	v_add_f32_e32 v24, v26, v24
	v_add_f32_e32 v25, v26, v25
	v_mul_f32_e32 v14, v14, v50
	v_mul_f32_e32 v15, v15, v50
	v_fma_f32 v8, v8, v48, -v12
	v_fma_f32 v9, v9, v48, -v13
	v_fma_f32 v10, v10, v48, -v14
	v_fma_f32 v11, v11, v48, -v15
	v_fma_f32 v12, v8, v8, v24
	v_fma_f32 v13, v9, v9, v25
	v_mul_f32_e32 v14, v9, v9
	v_add_f32_e32 v12, v14, v12
	v_add_f32_e32 v13, v14, v13
	v_fma_f32 v12, v10, v10, v12
	v_fma_f32 v13, v11, v11, v13
	v_mul_f32_e32 v14, v11, v11
	v_add_f32_e32 v12, v14, v12
	v_add_f32_e32 v13, v14, v13
	v_mul_f32_e32 v14, v30, v50
	v_mul_f32_e32 v15, v31, v50
	v_mul_f32_e32 v0, v0, v50
	v_mul_f32_e32 v1, v1, v50
	v_fma_f32 v14, v22, v48, -v14
	v_fma_f32 v15, v23, v48, -v15
	v_mul_f32_e32 v22, v28, v50
	v_mul_f32_e32 v23, v29, v50
	v_mul_f32_e32 v2, v2, v50
	v_mul_f32_e32 v3, v3, v50
	v_fma_f32 v20, v20, v48, -v22
	v_fma_f32 v21, v21, v48, -v23
	v_fma_f32 v0, v4, v48, -v0
	v_fma_f32 v1, v5, v48, -v1
	v_fma_f32 v12, v20, v20, v12
	v_fma_f32 v13, v21, v21, v13
	v_mul_f32_e32 v22, v21, v21
	v_add_f32_e32 v12, v22, v12
	v_add_f32_e32 v13, v22, v13
	v_fma_f32 v12, v14, v14, v12
	v_fma_f32 v13, v15, v15, v13
	v_mul_f32_e32 v22, v15, v15
	v_add_f32_e32 v12, v22, v12
	v_add_f32_e32 v13, v22, v13
	v_fma_f32 v2, v6, v48, -v2
	v_fma_f32 v3, v7, v48, -v3
	v_fma_f32 v4, v0, v0, v12
	v_fma_f32 v5, v1, v1, v13
	v_mul_f32_e32 v6, v1, v1
	v_add_f32_e32 v4, v6, v4
	v_add_f32_e32 v5, v6, v5
	v_fma_f32 v4, v2, v2, v4
	v_fma_f32 v5, v3, v3, v5
	v_mul_f32_e32 v6, v3, v3
	v_add_f32_e32 v4, v6, v4
	v_add_f32_e32 v5, v6, v5
	v_mov_b32_e32 v5, v4
	s_nop 1
	v_permlane16_swap_b32_e32 v4, v5
	v_add_f32_e32 v4, v4, v5
	v_mov_b32_e32 v5, v4
	s_nop 1
	v_permlane32_swap_b32_e32 v4, v5
	v_add_f32_e32 v4, v4, v5
	v_fmamk_f32 v4, v4, 0x3c800000, v229
	v_cmp_gt_f32_e32 vcc, s55, v4
	v_mul_f32_e32 v5, 0x4b800000, v4
	v_lshl_add_u64 v[26:27], v[52:53], 0, v[64:65]
	v_cndmask_b32_e32 v4, v4, v5, vcc
	v_rsq_f32_e32 v4, v4
	v_lshl_add_u64 v[52:53], v[26:27], 0, s[6:7]
	s_mov_b32 s6, 0xf000000
	v_mul_f32_e32 v5, 0x45800000, v4
	v_cndmask_b32_e32 v4, v4, v5, vcc
	v_mul_f32_e32 v4, v49, v4
	v_mul_f32_e32 v6, v16, v4
	v_mul_f32_e32 v7, v17, v4
	v_mul_f32_e32 v12, v18, v4
	v_mul_f32_e32 v13, v19, v4
	v_mul_f32_e32 v0, v0, v4
	v_mul_f32_e32 v1, v1, v4
	v_mul_f32_e32 v2, v2, v4
	v_mul_f32_e32 v3, v3, v4
	s_waitcnt vmcnt(3)
	v_mul_f32_e32 v6, v32, v6
	v_mul_f32_e32 v7, v33, v7
	v_mul_f32_e32 v12, v34, v12
	v_mul_f32_e32 v13, v35, v13
	v_cvt_pk_bf16_f32 v6, v6, v7
	v_cvt_pk_bf16_f32 v7, v12, v13
	v_add_co_u32_e32 v12, vcc, s6, v26
	s_waitcnt vmcnt(0)
	v_mul_f32_e32 v0, v44, v0
	v_mul_f32_e32 v1, v45, v1
	v_addc_co_u32_e32 v13, vcc, 0, v27, vcc
	global_store_dwordx2 v[12:13], v[6:7], off offset:1536
	v_mul_f32_e32 v6, v8, v4
	v_mul_f32_e32 v7, v9, v4
	v_mul_f32_e32 v8, v10, v4
	v_mul_f32_e32 v9, v11, v4
	v_mul_f32_e32 v6, v36, v6
	v_mul_f32_e32 v7, v37, v7
	v_mul_f32_e32 v8, v38, v8
	v_mul_f32_e32 v9, v39, v9
	v_cvt_pk_bf16_f32 v6, v6, v7
	v_cvt_pk_bf16_f32 v7, v8, v9
	global_store_dwordx2 v[52:53], v[6:7], off offset:32
	v_mul_f32_e32 v6, v20, v4
	v_mul_f32_e32 v7, v21, v4
	v_mul_f32_e32 v8, v14, v4
	v_mul_f32_e32 v9, v15, v4
	v_mul_f32_e32 v6, v40, v6
	v_mul_f32_e32 v7, v41, v7
	v_mul_f32_e32 v8, v42, v8
	v_mul_f32_e32 v9, v43, v9
	v_mul_f32_e32 v2, v46, v2
	v_mul_f32_e32 v3, v47, v3
	v_cvt_pk_bf16_f32 v6, v6, v7
	v_cvt_pk_bf16_f32 v7, v8, v9
	v_cvt_pk_bf16_f32 v0, v0, v1
	v_cvt_pk_bf16_f32 v1, v2, v3
	global_store_dwordx2 v[52:53], v[6:7], off offset:64
	global_store_dwordx2 v[52:53], v[0:1], off offset:96
	s_mov_b64 s[6:7], 0

.LBB0_1046:
	s_andn2_b64 vcc, exec, s[6:7]
	s_cbranch_vccnz .LBB0_1052
	v_mov_b32_e32 v12, v228
	s_load_dwordx2 s[6:7], s[0:1], 0x100
	s_load_dwordx2 s[8:9], s[0:1], 0xb8
	s_lshl_b32 s11, s86, 5
	s_and_b32 s16, s11, 0xff00
	s_bfe_u32 s10, s86, 0x20001
	s_add_i32 s17, s16, 0xffff5e00
	s_waitcnt lgkmcnt(0)
	s_add_u32 s12, s6, 0xae00000
	s_addc_u32 s13, s7, 0
	s_lshl_b32 s14, s86, 7
	s_and_b32 s18, s14, 0x80
	s_lshl_b32 s14, s45, 2
	s_or_b32 s14, s14, s10
	s_ashr_i32 s15, s14, 31
	s_lshl_b64 s[14:15], s[14:15], 2
	s_add_u32 s8, s8, s14
	v_and_b32_e32 v14, 15, v12
	v_ashrrev_i32_e32 v0, 2, v12
	s_addc_u32 s9, s9, s15
	s_or_b32 s14, s18, s17
	v_and_b32_e32 v0, -16, v0
	v_or_b32_e32 v1, s14, v14
	v_bfe_u32 v13, v12, 4, 2
	v_add_u32_e32 v56, v1, v0
	v_mov_b64_e32 v[0:1], s[12:13]
	v_ashrrev_i32_e32 v15, 3, v12
	v_lshlrev_b32_e32 v8, 4, v12
	v_add_u32_e32 v12, 0x200, v12
	v_mad_i64_i32 v[0:1], s[14:15], v56, s93, v[0:1]
	s_lshl_b32 s96, s10, 7
	v_and_b32_e32 v44, 0x70, v8
	v_mov_b32_e32 v45, v65
	v_ashrrev_i32_e32 v57, 3, v12
	v_lshl_add_u64 v[0:1], v[0:1], 0, s[96:97]
	v_lshlrev_b32_e32 v64, 4, v13
	v_lshl_add_u64 v[36:37], s[12:13], 0, v[44:45]
	v_add_u32_e32 v12, s17, v57
	s_add_i32 s16, s16, 0xffff5e80
	v_lshl_add_u64 v[4:5], v[0:1], 0, v[64:65]
	v_add_u32_e32 v8, s17, v15
	v_mad_i64_i32 v[20:21], s[12:13], v12, s93, v[36:37]
	v_add_u32_e32 v12, s16, v15
	global_load_dwordx4 v[0:3], v[4:5], off offset:3072
	s_nop 0
	global_load_dwordx4 v[4:7], v[4:5], off offset:3136
	v_mad_i64_i32 v[8:9], s[12:13], v8, s93, v[36:37]
	s_and_b32 s96, s11, 0x80
	v_mad_i64_i32 v[28:29], s[12:13], v12, s93, v[36:37]
	v_add_u32_e32 v12, s16, v57
	v_lshl_add_u64 v[16:17], v[8:9], 0, s[96:97]
	v_lshl_add_u64 v[24:25], v[20:21], 0, s[96:97]
	v_lshl_add_u64 v[32:33], v[28:29], 0, s[96:97]
	v_mad_i64_i32 v[36:37], s[12:13], v12, s93, v[36:37]
	global_load_dwordx4 v[8:11], v[16:17], off offset:3584
	s_nop 0
	global_load_dwordx4 v[16:19], v[16:17], off offset:3840
	s_nop 0
	global_load_dwordx4 v[20:23], v[24:25], off offset:3584
	s_nop 0
	global_load_dwordx4 v[24:27], v[24:25], off offset:3840
	s_nop 0
	global_load_dwordx4 v[28:31], v[32:33], off offset:3584
	s_nop 0
	global_load_dwordx4 v[32:35], v[32:33], off offset:3840
	v_lshl_add_u64 v[40:41], v[36:37], 0, s[96:97]
	global_load_dwordx4 v[36:39], v[40:41], off offset:3584
	s_nop 0
	global_load_dwordx4 v[40:43], v[40:41], off offset:3840
	s_nop 0
	global_load_dword v66, v65, s[8:9]
	v_add_u32_e32 v12, 0, v44
	s_mov_b32 s8, 0x3e38aa3b
	s_barrier
	v_cmp_eq_u32_e32 vcc, 0, v13
	s_waitcnt vmcnt(0)
	v_lshlrev_b32_e32 v44, 16, v0
	v_and_b32_e32 v45, 0xffff0000, v0
	v_lshlrev_b32_e32 v0, 16, v1
	v_and_b32_e32 v1, 0xffff0000, v1
	v_lshlrev_b32_e32 v46, 16, v2
	v_and_b32_e32 v47, 0xffff0000, v2
	v_lshlrev_b32_e32 v2, 16, v3
	v_and_b32_e32 v3, 0xffff0000, v3
	v_lshlrev_b32_e32 v48, 16, v4
	v_and_b32_e32 v49, 0xffff0000, v4
	v_lshlrev_b32_e32 v4, 16, v5
	v_and_b32_e32 v5, 0xffff0000, v5
	v_lshlrev_b32_e32 v50, 16, v6
	v_and_b32_e32 v51, 0xffff0000, v6
	v_lshlrev_b32_e32 v6, 16, v7
	v_and_b32_e32 v7, 0xffff0000, v7
	v_mul_f32_e32 v44, s8, v44
	v_mul_f32_e32 v45, s8, v45
	v_mul_f32_e32 v52, s8, v0
	v_mul_f32_e32 v53, s8, v1
	v_mul_f32_e32 v46, s8, v46
	v_mul_f32_e32 v47, s8, v47
	v_mul_f32_e32 v54, s8, v2
	v_mul_f32_e32 v55, s8, v3
	v_mul_f32_e32 v58, s8, v48
	v_mul_f32_e32 v59, s8, v49
	v_mul_f32_e32 v60, s8, v4
	v_mul_f32_e32 v61, s8, v5
	v_mul_f32_e32 v50, s8, v50
	v_mul_f32_e32 v51, s8, v51
	v_mul_f32_e32 v62, s8, v6
	v_mul_f32_e32 v63, s8, v7
	v_mad_u64_u32 v[4:5], s[8:9], v15, s94, v[12:13]
	v_mad_u64_u32 v[6:7], s[8:9], v57, s94, v[12:13]
	v_add_u32_e32 v48, 0, v64
	ds_write_b128 v4, v[8:11]
	ds_write_b128 v4, v[16:19] offset:18432
	ds_write_b128 v6, v[20:23]
	ds_write_b128 v6, v[24:27] offset:18432
	s_waitcnt lgkmcnt(0)
	s_barrier
	v_mad_u32_u24 v12, v14, s94, v48
	ds_write_b128 v4, v[28:31] offset:36864
	ds_write_b128 v4, v[32:35] offset:55296
	ds_write_b128 v6, v[36:39] offset:36864
	ds_write_b128 v6, v[40:43] offset:55296
	ds_read_b128 v[16:19], v12
	ds_read_b128 v[20:23], v12 offset:64
	v_mul_f32_e32 v15, 0x3fb8aa3b, v66
	v_xor_b32_e32 v8, 0x80000000, v15
	v_cvt_pk_bf16_f32 v0, v44, v45
	v_cvt_pk_bf16_f32 v1, v52, v53
	v_cvt_pk_bf16_f32 v2, v46, v47
	v_cvt_pk_bf16_f32 v3, v54, v55
	v_mov_b32_e32 v9, v8
	v_mov_b32_e32 v10, v8
	v_mov_b32_e32 v11, v8
	ds_read_b128 v[24:27], v12 offset:2304
	v_cvt_pk_bf16_f32 v4, v58, v59
	s_waitcnt lgkmcnt(2)
	v_mfma_f32_16x16x32_bf16 v[16:19], v[16:19], v[0:3], v[8:11]
	v_cvt_pk_bf16_f32 v5, v60, v61
	v_cvt_pk_bf16_f32 v6, v50, v51
	v_cvt_pk_bf16_f32 v7, v62, v63
	ds_read_b128 v[50:53], v12 offset:13824
	s_waitcnt lgkmcnt(2)
	v_mfma_f32_16x16x32_bf16 v[44:47], v[20:23], v[4:7], v[16:19]
	s_nop 2
	ds_read_b128 v[16:19], v12 offset:2368
	s_waitcnt lgkmcnt(2)
	v_mfma_f32_16x16x32_bf16 v[20:23], v[24:27], v[0:3], v[8:11]
	ds_read_b128 v[24:27], v12 offset:4608
	s_waitcnt lgkmcnt(1)
	v_mfma_f32_16x16x32_bf16 v[40:43], v[16:19], v[4:7], v[20:23]
	ds_read_b128 v[16:19], v12 offset:4672
	s_waitcnt lgkmcnt(1)
	v_mfma_f32_16x16x32_bf16 v[20:23], v[24:27], v[0:3], v[8:11]
	ds_read_b128 v[24:27], v12 offset:6912
	s_waitcnt lgkmcnt(1)
	v_mfma_f32_16x16x32_bf16 v[36:39], v[16:19], v[4:7], v[20:23]
	ds_read_b128 v[16:19], v12 offset:6976
	s_waitcnt lgkmcnt(1)
	v_mfma_f32_16x16x32_bf16 v[20:23], v[24:27], v[0:3], v[8:11]
	ds_read_b128 v[24:27], v12 offset:9216
	s_waitcnt lgkmcnt(1)
	v_mfma_f32_16x16x32_bf16 v[32:35], v[16:19], v[4:7], v[20:23]
	ds_read_b128 v[16:19], v12 offset:9280
	s_waitcnt lgkmcnt(1)
	v_mfma_f32_16x16x32_bf16 v[20:23], v[24:27], v[0:3], v[8:11]
	ds_read_b128 v[24:27], v12 offset:11520
	s_waitcnt lgkmcnt(1)
	v_mfma_f32_16x16x32_bf16 v[28:31], v[16:19], v[4:7], v[20:23]
	ds_read_b128 v[16:19], v12 offset:11584
	s_waitcnt lgkmcnt(1)
	v_mfma_f32_16x16x32_bf16 v[20:23], v[24:27], v[0:3], v[8:11]
	s_waitcnt lgkmcnt(0)
	v_mfma_f32_16x16x32_bf16 v[24:27], v[16:19], v[4:7], v[20:23]
	ds_read_b128 v[16:19], v12 offset:13888
	v_mfma_f32_16x16x32_bf16 v[20:23], v[50:53], v[0:3], v[8:11]
	ds_read_b128 v[50:53], v12 offset:16128
	s_waitcnt lgkmcnt(1)
	v_mfma_f32_16x16x32_bf16 v[20:23], v[16:19], v[4:7], v[20:23]
	ds_read_b128 v[16:19], v12 offset:16192
	v_mov_b32_e32 v12, 0
	s_waitcnt lgkmcnt(1)
	v_mfma_f32_16x16x32_bf16 v[52:55], v[50:53], v[0:3], v[8:11]
	v_cndmask_b32_e64 v50, 0, 1.0, vcc
	s_nop 1
	v_max3_f32 v9, v46, v44, v45
	v_max3_f32 v9, v47, v9, v40
	v_max3_f32 v9, v42, v41, v9
	v_max3_f32 v9, v36, v43, v9
	v_max3_f32 v9, v38, v37, v9
	v_max3_f32 v9, v32, v39, v9
	v_max3_f32 v9, v34, v33, v9
	v_max3_f32 v9, v28, v35, v9
	v_max3_f32 v9, v30, v29, v9
	s_waitcnt lgkmcnt(0)
	v_mfma_f32_16x16x32_bf16 v[16:19], v[16:19], v[4:7], v[52:55]
	v_max3_f32 v9, v24, v31, v9
	v_max3_f32 v9, v26, v25, v9
	v_max3_f32 v9, v20, v27, v9
	v_max3_f32 v9, v22, v21, v9
	s_nop 3
	v_max3_f32 v9, v16, v23, v9
	v_max3_f32 v9, v18, v17, v9
	v_max_f32_e32 v10, v19, v19
	v_max_f32_e32 v9, v10, v9
	v_cmp_lt_f32_e32 vcc, s52, v9
	s_cbranch_vccz .LBB0_1049
	v_max_f32_e32 v8, v45, v45
	v_max_f32_e32 v9, v44, v44
	v_max_f32_e32 v8, v9, v8
	v_max3_f32 v8, v8, v46, v47
	v_max3_f32 v8, v8, v40, v41
	v_max3_f32 v8, v8, v42, v43
	v_max3_f32 v8, v8, v36, v37
	v_max3_f32 v8, v8, v38, v39
	v_max3_f32 v8, v8, v32, v33
	v_max3_f32 v8, v8, v34, v35
	v_max3_f32 v8, v8, v28, v29
	v_max3_f32 v8, v8, v30, v31
	v_max3_f32 v8, v8, v24, v25
	v_max3_f32 v8, v8, v26, v27
	v_max3_f32 v8, v8, v20, v21
	v_max3_f32 v8, v8, v22, v23
	v_max3_f32 v8, v8, v16, v17
	v_max3_f32 v8, v8, v18, v19
	v_mov_b32_e32 v9, v8
	s_nop 1
	v_permlane16_swap_b32_e32 v8, v9
	v_max_f32_e32 v9, v9, v9
	v_max_f32_e32 v8, v8, v8
	v_max_f32_e32 v8, v8, v9
	v_mov_b32_e32 v9, v8
	s_nop 1
	v_permlane32_swap_b32_e32 v8, v9
	v_max_f32_e32 v9, v9, v9
	v_max_f32_e32 v8, v8, v8
	v_max_f32_e32 v8, v8, v9
	v_cmp_lt_f32_e32 vcc, s52, v8
	s_nop 1
	v_cndmask_b32_e32 v8, 0, v8, vcc
	v_exp_f32_e64 v9, -v8
	v_add_f32_e32 v10, v15, v8
	v_mul_f32_e32 v50, v50, v9
	v_sub_f32_e32 v44, v44, v8
	v_sub_f32_e32 v45, v45, v8
	v_sub_f32_e32 v46, v46, v8
	v_sub_f32_e32 v47, v47, v8
	v_sub_f32_e32 v40, v40, v8
	v_sub_f32_e32 v41, v41, v8
	v_sub_f32_e32 v42, v42, v8
	v_sub_f32_e32 v43, v43, v8
	v_sub_f32_e32 v36, v36, v8
	v_sub_f32_e32 v37, v37, v8
	v_sub_f32_e32 v38, v38, v8
	v_sub_f32_e32 v39, v39, v8
	v_sub_f32_e32 v32, v32, v8
	v_sub_f32_e32 v33, v33, v8
	v_sub_f32_e32 v34, v34, v8
	v_sub_f32_e32 v35, v35, v8
	v_sub_f32_e32 v28, v28, v8
	v_sub_f32_e32 v29, v29, v8
	v_sub_f32_e32 v30, v30, v8
	v_sub_f32_e32 v31, v31, v8
	v_sub_f32_e32 v24, v24, v8
	v_sub_f32_e32 v25, v25, v8
	v_sub_f32_e32 v26, v26, v8
	v_sub_f32_e32 v27, v27, v8
	v_sub_f32_e32 v20, v20, v8
	v_sub_f32_e32 v21, v21, v8
	v_sub_f32_e32 v22, v22, v8
	v_sub_f32_e32 v23, v23, v8
	v_sub_f32_e32 v16, v16, v8
	v_sub_f32_e32 v17, v17, v8
	v_sub_f32_e32 v18, v18, v8
	v_sub_f32_e32 v19, v19, v8
	v_mul_f32_e32 v12, 0, v9
	v_xor_b32_e32 v8, 0x80000000, v10
.LBB0_1049:
	v_exp_f32_e32 v44, v44
	v_exp_f32_e32 v45, v45
	v_exp_f32_e32 v46, v46
	v_exp_f32_e32 v47, v47
	v_add_f32_e32 v51, 0, v44
	v_exp_f32_e32 v40, v40
	v_add_f32_e32 v51, v45, v51
	v_exp_f32_e32 v41, v41
	v_add_f32_e32 v51, v46, v51
	v_exp_f32_e32 v42, v42
	v_add_f32_e32 v51, v47, v51
	v_exp_f32_e32 v43, v43
	v_add_f32_e32 v51, v40, v51
	v_exp_f32_e32 v36, v36
	v_add_f32_e32 v51, v41, v51
	v_exp_f32_e32 v37, v37
	v_add_f32_e32 v51, v42, v51
	v_exp_f32_e32 v38, v38
	v_add_f32_e32 v51, v43, v51
	v_exp_f32_e32 v39, v39
	v_add_f32_e32 v51, v51, v36
	v_exp_f32_e32 v32, v32
	v_add_f32_e32 v51, v37, v51
	v_exp_f32_e32 v33, v33
	v_add_f32_e32 v51, v38, v51
	v_exp_f32_e32 v34, v34
	v_add_f32_e32 v51, v39, v51
	v_exp_f32_e32 v35, v35
	v_add_f32_e32 v51, v32, v51
	v_exp_f32_e32 v28, v28
	v_add_f32_e32 v51, v33, v51
	v_exp_f32_e32 v29, v29
	v_add_f32_e32 v51, v34, v51
	v_exp_f32_e32 v30, v30
	v_add_f32_e32 v51, v35, v51
	v_exp_f32_e32 v31, v31
	v_add_f32_e32 v51, v28, v51
	v_exp_f32_e32 v52, v24
	v_add_f32_e32 v51, v29, v51
	v_add_f32_e32 v51, v30, v51
	v_add_f32_e32 v51, v31, v51
	v_add_f32_e32 v24, v52, v51
	v_exp_f32_e32 v51, v25
	v_exp_f32_e32 v53, v26
	v_exp_f32_e32 v54, v27
	v_exp_f32_e32 v55, v20
	v_add_f32_e32 v24, v51, v24
	v_exp_f32_e32 v57, v21
	v_add_f32_e32 v24, v53, v24
	v_exp_f32_e32 v61, v22
	v_add_f32_e32 v24, v54, v24
	v_exp_f32_e32 v62, v23
	v_lshlrev_b32_e32 v58, 2, v13
	v_lshrrev_b32_e32 v10, 2, v14
	v_add_f32_e32 v20, v55, v24
	v_exp_f32_e32 v63, v16
	v_lshlrev_b32_e32 v9, 3, v14
	v_or_b32_e32 v10, v58, v10
	v_add_f32_e32 v20, v57, v20
	v_and_b32_e32 v9, 24, v9
	v_mul_u32_u24_e32 v10, 0x90, v10
	v_add_f32_e32 v20, v61, v20
	v_add3_u32 v59, 0, v9, v10
	v_add_f32_e32 v20, v62, v20
	v_add_f32_e32 v16, v63, v20
	v_cvt_pk_bf16_f32 v20, v36, v37
	v_cvt_pk_bf16_f32 v21, v38, v39
	v_cvt_pk_bf16_f32 v22, v32, v33
	v_cvt_pk_bf16_f32 v23, v34, v35
	ds_read_b64_tr_b16 v[34:35], v59 offset:20736
	ds_read_b64_tr_b16 v[32:33], v59 offset:18432
	ds_read_b64_tr_b16 v[36:37], v59 offset:18464
	ds_read_b64_tr_b16 v[38:39], v59 offset:20768
	v_cvt_pk_bf16_f32 v24, v44, v45
	v_cvt_pk_bf16_f32 v25, v46, v47
	v_cvt_pk_bf16_f32 v26, v40, v41
	v_cvt_pk_bf16_f32 v27, v42, v43
	ds_read_b64_tr_b16 v[40:41], v59 offset:18496
	ds_read_b64_tr_b16 v[42:43], v59 offset:20800
	ds_read_b64_tr_b16 v[44:45], v59 offset:18528
	ds_read_b64_tr_b16 v[46:47], v59 offset:20832
	v_mul_u32_u24_e32 v49, 0x90, v14
	v_mov_b32_e32 v13, v12
	v_mov_b32_e32 v14, v12
	v_mov_b32_e32 v15, v12
	v_exp_f32_e32 v64, v17
	v_exp_f32_e32 v66, v18
	s_waitcnt lgkmcnt(6)
	v_mfma_f32_16x16x32_bf16 v[32:35], v[32:35], v[24:27], v[12:15]
	v_exp_f32_e32 v67, v19
	v_add_f32_e32 v16, v64, v16
	v_add_f32_e32 v16, v66, v16
	s_waitcnt lgkmcnt(4)
	v_mfma_f32_16x16x32_bf16 v[36:39], v[36:39], v[24:27], v[12:15]
	v_add_f32_e32 v16, v67, v16
	v_add_f32_e32 v60, v50, v16
	v_cvt_pk_bf16_f32 v16, v28, v29
	s_waitcnt lgkmcnt(2)
	v_mfma_f32_16x16x32_bf16 v[40:43], v[40:43], v[24:27], v[12:15]
	v_cvt_pk_bf16_f32 v17, v30, v31
	v_cvt_pk_bf16_f32 v18, v52, v51
	v_cvt_pk_bf16_f32 v19, v53, v54
	s_waitcnt lgkmcnt(0)
	v_mfma_f32_16x16x32_bf16 v[12:15], v[44:47], v[24:27], v[12:15]
	ds_read_b64_tr_b16 v[24:25], v59 offset:23040
	ds_read_b64_tr_b16 v[26:27], v59 offset:25344
	v_cvt_pk_bf16_f32 v28, v55, v57
	v_cvt_pk_bf16_f32 v29, v61, v62
	s_waitcnt lgkmcnt(0)
	v_mfma_f32_16x16x32_bf16 v[24:27], v[24:27], v[20:23], v[32:35]
	s_nop 2
	ds_read_b64_tr_b16 v[32:33], v59 offset:23072
	ds_read_b64_tr_b16 v[34:35], v59 offset:25376
	v_cvt_pk_bf16_f32 v30, v63, v64
	v_cvt_pk_bf16_f32 v31, v66, v67
	s_waitcnt lgkmcnt(0)
	v_mfma_f32_16x16x32_bf16 v[32:35], v[32:35], v[20:23], v[36:39]
	s_nop 2
	ds_read_b64_tr_b16 v[36:37], v59 offset:23104
	ds_read_b64_tr_b16 v[38:39], v59 offset:25408
	v_add_u32_e32 v57, v48, v49
	v_mov_b32_e32 v9, v8
	s_waitcnt lgkmcnt(0)
	v_mfma_f32_16x16x32_bf16 v[36:39], v[36:39], v[20:23], v[40:43]
	s_nop 2
	ds_read_b64_tr_b16 v[40:41], v59 offset:23136
	ds_read_b64_tr_b16 v[42:43], v59 offset:25440
	v_mov_b32_e32 v10, v8
	v_mov_b32_e32 v11, v8
	s_waitcnt lgkmcnt(0)
	v_mfma_f32_16x16x32_bf16 v[12:15], v[40:43], v[20:23], v[12:15]
	ds_read_b64_tr_b16 v[20:21], v59 offset:27648
	ds_read_b64_tr_b16 v[22:23], v59 offset:29952
	s_waitcnt lgkmcnt(0)
	v_mfma_f32_16x16x32_bf16 v[20:23], v[20:23], v[16:19], v[24:27]
	s_nop 2
	ds_read_b64_tr_b16 v[24:25], v59 offset:27680
	ds_read_b64_tr_b16 v[26:27], v59 offset:29984
	s_waitcnt lgkmcnt(0)
	v_mfma_f32_16x16x32_bf16 v[32:35], v[24:27], v[16:19], v[32:35]
	ds_read_b64_tr_b16 v[24:25], v59 offset:27712
	ds_read_b64_tr_b16 v[26:27], v59 offset:30016
	s_waitcnt lgkmcnt(0)
	v_mfma_f32_16x16x32_bf16 v[36:39], v[24:27], v[16:19], v[36:39]
	ds_read_b64_tr_b16 v[24:25], v59 offset:27744
	ds_read_b64_tr_b16 v[26:27], v59 offset:30048
	s_waitcnt lgkmcnt(0)
	v_mfma_f32_16x16x32_bf16 v[12:15], v[24:27], v[16:19], v[12:15]
	ds_read_b64_tr_b16 v[16:17], v59 offset:32256
	ds_read_b64_tr_b16 v[18:19], v59 offset:34560
	s_waitcnt lgkmcnt(0)
	v_mfma_f32_16x16x32_bf16 v[24:27], v[16:19], v[28:31], v[20:23]
	ds_read_b64_tr_b16 v[16:17], v59 offset:32288
	ds_read_b64_tr_b16 v[18:19], v59 offset:34592
	s_waitcnt lgkmcnt(0)
	v_mfma_f32_16x16x32_bf16 v[20:23], v[16:19], v[28:31], v[32:35]
	ds_read_b64_tr_b16 v[16:17], v59 offset:32320
	ds_read_b64_tr_b16 v[18:19], v59 offset:34624
	s_nop 0
	ds_read_b64_tr_b16 v[32:33], v59 offset:32352
	ds_read_b64_tr_b16 v[34:35], v59 offset:34656
	s_waitcnt lgkmcnt(0)
	v_mfma_f32_16x16x32_bf16 v[16:19], v[16:19], v[28:31], v[36:39]
	s_barrier
	v_mfma_f32_16x16x32_bf16 v[12:15], v[32:35], v[28:31], v[12:15]
	ds_read_b128 v[28:31], v57 offset:36864
	ds_read_b128 v[32:35], v57 offset:36928
	s_waitcnt lgkmcnt(1)
	v_mfma_f32_16x16x32_bf16 v[28:31], v[28:31], v[0:3], v[8:11]
	s_waitcnt lgkmcnt(0)
	v_mfma_f32_16x16x32_bf16 v[28:31], v[32:35], v[4:7], v[28:31]
	ds_read_b128 v[32:35], v57 offset:39168
	ds_read_b128 v[36:39], v57 offset:39232
	s_waitcnt lgkmcnt(1)
	v_mfma_f32_16x16x32_bf16 v[32:35], v[32:35], v[0:3], v[8:11]
	s_waitcnt lgkmcnt(0)
	v_mfma_f32_16x16x32_bf16 v[32:35], v[36:39], v[4:7], v[32:35]
	ds_read_b128 v[36:39], v57 offset:41472
	ds_read_b128 v[40:43], v57 offset:41536
	s_waitcnt lgkmcnt(1)
	v_mfma_f32_16x16x32_bf16 v[36:39], v[36:39], v[0:3], v[8:11]
	s_waitcnt lgkmcnt(0)
	v_mfma_f32_16x16x32_bf16 v[36:39], v[40:43], v[4:7], v[36:39]
	ds_read_b128 v[40:43], v57 offset:43776
	ds_read_b128 v[44:47], v57 offset:43840
	s_waitcnt lgkmcnt(1)
	v_mfma_f32_16x16x32_bf16 v[40:43], v[40:43], v[0:3], v[8:11]
	s_waitcnt lgkmcnt(0)
	v_mfma_f32_16x16x32_bf16 v[40:43], v[44:47], v[4:7], v[40:43]
	ds_read_b128 v[44:47], v57 offset:46080
	ds_read_b128 v[48:51], v57 offset:46144
	s_waitcnt lgkmcnt(1)
	v_mfma_f32_16x16x32_bf16 v[44:47], v[44:47], v[0:3], v[8:11]
	s_waitcnt lgkmcnt(0)
	v_mfma_f32_16x16x32_bf16 v[44:47], v[48:51], v[4:7], v[44:47]
	ds_read_b128 v[48:51], v57 offset:48384
	ds_read_b128 v[52:55], v57 offset:48448
	s_waitcnt lgkmcnt(1)
	v_mfma_f32_16x16x32_bf16 v[48:51], v[48:51], v[0:3], v[8:11]
	s_waitcnt lgkmcnt(0)
	v_mfma_f32_16x16x32_bf16 v[48:51], v[52:55], v[4:7], v[48:51]
	ds_read_b128 v[52:55], v57 offset:50688
	ds_read_b128 v[66:69], v57 offset:50752
	s_waitcnt lgkmcnt(1)
	v_mfma_f32_16x16x32_bf16 v[52:55], v[52:55], v[0:3], v[8:11]
	s_waitcnt lgkmcnt(0)
	v_mfma_f32_16x16x32_bf16 v[52:55], v[66:69], v[4:7], v[52:55]
	ds_read_b128 v[66:69], v57 offset:52992
	ds_read_b128 v[70:73], v57 offset:53056
	s_waitcnt lgkmcnt(1)
	v_mfma_f32_16x16x32_bf16 v[0:3], v[66:69], v[0:3], v[8:11]
	s_waitcnt lgkmcnt(0)
	v_mfma_f32_16x16x32_bf16 v[0:3], v[70:73], v[4:7], v[0:3]
	v_max3_f32 v4, v30, v28, v29
	v_max3_f32 v4, v31, v4, v32
	v_max3_f32 v4, v34, v33, v4
	v_max3_f32 v4, v36, v35, v4
	v_max3_f32 v4, v38, v37, v4
	v_max3_f32 v4, v40, v39, v4
	v_max3_f32 v4, v42, v41, v4
	v_max3_f32 v4, v44, v43, v4
	v_max3_f32 v4, v46, v45, v4
	v_max3_f32 v4, v48, v47, v4
	v_max3_f32 v4, v50, v49, v4
	v_max3_f32 v4, v52, v51, v4
	v_max3_f32 v4, v54, v53, v4
	v_max3_f32 v4, v0, v55, v4
	v_max3_f32 v4, v2, v1, v4
	v_max_f32_e32 v5, v3, v3
	v_max_f32_e32 v4, v5, v4
	v_cmp_lt_f32_e32 vcc, s52, v4
	s_cbranch_vccz .LBB0_1051
	v_max_f32_e32 v4, v29, v29
	v_max_f32_e32 v5, v28, v28
	v_max_f32_e32 v4, v5, v4
	v_max3_f32 v4, v4, v30, v31
	v_max3_f32 v4, v4, v32, v33
	v_max3_f32 v4, v4, v34, v35
	v_max3_f32 v4, v4, v36, v37
	v_max3_f32 v4, v4, v38, v39
	v_max3_f32 v4, v4, v40, v41
	v_max3_f32 v4, v4, v42, v43
	v_max3_f32 v4, v4, v44, v45
	v_max3_f32 v4, v4, v46, v47
	v_max3_f32 v4, v4, v48, v49
	v_max3_f32 v4, v4, v50, v51
	v_max3_f32 v4, v4, v52, v53
	v_max3_f32 v4, v4, v54, v55
	v_max3_f32 v4, v4, v0, v1
	v_max3_f32 v4, v4, v2, v3
	v_mov_b32_e32 v5, v4
	s_nop 1
	v_permlane16_swap_b32_e32 v4, v5
	v_max_f32_e32 v5, v5, v5
	v_max_f32_e32 v4, v4, v4
	v_max_f32_e32 v4, v4, v5
	v_mov_b32_e32 v5, v4
	s_nop 1
	v_permlane32_swap_b32_e32 v4, v5
	v_max_f32_e32 v5, v5, v5
	v_max_f32_e32 v4, v4, v4
	v_max_f32_e32 v4, v4, v5
	v_cmp_lt_f32_e32 vcc, s52, v4
	s_nop 1
	v_cndmask_b32_e32 v4, 0, v4, vcc
	v_exp_f32_e64 v6, -v4
	v_sub_f32_e32 v28, v28, v4
	v_sub_f32_e32 v29, v29, v4
	v_sub_f32_e32 v30, v30, v4
	v_sub_f32_e32 v31, v31, v4
	v_sub_f32_e32 v32, v32, v4
	v_sub_f32_e32 v33, v33, v4
	v_mul_f32_e32 v60, v60, v6
	v_sub_f32_e32 v34, v34, v4
	v_sub_f32_e32 v35, v35, v4
	v_sub_f32_e32 v36, v36, v4
	v_sub_f32_e32 v37, v37, v4
	v_sub_f32_e32 v38, v38, v4
	v_sub_f32_e32 v39, v39, v4
	v_sub_f32_e32 v40, v40, v4
	v_sub_f32_e32 v41, v41, v4
	v_sub_f32_e32 v42, v42, v4
	v_sub_f32_e32 v43, v43, v4
	v_sub_f32_e32 v44, v44, v4
	v_sub_f32_e32 v45, v45, v4
	v_sub_f32_e32 v46, v46, v4
	v_sub_f32_e32 v47, v47, v4
	v_sub_f32_e32 v48, v48, v4
	v_sub_f32_e32 v49, v49, v4
	v_sub_f32_e32 v50, v50, v4
	v_sub_f32_e32 v51, v51, v4
	v_sub_f32_e32 v52, v52, v4
	v_sub_f32_e32 v53, v53, v4
	v_sub_f32_e32 v54, v54, v4
	v_sub_f32_e32 v55, v55, v4
	v_sub_f32_e32 v0, v0, v4
	v_sub_f32_e32 v1, v1, v4
	v_sub_f32_e32 v2, v2, v4
	v_sub_f32_e32 v3, v3, v4
	v_mul_f32_e32 v14, v14, v6
	v_mul_f32_e32 v15, v15, v6
	v_mul_f32_e32 v12, v12, v6
	v_mul_f32_e32 v13, v13, v6
	v_mul_f32_e32 v18, v18, v6
	v_mul_f32_e32 v19, v19, v6
	v_mul_f32_e32 v16, v16, v6
	v_mul_f32_e32 v17, v17, v6
	v_mul_f32_e32 v22, v22, v6
	v_mul_f32_e32 v23, v23, v6
	v_mul_f32_e32 v20, v20, v6
	v_mul_f32_e32 v21, v21, v6
	v_mul_f32_e32 v26, v26, v6
	v_mul_f32_e32 v27, v27, v6
	v_mul_f32_e32 v24, v24, v6
	v_mul_f32_e32 v25, v25, v6
.LBB0_1051:
	v_exp_f32_e32 v4, v28
	v_exp_f32_e32 v6, v29
	v_exp_f32_e32 v7, v30
	v_exp_f32_e32 v8, v31
	v_add_f32_e32 v5, 0, v4
	v_exp_f32_e32 v9, v32
	v_add_f32_e32 v5, v6, v5
	v_exp_f32_e32 v10, v33
	v_add_f32_e32 v5, v7, v5
	v_exp_f32_e32 v11, v34
	v_add_f32_e32 v5, v8, v5
	v_exp_f32_e32 v29, v35
	v_add_f32_e32 v5, v9, v5
	v_exp_f32_e32 v34, v36
	v_add_f32_e32 v5, v10, v5
	v_exp_f32_e32 v35, v37
	v_add_f32_e32 v5, v11, v5
	v_exp_f32_e32 v36, v38
	v_add_f32_e32 v5, v29, v5
	v_exp_f32_e32 v37, v39
	v_add_f32_e32 v5, v5, v34
	v_exp_f32_e32 v38, v40
	v_add_f32_e32 v5, v35, v5
	v_exp_f32_e32 v39, v41
	v_add_f32_e32 v5, v36, v5
	v_add_f32_e32 v5, v37, v5
	v_add_f32_e32 v5, v38, v5
	v_exp_f32_e32 v40, v42
	v_add_f32_e32 v5, v39, v5
	v_exp_f32_e32 v41, v43
	v_cvt_pk_bf16_f32 v31, v7, v8
	v_cvt_pk_bf16_f32 v32, v9, v10
	v_cvt_pk_bf16_f32 v8, v34, v35
	v_cvt_pk_bf16_f32 v9, v36, v37
	v_cvt_pk_bf16_f32 v10, v38, v39
	ds_read_b64_tr_b16 v[36:37], v59 offset:57600
	ds_read_b64_tr_b16 v[34:35], v59 offset:55296
	ds_read_b64_tr_b16 v[38:39], v59 offset:55328
	v_add_f32_e32 v5, v40, v5
	v_cvt_pk_bf16_f32 v30, v4, v6
	v_cvt_pk_bf16_f32 v33, v11, v29
	v_add_f32_e32 v5, v41, v5
	v_cvt_pk_bf16_f32 v11, v40, v41
	s_waitcnt lgkmcnt(1)
	v_mfma_f32_16x16x32_bf16 v[24:27], v[34:37], v[30:33], v[24:27]
	ds_read_b64_tr_b16 v[40:41], v59 offset:57632
	ds_read_b64_tr_b16 v[34:35], v59 offset:55360
	ds_read_b64_tr_b16 v[36:37], v59 offset:57664
	v_exp_f32_e32 v42, v44
	s_waitcnt lgkmcnt(0)
	v_mfma_f32_16x16x32_bf16 v[16:19], v[34:37], v[30:33], v[16:19]
	ds_read_b64_tr_b16 v[34:35], v59 offset:55392
	ds_read_b64_tr_b16 v[36:37], v59 offset:57696
	v_exp_f32_e32 v43, v45
	v_exp_f32_e32 v44, v46
	v_mfma_f32_16x16x32_bf16 v[20:23], v[38:41], v[30:33], v[20:23]
	v_exp_f32_e32 v45, v47
	v_add_f32_e32 v5, v42, v5
	v_exp_f32_e32 v46, v48
	s_waitcnt lgkmcnt(0)
	v_mfma_f32_16x16x32_bf16 v[12:15], v[34:37], v[30:33], v[12:15]
	ds_read_b64_tr_b16 v[30:31], v59 offset:59904
	ds_read_b64_tr_b16 v[32:33], v59 offset:62208
	v_add_f32_e32 v5, v43, v5
	v_exp_f32_e32 v47, v49
	s_waitcnt lgkmcnt(0)
	v_mfma_f32_16x16x32_bf16 v[24:27], v[30:33], v[8:11], v[24:27]
	ds_read_b64_tr_b16 v[30:31], v59 offset:59936
	ds_read_b64_tr_b16 v[32:33], v59 offset:62240
	v_add_f32_e32 v5, v44, v5
	v_exp_f32_e32 v48, v50
	s_waitcnt lgkmcnt(0)
	v_mfma_f32_16x16x32_bf16 v[20:23], v[30:33], v[8:11], v[20:23]
	ds_read_b64_tr_b16 v[30:31], v59 offset:59968
	ds_read_b64_tr_b16 v[32:33], v59 offset:62272
	v_add_f32_e32 v5, v45, v5
	v_exp_f32_e32 v49, v51
	v_add_f32_e32 v5, v46, v5
	v_exp_f32_e32 v50, v52
	s_waitcnt lgkmcnt(0)
	v_mfma_f32_16x16x32_bf16 v[16:19], v[30:33], v[8:11], v[16:19]
	ds_read_b64_tr_b16 v[30:31], v59 offset:60000
	ds_read_b64_tr_b16 v[32:33], v59 offset:62304
	v_add_f32_e32 v5, v47, v5
	v_exp_f32_e32 v51, v53
	v_add_f32_e32 v5, v48, v5
	v_exp_f32_e32 v52, v54
	v_add_f32_e32 v5, v49, v5
	v_exp_f32_e32 v53, v55
	v_add_f32_e32 v5, v50, v5
	v_exp_f32_e32 v54, v0
	v_add_u32_e32 v61, 0xd800, v59
	v_add_f32_e32 v5, v51, v5
	s_waitcnt lgkmcnt(0)
	v_mfma_f32_16x16x32_bf16 v[8:11], v[30:33], v[8:11], v[12:15]
	s_nop 2
	ds_read_b64_tr_b16 v[12:13], v59 offset:64512
	ds_read_b64_tr_b16 v[14:15], v61 offset:11520
	ds_read_b64_tr_b16 v[32:33], v61 offset:11552
	v_add_f32_e32 v5, v52, v5
	v_add_f32_e32 v5, v53, v5
	v_add_f32_e32 v0, v54, v5
	v_cvt_pk_bf16_f32 v4, v42, v43
	v_cvt_pk_bf16_f32 v5, v44, v45
	v_cvt_pk_bf16_f32 v6, v46, v47
	v_cvt_pk_bf16_f32 v7, v48, v49
	ds_read_b64_tr_b16 v[30:31], v59 offset:64544
	v_exp_f32_e32 v55, v1
	s_waitcnt lgkmcnt(2)
	v_mfma_f32_16x16x32_bf16 v[12:15], v[12:15], v[4:7], v[24:27]
	s_nop 2
	ds_read_b64_tr_b16 v[24:25], v59 offset:64576
	ds_read_b64_tr_b16 v[26:27], v61 offset:11584
	v_exp_f32_e32 v62, v2
	v_exp_f32_e32 v3, v3
	s_waitcnt lgkmcnt(0)
	v_mfma_f32_16x16x32_bf16 v[16:19], v[24:27], v[4:7], v[16:19]
	ds_read_b64_tr_b16 v[24:25], v59 offset:64608
	ds_read_b64_tr_b16 v[26:27], v61 offset:11616
	v_add_f32_e32 v0, v55, v0
	v_add_f32_e32 v0, v62, v0
	v_mfma_f32_16x16x32_bf16 v[20:23], v[30:33], v[4:7], v[20:23]
	v_add_f32_e32 v0, v3, v0
	v_add_f32_e32 v28, v60, v0
	v_cvt_pk_bf16_f32 v0, v50, v51
	s_waitcnt lgkmcnt(0)
	v_mfma_f32_16x16x32_bf16 v[4:7], v[24:27], v[4:7], v[8:11]
	s_nop 2
	ds_read_b64_tr_b16 v[8:9], v61 offset:13824
	ds_read_b64_tr_b16 v[10:11], v61 offset:16128
	v_cvt_pk_bf16_f32 v1, v52, v53
	v_cvt_pk_bf16_f32 v2, v54, v55
	v_cvt_pk_bf16_f32 v3, v62, v3
	v_ashrrev_i32_e32 v57, 31, v56
	s_lshl_b32 s8, s10, 6
	s_waitcnt lgkmcnt(0)
	v_mfma_f32_16x16x32_bf16 v[8:11], v[8:11], v[0:3], v[12:15]
	s_nop 2
	ds_read_b64_tr_b16 v[12:13], v61 offset:13856
	ds_read_b64_tr_b16 v[14:15], v61 offset:16160
	s_lshl_b32 s96, s8, 1
	v_lshlrev_b32_e32 v64, 1, v58
	s_waitcnt lgkmcnt(0)
	v_mfma_f32_16x16x32_bf16 v[12:15], v[12:15], v[0:3], v[20:23]
	s_nop 2
	ds_read_b64_tr_b16 v[20:21], v61 offset:13888
	ds_read_b64_tr_b16 v[22:23], v61 offset:16192
	s_waitcnt lgkmcnt(0)
	v_mfma_f32_16x16x32_bf16 v[16:19], v[20:23], v[0:3], v[16:19]
	ds_read_b64_tr_b16 v[20:21], v61 offset:13920
	ds_read_b64_tr_b16 v[22:23], v61 offset:16224
	s_waitcnt lgkmcnt(0)
	s_barrier
	v_mfma_f32_16x16x32_bf16 v[0:3], v[20:23], v[0:3], v[4:7]
	s_nop 2
	v_mov_b32_e32 v4, v28
	s_nop 1
	v_permlane16_swap_b32_e32 v28, v4
	v_add_f32_e32 v4, v28, v4
	v_mov_b32_e32 v5, v4
	s_nop 1
	v_permlane32_swap_b32_e32 v4, v5
	v_add_f32_e32 v4, v4, v5
	v_lshlrev_b64 v[6:7], 11, v[56:57]
	v_rcp_f32_e32 v4, v4
	v_lshl_add_u64 v[6:7], s[6:7], 0, v[6:7]
	v_lshl_add_u64 v[6:7], v[6:7], 0, s[96:97]
	v_lshl_add_u64 v[6:7], v[6:7], 0, v[64:65]
	s_mov_b64 s[6:7], 0xf000400
	v_lshl_add_u64 v[20:21], v[6:7], 0, s[6:7]
	s_mov_b32 s6, 0xf000000
	v_mul_f32_e32 v8, v8, v4
	v_mul_f32_e32 v9, v9, v4
	v_mul_f32_e32 v10, v10, v4
	v_mul_f32_e32 v11, v11, v4
	v_add_co_u32_e32 v6, vcc, s6, v6
	v_cvt_pk_bf16_f32 v8, v8, v9
	v_cvt_pk_bf16_f32 v9, v10, v11
	v_addc_co_u32_e32 v7, vcc, 0, v7, vcc
	global_store_dwordx2 v[6:7], v[8:9], off offset:1024
	v_mul_f32_e32 v6, v12, v4
	v_mul_f32_e32 v7, v13, v4
	v_mul_f32_e32 v8, v14, v4
	v_mul_f32_e32 v9, v15, v4
	v_cvt_pk_bf16_f32 v6, v6, v7
	v_cvt_pk_bf16_f32 v7, v8, v9
	global_store_dwordx2 v[20:21], v[6:7], off offset:32
	v_mul_f32_e32 v6, v16, v4
	v_mul_f32_e32 v7, v17, v4
	v_mul_f32_e32 v8, v18, v4
	v_mul_f32_e32 v9, v19, v4
	v_mul_f32_e32 v0, v0, v4
	v_mul_f32_e32 v1, v1, v4
	v_mul_f32_e32 v2, v2, v4
	v_mul_f32_e32 v3, v3, v4
	v_cvt_pk_bf16_f32 v6, v6, v7
	v_cvt_pk_bf16_f32 v7, v8, v9
	v_cvt_pk_bf16_f32 v0, v0, v1
	v_cvt_pk_bf16_f32 v1, v2, v3
	global_store_dwordx2 v[20:21], v[6:7], off offset:64
	global_store_dwordx2 v[20:21], v[0:1], off offset:96

.LBB0_1060:
	s_or_b64 exec, exec, s[8:9]
	v_add_u32_e32 v40, 0, v40
	v_mad_u64_u32 v[46:47], s[8:9], v41, s94, v[40:41]
	ds_write_b128 v46, v[0:3]
	ds_write_b128 v46, v[4:7] offset:18432
	v_mad_u64_u32 v[0:1], s[8:9], v44, s94, v[40:41]
	v_add_u32_e32 v94, 0, v64
	ds_write_b128 v0, v[8:11]
	ds_write_b128 v0, v[12:15] offset:18432
	s_waitcnt lgkmcnt(0)
	s_barrier
	v_mad_u32_u24 v66, v75, s94, v94
	ds_write_b128 v46, v[16:19] offset:36864
	ds_write_b128 v46, v[20:23] offset:55296
	ds_write_b128 v0, v[24:27] offset:36864
	ds_write_b128 v0, v[28:31] offset:55296
	ds_read_b128 v[0:3], v66
	ds_read_b128 v[4:7], v66 offset:64
	ds_read_b128 v[8:11], v66 offset:2304
	ds_read_b128 v[12:15], v66 offset:2368
	s_waitcnt lgkmcnt(3)
	v_mfma_f32_16x16x32_bf16 v[0:3], v[0:3], v[32:35], 0
	v_lshlrev_b32_e32 v91, 2, v42
	v_or_b32_e32 v78, 32, v91
	s_add_i32 s8, 0, 0x12000
	s_waitcnt lgkmcnt(2)
	v_mfma_f32_16x16x32_bf16 v[40:43], v[4:7], v[36:39], v[0:3]
	v_readlane_b32 s9, v255, 19
	v_or_b32_e32 v79, 48, v91
	v_or_b32_e32 v80, 64, v91
	ds_read_b128 v[0:3], v66 offset:4608
	s_waitcnt lgkmcnt(2)
	v_mfma_f32_16x16x32_bf16 v[4:7], v[8:11], v[32:35], 0
	ds_read_b128 v[8:11], v66 offset:4672
	v_or_b32_e32 v81, 0x50, v91
	v_or_b32_e32 v82, 0x60, v91
	s_waitcnt lgkmcnt(2)
	v_mfma_f32_16x16x32_bf16 v[44:47], v[12:15], v[36:39], v[4:7]
	v_lshlrev_b32_e32 v12, 2, v78
	v_add_u32_e32 v100, s8, v12
	v_add_u32_e32 v97, s9, v12
	ds_read_b128 v[4:7], v66 offset:6912
	ds_read_b128 v[12:15], v66 offset:6976
	s_waitcnt lgkmcnt(3)
	v_mfma_f32_16x16x32_bf16 v[0:3], v[0:3], v[32:35], 0
	v_add_u32_e32 v95, s8, v64
	v_or_b32_e32 v77, 16, v91
	v_or_b32_e32 v83, 0x70, v91
	s_waitcnt lgkmcnt(2)
	v_mfma_f32_16x16x32_bf16 v[48:51], v[8:11], v[36:39], v[0:3]
	v_lshlrev_b32_e32 v8, 2, v79
	v_add_u32_e32 v102, s8, v8
	v_add_u32_e32 v99, s9, v8
	ds_read_b128 v[0:3], v66 offset:9216
	ds_read_b128 v[8:11], v66 offset:9280
	s_waitcnt lgkmcnt(3)
	v_mfma_f32_16x16x32_bf16 v[4:7], v[4:7], v[32:35], 0
	s_lshl_b32 s10, s12, 6
	v_lshlrev_b32_e32 v16, 2, v77
	v_readfirstlane_b32 s11, v92
	s_waitcnt lgkmcnt(2)
	v_mfma_f32_16x16x32_bf16 v[52:55], v[12:15], v[36:39], v[4:7]
	v_lshlrev_b32_e32 v12, 2, v80
	v_add_u32_e32 v104, s8, v12
	v_add_u32_e32 v101, s9, v12
	ds_read_b128 v[4:7], v66 offset:11520
	ds_read_b128 v[12:15], v66 offset:11584
	s_waitcnt lgkmcnt(3)
	v_mfma_f32_16x16x32_bf16 v[0:3], v[0:3], v[32:35], 0
	v_ashrrev_i32_e32 v87, 31, v86
	v_add_u32_e32 v98, s8, v16
	v_add_u32_e32 v96, s9, v16
	s_waitcnt lgkmcnt(2)
	v_mfma_f32_16x16x32_bf16 v[56:59], v[8:11], v[36:39], v[0:3]
	v_lshlrev_b32_e32 v8, 2, v81
	v_add_u32_e32 v106, s8, v8
	v_add_u32_e32 v103, s9, v8
	ds_read_b128 v[0:3], v66 offset:13824
	ds_read_b128 v[8:11], v66 offset:13888
	s_waitcnt lgkmcnt(3)
	v_mfma_f32_16x16x32_bf16 v[4:7], v[4:7], v[32:35], 0
	s_cmpk_lt_i32 s11, 0x80
	s_waitcnt lgkmcnt(2)
	v_mfma_f32_16x16x32_bf16 v[60:63], v[12:15], v[36:39], v[4:7]
	v_lshlrev_b32_e32 v12, 2, v82
	v_add_u32_e32 v107, s8, v12
	v_add_u32_e32 v105, s9, v12
	s_nop 1
	ds_read_b128 v[4:7], v66 offset:16128
	ds_read_b128 v[12:15], v66 offset:16192
	s_waitcnt lgkmcnt(3)
	v_mfma_f32_16x16x32_bf16 v[0:3], v[0:3], v[32:35], 0
	s_waitcnt lgkmcnt(2)
	v_mfma_f32_16x16x32_bf16 v[66:69], v[8:11], v[36:39], v[0:3]
	v_cvt_f32_i32_e32 v9, v90
	v_lshlrev_b32_e32 v8, 2, v83
	v_add_u32_e32 v108, s8, v8
	s_waitcnt lgkmcnt(1)
	v_mfma_f32_16x16x32_bf16 v[0:3], v[4:7], v[32:35], 0
	v_mul_f32_e32 v4, v76, v9
	v_exp_f32_e32 v64, v4
	v_add_u32_e32 v109, s9, v8
	s_waitcnt lgkmcnt(0)
	v_mfma_f32_16x16x32_bf16 v[70:73], v[12:15], v[36:39], v[0:3]
	s_mov_b64 s[8:9], -1
	s_cbranch_scc0 .LBB0_1066
	s_nop 0
	v_sub_u32_e32 v0, 0, v90
	v_cvt_f32_i32_e32 v0, v0
	s_cmp_lt_i32 s11, -15
	v_mul_f32_e32 v0, v93, v0
	v_exp_f32_e32 v74, v0
	s_cbranch_scc1 .LBB0_1063
	v_add_u32_e32 v84, 0x12200, v94
	ds_read_b128 v[0:3], v95
	ds_read_b128 v[4:7], v98
	ds_read_b128 v[8:11], v96
	ds_read_b128 v[12:15], v100
	ds_read_b128 v[16:19], v97
	ds_read_b128 v[20:23], v102
	ds_read_b128 v[24:27], v99
	ds_read_b128 v[28:31], v104
	ds_read_b128 v[110:113], v101
	ds_read_b128 v[114:117], v106
	ds_read_b128 v[118:121], v103
	ds_read_b128 v[122:125], v107
	ds_read_b128 v[126:129], v105
	ds_read_b128 v[130:133], v108
	ds_read_b128 v[134:137], v84
	ds_read_b128 v[138:141], v109
	v_or_b32_e32 v165, 0x72, v91
	v_or_b32_e32 v164, 0x73, v91
	s_waitcnt lgkmcnt(2)
	v_mul_f32_e32 v84, v64, v132
	v_mul_f32_e32 v85, v64, v133
	s_waitcnt lgkmcnt(1)
	v_mul_f32_e32 v132, v74, v134
	v_mul_f32_e32 v133, v74, v135
	v_mul_f32_e32 v134, v74, v136
	v_mul_f32_e32 v135, v74, v137
	s_waitcnt lgkmcnt(0)
	v_mul_f32_e32 v136, v74, v140
	v_mul_f32_e32 v137, v74, v141
	v_cmp_ne_u32_e32 vcc, v90, v165
	v_or_b32_e32 v162, 0x62, v91
	v_or_b32_e32 v161, 0x63, v91
	v_cndmask_b32_e32 v136, v237, v136, vcc
	v_cmp_ne_u32_e32 vcc, v90, v164
	v_mul_f32_e32 v128, v74, v128
	v_mul_f32_e32 v129, v74, v129
	v_or_b32_e32 v159, 0x52, v91
	v_cndmask_b32_e32 v137, v237, v137, vcc
	v_cmp_ne_u32_e32 vcc, v90, v162
	v_or_b32_e32 v158, 0x53, v91
	v_mul_f32_e32 v120, v74, v120
	v_mul_f32_e32 v121, v74, v121
	v_cndmask_b32_e32 v128, v237, v128, vcc
	v_cmp_ne_u32_e32 vcc, v90, v161
	v_or_b32_e32 v156, 0x42, v91
	v_or_b32_e32 v155, 0x43, v91
	v_cndmask_b32_e32 v129, v237, v129, vcc
	v_cmp_ne_u32_e32 vcc, v90, v159
	v_mul_f32_e32 v112, v74, v112
	v_mul_f32_e32 v113, v74, v113
	v_or_b32_e32 v153, 50, v91
	v_cndmask_b32_e32 v120, v237, v120, vcc
	v_cmp_ne_u32_e32 vcc, v90, v158
	v_or_b32_e32 v152, 51, v91
	v_mul_f32_e32 v26, v74, v26
	v_mul_f32_e32 v27, v74, v27
	v_cndmask_b32_e32 v121, v237, v121, vcc
	v_cmp_ne_u32_e32 vcc, v90, v156
	v_or_b32_e32 v150, 34, v91
	v_or_b32_e32 v149, 35, v91
	v_cndmask_b32_e32 v112, v237, v112, vcc
	v_cmp_ne_u32_e32 vcc, v90, v155
	v_mul_f32_e32 v18, v74, v18
	v_mul_f32_e32 v19, v74, v19
	v_or_b32_e32 v147, 18, v91
	v_cndmask_b32_e32 v113, v237, v113, vcc
	v_cmp_ne_u32_e32 vcc, v90, v153
	v_or_b32_e32 v146, 19, v91
	v_mul_f32_e32 v10, v74, v10
	v_mul_f32_e32 v11, v74, v11
	v_cndmask_b32_e32 v26, v237, v26, vcc
	v_cmp_ne_u32_e32 vcc, v90, v152
	v_or_b32_e32 v144, 2, v91
	v_or_b32_e32 v143, 3, v91
	v_cndmask_b32_e32 v27, v237, v27, vcc
	v_cmp_ne_u32_e32 vcc, v90, v150
	v_or_b32_e32 v163, 0x71, v91
	v_mul_f32_e32 v138, v74, v138
	v_mul_f32_e32 v139, v74, v139
	v_cndmask_b32_e32 v18, v237, v18, vcc
	v_cmp_ne_u32_e32 vcc, v90, v149
	v_or_b32_e32 v160, 0x61, v91
	v_mul_f32_e32 v126, v74, v126
	v_mul_f32_e32 v127, v74, v127
	v_cndmask_b32_e32 v19, v237, v19, vcc
	v_cmp_ne_u32_e32 vcc, v90, v147
	v_or_b32_e32 v157, 0x51, v91
	v_mul_f32_e32 v118, v74, v118
	v_mul_f32_e32 v119, v74, v119
	v_cndmask_b32_e32 v10, v237, v10, vcc
	v_cmp_ne_u32_e32 vcc, v90, v146
	v_or_b32_e32 v154, 0x41, v91
	v_mul_f32_e32 v110, v74, v110
	v_mul_f32_e32 v111, v74, v111
	v_cndmask_b32_e32 v11, v237, v11, vcc
	v_cmp_ne_u32_e32 vcc, v90, v144
	v_or_b32_e32 v151, 49, v91
	v_mul_f32_e32 v24, v74, v24
	v_mul_f32_e32 v25, v74, v25
	v_cndmask_b32_e32 v134, v237, v134, vcc
	v_cmp_ne_u32_e32 vcc, v90, v143
	v_or_b32_e32 v148, 33, v91
	v_mul_f32_e32 v16, v74, v16
	v_mul_f32_e32 v17, v74, v17
	v_cndmask_b32_e32 v135, v237, v135, vcc
	v_cmp_ne_u32_e32 vcc, v90, v83
	v_or_b32_e32 v145, 17, v91
	v_mul_f32_e32 v8, v74, v8
	v_mul_f32_e32 v9, v74, v9
	v_cndmask_b32_e32 v138, v237, v138, vcc
	v_cmp_ne_u32_e32 vcc, v90, v163
	v_or_b32_e32 v142, 1, v91
	v_mul_f32_e32 v2, v64, v2
	v_mul_f32_e32 v3, v64, v3
	v_cndmask_b32_e32 v139, v237, v139, vcc
	v_cmp_ne_u32_e32 vcc, v90, v82
	v_mul_f32_e32 v6, v64, v6
	v_mul_f32_e32 v7, v64, v7
	v_mul_f32_e32 v14, v64, v14
	v_mul_f32_e32 v15, v64, v15
	v_cndmask_b32_e32 v126, v237, v126, vcc
	v_cmp_ne_u32_e32 vcc, v90, v160
	v_mul_f32_e32 v22, v64, v22
	v_mul_f32_e32 v23, v64, v23
	v_mul_f32_e32 v30, v64, v30
	v_mul_f32_e32 v31, v64, v31
	v_cndmask_b32_e32 v127, v237, v127, vcc
	v_cmp_ne_u32_e32 vcc, v90, v81
	v_mul_f32_e32 v116, v64, v116
	v_mul_f32_e32 v117, v64, v117
	v_mul_f32_e32 v124, v64, v124
	v_mul_f32_e32 v125, v64, v125
	v_cndmask_b32_e32 v118, v237, v118, vcc
	v_cmp_ne_u32_e32 vcc, v90, v157
	v_mul_f32_e32 v0, v64, v0
	v_mul_f32_e32 v1, v64, v1
	v_mul_f32_e32 v4, v64, v4
	v_mul_f32_e32 v5, v64, v5
	v_cndmask_b32_e32 v119, v237, v119, vcc
	v_cmp_ne_u32_e32 vcc, v90, v80
	v_mul_f32_e32 v12, v64, v12
	v_mul_f32_e32 v13, v64, v13
	v_mul_f32_e32 v20, v64, v20
	v_mul_f32_e32 v21, v64, v21
	v_cndmask_b32_e32 v110, v237, v110, vcc
	v_cmp_ne_u32_e32 vcc, v90, v154
	v_mul_f32_e32 v28, v64, v28
	v_mul_f32_e32 v29, v64, v29
	v_mul_f32_e32 v114, v64, v114
	v_mul_f32_e32 v115, v64, v115
	v_cndmask_b32_e32 v111, v237, v111, vcc
	v_cmp_ne_u32_e32 vcc, v90, v79
	v_mul_f32_e32 v122, v64, v122
	v_mul_f32_e32 v123, v64, v123
	v_mul_f32_e32 v130, v64, v130
	v_mul_f32_e32 v131, v64, v131
	v_cndmask_b32_e32 v24, v237, v24, vcc
	v_cmp_ne_u32_e32 vcc, v90, v151
	s_mov_b64 s[8:9], 0
	s_nop 0
	v_cndmask_b32_e32 v25, v237, v25, vcc
	v_cmp_ne_u32_e32 vcc, v90, v78
	s_nop 1
	v_cndmask_b32_e32 v140, v237, v16, vcc
	v_cmp_ne_u32_e32 vcc, v90, v148
	s_nop 1
	v_cndmask_b32_e32 v141, v237, v17, vcc
	v_cmp_ne_u32_e32 vcc, v90, v77
	s_nop 1
	v_cndmask_b32_e32 v166, v237, v8, vcc
	v_cmp_ne_u32_e32 vcc, v90, v145
	s_nop 1
	v_cndmask_b32_e32 v167, v237, v9, vcc
	v_cmp_ne_u32_e32 vcc, v90, v91
	s_nop 1
	v_cndmask_b32_e32 v132, v237, v132, vcc
	v_cmp_ne_u32_e32 vcc, v90, v142
	s_nop 1
	v_cndmask_b32_e32 v133, v237, v133, vcc
	v_cmp_gt_i32_e32 vcc, v90, v143
	s_nop 1
	v_cndmask_b32_e32 v3, v135, v3, vcc
	v_cmp_gt_i32_e32 vcc, v90, v144
	s_nop 1
	v_cndmask_b32_e32 v2, v134, v2, vcc
	v_cmp_gt_i32_e32 vcc, v90, v146
	v_mul_f32_e32 v2, v42, v2
	v_mul_f32_e32 v3, v43, v3
	s_nop 0
	v_cndmask_b32_e32 v7, v11, v7, vcc
	v_cmp_gt_i32_e32 vcc, v90, v147
	s_nop 1
	v_cndmask_b32_e32 v6, v10, v6, vcc
	v_cmp_gt_i32_e32 vcc, v90, v149
	v_mul_f32_e32 v6, v46, v6
	v_mul_f32_e32 v7, v47, v7
	s_nop 0
	v_cndmask_b32_e32 v9, v19, v15, vcc
	v_cmp_gt_i32_e32 vcc, v90, v150
	s_nop 1
	v_cndmask_b32_e32 v8, v18, v14, vcc
	v_cmp_gt_i32_e32 vcc, v90, v152
	s_nop 1
	v_cndmask_b32_e32 v11, v27, v23, vcc
	v_cmp_gt_i32_e32 vcc, v90, v153
	s_nop 1
	v_cndmask_b32_e32 v10, v26, v22, vcc
	v_cmp_gt_i32_e32 vcc, v90, v155
	s_nop 1
	v_cndmask_b32_e32 v15, v113, v31, vcc
	v_cmp_gt_i32_e32 vcc, v90, v156
	s_nop 1
	v_cndmask_b32_e32 v14, v112, v30, vcc
	v_cmp_gt_i32_e32 vcc, v90, v158
	s_nop 1
	v_cndmask_b32_e32 v17, v121, v117, vcc
	v_cmp_gt_i32_e32 vcc, v90, v159
	s_nop 1
	v_cndmask_b32_e32 v16, v120, v116, vcc
	v_cmp_gt_i32_e32 vcc, v90, v161
	s_nop 1
	v_cndmask_b32_e32 v19, v129, v125, vcc
	v_cmp_gt_i32_e32 vcc, v90, v162
	s_nop 1
	v_cndmask_b32_e32 v18, v128, v124, vcc
	v_cmp_gt_i32_e32 vcc, v90, v164
	v_mul_f32_e32 v26, v68, v18
	v_mul_f32_e32 v27, v69, v19
	v_mul_f32_e32 v18, v58, v14
	v_mul_f32_e32 v19, v59, v15
	v_cndmask_b32_e32 v23, v137, v85, vcc
	v_cmp_gt_i32_e32 vcc, v90, v165
	v_mul_f32_e32 v14, v54, v10
	v_mul_f32_e32 v15, v55, v11
	v_mul_f32_e32 v10, v50, v8
	v_mul_f32_e32 v11, v51, v9
	v_cndmask_b32_e32 v22, v136, v84, vcc
	v_cmp_gt_i32_e32 vcc, v90, v142
	v_mul_f32_e32 v30, v72, v22
	v_mul_f32_e32 v31, v73, v23
	v_mul_f32_e32 v22, v62, v16
	v_mul_f32_e32 v23, v63, v17
	v_cndmask_b32_e32 v1, v133, v1, vcc
	v_cmp_gt_i32_e32 vcc, v90, v91
	s_nop 1
	v_cndmask_b32_e32 v0, v132, v0, vcc
	v_cmp_gt_i32_e32 vcc, v90, v145
	v_mul_f32_e32 v0, v40, v0
	v_mul_f32_e32 v1, v41, v1
	s_nop 0
	v_cndmask_b32_e32 v5, v167, v5, vcc
	v_cmp_gt_i32_e32 vcc, v90, v77
	s_nop 1
	v_cndmask_b32_e32 v4, v166, v4, vcc
	v_cmp_gt_i32_e32 vcc, v90, v148
	v_mul_f32_e32 v4, v44, v4
	v_mul_f32_e32 v5, v45, v5
	s_nop 0
	v_cndmask_b32_e32 v85, v141, v13, vcc
	v_cmp_gt_i32_e32 vcc, v90, v78
	s_nop 1
	v_cndmask_b32_e32 v84, v140, v12, vcc
	v_cmp_gt_i32_e32 vcc, v90, v151
	v_mul_f32_e32 v8, v48, v84
	v_mul_f32_e32 v9, v49, v85
	s_nop 0
	v_cndmask_b32_e32 v13, v25, v21, vcc
	v_cmp_gt_i32_e32 vcc, v90, v79
	s_nop 1
	v_cndmask_b32_e32 v12, v24, v20, vcc
	v_cmp_gt_i32_e32 vcc, v90, v154
	v_mul_f32_e32 v12, v52, v12
	v_mul_f32_e32 v13, v53, v13
	s_nop 0
	v_cndmask_b32_e32 v79, v111, v29, vcc
	v_cmp_gt_i32_e32 vcc, v90, v80
	s_nop 1
	v_cndmask_b32_e32 v78, v110, v28, vcc
	v_cmp_gt_i32_e32 vcc, v90, v157
	v_mul_f32_e32 v16, v56, v78
	v_mul_f32_e32 v17, v57, v79
	s_nop 0
	v_cndmask_b32_e32 v21, v119, v115, vcc
	v_cmp_gt_i32_e32 vcc, v90, v81
	s_nop 1
	v_cndmask_b32_e32 v20, v118, v114, vcc
	v_cmp_gt_i32_e32 vcc, v90, v160
	v_mul_f32_e32 v20, v60, v20
	v_mul_f32_e32 v21, v61, v21
	s_nop 0
	v_cndmask_b32_e32 v25, v127, v123, vcc
	v_cmp_gt_i32_e32 vcc, v90, v82
	s_nop 1
	v_cndmask_b32_e32 v24, v126, v122, vcc
	v_cmp_gt_i32_e32 vcc, v90, v163
	v_mul_f32_e32 v24, v66, v24
	v_mul_f32_e32 v25, v67, v25
	s_nop 0
	v_cndmask_b32_e32 v29, v139, v131, vcc
	v_cmp_gt_i32_e32 vcc, v90, v83
	s_nop 1
	v_cndmask_b32_e32 v28, v138, v130, vcc
	v_mul_f32_e32 v28, v70, v28
	v_mul_f32_e32 v29, v71, v29
.LBB0_1063:
	s_andn2_b64 vcc, exec, s[8:9]
	s_cbranch_vccnz .LBB0_1065
	v_add_u32_e32 v28, 0x12200, v94
	ds_read_b128 v[0:3], v28
	ds_read_b128 v[4:7], v28 offset:64
	ds_read_b128 v[8:11], v28 offset:128
	ds_read_b128 v[12:15], v28 offset:192
	ds_read_b128 v[16:19], v28 offset:256
	ds_read_b128 v[20:23], v28 offset:320
	ds_read_b128 v[24:27], v28 offset:384
	ds_read_b128 v[28:31], v28 offset:448
	s_waitcnt lgkmcnt(7)
	v_mul_f32_e32 v2, v74, v2
	v_mul_f32_e32 v3, v74, v3
	s_waitcnt lgkmcnt(6)
	v_mul_f32_e32 v6, v74, v6
	v_mul_f32_e32 v7, v74, v7
	s_waitcnt lgkmcnt(5)
	v_mul_f32_e32 v10, v74, v10
	v_mul_f32_e32 v11, v74, v11
	s_waitcnt lgkmcnt(4)
	v_mul_f32_e32 v14, v74, v14
	v_mul_f32_e32 v15, v74, v15
	s_waitcnt lgkmcnt(3)
	v_mul_f32_e32 v18, v74, v18
	v_mul_f32_e32 v19, v74, v19
	s_waitcnt lgkmcnt(2)
	v_mul_f32_e32 v22, v74, v22
	v_mul_f32_e32 v23, v74, v23
	s_waitcnt lgkmcnt(1)
	v_mul_f32_e32 v26, v74, v26
	v_mul_f32_e32 v27, v74, v27
	s_waitcnt lgkmcnt(0)
	v_mul_f32_e32 v30, v74, v30
	v_mul_f32_e32 v31, v74, v31
	v_mul_f32_e32 v0, v74, v0
	v_mul_f32_e32 v1, v74, v1
	v_mul_f32_e32 v4, v74, v4
	v_mul_f32_e32 v5, v74, v5
	v_mul_f32_e32 v8, v74, v8
	v_mul_f32_e32 v9, v74, v9
	v_mul_f32_e32 v12, v74, v12
	v_mul_f32_e32 v13, v74, v13
	v_mul_f32_e32 v16, v74, v16
	v_mul_f32_e32 v17, v74, v17
	v_mul_f32_e32 v20, v74, v20
	v_mul_f32_e32 v21, v74, v21
	v_mul_f32_e32 v24, v74, v24
	v_mul_f32_e32 v25, v74, v25
	v_mul_f32_e32 v28, v74, v28
	v_mul_f32_e32 v29, v74, v29
	v_mul_f32_e32 v28, v70, v28
	v_mul_f32_e32 v29, v71, v29
	v_mul_f32_e32 v24, v66, v24
	v_mul_f32_e32 v25, v67, v25
	v_mul_f32_e32 v20, v60, v20
	v_mul_f32_e32 v21, v61, v21
	v_mul_f32_e32 v16, v56, v16
	v_mul_f32_e32 v17, v57, v17
	v_mul_f32_e32 v12, v52, v12
	v_mul_f32_e32 v13, v53, v13
	v_mul_f32_e32 v8, v48, v8
	v_mul_f32_e32 v9, v49, v9
	v_mul_f32_e32 v4, v44, v4
	v_mul_f32_e32 v5, v45, v5
	v_mul_f32_e32 v0, v40, v0
	v_mul_f32_e32 v1, v41, v1
	v_mul_f32_e32 v30, v72, v30
	v_mul_f32_e32 v31, v73, v31
	v_mul_f32_e32 v26, v68, v26
	v_mul_f32_e32 v27, v69, v27
	v_mul_f32_e32 v22, v62, v22
	v_mul_f32_e32 v23, v63, v23
	v_mul_f32_e32 v18, v58, v18
	v_mul_f32_e32 v19, v59, v19
	v_mul_f32_e32 v14, v54, v14
	v_mul_f32_e32 v15, v55, v15
	v_mul_f32_e32 v10, v50, v10
	v_mul_f32_e32 v11, v51, v11
	v_mul_f32_e32 v6, v46, v6
	v_mul_f32_e32 v7, v47, v7
	v_mul_f32_e32 v2, v42, v2
	v_mul_f32_e32 v3, v43, v3

.LBB0_1066:
	s_andn2_b64 vcc, exec, s[8:9]
	v_add_u32_e32 v110, 0x12000, v94
	s_cbranch_vccnz .LBB0_1068
	ds_read_b128 v[0:3], v110
	ds_read_b128 v[4:7], v110 offset:64
	ds_read_b128 v[8:11], v110 offset:128
	ds_read_b128 v[12:15], v110 offset:192
	ds_read_b128 v[16:19], v110 offset:256
	ds_read_b128 v[20:23], v110 offset:320
	ds_read_b128 v[24:27], v110 offset:384
	ds_read_b128 v[28:31], v110 offset:448
	s_waitcnt lgkmcnt(7)
	v_mul_f32_e32 v2, v64, v2
	v_mul_f32_e32 v3, v64, v3
	s_waitcnt lgkmcnt(6)
	v_mul_f32_e32 v6, v64, v6
	v_mul_f32_e32 v7, v64, v7
	s_waitcnt lgkmcnt(5)
	v_mul_f32_e32 v10, v64, v10
	v_mul_f32_e32 v11, v64, v11
	s_waitcnt lgkmcnt(4)
	v_mul_f32_e32 v14, v64, v14
	v_mul_f32_e32 v15, v64, v15
	s_waitcnt lgkmcnt(3)
	v_mul_f32_e32 v18, v64, v18
	v_mul_f32_e32 v19, v64, v19
	s_waitcnt lgkmcnt(2)
	v_mul_f32_e32 v22, v64, v22
	v_mul_f32_e32 v23, v64, v23
	s_waitcnt lgkmcnt(1)
	v_mul_f32_e32 v26, v64, v26
	v_mul_f32_e32 v27, v64, v27
	s_waitcnt lgkmcnt(0)
	v_mul_f32_e32 v30, v64, v30
	v_mul_f32_e32 v31, v64, v31
	v_mul_f32_e32 v0, v64, v0
	v_mul_f32_e32 v1, v64, v1
	v_mul_f32_e32 v4, v64, v4
	v_mul_f32_e32 v5, v64, v5
	v_mul_f32_e32 v8, v64, v8
	v_mul_f32_e32 v9, v64, v9
	v_mul_f32_e32 v12, v64, v12
	v_mul_f32_e32 v13, v64, v13
	v_mul_f32_e32 v16, v64, v16
	v_mul_f32_e32 v17, v64, v17
	v_mul_f32_e32 v20, v64, v20
	v_mul_f32_e32 v21, v64, v21
	v_mul_f32_e32 v24, v64, v24
	v_mul_f32_e32 v25, v64, v25
	v_mul_f32_e32 v28, v64, v28
	v_mul_f32_e32 v29, v64, v29
	v_mul_f32_e32 v28, v70, v28
	v_mul_f32_e32 v29, v71, v29
	v_mul_f32_e32 v24, v66, v24
	v_mul_f32_e32 v25, v67, v25
	v_mul_f32_e32 v20, v60, v20
	v_mul_f32_e32 v21, v61, v21
	v_mul_f32_e32 v16, v56, v16
	v_mul_f32_e32 v17, v57, v17
	v_mul_f32_e32 v12, v52, v12
	v_mul_f32_e32 v13, v53, v13
	v_mul_f32_e32 v8, v48, v8
	v_mul_f32_e32 v9, v49, v9
	v_mul_f32_e32 v4, v44, v4
	v_mul_f32_e32 v5, v45, v5
	v_mul_f32_e32 v0, v40, v0
	v_mul_f32_e32 v1, v41, v1
	v_mul_f32_e32 v30, v72, v30
	v_mul_f32_e32 v31, v73, v31
	v_mul_f32_e32 v26, v68, v26
	v_mul_f32_e32 v27, v69, v27
	v_mul_f32_e32 v22, v62, v22
	v_mul_f32_e32 v23, v63, v23
	v_mul_f32_e32 v18, v58, v18
	v_mul_f32_e32 v19, v59, v19
	v_mul_f32_e32 v14, v54, v14
	v_mul_f32_e32 v15, v55, v15
	v_mul_f32_e32 v10, v50, v10
	v_mul_f32_e32 v11, v51, v11
	v_mul_f32_e32 v6, v46, v6
	v_mul_f32_e32 v7, v47, v7
	v_mul_f32_e32 v2, v42, v2
	v_mul_f32_e32 v3, v43, v3
.LBB0_1068:
	v_lshrrev_b32_e32 v40, 2, v75
	v_or_b32_e32 v40, v91, v40
	v_lshlrev_b32_e32 v41, 3, v75
	v_and_b32_e32 v41, 24, v41
	v_mul_u32_u24_e32 v40, 0x90, v40
	v_add3_u32 v64, 0, v41, v40
	v_cvt_pk_bf16_f32 v42, v4, v5
	v_cvt_pk_bf16_f32 v8, v8, v9
	v_cvt_pk_bf16_f32 v9, v10, v11
	v_cvt_pk_bf16_f32 v10, v12, v13
	v_cvt_pk_bf16_f32 v11, v14, v15
	v_cvt_pk_bf16_f32 v4, v16, v17
	v_cvt_pk_bf16_f32 v5, v18, v19
	ds_read_b64_tr_b16 v[14:15], v64 offset:20736
	ds_read_b64_tr_b16 v[12:13], v64 offset:18432
	ds_read_b64_tr_b16 v[16:17], v64 offset:18464
	ds_read_b64_tr_b16 v[18:19], v64 offset:20768
	v_cvt_pk_bf16_f32 v40, v0, v1
	v_cvt_pk_bf16_f32 v41, v2, v3
	v_cvt_pk_bf16_f32 v43, v6, v7
	v_cvt_pk_bf16_f32 v6, v20, v21
	v_cvt_pk_bf16_f32 v7, v22, v23
	v_cvt_pk_bf16_f32 v0, v24, v25
	v_cvt_pk_bf16_f32 v1, v26, v27
	v_cvt_pk_bf16_f32 v2, v28, v29
	v_cvt_pk_bf16_f32 v3, v30, v31
	ds_read_b64_tr_b16 v[20:21], v64 offset:18496
	ds_read_b64_tr_b16 v[22:23], v64 offset:20800
	ds_read_b64_tr_b16 v[24:25], v64 offset:18528
	ds_read_b64_tr_b16 v[26:27], v64 offset:20832
	ds_read_b64_tr_b16 v[28:29], v64 offset:23040
	ds_read_b64_tr_b16 v[30:31], v64 offset:25344
	s_waitcnt lgkmcnt(8)
	v_mfma_f32_16x16x32_bf16 v[12:15], v[12:15], v[40:43], 0
	v_mul_u32_u24_e32 v56, 0x90, v75
	v_readfirstlane_b32 s11, v92
	s_mov_b64 s[8:9], -1
	s_waitcnt lgkmcnt(0)
	v_mfma_f32_16x16x32_bf16 v[12:15], v[28:31], v[8:11], v[12:15]
	ds_read_b64_tr_b16 v[28:29], v64 offset:23072
	ds_read_b64_tr_b16 v[30:31], v64 offset:25376
	s_cmpk_lt_i32 s11, 0x100
	v_mfma_f32_16x16x32_bf16 v[16:19], v[16:19], v[40:43], 0
	s_waitcnt lgkmcnt(0)
	v_mfma_f32_16x16x32_bf16 v[16:19], v[28:31], v[8:11], v[16:19]
	ds_read_b64_tr_b16 v[28:29], v64 offset:23104
	ds_read_b64_tr_b16 v[30:31], v64 offset:25408
	v_mfma_f32_16x16x32_bf16 v[20:23], v[20:23], v[40:43], 0
	s_waitcnt lgkmcnt(0)
	v_mfma_f32_16x16x32_bf16 v[20:23], v[28:31], v[8:11], v[20:23]
	ds_read_b64_tr_b16 v[28:29], v64 offset:23136
	ds_read_b64_tr_b16 v[30:31], v64 offset:25440
	v_mfma_f32_16x16x32_bf16 v[24:27], v[24:27], v[40:43], 0
	s_waitcnt lgkmcnt(0)
	v_mfma_f32_16x16x32_bf16 v[8:11], v[28:31], v[8:11], v[24:27]
	s_nop 5
	ds_read_b64_tr_b16 v[24:25], v64 offset:27648
	ds_read_b64_tr_b16 v[26:27], v64 offset:29952
	s_waitcnt lgkmcnt(0)
	v_mfma_f32_16x16x32_bf16 v[12:15], v[24:27], v[4:7], v[12:15]
	ds_read_b64_tr_b16 v[24:25], v64 offset:27680
	ds_read_b64_tr_b16 v[26:27], v64 offset:29984
	s_waitcnt lgkmcnt(0)
	v_mfma_f32_16x16x32_bf16 v[16:19], v[24:27], v[4:7], v[16:19]
	ds_read_b64_tr_b16 v[24:25], v64 offset:27712
	ds_read_b64_tr_b16 v[26:27], v64 offset:30016
	s_waitcnt lgkmcnt(0)
	v_mfma_f32_16x16x32_bf16 v[20:23], v[24:27], v[4:7], v[20:23]
	ds_read_b64_tr_b16 v[24:25], v64 offset:27744
	ds_read_b64_tr_b16 v[26:27], v64 offset:30048
	s_waitcnt lgkmcnt(0)
	v_mfma_f32_16x16x32_bf16 v[4:7], v[24:27], v[4:7], v[8:11]
	s_nop 2
	ds_read_b64_tr_b16 v[8:9], v64 offset:32256
	ds_read_b64_tr_b16 v[10:11], v64 offset:34560
	s_waitcnt lgkmcnt(0)
	v_mfma_f32_16x16x32_bf16 v[48:51], v[8:11], v[0:3], v[12:15]
	ds_read_b64_tr_b16 v[8:9], v64 offset:32288
	ds_read_b64_tr_b16 v[10:11], v64 offset:34592
	s_waitcnt lgkmcnt(0)
	v_mfma_f32_16x16x32_bf16 v[52:55], v[8:11], v[0:3], v[16:19]
	ds_read_b64_tr_b16 v[8:9], v64 offset:32320
	ds_read_b64_tr_b16 v[10:11], v64 offset:34624
	s_nop 0
	v_add_u32_e32 v16, v94, v56
	s_waitcnt lgkmcnt(0)
	v_mfma_f32_16x16x32_bf16 v[44:47], v[8:11], v[0:3], v[20:23]
	ds_read_b64_tr_b16 v[8:9], v64 offset:32352
	ds_read_b64_tr_b16 v[10:11], v64 offset:34656
	s_waitcnt lgkmcnt(0)
	s_barrier
	v_mfma_f32_16x16x32_bf16 v[40:43], v[8:11], v[0:3], v[4:7]
	v_add_u32_e32 v8, 0xffffff80, v90
	v_cvt_f32_i32_e32 v8, v8
	ds_read_b128 v[0:3], v16 offset:41472
	ds_read_b128 v[4:7], v16 offset:41536
	s_waitcnt lgkmcnt(1)
	v_mfma_f32_16x16x32_bf16 v[0:3], v[0:3], v[32:35], 0
	v_mul_f32_e32 v17, v76, v8
	ds_read_b128 v[8:11], v16 offset:36864
	ds_read_b128 v[12:15], v16 offset:36928
	s_waitcnt lgkmcnt(1)
	v_mfma_f32_16x16x32_bf16 v[8:11], v[8:11], v[32:35], 0
	s_waitcnt lgkmcnt(0)
	v_mfma_f32_16x16x32_bf16 v[56:59], v[12:15], v[36:39], v[8:11]
	s_nop 5
	ds_read_b128 v[8:11], v16 offset:39168
	ds_read_b128 v[12:15], v16 offset:39232
	v_mfma_f32_16x16x32_bf16 v[66:69], v[4:7], v[36:39], v[0:3]
	s_nop 2
	ds_read_b128 v[0:3], v16 offset:43776
	ds_read_b128 v[4:7], v16 offset:43840
	s_waitcnt lgkmcnt(1)
	v_mfma_f32_16x16x32_bf16 v[0:3], v[0:3], v[32:35], 0
	s_waitcnt lgkmcnt(0)
	v_mfma_f32_16x16x32_bf16 v[70:73], v[4:7], v[36:39], v[0:3]
	s_nop 5
	ds_read_b128 v[0:3], v16 offset:46080
	ds_read_b128 v[4:7], v16 offset:46144
	s_waitcnt lgkmcnt(1)
	v_mfma_f32_16x16x32_bf16 v[0:3], v[0:3], v[32:35], 0
	s_waitcnt lgkmcnt(0)
	v_mfma_f32_16x16x32_bf16 v[74:77], v[4:7], v[36:39], v[0:3]
	s_nop 5
	ds_read_b128 v[0:3], v16 offset:48384
	ds_read_b128 v[4:7], v16 offset:48448
	s_waitcnt lgkmcnt(1)
	v_mfma_f32_16x16x32_bf16 v[0:3], v[0:3], v[32:35], 0
	s_waitcnt lgkmcnt(0)
	v_mfma_f32_16x16x32_bf16 v[78:81], v[4:7], v[36:39], v[0:3]
	s_nop 5
	ds_read_b128 v[0:3], v16 offset:50688
	ds_read_b128 v[4:7], v16 offset:50752
	s_waitcnt lgkmcnt(1)
	v_mfma_f32_16x16x32_bf16 v[0:3], v[0:3], v[32:35], 0
	s_waitcnt lgkmcnt(0)
	v_mfma_f32_16x16x32_bf16 v[82:85], v[4:7], v[36:39], v[0:3]
	s_nop 5
	ds_read_b128 v[0:3], v16 offset:52992
	ds_read_b128 v[4:7], v16 offset:53056
	v_mfma_f32_16x16x32_bf16 v[8:11], v[8:11], v[32:35], 0
	s_waitcnt lgkmcnt(1)
	v_mfma_f32_16x16x32_bf16 v[0:3], v[0:3], v[32:35], 0
	v_mfma_f32_16x16x32_bf16 v[60:63], v[12:15], v[36:39], v[8:11]
	s_waitcnt lgkmcnt(0)
	v_mfma_f32_16x16x32_bf16 v[32:35], v[4:7], v[36:39], v[0:3]
	v_exp_f32_e32 v36, v17
	s_cbranch_scc0 .LBB0_1074
	s_nop 2
	v_sub_u32_e32 v0, 0x80, v90
	v_cvt_f32_i32_e32 v0, v0
	s_cmpk_lt_i32 s11, 0x71
	v_add_u32_e32 v37, 0x12200, v94
	v_mul_f32_e32 v0, v93, v0
	v_exp_f32_e32 v38, v0
	s_cbranch_scc1 .LBB0_1071
	ds_read_b128 v[0:3], v95
	ds_read_b128 v[4:7], v98
	ds_read_b128 v[8:11], v96
	ds_read_b128 v[12:15], v100
	ds_read_b128 v[16:19], v97
	ds_read_b128 v[20:23], v102
	ds_read_b128 v[24:27], v99
	ds_read_b128 v[28:31], v104
	ds_read_b128 v[92:95], v101
	ds_read_b128 v[96:99], v106
	ds_read_b128 v[100:103], v103
	ds_read_b128 v[112:115], v107
	ds_read_b128 v[104:107], v105
	ds_read_b128 v[116:119], v108
	ds_read_b128 v[120:123], v37
	ds_read_b128 v[124:127], v109
	v_or_b32_e32 v39, 0x81, v91
	v_or_b32_e32 v157, 0xf2, v91
	v_or_b32_e32 v156, 0xf3, v91
	s_waitcnt lgkmcnt(2)
	v_mul_f32_e32 v108, v36, v118
	v_mul_f32_e32 v109, v36, v119
	s_waitcnt lgkmcnt(1)
	v_mul_f32_e32 v118, v38, v122
	v_mul_f32_e32 v119, v38, v123
	s_waitcnt lgkmcnt(0)
	v_mul_f32_e32 v122, v38, v126
	v_mul_f32_e32 v123, v38, v127
	v_cmp_ne_u32_e32 vcc, v90, v157
	v_or_b32_e32 v153, 0xe2, v91
	v_or_b32_e32 v152, 0xe3, v91
	v_cndmask_b32_e32 v122, v237, v122, vcc
	v_cmp_ne_u32_e32 vcc, v90, v156
	v_mul_f32_e32 v106, v38, v106
	v_mul_f32_e32 v107, v38, v107
	v_or_b32_e32 v149, 0xd2, v91
	v_cndmask_b32_e32 v123, v237, v123, vcc
	v_cmp_ne_u32_e32 vcc, v90, v153
	v_or_b32_e32 v148, 0xd3, v91
	v_mul_f32_e32 v102, v38, v102
	v_mul_f32_e32 v103, v38, v103
	v_cndmask_b32_e32 v106, v237, v106, vcc
	v_cmp_ne_u32_e32 vcc, v90, v152
	v_or_b32_e32 v145, 0xc2, v91
	v_or_b32_e32 v144, 0xc3, v91
	v_cndmask_b32_e32 v107, v237, v107, vcc
	v_cmp_ne_u32_e32 vcc, v90, v149
	v_mul_f32_e32 v94, v38, v94
	v_mul_f32_e32 v95, v38, v95
	v_or_b32_e32 v141, 0xb2, v91
	v_cndmask_b32_e32 v102, v237, v102, vcc
	v_cmp_ne_u32_e32 vcc, v90, v148
	v_or_b32_e32 v140, 0xb3, v91
	v_mul_f32_e32 v26, v38, v26
	v_mul_f32_e32 v27, v38, v27
	v_cndmask_b32_e32 v103, v237, v103, vcc
	v_cmp_ne_u32_e32 vcc, v90, v145
	v_or_b32_e32 v137, 0xa2, v91
	v_or_b32_e32 v136, 0xa3, v91
	v_cndmask_b32_e32 v94, v237, v94, vcc
	v_cmp_ne_u32_e32 vcc, v90, v144
	v_mul_f32_e32 v18, v38, v18
	v_mul_f32_e32 v19, v38, v19
	v_or_b32_e32 v133, 0x92, v91
	v_cndmask_b32_e32 v95, v237, v95, vcc
	v_cmp_ne_u32_e32 vcc, v90, v141
	v_or_b32_e32 v132, 0x93, v91
	v_mul_f32_e32 v10, v38, v10
	v_mul_f32_e32 v11, v38, v11
	v_cndmask_b32_e32 v26, v237, v26, vcc
	v_cmp_ne_u32_e32 vcc, v90, v140
	v_or_b32_e32 v111, 0x80, v91
	v_mul_f32_e32 v120, v38, v120
	v_mul_f32_e32 v121, v38, v121
	v_cndmask_b32_e32 v27, v237, v27, vcc
	v_cmp_ne_u32_e32 vcc, v90, v137
	v_or_b32_e32 v129, 0x82, v91
	v_or_b32_e32 v128, 0x83, v91
	v_cndmask_b32_e32 v18, v237, v18, vcc
	v_cmp_ne_u32_e32 vcc, v90, v136
	v_or_b32_e32 v155, 0xf0, v91
	v_or_b32_e32 v154, 0xf1, v91
	v_cndmask_b32_e32 v19, v237, v19, vcc
	v_cmp_ne_u32_e32 vcc, v90, v133
	v_mul_f32_e32 v124, v38, v124
	v_mul_f32_e32 v125, v38, v125
	v_or_b32_e32 v151, 0xe0, v91
	v_cndmask_b32_e32 v10, v237, v10, vcc
	v_cmp_ne_u32_e32 vcc, v90, v132
	v_or_b32_e32 v150, 0xe1, v91
	v_mul_f32_e32 v104, v38, v104
	v_mul_f32_e32 v105, v38, v105
	v_cndmask_b32_e32 v11, v237, v11, vcc
	v_cmp_ne_u32_e32 vcc, v90, v111
	v_or_b32_e32 v147, 0xd0, v91
	v_or_b32_e32 v146, 0xd1, v91
	v_cndmask_b32_e32 v120, v237, v120, vcc
	v_cmp_ne_u32_e32 vcc, v90, v39
	v_mul_f32_e32 v100, v38, v100
	v_mul_f32_e32 v101, v38, v101
	v_or_b32_e32 v143, 0xc0, v91
	v_cndmask_b32_e32 v121, v237, v121, vcc
	v_cmp_ne_u32_e32 vcc, v90, v129
	v_or_b32_e32 v142, 0xc1, v91
	v_mul_f32_e32 v92, v38, v92
	v_mul_f32_e32 v93, v38, v93
	v_cndmask_b32_e32 v118, v237, v118, vcc
	v_cmp_ne_u32_e32 vcc, v90, v128
	v_or_b32_e32 v139, 0xb0, v91
	v_or_b32_e32 v138, 0xb1, v91
	v_cndmask_b32_e32 v119, v237, v119, vcc
	v_cmp_ne_u32_e32 vcc, v90, v155
	v_mul_f32_e32 v24, v38, v24
	v_mul_f32_e32 v25, v38, v25
	v_or_b32_e32 v135, 0xa0, v91
	v_cndmask_b32_e32 v124, v237, v124, vcc
	v_cmp_ne_u32_e32 vcc, v90, v154
	v_or_b32_e32 v134, 0xa1, v91
	v_mul_f32_e32 v16, v38, v16
	v_mul_f32_e32 v17, v38, v17
	v_cndmask_b32_e32 v125, v237, v125, vcc
	v_cmp_ne_u32_e32 vcc, v90, v151
	v_or_b32_e32 v131, 0x90, v91
	v_or_b32_e32 v130, 0x91, v91
	v_cndmask_b32_e32 v104, v237, v104, vcc
	v_cmp_ne_u32_e32 vcc, v90, v150
	v_mul_f32_e32 v8, v38, v8
	v_mul_f32_e32 v9, v38, v9
	v_mul_f32_e32 v2, v36, v2
	v_mul_f32_e32 v3, v36, v3
	v_cndmask_b32_e32 v105, v237, v105, vcc
	v_cmp_ne_u32_e32 vcc, v90, v147
	v_mul_f32_e32 v0, v36, v0
	v_mul_f32_e32 v1, v36, v1
	v_mul_f32_e32 v4, v36, v4
	v_mul_f32_e32 v5, v36, v5
	v_cndmask_b32_e32 v100, v237, v100, vcc
	v_cmp_ne_u32_e32 vcc, v90, v146
	v_mul_f32_e32 v6, v36, v6
	v_mul_f32_e32 v7, v36, v7
	v_mul_f32_e32 v12, v36, v12
	v_mul_f32_e32 v13, v36, v13
	v_cndmask_b32_e32 v101, v237, v101, vcc
	v_cmp_ne_u32_e32 vcc, v90, v143
	v_mul_f32_e32 v14, v36, v14
	v_mul_f32_e32 v15, v36, v15
	v_mul_f32_e32 v20, v36, v20
	v_mul_f32_e32 v21, v36, v21
	v_cndmask_b32_e32 v92, v237, v92, vcc
	v_cmp_ne_u32_e32 vcc, v90, v142
	v_mul_f32_e32 v22, v36, v22
	v_mul_f32_e32 v23, v36, v23
	v_mul_f32_e32 v28, v36, v28
	v_mul_f32_e32 v29, v36, v29
	v_cndmask_b32_e32 v93, v237, v93, vcc
	v_cmp_ne_u32_e32 vcc, v90, v139
	v_mul_f32_e32 v30, v36, v30
	v_mul_f32_e32 v31, v36, v31
	v_mul_f32_e32 v96, v36, v96
	v_mul_f32_e32 v97, v36, v97
	v_cndmask_b32_e32 v24, v237, v24, vcc
	v_cmp_ne_u32_e32 vcc, v90, v138
	v_mul_f32_e32 v98, v36, v98
	v_mul_f32_e32 v99, v36, v99
	v_mul_f32_e32 v112, v36, v112
	v_mul_f32_e32 v113, v36, v113
	v_cndmask_b32_e32 v25, v237, v25, vcc
	v_cmp_ne_u32_e32 vcc, v90, v135
	v_mul_f32_e32 v114, v36, v114
	v_mul_f32_e32 v115, v36, v115
	v_mul_f32_e32 v116, v36, v116
	v_mul_f32_e32 v117, v36, v117
	v_cndmask_b32_e32 v16, v237, v16, vcc
	v_cmp_ne_u32_e32 vcc, v90, v134
	s_mov_b64 s[8:9], 0
	s_nop 0
	v_cndmask_b32_e32 v17, v237, v17, vcc
	v_cmp_ne_u32_e32 vcc, v90, v131
	s_nop 1
	v_cndmask_b32_e32 v8, v237, v8, vcc
	v_cmp_ne_u32_e32 vcc, v90, v130
	s_nop 1
	v_cndmask_b32_e32 v9, v237, v9, vcc
	v_cmp_gt_i32_e32 vcc, v90, v128
	s_nop 1
	v_cndmask_b32_e32 v3, v119, v3, vcc
	v_cmp_gt_i32_e32 vcc, v90, v129
	s_nop 1
	v_cndmask_b32_e32 v2, v118, v2, vcc
	v_cmp_gt_i32_e32 vcc, v90, v39
	v_mul_f32_e32 v2, v58, v2
	v_mul_f32_e32 v3, v59, v3
	s_nop 0
	v_cndmask_b32_e32 v1, v121, v1, vcc
	v_cmp_gt_i32_e32 vcc, v90, v111
	s_nop 1
	v_cndmask_b32_e32 v0, v120, v0, vcc
	v_cmp_gt_i32_e32 vcc, v90, v130
	v_mul_f32_e32 v0, v56, v0
	v_mul_f32_e32 v1, v57, v1
	s_nop 0
	v_cndmask_b32_e32 v5, v9, v5, vcc
	v_cmp_gt_i32_e32 vcc, v90, v131
	s_nop 1
	v_cndmask_b32_e32 v4, v8, v4, vcc
	v_cmp_gt_i32_e32 vcc, v90, v132
	v_mul_f32_e32 v4, v60, v4
	v_mul_f32_e32 v5, v61, v5
	s_nop 0
	v_cndmask_b32_e32 v7, v11, v7, vcc
	v_cmp_gt_i32_e32 vcc, v90, v133
	s_nop 1
	v_cndmask_b32_e32 v6, v10, v6, vcc
	v_cmp_gt_i32_e32 vcc, v90, v134
	v_mul_f32_e32 v6, v62, v6
	v_mul_f32_e32 v7, v63, v7
	s_nop 0
	v_cndmask_b32_e32 v9, v17, v13, vcc
	v_cmp_gt_i32_e32 vcc, v90, v135
	s_nop 1
	v_cndmask_b32_e32 v8, v16, v12, vcc
	v_cmp_gt_i32_e32 vcc, v90, v136
	v_mul_f32_e32 v8, v66, v8
	v_mul_f32_e32 v9, v67, v9
	s_nop 0
	v_cndmask_b32_e32 v11, v19, v15, vcc
	v_cmp_gt_i32_e32 vcc, v90, v137
	s_nop 1
	v_cndmask_b32_e32 v10, v18, v14, vcc
	v_cmp_gt_i32_e32 vcc, v90, v138
	v_mul_f32_e32 v10, v68, v10
	v_mul_f32_e32 v11, v69, v11
	s_nop 0
	v_cndmask_b32_e32 v13, v25, v21, vcc
	v_cmp_gt_i32_e32 vcc, v90, v139
	s_nop 1
	v_cndmask_b32_e32 v12, v24, v20, vcc
	v_cmp_gt_i32_e32 vcc, v90, v140
	v_mul_f32_e32 v12, v70, v12
	v_mul_f32_e32 v13, v71, v13
	s_nop 0
	v_cndmask_b32_e32 v15, v27, v23, vcc
	v_cmp_gt_i32_e32 vcc, v90, v141
	s_nop 1
	v_cndmask_b32_e32 v14, v26, v22, vcc
	v_cmp_gt_i32_e32 vcc, v90, v142
	v_mul_f32_e32 v14, v72, v14
	v_mul_f32_e32 v15, v73, v15
	s_nop 0
	v_cndmask_b32_e32 v17, v93, v29, vcc
	v_cmp_gt_i32_e32 vcc, v90, v143
	s_nop 1
	v_cndmask_b32_e32 v16, v92, v28, vcc
	v_cmp_gt_i32_e32 vcc, v90, v144
	v_mul_f32_e32 v16, v74, v16
	v_mul_f32_e32 v17, v75, v17
	s_nop 0
	v_cndmask_b32_e32 v19, v95, v31, vcc
	v_cmp_gt_i32_e32 vcc, v90, v145
	s_nop 1
	v_cndmask_b32_e32 v18, v94, v30, vcc
	v_cmp_gt_i32_e32 vcc, v90, v146
	v_mul_f32_e32 v18, v76, v18
	v_mul_f32_e32 v19, v77, v19
	s_nop 0
	v_cndmask_b32_e32 v21, v101, v97, vcc
	v_cmp_gt_i32_e32 vcc, v90, v147
	s_nop 1
	v_cndmask_b32_e32 v20, v100, v96, vcc
	v_cmp_gt_i32_e32 vcc, v90, v148
	v_mul_f32_e32 v20, v78, v20
	v_mul_f32_e32 v21, v79, v21
	s_nop 0
	v_cndmask_b32_e32 v23, v103, v99, vcc
	v_cmp_gt_i32_e32 vcc, v90, v149
	s_nop 1
	v_cndmask_b32_e32 v22, v102, v98, vcc
	v_cmp_gt_i32_e32 vcc, v90, v150
	v_mul_f32_e32 v22, v80, v22
	v_mul_f32_e32 v23, v81, v23
	s_nop 0
	v_cndmask_b32_e32 v25, v105, v113, vcc
	v_cmp_gt_i32_e32 vcc, v90, v151
	s_nop 1
	v_cndmask_b32_e32 v24, v104, v112, vcc
	v_cmp_gt_i32_e32 vcc, v90, v152
	v_mul_f32_e32 v24, v82, v24
	v_mul_f32_e32 v25, v83, v25
	s_nop 0
	v_cndmask_b32_e32 v27, v107, v115, vcc
	v_cmp_gt_i32_e32 vcc, v90, v153
	s_nop 1
	v_cndmask_b32_e32 v26, v106, v114, vcc
	v_cmp_gt_i32_e32 vcc, v90, v154
	v_mul_f32_e32 v26, v84, v26
	v_mul_f32_e32 v27, v85, v27
	s_nop 0
	v_cndmask_b32_e32 v29, v125, v117, vcc
	v_cmp_gt_i32_e32 vcc, v90, v155
	s_nop 1
	v_cndmask_b32_e32 v28, v124, v116, vcc
	v_cmp_gt_i32_e32 vcc, v90, v156
	v_mul_f32_e32 v28, v32, v28
	v_mul_f32_e32 v29, v33, v29
	s_nop 0
	v_cndmask_b32_e32 v31, v123, v109, vcc
	v_cmp_gt_i32_e32 vcc, v90, v157
	s_nop 1
	v_cndmask_b32_e32 v30, v122, v108, vcc
	v_mul_f32_e32 v30, v34, v30
	v_mul_f32_e32 v31, v35, v31
.LBB0_1071:
	s_andn2_b64 vcc, exec, s[8:9]
	s_cbranch_vccnz .LBB0_1073
	ds_read_b128 v[0:3], v37
	ds_read_b128 v[4:7], v37 offset:64
	ds_read_b128 v[8:11], v37 offset:128
	ds_read_b128 v[12:15], v37 offset:192
	ds_read_b128 v[16:19], v37 offset:256
	ds_read_b128 v[20:23], v37 offset:320
	ds_read_b128 v[24:27], v37 offset:384
	ds_read_b128 v[28:31], v37 offset:448
	s_waitcnt lgkmcnt(7)
	v_mul_f32_e32 v2, v38, v2
	v_mul_f32_e32 v3, v38, v3
	s_waitcnt lgkmcnt(6)
	v_mul_f32_e32 v6, v38, v6
	v_mul_f32_e32 v7, v38, v7
	s_waitcnt lgkmcnt(5)
	v_mul_f32_e32 v10, v38, v10
	v_mul_f32_e32 v11, v38, v11
	s_waitcnt lgkmcnt(4)
	v_mul_f32_e32 v14, v38, v14
	v_mul_f32_e32 v15, v38, v15
	s_waitcnt lgkmcnt(3)
	v_mul_f32_e32 v18, v38, v18
	v_mul_f32_e32 v19, v38, v19
	s_waitcnt lgkmcnt(2)
	v_mul_f32_e32 v22, v38, v22
	v_mul_f32_e32 v23, v38, v23
	s_waitcnt lgkmcnt(1)
	v_mul_f32_e32 v26, v38, v26
	v_mul_f32_e32 v27, v38, v27
	s_waitcnt lgkmcnt(0)
	v_mul_f32_e32 v30, v38, v30
	v_mul_f32_e32 v31, v38, v31
	v_mul_f32_e32 v0, v38, v0
	v_mul_f32_e32 v1, v38, v1
	v_mul_f32_e32 v4, v38, v4
	v_mul_f32_e32 v5, v38, v5
	v_mul_f32_e32 v8, v38, v8
	v_mul_f32_e32 v9, v38, v9
	v_mul_f32_e32 v12, v38, v12
	v_mul_f32_e32 v13, v38, v13
	v_mul_f32_e32 v16, v38, v16
	v_mul_f32_e32 v17, v38, v17
	v_mul_f32_e32 v20, v38, v20
	v_mul_f32_e32 v21, v38, v21
	v_mul_f32_e32 v24, v38, v24
	v_mul_f32_e32 v25, v38, v25
	v_mul_f32_e32 v28, v38, v28
	v_mul_f32_e32 v29, v38, v29
	v_mul_f32_e32 v28, v32, v28
	v_mul_f32_e32 v29, v33, v29
	v_mul_f32_e32 v24, v82, v24
	v_mul_f32_e32 v25, v83, v25
	v_mul_f32_e32 v20, v78, v20
	v_mul_f32_e32 v21, v79, v21
	v_mul_f32_e32 v16, v74, v16
	v_mul_f32_e32 v17, v75, v17
	v_mul_f32_e32 v12, v70, v12
	v_mul_f32_e32 v13, v71, v13
	v_mul_f32_e32 v8, v66, v8
	v_mul_f32_e32 v9, v67, v9
	v_mul_f32_e32 v4, v60, v4
	v_mul_f32_e32 v5, v61, v5
	v_mul_f32_e32 v0, v56, v0
	v_mul_f32_e32 v1, v57, v1
	v_mul_f32_e32 v30, v34, v30
	v_mul_f32_e32 v31, v35, v31
	v_mul_f32_e32 v26, v84, v26
	v_mul_f32_e32 v27, v85, v27
	v_mul_f32_e32 v22, v80, v22
	v_mul_f32_e32 v23, v81, v23
	v_mul_f32_e32 v18, v76, v18
	v_mul_f32_e32 v19, v77, v19
	v_mul_f32_e32 v14, v72, v14
	v_mul_f32_e32 v15, v73, v15
	v_mul_f32_e32 v10, v68, v10
	v_mul_f32_e32 v11, v69, v11
	v_mul_f32_e32 v6, v62, v6
	v_mul_f32_e32 v7, v63, v7
	v_mul_f32_e32 v2, v58, v2
	v_mul_f32_e32 v3, v59, v3

.LBB0_1074:
	s_andn2_b64 vcc, exec, s[8:9]
	s_cbranch_vccnz .LBB0_1076
	s_nop 0
	ds_read_b128 v[0:3], v110
	ds_read_b128 v[4:7], v110 offset:64
	ds_read_b128 v[8:11], v110 offset:128
	ds_read_b128 v[12:15], v110 offset:192
	ds_read_b128 v[16:19], v110 offset:256
	ds_read_b128 v[20:23], v110 offset:320
	ds_read_b128 v[24:27], v110 offset:384
	ds_read_b128 v[28:31], v110 offset:448
	s_waitcnt lgkmcnt(7)
	v_mul_f32_e32 v2, v36, v2
	v_mul_f32_e32 v3, v36, v3
	s_waitcnt lgkmcnt(6)
	v_mul_f32_e32 v6, v36, v6
	v_mul_f32_e32 v7, v36, v7
	s_waitcnt lgkmcnt(5)
	v_mul_f32_e32 v10, v36, v10
	v_mul_f32_e32 v11, v36, v11
	s_waitcnt lgkmcnt(4)
	v_mul_f32_e32 v14, v36, v14
	v_mul_f32_e32 v15, v36, v15
	s_waitcnt lgkmcnt(3)
	v_mul_f32_e32 v18, v36, v18
	v_mul_f32_e32 v19, v36, v19
	s_waitcnt lgkmcnt(2)
	v_mul_f32_e32 v22, v36, v22
	v_mul_f32_e32 v23, v36, v23
	s_waitcnt lgkmcnt(1)
	v_mul_f32_e32 v26, v36, v26
	v_mul_f32_e32 v27, v36, v27
	s_waitcnt lgkmcnt(0)
	v_mul_f32_e32 v30, v36, v30
	v_mul_f32_e32 v31, v36, v31
	v_mul_f32_e32 v0, v36, v0
	v_mul_f32_e32 v1, v36, v1
	v_mul_f32_e32 v4, v36, v4
	v_mul_f32_e32 v5, v36, v5
	v_mul_f32_e32 v8, v36, v8
	v_mul_f32_e32 v9, v36, v9
	v_mul_f32_e32 v12, v36, v12
	v_mul_f32_e32 v13, v36, v13
	v_mul_f32_e32 v16, v36, v16
	v_mul_f32_e32 v17, v36, v17
	v_mul_f32_e32 v20, v36, v20
	v_mul_f32_e32 v21, v36, v21
	v_mul_f32_e32 v24, v36, v24
	v_mul_f32_e32 v25, v36, v25
	v_mul_f32_e32 v28, v36, v28
	v_mul_f32_e32 v29, v36, v29
	v_mul_f32_e32 v28, v32, v28
	v_mul_f32_e32 v29, v33, v29
	v_mul_f32_e32 v24, v82, v24
	v_mul_f32_e32 v25, v83, v25
	v_mul_f32_e32 v20, v78, v20
	v_mul_f32_e32 v21, v79, v21
	v_mul_f32_e32 v16, v74, v16
	v_mul_f32_e32 v17, v75, v17
	v_mul_f32_e32 v12, v70, v12
	v_mul_f32_e32 v13, v71, v13
	v_mul_f32_e32 v8, v66, v8
	v_mul_f32_e32 v9, v67, v9
	v_mul_f32_e32 v4, v60, v4
	v_mul_f32_e32 v5, v61, v5
	v_mul_f32_e32 v0, v56, v0
	v_mul_f32_e32 v1, v57, v1
	v_mul_f32_e32 v30, v34, v30
	v_mul_f32_e32 v31, v35, v31
	v_mul_f32_e32 v26, v84, v26
	v_mul_f32_e32 v27, v85, v27
	v_mul_f32_e32 v22, v80, v22
	v_mul_f32_e32 v23, v81, v23
	v_mul_f32_e32 v18, v76, v18
	v_mul_f32_e32 v19, v77, v19
	v_mul_f32_e32 v14, v72, v14
	v_mul_f32_e32 v15, v73, v15
	v_mul_f32_e32 v10, v68, v10
	v_mul_f32_e32 v11, v69, v11
	v_mul_f32_e32 v6, v62, v6
	v_mul_f32_e32 v7, v63, v7
	v_mul_f32_e32 v2, v58, v2
	v_mul_f32_e32 v3, v59, v3
.LBB0_1076:
	s_nop 3
	v_cvt_pk_bf16_f32 v34, v4, v5
	v_cvt_pk_bf16_f32 v8, v8, v9
	v_cvt_pk_bf16_f32 v9, v10, v11
	v_cvt_pk_bf16_f32 v10, v12, v13
	v_cvt_pk_bf16_f32 v11, v14, v15
	v_cvt_pk_bf16_f32 v4, v16, v17
	v_cvt_pk_bf16_f32 v5, v18, v19
	ds_read_b64_tr_b16 v[14:15], v64 offset:57600
	ds_read_b64_tr_b16 v[12:13], v64 offset:55296
	ds_read_b64_tr_b16 v[16:17], v64 offset:55328
	ds_read_b64_tr_b16 v[18:19], v64 offset:57632
	v_cvt_pk_bf16_f32 v32, v0, v1
	v_cvt_pk_bf16_f32 v33, v2, v3
	v_cvt_pk_bf16_f32 v35, v6, v7
	v_cvt_pk_bf16_f32 v6, v20, v21
	v_cvt_pk_bf16_f32 v7, v22, v23
	v_cvt_pk_bf16_f32 v0, v24, v25
	v_cvt_pk_bf16_f32 v1, v26, v27
	v_cvt_pk_bf16_f32 v2, v28, v29
	v_cvt_pk_bf16_f32 v3, v30, v31
	ds_read_b64_tr_b16 v[20:21], v64 offset:55360
	ds_read_b64_tr_b16 v[22:23], v64 offset:57664
	ds_read_b64_tr_b16 v[24:25], v64 offset:55392
	ds_read_b64_tr_b16 v[26:27], v64 offset:57696
	ds_read_b64_tr_b16 v[28:29], v64 offset:59904
	ds_read_b64_tr_b16 v[30:31], v64 offset:62208
	s_waitcnt lgkmcnt(8)
	v_mfma_f32_16x16x32_bf16 v[12:15], v[12:15], v[32:35], v[48:51]
	v_add_u32_e32 v36, 0xd800, v64
	s_lshl_b32 s12, s45, 8
	s_ashr_i32 s13, s12, 31
	s_waitcnt lgkmcnt(0)
	v_mfma_f32_16x16x32_bf16 v[12:15], v[28:31], v[8:11], v[12:15]
	ds_read_b64_tr_b16 v[28:29], v64 offset:59936
	ds_read_b64_tr_b16 v[30:31], v64 offset:62240
	s_lshl_b64 s[12:13], s[12:13], 2
	v_mfma_f32_16x16x32_bf16 v[16:19], v[16:19], v[32:35], v[52:55]
	s_waitcnt lgkmcnt(0)
	v_mfma_f32_16x16x32_bf16 v[16:19], v[28:31], v[8:11], v[16:19]
	ds_read_b64_tr_b16 v[28:29], v64 offset:59968
	ds_read_b64_tr_b16 v[30:31], v64 offset:62272
	v_mfma_f32_16x16x32_bf16 v[20:23], v[20:23], v[32:35], v[44:47]
	s_waitcnt lgkmcnt(0)
	v_mfma_f32_16x16x32_bf16 v[20:23], v[28:31], v[8:11], v[20:23]
	ds_read_b64_tr_b16 v[28:29], v64 offset:60000
	ds_read_b64_tr_b16 v[30:31], v64 offset:62304
	v_mfma_f32_16x16x32_bf16 v[24:27], v[24:27], v[32:35], v[40:43]
	s_waitcnt lgkmcnt(0)
	v_mfma_f32_16x16x32_bf16 v[8:11], v[28:31], v[8:11], v[24:27]
	s_nop 5
	ds_read_b64_tr_b16 v[24:25], v64 offset:64512
	ds_read_b64_tr_b16 v[26:27], v36 offset:11520
	ds_read_b64_tr_b16 v[28:29], v36 offset:11552
	s_waitcnt lgkmcnt(1)
	v_mfma_f32_16x16x32_bf16 v[12:15], v[24:27], v[4:7], v[12:15]
	ds_read_b64_tr_b16 v[26:27], v64 offset:64544
	s_waitcnt lgkmcnt(0)
	v_mfma_f32_16x16x32_bf16 v[16:19], v[26:29], v[4:7], v[16:19]
	ds_read_b64_tr_b16 v[24:25], v64 offset:64576
	ds_read_b64_tr_b16 v[26:27], v36 offset:11584
	s_waitcnt lgkmcnt(0)
	v_mfma_f32_16x16x32_bf16 v[24:27], v[24:27], v[4:7], v[20:23]
	s_nop 2
	ds_read_b64_tr_b16 v[20:21], v64 offset:64608
	ds_read_b64_tr_b16 v[22:23], v36 offset:11616
	v_lshlrev_b32_e32 v64, 1, v91
	v_lshl_add_u64 v[34:35], v[88:89], 0, v[64:65]
	s_waitcnt lgkmcnt(0)
	v_mfma_f32_16x16x32_bf16 v[4:7], v[20:23], v[4:7], v[8:11]
	s_nop 2
	ds_read_b64_tr_b16 v[8:9], v36 offset:13824
	ds_read_b64_tr_b16 v[10:11], v36 offset:16128
	s_waitcnt lgkmcnt(0)
	v_mfma_f32_16x16x32_bf16 v[28:31], v[8:11], v[0:3], v[12:15]
	ds_read_b64_tr_b16 v[8:9], v36 offset:13856
	ds_read_b64_tr_b16 v[10:11], v36 offset:16160
	s_waitcnt lgkmcnt(0)
	v_mfma_f32_16x16x32_bf16 v[20:23], v[8:11], v[0:3], v[16:19]
	ds_read_b64_tr_b16 v[8:9], v36 offset:13888
	ds_read_b64_tr_b16 v[10:11], v36 offset:16192
	s_waitcnt lgkmcnt(0)
	v_mfma_f32_16x16x32_bf16 v[16:19], v[8:11], v[0:3], v[24:27]
	ds_read_b64_tr_b16 v[8:9], v36 offset:13920
	ds_read_b64_tr_b16 v[10:11], v36 offset:16224
	s_waitcnt lgkmcnt(0)
	s_barrier
	v_mfma_f32_16x16x32_bf16 v[4:7], v[8:11], v[0:3], v[4:7]
	v_add_f32_e32 v0, v28, v29
	v_add_f32_e32 v1, v30, v31
	v_add_f32_e32 v0, v0, v1
	v_add_f32_e32 v1, v20, v21
	v_add_f32_e32 v2, v22, v23
	v_add_f32_e32 v0, 0, v0
	v_add_f32_e32 v1, v1, v2
	v_add_f32_e32 v0, v0, v1
	v_add_f32_e32 v1, v16, v17
	v_add_f32_e32 v2, v18, v19
	v_add_f32_e32 v1, v1, v2
	v_add_f32_e32 v0, v0, v1
	v_add_f32_e32 v1, v4, v5
	v_add_f32_e32 v2, v6, v7
	s_load_dwordx2 s[8:9], s[0:1], 0x78
	v_add_f32_e32 v1, v1, v2
	v_add_f32_e32 v0, v0, v1
	v_mov_b32_e32 v1, v0
	s_nop 1
	v_permlane16_swap_b32_e32 v0, v1
	v_add_f32_e32 v0, v0, v1
	s_waitcnt lgkmcnt(0)
	s_add_u32 s8, s8, s12
	v_mov_b32_e32 v1, v0
	s_addc_u32 s9, s9, s13
	s_lshl_b32 s11, s10, 2
	v_permlane32_swap_b32_e32 v0, v1
	s_add_u32 s8, s8, s11
	v_add_f32_e32 v0, v0, v1
	s_addc_u32 s9, s9, 0
	v_lshlrev_b32_e32 v24, 2, v91
	v_mul_f32_e32 v32, 0x3c800000, v0
	global_load_dwordx4 v[0:3], v24, s[8:9]
	global_load_dwordx2 v[36:37], v[34:35], off offset:1536
	global_load_dwordx4 v[12:15], v24, s[8:9] offset:64
	global_load_dwordx2 v[46:47], v[34:35], off offset:1568
	global_load_dwordx4 v[8:11], v24, s[8:9] offset:128
	global_load_dwordx2 v[44:45], v[34:35], off offset:1600
	s_nop 0
	global_load_dwordx4 v[24:27], v24, s[8:9] offset:192
	s_nop 0
	global_load_dwordx2 v[38:39], v[34:35], off offset:1632
	v_sub_f32_e32 v30, v30, v32
	v_sub_f32_e32 v31, v31, v32
	v_sub_f32_e32 v28, v28, v32
	v_sub_f32_e32 v29, v29, v32
	v_lshlrev_b64 v[34:35], 11, v[86:87]
	v_mul_f32_e32 v42, v29, v29
	v_fma_f32 v43, v29, v29, v42
	v_fma_f32 v42, v28, v28, v42
	v_lshl_add_u64 v[34:35], s[6:7], 0, v[34:35]
	v_fma_f32 v42, v30, v30, v42
	v_fma_f32 v43, v31, v31, v43
	s_lshl_b32 s96, s10, 1
	v_lshl_add_u64 v[34:35], v[34:35], 0, s[96:97]
	s_mov_b64 s[6:7], 0xf000000
	s_waitcnt vmcnt(6)
	v_lshlrev_b32_e32 v48, 16, v36
	v_mul_f32_e32 v33, 0xbfb8aa3b, v48
	v_exp_f32_e32 v33, v33
	v_and_b32_e32 v49, 0xffff0000, v36
	v_lshlrev_b32_e32 v40, 16, v37
	v_and_b32_e32 v41, 0xffff0000, v37
	v_add_f32_e32 v33, 1.0, v33
	v_rcp_f32_e32 v36, v33
	v_mul_f32_e32 v33, 0xbfb8aa3b, v49
	v_exp_f32_e32 v33, v33
	s_waitcnt vmcnt(4)
	v_lshlrev_b32_e32 v50, 16, v47
	v_and_b32_e32 v51, 0xffff0000, v47
	v_add_f32_e32 v33, 1.0, v33
	v_rcp_f32_e32 v37, v33
	v_mul_f32_e32 v33, 0xbfb8aa3b, v40
	v_exp_f32_e32 v33, v33
	v_mul_f32_e32 v36, v36, v48
	v_mul_f32_e32 v37, v37, v49
	v_mul_f32_e32 v48, v31, v31
	v_add_f32_e32 v33, 1.0, v33
	v_add_f32_e32 v49, v48, v43
	v_add_f32_e32 v48, v48, v42
	v_rcp_f32_e32 v42, v33
	v_mul_f32_e32 v33, 0xbfb8aa3b, v41
	v_exp_f32_e32 v33, v33
	s_nop 0
	v_add_f32_e32 v33, 1.0, v33
	v_sub_f32_e32 v20, v20, v32
	v_sub_f32_e32 v21, v21, v32
	v_rcp_f32_e32 v43, v33
	v_fma_f32 v48, v20, v20, v48
	v_fma_f32 v49, v21, v21, v49
	v_mul_f32_e32 v52, v21, v21
	v_add_f32_e32 v48, v52, v48
	v_add_f32_e32 v49, v52, v49
	v_lshlrev_b32_e32 v52, 16, v46
	v_sub_f32_e32 v22, v22, v32
	v_sub_f32_e32 v23, v23, v32
	v_mul_f32_e32 v33, 0xbfb8aa3b, v52
	v_exp_f32_e32 v33, v33
	v_and_b32_e32 v53, 0xffff0000, v46
	v_fma_f32 v48, v22, v22, v48
	v_fma_f32 v49, v23, v23, v49
	v_mul_f32_e32 v42, v42, v40
	v_mul_f32_e32 v43, v43, v41
	v_add_f32_e32 v33, 1.0, v33
	v_rcp_f32_e32 v46, v33
	v_mul_f32_e32 v33, 0xbfb8aa3b, v53
	v_exp_f32_e32 v33, v33
	v_lshl_add_u64 v[40:41], v[34:35], 0, v[64:65]
	v_lshl_add_u64 v[34:35], v[40:41], 0, s[6:7]
	s_mov_b32 s6, 0xf000000
	v_add_f32_e32 v33, 1.0, v33
	v_rcp_f32_e32 v47, v33
	v_mul_f32_e32 v33, 0xbfb8aa3b, v50
	v_exp_f32_e32 v33, v33
	v_mul_f32_e32 v46, v46, v52
	v_mul_f32_e32 v47, v47, v53
	v_mul_f32_e32 v52, v23, v23
	v_add_f32_e32 v33, 1.0, v33
	v_add_f32_e32 v48, v52, v48
	v_add_f32_e32 v49, v52, v49
	v_rcp_f32_e32 v52, v33
	v_mul_f32_e32 v33, 0xbfb8aa3b, v51
	v_exp_f32_e32 v33, v33
	s_nop 0
	v_add_f32_e32 v33, 1.0, v33
	v_sub_f32_e32 v16, v16, v32
	v_sub_f32_e32 v17, v17, v32
	v_rcp_f32_e32 v53, v33
	v_fma_f32 v48, v16, v16, v48
	v_fma_f32 v49, v17, v17, v49
	v_mul_f32_e32 v54, v17, v17
	v_add_f32_e32 v48, v54, v48
	v_add_f32_e32 v49, v54, v49
	s_waitcnt vmcnt(2)
	v_lshlrev_b32_e32 v54, 16, v44
	v_sub_f32_e32 v18, v18, v32
	v_sub_f32_e32 v19, v19, v32
	v_mul_f32_e32 v33, 0xbfb8aa3b, v54
	v_exp_f32_e32 v33, v33
	v_and_b32_e32 v55, 0xffff0000, v44
	v_mul_f32_e32 v50, v52, v50
	v_mul_f32_e32 v51, v53, v51
	v_lshlrev_b32_e32 v52, 16, v45
	v_add_f32_e32 v33, 1.0, v33
	v_rcp_f32_e32 v44, v33
	v_mul_f32_e32 v33, 0xbfb8aa3b, v55
	v_exp_f32_e32 v33, v33
	v_and_b32_e32 v53, 0xffff0000, v45
	v_fma_f32 v48, v18, v18, v48
	v_fma_f32 v49, v19, v19, v49
	v_add_f32_e32 v33, 1.0, v33
	v_rcp_f32_e32 v45, v33
	v_mul_f32_e32 v33, 0xbfb8aa3b, v52
	v_exp_f32_e32 v33, v33
	v_mul_f32_e32 v44, v44, v54
	v_mul_f32_e32 v45, v45, v55
	v_mul_f32_e32 v54, v19, v19
	v_add_f32_e32 v33, 1.0, v33
	v_add_f32_e32 v48, v54, v48
	v_add_f32_e32 v49, v54, v49
	v_rcp_f32_e32 v54, v33
	v_mul_f32_e32 v33, 0xbfb8aa3b, v53
	v_exp_f32_e32 v33, v33
	s_nop 0
	v_add_f32_e32 v33, 1.0, v33
	v_rcp_f32_e32 v55, v33
	v_sub_f32_e32 v4, v4, v32
	v_sub_f32_e32 v5, v5, v32
	v_sub_f32_e32 v6, v6, v32
	v_sub_f32_e32 v7, v7, v32
	v_fma_f32 v32, v4, v4, v48
	v_fma_f32 v33, v5, v5, v49
	v_mul_f32_e32 v48, v5, v5
	v_add_f32_e32 v32, v48, v32
	v_add_f32_e32 v33, v48, v33
	s_waitcnt vmcnt(0)
	v_lshlrev_b32_e32 v48, 16, v38
	v_and_b32_e32 v49, 0xffff0000, v38
	v_mul_f32_e32 v52, v54, v52
	v_mul_f32_e32 v53, v55, v53
	v_lshlrev_b32_e32 v54, 16, v39
	v_and_b32_e32 v55, 0xffff0000, v39
	v_mul_f32_e32 v38, 0xbfb8aa3b, v48
	v_mul_f32_e32 v39, 0xbfb8aa3b, v49
	v_exp_f32_e32 v38, v38
	v_exp_f32_e32 v39, v39
	v_fma_f32 v32, v6, v6, v32
	v_fma_f32 v33, v7, v7, v33
	v_add_f32_e32 v38, 1.0, v38
	v_add_f32_e32 v39, 1.0, v39
	v_rcp_f32_e32 v38, v38
	v_rcp_f32_e32 v39, v39
	s_nop 0
	v_mul_f32_e32 v38, v38, v48
	v_mul_f32_e32 v39, v39, v49
	v_mul_f32_e32 v48, v7, v7
	v_add_f32_e32 v32, v48, v32
	v_add_f32_e32 v33, v48, v33
	v_mov_b32_e32 v33, v32
	s_nop 1
	v_permlane16_swap_b32_e32 v32, v33
	v_add_f32_e32 v32, v32, v33
	v_mov_b32_e32 v33, v32
	s_nop 1
	v_permlane32_swap_b32_e32 v32, v33
	v_add_f32_e32 v32, v32, v33
	v_fmamk_f32 v32, v32, 0x3c800000, v229
	v_cmp_gt_f32_e32 vcc, s55, v32
	v_mul_f32_e32 v33, 0x4b800000, v32
	s_nop 0
	v_cndmask_b32_e32 v32, v32, v33, vcc
	v_rsq_f32_e32 v32, v32
	s_nop 0
	v_mul_f32_e32 v33, 0x45800000, v32
	v_cndmask_b32_e32 v32, v32, v33, vcc
	v_mul_f32_e32 v28, v28, v32
	v_mul_f32_e32 v29, v29, v32
	s_nop 0
	v_mul_f32_e32 v0, v0, v28
	v_mul_f32_e32 v1, v1, v29
	v_mul_f32_e32 v28, v30, v32
	v_mul_f32_e32 v29, v31, v32
	v_mul_f32_e32 v0, v36, v0
	v_mul_f32_e32 v1, v37, v1
	v_mul_f32_e32 v2, v2, v28
	v_mul_f32_e32 v3, v3, v29
	v_cvt_pk_bf16_f32 v0, v0, v1
	v_mul_f32_e32 v2, v42, v2
	v_mul_f32_e32 v3, v43, v3
	s_nop 0
	v_cvt_pk_bf16_f32 v1, v2, v3
	v_add_co_u32_e32 v2, vcc, s6, v40
	s_nop 1
	v_addc_co_u32_e32 v3, vcc, 0, v41, vcc
	global_store_dwordx2 v[2:3], v[0:1], off
	v_mul_f32_e32 v0, v20, v32
	v_mul_f32_e32 v1, v21, v32
	v_mul_f32_e32 v2, v22, v32
	v_mul_f32_e32 v3, v23, v32
	v_mul_f32_e32 v0, v12, v0
	v_mul_f32_e32 v1, v13, v1
	v_mul_f32_e32 v2, v14, v2
	v_mul_f32_e32 v3, v15, v3
	v_mul_f32_e32 v0, v0, v46
	v_mul_f32_e32 v1, v1, v47
	v_mul_f32_e32 v2, v2, v50
	v_mul_f32_e32 v3, v3, v51
	v_cvt_pk_bf16_f32 v0, v0, v1
	v_cvt_pk_bf16_f32 v1, v2, v3
	global_store_dwordx2 v[34:35], v[0:1], off offset:32
	v_mul_f32_e32 v0, v16, v32
	v_mul_f32_e32 v1, v17, v32
	v_mul_f32_e32 v2, v18, v32
	v_mul_f32_e32 v3, v19, v32
	v_mul_f32_e32 v0, v8, v0
	v_mul_f32_e32 v1, v9, v1
	v_mul_f32_e32 v2, v10, v2
	v_mul_f32_e32 v3, v11, v3
	v_mul_f32_e32 v0, v0, v44
	v_mul_f32_e32 v1, v1, v45
	v_mul_f32_e32 v2, v2, v52
	v_mul_f32_e32 v3, v3, v53
	v_cvt_pk_bf16_f32 v0, v0, v1
	v_cvt_pk_bf16_f32 v1, v2, v3
	v_mul_f32_e32 v2, 0xbfb8aa3b, v54
	v_mul_f32_e32 v3, 0xbfb8aa3b, v55
	v_exp_f32_e32 v2, v2
	v_exp_f32_e32 v3, v3
	global_store_dwordx2 v[34:35], v[0:1], off offset:64
	v_mul_f32_e32 v0, v4, v32
	v_mul_f32_e32 v1, v5, v32
	v_add_f32_e32 v2, 1.0, v2
	v_add_f32_e32 v3, 1.0, v3
	v_rcp_f32_e32 v2, v2
	v_rcp_f32_e32 v3, v3
	v_mul_f32_e32 v4, v6, v32
	v_mul_f32_e32 v5, v7, v32
	v_mul_f32_e32 v0, v24, v0
	v_mul_f32_e32 v1, v25, v1
	v_mul_f32_e32 v4, v26, v4
	v_mul_f32_e32 v5, v27, v5
	v_mul_f32_e32 v2, v2, v54
	v_mul_f32_e32 v3, v3, v55
	v_mul_f32_e32 v0, v0, v38
	v_mul_f32_e32 v1, v1, v39
	v_mul_f32_e32 v2, v4, v2
	v_mul_f32_e32 v3, v5, v3
	v_cvt_pk_bf16_f32 v0, v0, v1
	v_cvt_pk_bf16_f32 v1, v2, v3
	global_store_dwordx2 v[34:35], v[0:1], off offset:96

.LBB0_1098:
	v_cmp_eq_u32_e32 vcc, 0, v11
	v_lshlrev_b32_e32 v105, 2, v11
	s_waitcnt lgkmcnt(0)
	v_cndmask_b32_e64 v104, 0, 1.0, vcc
	s_and_b64 vcc, exec, s[16:17]
	s_barrier
	s_cbranch_vccz .LBB0_1832
	s_waitcnt vmcnt(0)
	v_lshlrev_b32_e32 v16, 16, v4
	v_and_b32_e32 v17, 0xffff0000, v4
	s_mov_b32 s16, 0x3e38aa3b
	v_lshlrev_b32_e32 v4, 16, v5
	v_and_b32_e32 v5, 0xffff0000, v5
	v_mul_f32_e32 v4, s16, v4
	v_mul_f32_e32 v5, s16, v5
	v_lshlrev_b32_e32 v18, 16, v6
	v_and_b32_e32 v19, 0xffff0000, v6
	v_lshlrev_b32_e32 v6, 16, v7
	v_and_b32_e32 v7, 0xffff0000, v7
	s_lshl_b64 s[14:15], s[14:15], 2
	v_mul_f32_e32 v6, s16, v6
	v_mul_f32_e32 v7, s16, v7
	v_cvt_pk_bf16_f32 v67, v4, v5
	v_lshlrev_b32_e32 v4, 16, v0
	v_and_b32_e32 v5, 0xffff0000, v0
	v_lshlrev_b32_e32 v0, 16, v1
	v_and_b32_e32 v1, 0xffff0000, v1
	s_add_u32 s8, s8, s14
	v_cvt_pk_bf16_f32 v69, v6, v7
	v_mul_f32_e32 v4, s16, v4
	v_mul_f32_e32 v5, s16, v5
	v_mul_f32_e32 v0, s16, v0
	v_mul_f32_e32 v1, s16, v1
	v_lshlrev_b32_e32 v6, 16, v2
	v_and_b32_e32 v7, 0xffff0000, v2
	v_lshlrev_b32_e32 v2, 16, v3
	v_and_b32_e32 v3, 0xffff0000, v3
	s_addc_u32 s9, s9, s15
	v_ashrrev_i32_e32 v9, 31, v8
	v_mul_f32_e32 v2, s16, v2
	v_mul_f32_e32 v3, s16, v3
	v_cvt_pk_bf16_f32 v70, v4, v5
	v_cvt_pk_bf16_f32 v71, v0, v1
	s_add_u32 s10, s10, s14
	v_and_b32_e32 v5, 7, v13
	v_lshlrev_b64 v[0:1], 9, v[8:9]
	v_cvt_pk_bf16_f32 v73, v2, v3
	s_addc_u32 s11, s11, s15
	v_lshl_add_u64 v[2:3], s[8:9], 0, v[0:1]
	v_lshlrev_b32_e32 v64, 4, v5
	v_lshl_add_u64 v[98:99], v[2:3], 0, v[64:65]
	v_lshl_add_u64 v[0:1], s[10:11], 0, v[0:1]
	v_lshlrev_b32_e32 v64, 5, v5
	v_mov_b32_e32 v97, v65
	v_lshl_add_u64 v[100:101], v[0:1], 0, v[64:65]
	v_lshl_add_u64 v[0:1], s[12:13], 0, v[96:97]
	s_lshl_b32 s96, s33, 1
	s_min_u32 s8, s25, 0x80
	v_lshlrev_b32_e32 v64, 2, v11
	v_lshrrev_b32_e32 v3, 2, v10
	v_lshl_add_u64 v[102:103], v[0:1], 0, s[96:97]
	v_add_u32_e32 v0, s8, v10
	v_ashrrev_i32_e32 v4, 3, v15
	v_lshlrev_b32_e32 v2, 3, v10
	v_or_b32_e32 v3, v64, v3
	s_sub_i32 s14, s8, s25
	v_add_u32_e32 v1, v0, v12
	v_sub_u32_e32 v0, v64, v0
	s_add_i32 s25, s25, s24
	v_mul_f32_e32 v16, s16, v16
	v_mul_f32_e32 v17, s16, v17
	v_and_b32_e32 v2, 24, v2
	v_mul_u32_u24_e32 v3, 0x90, v3
	v_sub_u32_e32 v112, v0, v12
	v_add_u32_e32 v0, s25, v4
	v_mul_f32_e32 v18, s16, v18
	v_mul_f32_e32 v19, s16, v19
	v_cvt_pk_bf16_f32 v66, v16, v17
	v_mul_f32_e32 v6, s16, v6
	v_mul_f32_e32 v7, s16, v7
	v_mul_lo_u32 v106, v8, s94
	v_lshl_add_u32 v16, v11, 4, 0
	v_mul_u32_u24_e32 v17, 0x90, v10
	v_add3_u32 v97, 0, v2, v3
	v_subrev_u32_e32 v113, s8, v0
	v_add_u32_e32 v0, s25, v8
	v_cvt_pk_bf16_f32 v68, v18, v19
	v_cvt_pk_bf16_f32 v72, v6, v7
	v_mul_f32_e32 v116, 0x3fb8aa3b, v14
	v_add_u32_e32 v107, 0, v106
	v_add_u32_e32 v108, 0, v96
	v_mul_lo_u32 v109, v4, s94
	v_add_u32_e32 v110, 0xd800, v97
	v_sub_u32_e32 v111, v1, v64
	s_mov_b32 s15, 0
	s_sub_i32 s16, 0, s22
	v_subrev_u32_e32 v114, s8, v0
	v_mov_b32_e32 v0, v65
	v_mov_b32_e32 v1, v65
	v_mov_b32_e32 v2, v65
	v_mov_b32_e32 v3, v65
	v_mov_b32_e32 v4, v65
	v_mov_b32_e32 v5, v65
	v_mov_b32_e32 v6, v65
	v_mov_b32_e32 v7, v65
	v_mov_b32_e32 v8, v65
	v_mov_b32_e32 v9, v65
	v_mov_b32_e32 v10, v65
	v_mov_b32_e32 v11, v65
	v_mov_b32_e32 v12, v65
	v_mov_b32_e32 v13, v65
	v_mov_b32_e32 v14, v65
	v_mov_b32_e32 v15, v65
	v_add_u32_e32 v115, v16, v17
	s_mov_b32 s17, 0
	s_mov_b32 s19, 0
	v_mov_b32_e32 v119, v104
	s_branch .LBB0_1103

.LBB0_1113:
	s_cmp_lt_i32 s19, s22
	s_cselect_b64 s[10:11], -1, 0
	s_cmp_ge_i32 s19, s22
	s_mov_b64 s[12:13], -1
	v_xor_b32_e32 v74, 0x80000000, v116
	s_cbranch_scc0 .LBB0_1117
	ds_read_b128 v[16:19], v115
	ds_read_b128 v[20:23], v115 offset:64
	v_mov_b32_e32 v75, v74
	v_mov_b32_e32 v76, v74
	v_mov_b32_e32 v77, v74
	ds_read_b128 v[24:27], v115 offset:2304
	ds_read_b128 v[28:31], v115 offset:2368
	s_waitcnt lgkmcnt(1)
	v_mfma_f32_16x16x32_bf16 v[24:27], v[24:27], v[66:69], v[74:77]
	v_mov_b32_e32 v117, v116
	v_mfma_f32_16x16x32_bf16 v[16:19], v[16:19], v[66:69], v[74:77]
	v_mfma_f32_16x16x32_bf16 v[90:93], v[20:23], v[70:73], v[16:19]
	ds_read_b128 v[20:23], v115 offset:4672
	s_nop 5
	ds_read_b128 v[16:19], v115 offset:4608
	s_waitcnt lgkmcnt(2)
	v_mfma_f32_16x16x32_bf16 v[86:89], v[28:31], v[70:73], v[24:27]
	s_waitcnt lgkmcnt(0)
	v_mfma_f32_16x16x32_bf16 v[16:19], v[16:19], v[66:69], v[74:77]
	s_nop 0
	ds_read_b128 v[24:27], v115 offset:6912
	v_mfma_f32_16x16x32_bf16 v[78:81], v[20:23], v[70:73], v[16:19]
	v_max3_f32 v20, v92, v90, v91
	s_nop 1
	v_max3_f32 v28, v93, v20, v86
	s_nop 0
	ds_read_b128 v[16:19], v115 offset:6976
	s_waitcnt lgkmcnt(1)
	v_mfma_f32_16x16x32_bf16 v[20:23], v[24:27], v[66:69], v[74:77]
	v_max3_f32 v24, v88, v87, v28
	v_max3_f32 v24, v78, v89, v24
	v_max3_f32 v24, v80, v79, v24
	s_waitcnt lgkmcnt(0)
	v_mfma_f32_16x16x32_bf16 v[82:85], v[16:19], v[70:73], v[20:23]
	v_mov_b32_e32 v75, v119
	s_nop 6
	v_max3_f32 v16, v82, v81, v24
	v_max3_f32 v16, v84, v83, v16
	v_max_f32_e32 v17, v85, v85
	v_max_f32_e32 v16, v17, v16
	v_cmp_lt_f32_e32 vcc, s52, v16
	v_mov_b64_e32 v[30:31], v[14:15]
	v_mov_b64_e32 v[28:29], v[12:13]
	v_mov_b64_e32 v[26:27], v[10:11]
	v_mov_b64_e32 v[24:25], v[8:9]
	v_mov_b64_e32 v[22:23], v[6:7]
	v_mov_b64_e32 v[20:21], v[4:5]
	v_mov_b64_e32 v[18:19], v[2:3]
	v_mov_b64_e32 v[16:17], v[0:1]
	s_cbranch_vccz .LBB0_1116
	v_max_f32_e32 v16, v91, v91
	v_max_f32_e32 v17, v90, v90
	v_max_f32_e32 v16, v17, v16
	v_max3_f32 v16, v16, v92, v93
	v_max3_f32 v16, v16, v86, v87
	v_max3_f32 v16, v16, v88, v89
	v_max3_f32 v16, v16, v78, v79
	v_max3_f32 v16, v16, v80, v81
	v_max3_f32 v16, v16, v82, v83
	v_max3_f32 v16, v16, v84, v85
	v_mov_b32_e32 v17, v16
	s_nop 1
	v_permlane16_swap_b32_e32 v16, v17
	v_max_f32_e32 v17, v17, v17
	v_max_f32_e32 v16, v16, v16
	v_max_f32_e32 v16, v16, v17
	v_mov_b32_e32 v17, v16
	s_nop 1
	v_permlane32_swap_b32_e32 v16, v17
	v_max_f32_e32 v17, v17, v17
	v_max_f32_e32 v16, v16, v16
	v_max_f32_e32 v16, v16, v17
	v_cmp_lt_f32_e32 vcc, s52, v16
	s_nop 1
	v_cndmask_b32_e32 v16, 0, v16, vcc
	v_exp_f32_e64 v76, -v16
	v_add_f32_e32 v117, v116, v16
	v_sub_f32_e32 v90, v90, v16
	v_sub_f32_e32 v91, v91, v16
	v_sub_f32_e32 v92, v92, v16
	v_sub_f32_e32 v93, v93, v16
	v_mul_f32_e32 v75, v119, v76
	v_sub_f32_e32 v86, v86, v16
	v_sub_f32_e32 v87, v87, v16
	v_sub_f32_e32 v88, v88, v16
	v_sub_f32_e32 v89, v89, v16
	v_sub_f32_e32 v78, v78, v16
	v_sub_f32_e32 v79, v79, v16
	v_sub_f32_e32 v80, v80, v16
	v_sub_f32_e32 v81, v81, v16
	v_sub_f32_e32 v82, v82, v16
	v_sub_f32_e32 v83, v83, v16
	v_sub_f32_e32 v84, v84, v16
	v_sub_f32_e32 v85, v85, v16
	v_mul_f32_e32 v30, v14, v76
	v_mul_f32_e32 v31, v15, v76
	v_mul_f32_e32 v28, v12, v76
	v_mul_f32_e32 v29, v13, v76
	v_mul_f32_e32 v26, v10, v76
	v_mul_f32_e32 v27, v11, v76
	v_mul_f32_e32 v24, v8, v76
	v_mul_f32_e32 v25, v9, v76
	v_mul_f32_e32 v22, v6, v76
	v_mul_f32_e32 v23, v7, v76
	v_mul_f32_e32 v20, v4, v76
	v_mul_f32_e32 v21, v5, v76
	v_mul_f32_e32 v18, v2, v76
	v_mul_f32_e32 v19, v3, v76
	v_mul_f32_e32 v16, v0, v76
	v_mul_f32_e32 v17, v1, v76

.LBB0_1117:
	s_and_b64 vcc, exec, s[12:13]
	s_cbranch_vccz .LBB0_1121
	ds_read_b128 v[16:19], v115
	ds_read_b128 v[20:23], v115 offset:64
	v_mov_b32_e32 v75, v74
	v_mov_b32_e32 v76, v74
	v_mov_b32_e32 v77, v74
	v_readfirstlane_b32 s12, v95
	s_add_i32 s13, s14, s12
	s_waitcnt lgkmcnt(1)
	v_mfma_f32_16x16x32_bf16 v[16:19], v[16:19], v[66:69], v[74:77]
	s_add_i32 s24, s21, s15
	s_add_i32 s13, s13, s17
	s_sub_i32 s12, s24, s12
	s_waitcnt lgkmcnt(0)
	v_mfma_f32_16x16x32_bf16 v[16:19], v[20:23], v[70:73], v[16:19]
	ds_read_b128 v[20:23], v115 offset:2304
	ds_read_b128 v[24:27], v115 offset:2368
	s_add_i32 s13, s13, 15
	s_addk_i32 s12, 0x7f
	s_waitcnt lgkmcnt(1)
	v_mfma_f32_16x16x32_bf16 v[20:23], v[20:23], v[66:69], v[74:77]
	s_max_i32 s12, s13, s12
	v_add_u32_e32 v117, s17, v111
	s_cmpk_gt_i32 s12, 0x80
	s_waitcnt lgkmcnt(0)
	v_mfma_f32_16x16x32_bf16 v[20:23], v[24:27], v[70:73], v[20:23]
	ds_read_b128 v[24:27], v115 offset:4608
	ds_read_b128 v[28:31], v115 offset:4672
	s_cselect_b64 s[12:13], -1, 0
	s_movk_i32 s24, 0x100
	s_waitcnt lgkmcnt(1)
	v_mfma_f32_16x16x32_bf16 v[24:27], v[24:27], v[66:69], v[74:77]
	s_waitcnt lgkmcnt(0)
	v_mfma_f32_16x16x32_bf16 v[24:27], v[28:31], v[70:73], v[24:27]
	ds_read_b128 v[28:31], v115 offset:6912
	ds_read_b128 v[78:81], v115 offset:6976
	s_waitcnt lgkmcnt(1)
	v_mfma_f32_16x16x32_bf16 v[28:31], v[28:31], v[66:69], v[74:77]
	s_waitcnt lgkmcnt(0)
	v_mfma_f32_16x16x32_bf16 v[28:31], v[78:81], v[70:73], v[28:31]
	ds_read_b128 v[78:81], v115 offset:9216
	ds_read_b128 v[82:85], v115 offset:9280
	s_waitcnt lgkmcnt(1)
	v_mfma_f32_16x16x32_bf16 v[78:81], v[78:81], v[66:69], v[74:77]
	s_waitcnt lgkmcnt(0)
	v_mfma_f32_16x16x32_bf16 v[90:93], v[82:85], v[70:73], v[78:81]
	s_nop 5
	ds_read_b128 v[78:81], v115 offset:11520
	ds_read_b128 v[82:85], v115 offset:11584
	s_waitcnt lgkmcnt(1)
	v_mfma_f32_16x16x32_bf16 v[78:81], v[78:81], v[66:69], v[74:77]
	s_waitcnt lgkmcnt(0)
	v_mfma_f32_16x16x32_bf16 v[120:123], v[82:85], v[70:73], v[78:81]
	s_nop 5
	ds_read_b128 v[78:81], v115 offset:13824
	ds_read_b128 v[82:85], v115 offset:13888
	s_waitcnt lgkmcnt(1)
	v_mfma_f32_16x16x32_bf16 v[78:81], v[78:81], v[66:69], v[74:77]
	s_waitcnt lgkmcnt(0)
	v_mfma_f32_16x16x32_bf16 v[124:127], v[82:85], v[70:73], v[78:81]
	s_nop 5
	ds_read_b128 v[78:81], v115 offset:16128
	ds_read_b128 v[82:85], v115 offset:16192
	s_waitcnt lgkmcnt(1)
	v_mfma_f32_16x16x32_bf16 v[74:77], v[78:81], v[66:69], v[74:77]
	s_waitcnt lgkmcnt(0)
	v_mfma_f32_16x16x32_bf16 v[128:131], v[82:85], v[70:73], v[74:77]
	s_nop 5
	v_add_u32_e32 v74, 0xffffff7f, v117
	v_cmp_gt_u32_e32 vcc, s54, v74
	s_and_b64 vcc, s[12:13], vcc
	s_nop 0
	v_cndmask_b32_e32 v84, v16, v236, vcc
	v_add_u32_e32 v16, s15, v112
	v_add_u32_e32 v16, 0x81, v16
	v_cmp_lt_u32_e32 vcc, s24, v16
	s_and_b64 vcc, s[12:13], vcc
	v_add_u32_e32 v16, 0xffffff7d, v117
	v_cndmask_b32_e32 v87, v17, v236, vcc
	v_cmp_gt_u32_e32 vcc, s54, v16
	s_and_b64 vcc, s[12:13], vcc
	v_add_u32_e32 v16, 0xffffff7c, v117
	v_cndmask_b32_e32 v88, v18, v236, vcc
	v_cmp_gt_u32_e32 vcc, s54, v16
	s_and_b64 vcc, s[12:13], vcc
	v_add_u32_e32 v16, 0xffffff6f, v117
	v_cndmask_b32_e32 v89, v19, v236, vcc
	v_cmp_gt_u32_e32 vcc, s54, v16
	s_and_b64 vcc, s[12:13], vcc
	v_add_u32_e32 v16, 0xffffff6e, v117
	v_cndmask_b32_e32 v86, v20, v236, vcc
	v_cmp_gt_u32_e32 vcc, s54, v16
	s_and_b64 vcc, s[12:13], vcc
	v_add_u32_e32 v16, 0xffffff6d, v117
	v_cndmask_b32_e32 v85, v21, v236, vcc
	v_cmp_gt_u32_e32 vcc, s54, v16
	s_and_b64 vcc, s[12:13], vcc
	v_add_u32_e32 v16, 0xffffff6c, v117
	v_cndmask_b32_e32 v83, v22, v236, vcc
	v_cmp_gt_u32_e32 vcc, s54, v16
	s_and_b64 vcc, s[12:13], vcc
	v_add_u32_e32 v16, 0xffffff5f, v117
	v_cndmask_b32_e32 v82, v23, v236, vcc
	v_cmp_gt_u32_e32 vcc, s54, v16
	s_and_b64 vcc, s[12:13], vcc
	v_add_u32_e32 v16, 0xffffff5e, v117
	v_cndmask_b32_e32 v81, v24, v236, vcc
	v_cmp_gt_u32_e32 vcc, s54, v16
	s_and_b64 vcc, s[12:13], vcc
	v_add_u32_e32 v16, 0xffffff5d, v117
	v_cndmask_b32_e32 v80, v25, v236, vcc
	v_cmp_gt_u32_e32 vcc, s54, v16
	s_and_b64 vcc, s[12:13], vcc
	v_add_u32_e32 v16, 0xffffff5c, v117
	v_cndmask_b32_e32 v79, v26, v236, vcc
	v_cmp_gt_u32_e32 vcc, s54, v16
	s_and_b64 vcc, s[12:13], vcc
	v_add_u32_e32 v16, 0xffffff4f, v117
	v_cndmask_b32_e32 v78, v27, v236, vcc
	v_cmp_gt_u32_e32 vcc, s54, v16
	s_and_b64 vcc, s[12:13], vcc
	v_add_u32_e32 v16, 0xffffff4e, v117
	v_cndmask_b32_e32 v77, v28, v236, vcc
	v_cmp_gt_u32_e32 vcc, s54, v16
	s_and_b64 vcc, s[12:13], vcc
	v_add_u32_e32 v16, 0xffffff4d, v117
	v_cndmask_b32_e32 v76, v29, v236, vcc
	v_cmp_gt_u32_e32 vcc, s54, v16
	s_and_b64 vcc, s[12:13], vcc
	v_add_u32_e32 v16, 0xffffff4c, v117
	v_cndmask_b32_e32 v75, v30, v236, vcc
	v_cmp_gt_u32_e32 vcc, s54, v16
	s_and_b64 vcc, s[12:13], vcc
	v_add_u32_e32 v16, 0xffffff3f, v117
	v_cndmask_b32_e32 v74, v31, v236, vcc
	v_cmp_gt_u32_e32 vcc, s54, v16
	s_and_b64 vcc, s[12:13], vcc
	v_add_u32_e32 v16, 0xffffff3e, v117
	v_cndmask_b32_e32 v31, v90, v236, vcc
	v_cmp_gt_u32_e32 vcc, s54, v16
	s_and_b64 vcc, s[12:13], vcc
	v_add_u32_e32 v16, 0xffffff3d, v117
	v_cndmask_b32_e32 v30, v91, v236, vcc
	v_cmp_gt_u32_e32 vcc, s54, v16
	s_and_b64 vcc, s[12:13], vcc
	v_add_u32_e32 v16, 0xffffff3c, v117
	v_cndmask_b32_e32 v29, v92, v236, vcc
	v_cmp_gt_u32_e32 vcc, s54, v16
	s_and_b64 vcc, s[12:13], vcc
	v_add_u32_e32 v16, 0xffffff2f, v117
	v_cndmask_b32_e32 v27, v93, v236, vcc
	v_cmp_gt_u32_e32 vcc, s54, v16
	s_and_b64 vcc, s[12:13], vcc
	v_add_u32_e32 v16, 0xffffff2e, v117
	v_cndmask_b32_e32 v25, v120, v236, vcc
	v_cmp_gt_u32_e32 vcc, s54, v16
	s_and_b64 vcc, s[12:13], vcc
	v_add_u32_e32 v16, 0xffffff2d, v117
	v_cndmask_b32_e32 v23, v121, v236, vcc
	v_cmp_gt_u32_e32 vcc, s54, v16
	s_and_b64 vcc, s[12:13], vcc
	v_add_u32_e32 v16, 0xffffff2c, v117
	v_cndmask_b32_e32 v20, v122, v236, vcc
	v_cmp_gt_u32_e32 vcc, s54, v16
	s_and_b64 vcc, s[12:13], vcc
	v_add_u32_e32 v17, 0xffffff1f, v117
	v_cndmask_b32_e32 v16, v123, v236, vcc
	v_cmp_gt_u32_e32 vcc, s54, v17
	s_and_b64 vcc, s[12:13], vcc
	v_add_u32_e32 v18, 0xffffff1e, v117
	v_cndmask_b32_e32 v17, v124, v236, vcc
	v_cmp_gt_u32_e32 vcc, s54, v18
	s_and_b64 vcc, s[12:13], vcc
	v_add_u32_e32 v19, 0xffffff1d, v117
	v_max3_f32 v90, v88, v84, v87
	v_cndmask_b32_e32 v18, v125, v236, vcc
	v_cmp_gt_u32_e32 vcc, s54, v19
	v_max3_f32 v90, v86, v89, v90
	s_and_b64 vcc, s[12:13], vcc
	v_add_u32_e32 v21, 0xffffff1c, v117
	v_max3_f32 v90, v83, v85, v90
	v_cndmask_b32_e32 v19, v126, v236, vcc
	v_cmp_gt_u32_e32 vcc, s54, v21
	v_max3_f32 v90, v81, v82, v90
	s_and_b64 vcc, s[12:13], vcc
	v_add_u32_e32 v22, 0xffffff0f, v117
	v_max3_f32 v90, v79, v80, v90
	v_cndmask_b32_e32 v21, v127, v236, vcc
	v_cmp_gt_u32_e32 vcc, s54, v22
	v_max3_f32 v90, v77, v78, v90
	s_and_b64 vcc, s[12:13], vcc
	v_add_u32_e32 v24, 0xffffff0e, v117
	v_max3_f32 v90, v75, v76, v90
	v_cndmask_b32_e32 v22, v128, v236, vcc
	v_cmp_gt_u32_e32 vcc, s54, v24
	v_max3_f32 v90, v31, v74, v90
	s_and_b64 vcc, s[12:13], vcc
	v_add_u32_e32 v26, 0xffffff0d, v117
	v_max3_f32 v90, v29, v30, v90
	v_cndmask_b32_e32 v24, v129, v236, vcc
	v_cmp_gt_u32_e32 vcc, s54, v26
	v_max3_f32 v90, v25, v27, v90
	s_and_b64 vcc, s[12:13], vcc
	v_add_u32_e32 v28, 0xffffff0c, v117
	v_max3_f32 v90, v20, v23, v90
	v_cndmask_b32_e32 v26, v130, v236, vcc
	v_cmp_gt_u32_e32 vcc, s54, v28
	v_max3_f32 v90, v17, v16, v90
	s_and_b64 vcc, s[12:13], vcc
	v_max3_f32 v90, v19, v18, v90
	v_cndmask_b32_e32 v28, v131, v236, vcc
	v_max3_f32 v90, v22, v21, v90
	v_max3_f32 v90, v26, v24, v90
	v_max_f32_e32 v91, v28, v28
	v_max_f32_e32 v90, v91, v90
	v_cmp_lt_f32_e32 vcc, s52, v90
	s_cbranch_vccz .LBB0_1120
	v_max_f32_e32 v90, v87, v87
	v_max_f32_e32 v91, v84, v84
	v_max_f32_e32 v90, v91, v90
	v_max3_f32 v90, v90, v88, v89
	v_max3_f32 v90, v90, v86, v85
	v_max3_f32 v90, v90, v83, v82
	v_max3_f32 v90, v90, v81, v80
	v_max3_f32 v90, v90, v79, v78
	v_max3_f32 v90, v90, v77, v76
	v_max3_f32 v90, v90, v75, v74
	v_max3_f32 v90, v90, v31, v30
	v_max3_f32 v90, v90, v29, v27
	v_max3_f32 v90, v90, v25, v23
	v_max3_f32 v90, v90, v20, v16
	v_max3_f32 v90, v90, v17, v18
	v_max3_f32 v90, v90, v19, v21
	v_max3_f32 v90, v90, v22, v24
	v_max3_f32 v90, v90, v26, v28
	v_mov_b32_e32 v91, v90
	s_nop 1
	v_permlane16_swap_b32_e32 v90, v91
	v_max_f32_e32 v91, v91, v91
	v_max_f32_e32 v90, v90, v90
	v_max_f32_e32 v90, v90, v91
	v_mov_b32_e32 v91, v90
	s_nop 1
	v_permlane32_swap_b32_e32 v90, v91
	v_max_f32_e32 v91, v91, v91
	v_max_f32_e32 v90, v90, v90
	v_max_f32_e32 v90, v90, v91
	v_cmp_lt_f32_e32 vcc, s52, v90
	s_nop 1
	v_cndmask_b32_e32 v91, 0, v90, vcc
	v_exp_f32_e64 v90, -v91
	v_add_f32_e32 v116, v116, v91
	v_sub_f32_e32 v84, v84, v91
	v_sub_f32_e32 v87, v87, v91
	v_mul_f32_e32 v119, v119, v90
	v_sub_f32_e32 v88, v88, v91
	v_sub_f32_e32 v89, v89, v91
	v_sub_f32_e32 v86, v86, v91
	v_sub_f32_e32 v85, v85, v91
	v_sub_f32_e32 v83, v83, v91
	v_sub_f32_e32 v82, v82, v91
	v_sub_f32_e32 v81, v81, v91
	v_sub_f32_e32 v80, v80, v91
	v_sub_f32_e32 v79, v79, v91
	v_sub_f32_e32 v78, v78, v91
	v_sub_f32_e32 v77, v77, v91
	v_sub_f32_e32 v76, v76, v91
	v_sub_f32_e32 v75, v75, v91
	v_sub_f32_e32 v74, v74, v91
	v_sub_f32_e32 v31, v31, v91
	v_sub_f32_e32 v30, v30, v91
	v_sub_f32_e32 v29, v29, v91
	v_sub_f32_e32 v27, v27, v91
	v_sub_f32_e32 v25, v25, v91
	v_sub_f32_e32 v23, v23, v91
	v_sub_f32_e32 v20, v20, v91
	v_sub_f32_e32 v16, v16, v91
	v_sub_f32_e32 v17, v17, v91
	v_sub_f32_e32 v18, v18, v91
	v_sub_f32_e32 v19, v19, v91
	v_sub_f32_e32 v21, v21, v91
	v_sub_f32_e32 v22, v22, v91
	v_sub_f32_e32 v24, v24, v91
	v_sub_f32_e32 v26, v26, v91
	v_sub_f32_e32 v28, v28, v91
	v_mul_f32_e32 v14, v14, v90
	v_mul_f32_e32 v15, v15, v90
	v_mul_f32_e32 v12, v12, v90
	v_mul_f32_e32 v13, v13, v90
	v_mul_f32_e32 v10, v10, v90
	v_mul_f32_e32 v11, v11, v90
	v_mul_f32_e32 v8, v8, v90
	v_mul_f32_e32 v9, v9, v90
	v_mul_f32_e32 v6, v6, v90
	v_mul_f32_e32 v7, v7, v90
	v_mul_f32_e32 v4, v4, v90
	v_mul_f32_e32 v5, v5, v90
	v_mul_f32_e32 v2, v2, v90
	v_mul_f32_e32 v3, v3, v90
	v_mul_f32_e32 v0, v0, v90
	v_mul_f32_e32 v1, v1, v90

.LBB0_1133:
	s_mov_b64 s[8:9], -1
	s_cmp_ge_i32 s18, s22
	v_xor_b32_e32 v74, 0x80000000, v117
	s_cbranch_scc0 .LBB0_1138
	ds_read_b128 v[0:3], v115 offset:36864
	ds_read_b128 v[4:7], v115 offset:36928
	v_mov_b32_e32 v75, v74
	v_mov_b32_e32 v76, v74
	v_mov_b32_e32 v77, v74
	s_waitcnt lgkmcnt(1)
	s_nop 0
	v_mfma_f32_16x16x32_bf16 v[0:3], v[0:3], v[66:69], v[74:77]
	s_waitcnt lgkmcnt(0)
	v_mfma_f32_16x16x32_bf16 v[90:93], v[4:7], v[70:73], v[0:3]
	s_nop 5
	ds_read_b128 v[0:3], v115 offset:39168
	ds_read_b128 v[4:7], v115 offset:39232
	s_waitcnt lgkmcnt(1)
	v_mfma_f32_16x16x32_bf16 v[0:3], v[0:3], v[66:69], v[74:77]
	s_waitcnt lgkmcnt(0)
	v_mfma_f32_16x16x32_bf16 v[86:89], v[4:7], v[70:73], v[0:3]
	s_nop 5
	ds_read_b128 v[0:3], v115 offset:41472
	ds_read_b128 v[4:7], v115 offset:41536
	s_waitcnt lgkmcnt(1)
	v_mfma_f32_16x16x32_bf16 v[0:3], v[0:3], v[66:69], v[74:77]
	s_waitcnt lgkmcnt(0)
	v_mfma_f32_16x16x32_bf16 v[78:81], v[4:7], v[70:73], v[0:3]
	s_nop 5
	ds_read_b128 v[0:3], v115 offset:43776
	ds_read_b128 v[4:7], v115 offset:43840
	s_waitcnt lgkmcnt(1)
	v_mfma_f32_16x16x32_bf16 v[0:3], v[0:3], v[66:69], v[74:77]
	s_waitcnt lgkmcnt(0)
	v_mfma_f32_16x16x32_bf16 v[82:85], v[4:7], v[70:73], v[0:3]
	s_nop 5
	v_max3_f32 v0, v92, v90, v91
	v_max3_f32 v0, v93, v0, v86
	v_max3_f32 v0, v88, v87, v0
	v_max3_f32 v0, v78, v89, v0
	v_max3_f32 v0, v80, v79, v0
	v_max3_f32 v0, v82, v81, v0
	v_max3_f32 v0, v84, v83, v0
	v_max_f32_e32 v1, v85, v85
	v_max_f32_e32 v0, v1, v0
	v_cmp_lt_f32_e32 vcc, s52, v0
	s_cbranch_vccz .LBB0_1136
	v_max_f32_e32 v0, v91, v91
	v_max_f32_e32 v1, v90, v90
	v_max_f32_e32 v0, v1, v0
	v_max3_f32 v0, v0, v92, v93
	v_max3_f32 v0, v0, v86, v87
	v_max3_f32 v0, v0, v88, v89
	v_max3_f32 v0, v0, v78, v79
	v_max3_f32 v0, v0, v80, v81
	v_max3_f32 v0, v0, v82, v83
	v_max3_f32 v0, v0, v84, v85
	v_mov_b32_e32 v1, v0
	s_nop 1
	v_permlane16_swap_b32_e32 v0, v1
	v_max_f32_e32 v1, v1, v1
	v_max_f32_e32 v0, v0, v0
	v_max_f32_e32 v0, v0, v1
	v_mov_b32_e32 v1, v0
	s_nop 1
	v_permlane32_swap_b32_e32 v0, v1
	v_max_f32_e32 v1, v1, v1
	v_max_f32_e32 v0, v0, v0
	v_max_f32_e32 v0, v0, v1
	v_cmp_lt_f32_e32 vcc, s52, v0
	s_nop 1
	v_cndmask_b32_e32 v0, 0, v0, vcc
	v_exp_f32_e64 v12, -v0
	v_add_f32_e32 v116, v117, v0
	v_sub_f32_e32 v90, v90, v0
	v_sub_f32_e32 v91, v91, v0
	v_sub_f32_e32 v92, v92, v0
	v_sub_f32_e32 v93, v93, v0
	v_mul_f32_e32 v75, v118, v12
	v_sub_f32_e32 v86, v86, v0
	v_sub_f32_e32 v87, v87, v0
	v_sub_f32_e32 v88, v88, v0
	v_sub_f32_e32 v89, v89, v0
	v_sub_f32_e32 v78, v78, v0
	v_sub_f32_e32 v79, v79, v0
	v_sub_f32_e32 v80, v80, v0
	v_sub_f32_e32 v81, v81, v0
	v_sub_f32_e32 v82, v82, v0
	v_sub_f32_e32 v83, v83, v0
	v_sub_f32_e32 v84, v84, v0
	v_sub_f32_e32 v85, v85, v0
	v_mul_f32_e32 v10, v26, v12
	v_mul_f32_e32 v11, v27, v12
	v_mul_f32_e32 v8, v24, v12
	v_mul_f32_e32 v9, v25, v12
	v_mul_f32_e32 v6, v22, v12
	v_mul_f32_e32 v7, v23, v12
	v_mul_f32_e32 v4, v20, v12
	v_mul_f32_e32 v5, v21, v12
	v_mul_f32_e32 v2, v18, v12
	v_mul_f32_e32 v3, v19, v12
	v_mul_f32_e32 v0, v16, v12
	v_mul_f32_e32 v1, v17, v12
	v_mul_f32_e32 v14, v30, v12
	v_mul_f32_e32 v15, v31, v12
	v_mul_f32_e32 v13, v29, v12
	v_mul_f32_e32 v12, v28, v12
	s_branch .LBB0_1137

.LBB0_1138:
	s_and_b64 vcc, exec, s[8:9]
	s_cbranch_vccz .LBB0_1101
	ds_read_b128 v[0:3], v115 offset:36864
	ds_read_b128 v[4:7], v115 offset:36928
	v_mov_b32_e32 v75, v74
	v_mov_b32_e32 v76, v74
	v_mov_b32_e32 v77, v74
	v_readfirstlane_b32 s8, v95
	s_add_i32 s9, s14, s8
	s_waitcnt lgkmcnt(1)
	v_mfma_f32_16x16x32_bf16 v[0:3], v[0:3], v[66:69], v[74:77]
	s_add_i32 s10, s21, s15
	s_add_i32 s9, s9, s17
	s_sub_i32 s8, s10, s8
	s_waitcnt lgkmcnt(0)
	v_mfma_f32_16x16x32_bf16 v[0:3], v[4:7], v[70:73], v[0:3]
	ds_read_b128 v[4:7], v115 offset:39168
	ds_read_b128 v[8:11], v115 offset:39232
	s_addk_i32 s9, 0xff8f
	s_addk_i32 s8, 0xff
	s_waitcnt lgkmcnt(1)
	v_mfma_f32_16x16x32_bf16 v[4:7], v[4:7], v[66:69], v[74:77]
	s_max_i32 s8, s9, s8
	s_cmpk_gt_i32 s8, 0x80
	v_add_u32_e32 v116, s17, v111
	s_waitcnt lgkmcnt(0)
	v_mfma_f32_16x16x32_bf16 v[4:7], v[8:11], v[70:73], v[4:7]
	ds_read_b128 v[8:11], v115 offset:41472
	ds_read_b128 v[12:15], v115 offset:41536
	s_cselect_b64 s[8:9], -1, 0
	s_movk_i32 s10, 0x100
	s_waitcnt lgkmcnt(1)
	v_mfma_f32_16x16x32_bf16 v[8:11], v[8:11], v[66:69], v[74:77]
	s_waitcnt lgkmcnt(0)
	v_mfma_f32_16x16x32_bf16 v[8:11], v[12:15], v[70:73], v[8:11]
	ds_read_b128 v[12:15], v115 offset:43776
	ds_read_b128 v[78:81], v115 offset:43840
	s_waitcnt lgkmcnt(1)
	v_mfma_f32_16x16x32_bf16 v[12:15], v[12:15], v[66:69], v[74:77]
	s_waitcnt lgkmcnt(0)
	v_mfma_f32_16x16x32_bf16 v[12:15], v[78:81], v[70:73], v[12:15]
	ds_read_b128 v[78:81], v115 offset:46080
	ds_read_b128 v[82:85], v115 offset:46144
	s_waitcnt lgkmcnt(1)
	v_mfma_f32_16x16x32_bf16 v[78:81], v[78:81], v[66:69], v[74:77]
	s_waitcnt lgkmcnt(0)
	v_mfma_f32_16x16x32_bf16 v[90:93], v[82:85], v[70:73], v[78:81]
	s_nop 5
	ds_read_b128 v[78:81], v115 offset:48384
	ds_read_b128 v[82:85], v115 offset:48448
	s_waitcnt lgkmcnt(1)
	v_mfma_f32_16x16x32_bf16 v[78:81], v[78:81], v[66:69], v[74:77]
	s_waitcnt lgkmcnt(0)
	v_mfma_f32_16x16x32_bf16 v[120:123], v[82:85], v[70:73], v[78:81]
	s_nop 5
	ds_read_b128 v[78:81], v115 offset:50688
	ds_read_b128 v[82:85], v115 offset:50752
	s_waitcnt lgkmcnt(1)
	v_mfma_f32_16x16x32_bf16 v[78:81], v[78:81], v[66:69], v[74:77]
	s_waitcnt lgkmcnt(0)
	v_mfma_f32_16x16x32_bf16 v[124:127], v[82:85], v[70:73], v[78:81]
	s_nop 5
	ds_read_b128 v[78:81], v115 offset:52992
	ds_read_b128 v[82:85], v115 offset:53056
	s_waitcnt lgkmcnt(1)
	v_mfma_f32_16x16x32_bf16 v[74:77], v[78:81], v[66:69], v[74:77]
	s_waitcnt lgkmcnt(0)
	v_mfma_f32_16x16x32_bf16 v[128:131], v[82:85], v[70:73], v[74:77]
	s_nop 5
	v_add_co_u32_e32 v74, vcc, s54, v116
	s_and_b64 vcc, s[8:9], vcc
	s_nop 0
	v_cndmask_b32_e32 v84, v0, v236, vcc
	v_add_u32_e32 v0, s15, v112
	v_add_u32_e32 v0, 0x101, v0
	v_cmp_lt_u32_e32 vcc, s10, v0
	s_and_b64 vcc, s[8:9], vcc
	v_add_u32_e32 v0, 0xfffffefd, v116
	v_cndmask_b32_e32 v87, v1, v236, vcc
	v_cmp_gt_u32_e32 vcc, s54, v0
	s_and_b64 vcc, s[8:9], vcc
	v_add_u32_e32 v0, 0xfffffefc, v116
	v_cndmask_b32_e32 v88, v2, v236, vcc
	v_cmp_gt_u32_e32 vcc, s54, v0
	s_and_b64 vcc, s[8:9], vcc
	v_add_u32_e32 v0, 0xfffffeef, v116
	v_cndmask_b32_e32 v89, v3, v236, vcc
	v_cmp_gt_u32_e32 vcc, s54, v0
	s_and_b64 vcc, s[8:9], vcc
	v_add_u32_e32 v0, 0xfffffeee, v116
	v_cndmask_b32_e32 v86, v4, v236, vcc
	v_cmp_gt_u32_e32 vcc, s54, v0
	s_and_b64 vcc, s[8:9], vcc
	v_add_u32_e32 v0, 0xfffffeed, v116
	v_cndmask_b32_e32 v85, v5, v236, vcc
	v_cmp_gt_u32_e32 vcc, s54, v0
	s_and_b64 vcc, s[8:9], vcc
	v_add_u32_e32 v0, 0xfffffeec, v116
	v_cndmask_b32_e32 v83, v6, v236, vcc
	v_cmp_gt_u32_e32 vcc, s54, v0
	s_and_b64 vcc, s[8:9], vcc
	v_add_u32_e32 v0, 0xfffffedf, v116
	v_cndmask_b32_e32 v82, v7, v236, vcc
	v_cmp_gt_u32_e32 vcc, s54, v0
	s_and_b64 vcc, s[8:9], vcc
	v_add_u32_e32 v0, 0xfffffede, v116
	v_cndmask_b32_e32 v81, v8, v236, vcc
	v_cmp_gt_u32_e32 vcc, s54, v0
	s_and_b64 vcc, s[8:9], vcc
	v_add_u32_e32 v0, 0xfffffedd, v116
	v_cndmask_b32_e32 v80, v9, v236, vcc
	v_cmp_gt_u32_e32 vcc, s54, v0
	s_and_b64 vcc, s[8:9], vcc
	v_add_u32_e32 v0, 0xfffffedc, v116
	v_cndmask_b32_e32 v79, v10, v236, vcc
	v_cmp_gt_u32_e32 vcc, s54, v0
	s_and_b64 vcc, s[8:9], vcc
	v_add_u32_e32 v0, 0xfffffecf, v116
	v_cndmask_b32_e32 v78, v11, v236, vcc
	v_cmp_gt_u32_e32 vcc, s54, v0
	s_and_b64 vcc, s[8:9], vcc
	v_add_u32_e32 v0, 0xfffffece, v116
	v_cndmask_b32_e32 v77, v12, v236, vcc
	v_cmp_gt_u32_e32 vcc, s54, v0
	s_and_b64 vcc, s[8:9], vcc
	v_add_u32_e32 v0, 0xfffffecd, v116
	v_cndmask_b32_e32 v76, v13, v236, vcc
	v_cmp_gt_u32_e32 vcc, s54, v0
	s_and_b64 vcc, s[8:9], vcc
	v_add_u32_e32 v0, 0xfffffecc, v116
	v_cndmask_b32_e32 v75, v14, v236, vcc
	v_cmp_gt_u32_e32 vcc, s54, v0
	s_and_b64 vcc, s[8:9], vcc
	v_add_u32_e32 v0, 0xfffffebf, v116
	v_cndmask_b32_e32 v74, v15, v236, vcc
	v_cmp_gt_u32_e32 vcc, s54, v0
	s_and_b64 vcc, s[8:9], vcc
	v_add_u32_e32 v0, 0xfffffebe, v116
	v_cndmask_b32_e32 v15, v90, v236, vcc
	v_cmp_gt_u32_e32 vcc, s54, v0
	s_and_b64 vcc, s[8:9], vcc
	v_add_u32_e32 v0, 0xfffffebd, v116
	v_cndmask_b32_e32 v14, v91, v236, vcc
	v_cmp_gt_u32_e32 vcc, s54, v0
	s_and_b64 vcc, s[8:9], vcc
	v_add_u32_e32 v0, 0xfffffebc, v116
	v_cndmask_b32_e32 v13, v92, v236, vcc
	v_cmp_gt_u32_e32 vcc, s54, v0
	s_and_b64 vcc, s[8:9], vcc
	v_add_u32_e32 v0, 0xfffffeaf, v116
	v_cndmask_b32_e32 v11, v93, v236, vcc
	v_cmp_gt_u32_e32 vcc, s54, v0
	s_and_b64 vcc, s[8:9], vcc
	v_add_u32_e32 v0, 0xfffffeae, v116
	v_cndmask_b32_e32 v9, v120, v236, vcc
	v_cmp_gt_u32_e32 vcc, s54, v0
	s_and_b64 vcc, s[8:9], vcc
	v_add_u32_e32 v0, 0xfffffead, v116
	v_cndmask_b32_e32 v7, v121, v236, vcc
	v_cmp_gt_u32_e32 vcc, s54, v0
	s_and_b64 vcc, s[8:9], vcc
	v_add_u32_e32 v0, 0xfffffeac, v116
	v_cndmask_b32_e32 v4, v122, v236, vcc
	v_cmp_gt_u32_e32 vcc, s54, v0
	s_and_b64 vcc, s[8:9], vcc
	v_add_u32_e32 v1, 0xfffffe9f, v116
	v_cndmask_b32_e32 v0, v123, v236, vcc
	v_cmp_gt_u32_e32 vcc, s54, v1
	s_and_b64 vcc, s[8:9], vcc
	v_add_u32_e32 v2, 0xfffffe9e, v116
	v_cndmask_b32_e32 v1, v124, v236, vcc
	v_cmp_gt_u32_e32 vcc, s54, v2
	s_and_b64 vcc, s[8:9], vcc
	v_add_u32_e32 v3, 0xfffffe9d, v116
	v_max3_f32 v90, v88, v84, v87
	v_cndmask_b32_e32 v2, v125, v236, vcc
	v_cmp_gt_u32_e32 vcc, s54, v3
	v_max3_f32 v90, v86, v89, v90
	s_and_b64 vcc, s[8:9], vcc
	v_add_u32_e32 v5, 0xfffffe9c, v116
	v_max3_f32 v90, v83, v85, v90
	v_cndmask_b32_e32 v3, v126, v236, vcc
	v_cmp_gt_u32_e32 vcc, s54, v5
	v_max3_f32 v90, v81, v82, v90
	s_and_b64 vcc, s[8:9], vcc
	v_add_u32_e32 v6, 0xfffffe8f, v116
	v_max3_f32 v90, v79, v80, v90
	v_cndmask_b32_e32 v5, v127, v236, vcc
	v_cmp_gt_u32_e32 vcc, s54, v6
	v_max3_f32 v90, v77, v78, v90
	s_and_b64 vcc, s[8:9], vcc
	v_add_u32_e32 v8, 0xfffffe8e, v116
	v_max3_f32 v90, v75, v76, v90
	v_cndmask_b32_e32 v6, v128, v236, vcc
	v_cmp_gt_u32_e32 vcc, s54, v8
	v_max3_f32 v90, v15, v74, v90
	s_and_b64 vcc, s[8:9], vcc
	v_add_u32_e32 v10, 0xfffffe8d, v116
	v_max3_f32 v90, v13, v14, v90
	v_cndmask_b32_e32 v8, v129, v236, vcc
	v_cmp_gt_u32_e32 vcc, s54, v10
	v_max3_f32 v90, v9, v11, v90
	s_and_b64 vcc, s[8:9], vcc
	v_add_u32_e32 v12, 0xfffffe8c, v116
	v_max3_f32 v90, v4, v7, v90
	v_cndmask_b32_e32 v10, v130, v236, vcc
	v_cmp_gt_u32_e32 vcc, s54, v12
	v_max3_f32 v90, v1, v0, v90
	s_and_b64 vcc, s[8:9], vcc
	v_max3_f32 v90, v3, v2, v90
	v_cndmask_b32_e32 v12, v131, v236, vcc
	v_max3_f32 v90, v6, v5, v90
	v_max3_f32 v90, v10, v8, v90
	v_max_f32_e32 v91, v12, v12
	v_max_f32_e32 v90, v91, v90
	v_cmp_lt_f32_e32 vcc, s52, v90
	s_cbranch_vccz .LBB0_1100
	v_max_f32_e32 v90, v87, v87
	v_max_f32_e32 v91, v84, v84
	v_max_f32_e32 v90, v91, v90
	v_max3_f32 v90, v90, v88, v89
	v_max3_f32 v90, v90, v86, v85
	v_max3_f32 v90, v90, v83, v82
	v_max3_f32 v90, v90, v81, v80
	v_max3_f32 v90, v90, v79, v78
	v_max3_f32 v90, v90, v77, v76
	v_max3_f32 v90, v90, v75, v74
	v_max3_f32 v90, v90, v15, v14
	v_max3_f32 v90, v90, v13, v11
	v_max3_f32 v90, v90, v9, v7
	v_max3_f32 v90, v90, v4, v0
	v_max3_f32 v90, v90, v1, v2
	v_max3_f32 v90, v90, v3, v5
	v_max3_f32 v90, v90, v6, v8
	v_max3_f32 v90, v90, v10, v12
	v_mov_b32_e32 v91, v90
	s_nop 1
	v_permlane16_swap_b32_e32 v90, v91
	v_max_f32_e32 v91, v91, v91
	v_max_f32_e32 v90, v90, v90
	v_max_f32_e32 v90, v90, v91
	v_mov_b32_e32 v91, v90
	s_nop 1
	v_permlane32_swap_b32_e32 v90, v91
	v_max_f32_e32 v91, v91, v91
	v_max_f32_e32 v90, v90, v90
	v_max_f32_e32 v90, v90, v91
	v_cmp_lt_f32_e32 vcc, s52, v90
	s_nop 1
	v_cndmask_b32_e32 v91, 0, v90, vcc
	v_exp_f32_e64 v90, -v91
	v_add_f32_e32 v117, v117, v91
	v_sub_f32_e32 v84, v84, v91
	v_sub_f32_e32 v87, v87, v91
	v_mul_f32_e32 v118, v118, v90
	v_sub_f32_e32 v88, v88, v91
	v_sub_f32_e32 v89, v89, v91
	v_sub_f32_e32 v86, v86, v91
	v_sub_f32_e32 v85, v85, v91
	v_sub_f32_e32 v83, v83, v91
	v_sub_f32_e32 v82, v82, v91
	v_sub_f32_e32 v81, v81, v91
	v_sub_f32_e32 v80, v80, v91
	v_sub_f32_e32 v79, v79, v91
	v_sub_f32_e32 v78, v78, v91
	v_sub_f32_e32 v77, v77, v91
	v_sub_f32_e32 v76, v76, v91
	v_sub_f32_e32 v75, v75, v91
	v_sub_f32_e32 v74, v74, v91
	v_sub_f32_e32 v15, v15, v91
	v_sub_f32_e32 v14, v14, v91
	v_sub_f32_e32 v13, v13, v91
	v_sub_f32_e32 v11, v11, v91
	v_sub_f32_e32 v9, v9, v91
	v_sub_f32_e32 v7, v7, v91
	v_sub_f32_e32 v4, v4, v91
	v_sub_f32_e32 v0, v0, v91
	v_sub_f32_e32 v1, v1, v91
	v_sub_f32_e32 v2, v2, v91
	v_sub_f32_e32 v3, v3, v91
	v_sub_f32_e32 v5, v5, v91
	v_sub_f32_e32 v6, v6, v91
	v_sub_f32_e32 v8, v8, v91
	v_sub_f32_e32 v10, v10, v91
	v_sub_f32_e32 v12, v12, v91
	v_mul_f32_e32 v26, v26, v90
	v_mul_f32_e32 v27, v27, v90
	v_mul_f32_e32 v24, v24, v90
	v_mul_f32_e32 v25, v25, v90
	v_mul_f32_e32 v22, v22, v90
	v_mul_f32_e32 v23, v23, v90
	v_mul_f32_e32 v20, v20, v90
	v_mul_f32_e32 v21, v21, v90
	v_mul_f32_e32 v18, v18, v90
	v_mul_f32_e32 v19, v19, v90
	v_mul_f32_e32 v16, v16, v90
	v_mul_f32_e32 v17, v17, v90
	v_mul_f32_e32 v30, v30, v90
	v_mul_f32_e32 v31, v31, v90
	v_mul_f32_e32 v28, v28, v90
	v_mul_f32_e32 v29, v29, v90
	s_branch .LBB0_1100

.LBB0_1143:
	v_mov_b32_e32 v16, v119
	s_nop 1
	v_permlane16_swap_b32_e32 v119, v16
	v_add_f32_e32 v16, v119, v16
	v_mov_b32_e32 v17, v16
	s_nop 1
	v_permlane32_swap_b32_e32 v16, v17
	v_ashrrev_i32_e32 v95, 31, v94
	v_add_f32_e32 v16, v16, v17
	s_lshl_b32 s8, s20, 6
	v_rcp_f32_e32 v16, v16
	v_lshlrev_b64 v[18:19], 11, v[94:95]
	v_lshl_add_u64 v[18:19], s[6:7], 0, v[18:19]
	s_lshl_b32 s96, s8, 1
	v_lshl_add_u64 v[18:19], v[18:19], 0, s[96:97]
	v_lshl_add_u64 v[18:19], v[64:65], 1, v[18:19]
	s_mov_b64 s[6:7], 0xf000400
	v_lshl_add_u64 v[20:21], v[18:19], 0, s[6:7]
	s_waitcnt vmcnt(0)
	v_mul_f32_e32 v0, v0, v16
	v_mul_f32_e32 v1, v1, v16
	v_mul_f32_e32 v2, v2, v16
	v_mul_f32_e32 v3, v3, v16
	s_mov_b32 s6, 0xf000000
	v_cvt_pk_bf16_f32 v0, v0, v1
	v_cvt_pk_bf16_f32 v1, v2, v3
	v_add_co_u32_e32 v2, vcc, s6, v18
	s_nop 1
	v_addc_co_u32_e32 v3, vcc, 0, v19, vcc
	global_store_dwordx2 v[2:3], v[0:1], off offset:1024
	v_mul_f32_e32 v0, v4, v16
	v_mul_f32_e32 v1, v5, v16
	v_mul_f32_e32 v2, v6, v16
	v_mul_f32_e32 v3, v7, v16
	v_cvt_pk_bf16_f32 v0, v0, v1
	v_cvt_pk_bf16_f32 v1, v2, v3
	global_store_dwordx2 v[20:21], v[0:1], off offset:32
	v_mul_f32_e32 v0, v8, v16
	v_mul_f32_e32 v1, v9, v16
	v_mul_f32_e32 v2, v10, v16
	v_mul_f32_e32 v3, v11, v16
	v_cvt_pk_bf16_f32 v0, v0, v1
	v_cvt_pk_bf16_f32 v1, v2, v3
	global_store_dwordx2 v[20:21], v[0:1], off offset:64
	v_mul_f32_e32 v0, v12, v16
	v_mul_f32_e32 v1, v13, v16
	v_mul_f32_e32 v2, v14, v16
	v_mul_f32_e32 v3, v15, v16
	v_cvt_pk_bf16_f32 v0, v0, v1
	v_cvt_pk_bf16_f32 v1, v2, v3
	global_store_dwordx2 v[20:21], v[0:1], off offset:96

.LBB0_1164:
	s_mov_b64 s[6:7], -1
	s_and_b64 vcc, exec, s[10:11]
	s_cbranch_vccz .LBB0_1166
	ds_read_b128 v[32:35], v223
	ds_read_b128 v[36:39], v223 offset:64
	s_cmpk_eq_i32 s19, 0x400
	s_cselect_b64 vcc, -1, 0
	v_cndmask_b32_e32 v52, v178, v201, vcc
	s_waitcnt lgkmcnt(1)
	v_mfma_f32_16x16x32_bf16 v[32:35], v[32:35], v[66:69], 0
	s_mov_b64 s[6:7], 0
	s_waitcnt lgkmcnt(0)
	v_mfma_f32_16x16x32_bf16 v[32:35], v[36:39], v[70:73], v[32:35]
	ds_read_b128 v[36:39], v223 offset:2304
	ds_read_b128 v[40:43], v223 offset:2368
	s_waitcnt lgkmcnt(1)
	v_mfma_f32_16x16x32_bf16 v[36:39], v[36:39], v[66:69], 0
	s_nop 3
	v_mul_f32_e64 v32, v52, v32
	v_mul_f32_e64 v33, v52, v33
	v_mul_f32_e32 v34, v52, v34
	v_mul_f32_e32 v35, v52, v35
	v_cvt_pk_bf16_f32 v32, v32, v33
	s_waitcnt lgkmcnt(0)
	v_mfma_f32_16x16x32_bf16 v[36:39], v[40:43], v[70:73], v[36:39]
	ds_read_b128 v[40:43], v223 offset:4608
	ds_read_b128 v[44:47], v223 offset:4672
	v_cvt_pk_bf16_f32 v33, v34, v35
	s_waitcnt lgkmcnt(1)
	v_mfma_f32_16x16x32_bf16 v[40:43], v[40:43], v[66:69], 0
	s_nop 2
	v_mul_f32_e64 v36, v52, v36
	v_mul_f32_e64 v37, v52, v37
	v_mul_f32_e32 v38, v52, v38
	v_mul_f32_e32 v39, v52, v39
	v_cvt_pk_bf16_f32 v34, v36, v37
	s_waitcnt lgkmcnt(0)
	v_mfma_f32_16x16x32_bf16 v[40:43], v[44:47], v[70:73], v[40:43]
	ds_read_b128 v[44:47], v223 offset:6912
	ds_read_b128 v[48:51], v223 offset:6976
	v_cvt_pk_bf16_f32 v35, v38, v39
	s_waitcnt lgkmcnt(1)
	v_mfma_f32_16x16x32_bf16 v[44:47], v[44:47], v[66:69], 0
	s_nop 2
	v_mul_f32_e64 v40, v52, v40
	v_mul_f32_e64 v41, v52, v41
	v_mul_f32_e32 v42, v52, v42
	v_mul_f32_e32 v43, v52, v43
	v_cvt_pk_bf16_f32 v36, v40, v41
	s_waitcnt lgkmcnt(0)
	v_mfma_f32_16x16x32_bf16 v[44:47], v[48:51], v[70:73], v[44:47]
	v_cvt_pk_bf16_f32 v37, v42, v43
	s_nop 6
	v_mul_f32_e32 v44, v52, v44
	v_mul_f32_e32 v45, v52, v45
	v_mul_f32_e32 v46, v52, v46
	v_mul_f32_e32 v47, v52, v47
	v_cvt_pk_bf16_f32 v38, v44, v45
	v_cvt_pk_bf16_f32 v39, v46, v47
	ds_read_b64_tr_b16 v[42:43], v203 offset:20736
	ds_read_b64_tr_b16 v[40:41], v203 offset:18432
	ds_read_b64_tr_b16 v[44:45], v203 offset:18464
	ds_read_b64_tr_b16 v[46:47], v203 offset:20768
	ds_read_b64_tr_b16 v[48:49], v203 offset:18496
	ds_read_b64_tr_b16 v[50:51], v203 offset:20800
	ds_read_b64_tr_b16 v[52:53], v203 offset:18528
	ds_read_b64_tr_b16 v[54:55], v203 offset:20832
	s_waitcnt lgkmcnt(6)
	v_mfma_f32_16x16x32_bf16 v[40:43], v[40:43], v[32:35], v[118:121]
	s_waitcnt lgkmcnt(4)
	v_mfma_f32_16x16x32_bf16 v[44:47], v[44:47], v[32:35], v[122:125]
	s_waitcnt lgkmcnt(2)
	v_mfma_f32_16x16x32_bf16 v[48:51], v[48:51], v[32:35], v[114:117]
	s_waitcnt lgkmcnt(0)
	v_mfma_f32_16x16x32_bf16 v[32:35], v[52:55], v[32:35], v[110:113]
	ds_read_b64_tr_b16 v[52:53], v203 offset:23040
	ds_read_b64_tr_b16 v[54:55], v203 offset:25344
	s_waitcnt lgkmcnt(0)
	v_mfma_f32_16x16x32_bf16 v[126:129], v[52:55], v[36:39], v[40:43]
	s_nop 2
	ds_read_b64_tr_b16 v[40:41], v203 offset:23072
	ds_read_b64_tr_b16 v[42:43], v203 offset:25376
	s_waitcnt lgkmcnt(0)
	v_mfma_f32_16x16x32_bf16 v[130:133], v[40:43], v[36:39], v[44:47]
	ds_read_b64_tr_b16 v[40:41], v203 offset:23104
	ds_read_b64_tr_b16 v[42:43], v203 offset:25408
	s_waitcnt lgkmcnt(0)
	v_mfma_f32_16x16x32_bf16 v[134:137], v[40:43], v[36:39], v[48:51]
	ds_read_b64_tr_b16 v[40:41], v203 offset:23136
	ds_read_b64_tr_b16 v[42:43], v203 offset:25440
	s_waitcnt lgkmcnt(0)
	v_mfma_f32_16x16x32_bf16 v[138:141], v[40:43], v[36:39], v[32:35]
.LBB0_1166:
	s_andn2_b64 vcc, exec, s[6:7]
	s_cbranch_vccnz .LBB0_1176
	s_nop 0
	v_cvt_f32_i32_e32 v32, v224
	s_add_i32 s20, s19, 0x7f
	v_readfirstlane_b32 s9, v186
	s_mov_b64 s[6:7], -1
	v_mul_f32_e32 v40, v187, v32
	ds_read_b128 v[32:35], v223
	ds_read_b128 v[36:39], v223 offset:64
	v_exp_f32_e32 v64, v40
	s_cmp_ge_i32 s20, s9
	s_waitcnt lgkmcnt(1)
	v_mfma_f32_16x16x32_bf16 v[32:35], v[32:35], v[66:69], 0
	s_waitcnt lgkmcnt(0)
	v_mfma_f32_16x16x32_bf16 v[126:129], v[36:39], v[70:73], v[32:35]
	s_nop 5
	ds_read_b128 v[32:35], v223 offset:2304
	ds_read_b128 v[36:39], v223 offset:2368
	s_waitcnt lgkmcnt(1)
	v_mfma_f32_16x16x32_bf16 v[32:35], v[32:35], v[66:69], 0
	s_waitcnt lgkmcnt(0)
	v_mfma_f32_16x16x32_bf16 v[130:133], v[36:39], v[70:73], v[32:35]
	s_nop 5
	ds_read_b128 v[32:35], v223 offset:4608
	ds_read_b128 v[36:39], v223 offset:4672
	s_waitcnt lgkmcnt(1)
	v_mfma_f32_16x16x32_bf16 v[32:35], v[32:35], v[66:69], 0
	s_waitcnt lgkmcnt(0)
	v_mfma_f32_16x16x32_bf16 v[134:137], v[36:39], v[70:73], v[32:35]
	s_nop 5
	ds_read_b128 v[32:35], v223 offset:6912
	ds_read_b128 v[36:39], v223 offset:6976
	s_waitcnt lgkmcnt(1)
	v_mfma_f32_16x16x32_bf16 v[32:35], v[32:35], v[66:69], 0
	s_waitcnt lgkmcnt(0)
	v_mfma_f32_16x16x32_bf16 v[138:141], v[36:39], v[70:73], v[32:35]
	s_nop 5
	ds_read_b128 v[32:35], v223 offset:9216
	ds_read_b128 v[36:39], v223 offset:9280
	s_waitcnt lgkmcnt(1)
	v_mfma_f32_16x16x32_bf16 v[32:35], v[32:35], v[66:69], 0
	s_waitcnt lgkmcnt(0)
	v_mfma_f32_16x16x32_bf16 v[142:145], v[36:39], v[70:73], v[32:35]
	s_nop 5
	ds_read_b128 v[32:35], v223 offset:11520
	ds_read_b128 v[36:39], v223 offset:11584
	s_waitcnt lgkmcnt(1)
	v_mfma_f32_16x16x32_bf16 v[32:35], v[32:35], v[66:69], 0
	s_waitcnt lgkmcnt(0)
	v_mfma_f32_16x16x32_bf16 v[146:149], v[36:39], v[70:73], v[32:35]
	s_nop 5
	ds_read_b128 v[32:35], v223 offset:13824
	ds_read_b128 v[36:39], v223 offset:13888
	s_waitcnt lgkmcnt(1)
	v_mfma_f32_16x16x32_bf16 v[32:35], v[32:35], v[66:69], 0
	s_waitcnt lgkmcnt(0)
	v_mfma_f32_16x16x32_bf16 v[150:153], v[36:39], v[70:73], v[32:35]
	s_nop 5
	ds_read_b128 v[32:35], v223 offset:16128
	ds_read_b128 v[36:39], v223 offset:16192
	s_waitcnt lgkmcnt(1)
	v_mfma_f32_16x16x32_bf16 v[32:35], v[32:35], v[66:69], 0
	s_waitcnt lgkmcnt(0)
	v_mfma_f32_16x16x32_bf16 v[154:157], v[36:39], v[70:73], v[32:35]
	s_cbranch_scc0 .LBB0_1173
	s_nop 4
	v_add_u32_e32 v32, s19, v220
	v_cvt_f32_i32_e32 v32, v32
	s_add_i32 s9, s9, 15
	s_cmp_gt_i32 s19, s9
	v_mul_f32_e32 v32, v188, v32
	v_exp_f32_e32 v182, v32
	s_cbranch_scc1 .LBB0_1170
	ds_read_b128 v[32:35], v206
	ds_read_b128 v[36:39], v207
	v_add_u32_e32 v62, s19, v191
	v_add_u32_e32 v63, 16, v62
	ds_read_b128 v[40:43], v205
	ds_read_b128 v[240:243], v204
	v_or_b32_e32 v44, 2, v63
	s_waitcnt lgkmcnt(3)
	v_mul_f32_e32 v34, v182, v34
	v_mul_f32_e32 v35, v182, v35
	v_cmp_ne_u32_e32 vcc, v6, v44
	ds_read_b128 v[244:247], v208
	ds_read_b128 v[158:161], v209
	v_cndmask_b32_e32 v34, v237, v34, vcc
	v_cmp_gt_i32_e32 vcc, v6, v44
	v_or_b32_e32 v44, 3, v63
	s_waitcnt lgkmcnt(3)
	v_mul_f32_e32 v42, v64, v42
	v_mul_f32_e32 v43, v64, v43
	v_cmp_ne_u32_e64 s[6:7], v7, v44
	v_add_u32_e32 v183, 32, v62
	v_cndmask_b32_e32 v184, v34, v42, vcc
	v_cndmask_b32_e64 v35, v237, v35, s[6:7]
	v_cmp_gt_i32_e64 s[6:7], v7, v44
	v_or_b32_e32 v42, 2, v183
	v_cmp_ne_u32_e32 vcc, v10, v42
	v_cndmask_b32_e64 v185, v35, v43, s[6:7]
	s_waitcnt lgkmcnt(1)
	v_mul_f32_e32 v34, v182, v246
	v_mul_f32_e32 v35, v182, v247
	ds_read_b128 v[168:171], v210
	ds_read_b128 v[56:59], v211
	v_cndmask_b32_e32 v34, v237, v34, vcc
	v_cmp_gt_i32_e32 vcc, v10, v42
	v_or_b32_e32 v42, 3, v183
	v_cmp_ne_u32_e64 s[6:7], v11, v42
	v_add_u32_e32 v225, 48, v62
	v_mul_f32_e32 v38, v64, v38
	v_mul_f32_e32 v39, v64, v39
	v_cndmask_b32_e64 v35, v237, v35, s[6:7]
	v_cmp_gt_i32_e64 s[6:7], v11, v42
	v_or_b32_e32 v44, 2, v225
	v_cndmask_b32_e32 v38, v34, v38, vcc
	v_cndmask_b32_e64 v39, v35, v39, s[6:7]
	s_waitcnt lgkmcnt(1)
	v_mul_f32_e32 v34, v182, v170
	v_mul_f32_e32 v35, v182, v171
	v_cmp_ne_u32_e32 vcc, v14, v44
	ds_read_b128 v[164:167], v212
	ds_read_b128 v[50:53], v213
	v_cndmask_b32_e32 v34, v237, v34, vcc
	v_cmp_gt_i32_e32 vcc, v14, v44
	v_or_b32_e32 v44, 3, v225
	v_cmp_ne_u32_e64 s[6:7], v15, v44
	v_add_u32_e32 v250, 64, v62
	v_mul_f32_e32 v42, v64, v160
	v_mul_f32_e32 v43, v64, v161
	v_cndmask_b32_e64 v35, v237, v35, s[6:7]
	v_cmp_gt_i32_e64 s[6:7], v15, v44
	v_or_b32_e32 v44, 2, v250
	v_cndmask_b32_e32 v170, v34, v42, vcc
	v_cndmask_b32_e64 v171, v35, v43, s[6:7]
	s_waitcnt lgkmcnt(1)
	v_mul_f32_e32 v34, v182, v166
	v_mul_f32_e32 v35, v182, v167
	v_cmp_ne_u32_e32 vcc, v18, v44
	ds_read_b128 v[160:163], v214
	ds_read_b128 v[46:49], v215
	v_cndmask_b32_e32 v34, v237, v34, vcc
	v_cmp_gt_i32_e32 vcc, v18, v44
	v_or_b32_e32 v44, 3, v250
	v_cmp_ne_u32_e64 s[6:7], v19, v44
	v_add_u32_e32 v251, 0x50, v62
	v_mul_f32_e32 v42, v64, v58
	v_mul_f32_e32 v43, v64, v59
	v_cndmask_b32_e64 v35, v237, v35, s[6:7]
	v_cmp_gt_i32_e64 s[6:7], v19, v44
	v_or_b32_e32 v44, 2, v251
	v_cndmask_b32_e32 v166, v34, v42, vcc
	v_cndmask_b32_e64 v167, v35, v43, s[6:7]
	s_waitcnt lgkmcnt(1)
	v_mul_f32_e32 v34, v182, v162
	v_mul_f32_e32 v35, v182, v163
	v_cmp_ne_u32_e32 vcc, v22, v44
	v_mul_f32_e32 v42, v64, v52
	v_mul_f32_e32 v43, v64, v53
	v_add_u32_e32 v252, 0x60, v62
	v_cndmask_b32_e32 v34, v237, v34, vcc
	v_cmp_gt_i32_e32 vcc, v22, v44
	v_or_b32_e32 v44, 3, v251
	v_cmp_ne_u32_e64 s[6:7], v23, v44
	v_cndmask_b32_e32 v162, v34, v42, vcc
	v_or_b32_e32 v52, 2, v252
	v_cndmask_b32_e64 v35, v237, v35, s[6:7]
	v_cmp_gt_i32_e64 s[6:7], v23, v44
	v_cmp_ne_u32_e32 vcc, v26, v52
	s_waitcnt lgkmcnt(0)
	v_mul_f32_e32 v48, v64, v48
	v_mul_f32_e32 v49, v64, v49
	v_cndmask_b32_e64 v163, v35, v43, s[6:7]
	ds_read_b128 v[58:61], v216
	ds_read_b128 v[42:45], v217
	v_add_u32_e32 v253, 0x70, v62
	v_add_u32_e32 v226, 1, v62
	v_mul_f32_e32 v32, v182, v32
	v_mul_f32_e32 v33, v182, v33
	s_waitcnt lgkmcnt(1)
	v_mul_f32_e32 v34, v182, v60
	v_mul_f32_e32 v35, v182, v61
	v_cndmask_b32_e32 v34, v237, v34, vcc
	v_cmp_gt_i32_e32 vcc, v26, v52
	v_or_b32_e32 v52, 3, v252
	v_cmp_ne_u32_e64 s[6:7], v27, v52
	v_cndmask_b32_e32 v48, v34, v48, vcc
	v_add_u32_e32 v34, 0x12200, v202
	v_cndmask_b32_e64 v35, v237, v35, s[6:7]
	v_cmp_gt_i32_e64 s[6:7], v27, v52
	ds_read_b128 v[246:249], v34
	ds_read_b128 v[52:55], v218
	v_cndmask_b32_e64 v49, v35, v49, s[6:7]
	v_or_b32_e32 v60, 2, v253
	v_cmp_ne_u32_e32 vcc, v30, v60
	s_waitcnt lgkmcnt(2)
	v_mul_f32_e32 v44, v64, v44
	v_mul_f32_e32 v45, v64, v45
	s_waitcnt lgkmcnt(0)
	v_mul_f32_e32 v34, v182, v54
	v_mul_f32_e32 v35, v182, v55
	v_or_b32_e32 v54, 3, v253
	v_cmp_ne_u32_e64 s[6:7], v31, v54
	v_cndmask_b32_e32 v34, v237, v34, vcc
	v_cmp_gt_i32_e32 vcc, v30, v60
	v_cndmask_b32_e64 v35, v237, v35, s[6:7]
	v_cmp_gt_i32_e64 s[6:7], v31, v54
	v_or_b32_e32 v60, 2, v62
	v_cndmask_b32_e32 v44, v34, v44, vcc
	v_cndmask_b32_e64 v45, v35, v45, s[6:7]
	v_mul_f32_e32 v34, v182, v248
	v_mul_f32_e32 v35, v182, v249
	v_cmp_ne_u32_e32 vcc, v2, v60
	v_mul_f32_e32 v54, v64, v242
	v_mul_f32_e32 v55, v64, v243
	v_mul_f32_e32 v40, v64, v40
	v_mul_f32_e32 v41, v64, v41
	v_cndmask_b32_e32 v34, v237, v34, vcc
	v_cmp_gt_i32_e32 vcc, v2, v60
	v_or_b32_e32 v60, 3, v62
	v_cmp_ne_u32_e64 s[6:7], v3, v60
	v_cndmask_b32_e32 v34, v34, v54, vcc
	v_cmp_ne_u32_e32 vcc, v1, v226
	v_cndmask_b32_e64 v35, v237, v35, s[6:7]
	v_cmp_gt_i32_e64 s[6:7], v3, v60
	v_mul_f32_e32 v60, v182, v246
	v_mul_f32_e32 v61, v182, v247
	v_cndmask_b32_e32 v61, v237, v61, vcc
	v_cndmask_b32_e64 v35, v35, v55, s[6:7]
	v_cmp_ne_u32_e64 s[6:7], v0, v62
	v_mul_f32_e32 v54, v64, v240
	v_mul_f32_e32 v55, v64, v241
	v_cmp_gt_i32_e32 vcc, v1, v226
	v_cndmask_b32_e64 v60, v237, v60, s[6:7]
	v_cmp_gt_i32_e64 s[6:7], v0, v62
	v_cndmask_b32_e32 v227, v61, v55, vcc
	v_cmp_ne_u32_e32 vcc, v4, v63
	v_cndmask_b32_e64 v226, v60, v54, s[6:7]
	v_add_u32_e32 v54, 17, v62
	v_cmp_ne_u32_e64 s[6:7], v5, v54
	v_cndmask_b32_e32 v32, v237, v32, vcc
	v_cmp_gt_i32_e32 vcc, v4, v63
	v_cndmask_b32_e64 v33, v237, v33, s[6:7]
	v_cmp_gt_i32_e64 s[6:7], v5, v54
	v_add_u32_e32 v54, 33, v62
	v_cndmask_b32_e32 v32, v32, v40, vcc
	v_cndmask_b32_e64 v33, v33, v41, s[6:7]
	v_mul_f32_e32 v40, v182, v244
	v_mul_f32_e32 v41, v182, v245
	v_cmp_ne_u32_e32 vcc, v8, v183
	v_cmp_ne_u32_e64 s[6:7], v9, v54
	v_mul_f32_e32 v36, v64, v36
	v_mul_f32_e32 v37, v64, v37
	v_cndmask_b32_e32 v40, v237, v40, vcc
	v_cmp_gt_i32_e32 vcc, v8, v183
	v_cndmask_b32_e64 v41, v237, v41, s[6:7]
	v_cmp_gt_i32_e64 s[6:7], v9, v54
	v_add_u32_e32 v60, 49, v62
	v_cndmask_b32_e32 v36, v40, v36, vcc
	v_cndmask_b32_e64 v37, v41, v37, s[6:7]
	v_mul_f32_e32 v54, v182, v168
	v_mul_f32_e32 v55, v182, v169
	v_cmp_ne_u32_e32 vcc, v12, v225
	v_cmp_ne_u32_e64 s[6:7], v13, v60
	v_mul_f32_e32 v40, v64, v158
	v_mul_f32_e32 v41, v64, v159
	v_cndmask_b32_e32 v54, v237, v54, vcc
	v_cmp_gt_i32_e32 vcc, v12, v225
	v_cndmask_b32_e64 v55, v237, v55, s[6:7]
	v_cmp_gt_i32_e64 s[6:7], v13, v60
	v_cndmask_b32_e32 v40, v54, v40, vcc
	v_cmp_ne_u32_e32 vcc, v16, v250
	v_cndmask_b32_e64 v41, v55, v41, s[6:7]
	v_mul_f32_e32 v54, v64, v56
	v_mul_f32_e32 v55, v64, v57
	v_mul_f32_e32 v56, v182, v164
	v_mul_f32_e32 v57, v182, v165
	v_add_u32_e32 v60, 0x41, v62
	v_cndmask_b32_e32 v56, v237, v56, vcc
	v_cmp_gt_i32_e32 vcc, v16, v250
	v_cmp_ne_u32_e64 s[6:7], v17, v60
	v_mul_f32_e32 v50, v64, v50
	v_mul_f32_e32 v51, v64, v51
	v_cndmask_b32_e32 v158, v56, v54, vcc
	v_cndmask_b32_e64 v57, v237, v57, s[6:7]
	v_cmp_gt_i32_e64 s[6:7], v17, v60
	v_add_u32_e32 v56, 0x51, v62
	v_cmp_ne_u32_e32 vcc, v20, v251
	v_cndmask_b32_e64 v159, v57, v55, s[6:7]
	v_mul_f32_e32 v54, v182, v160
	v_mul_f32_e32 v55, v182, v161
	v_cmp_ne_u32_e64 s[6:7], v21, v56
	v_cndmask_b32_e32 v54, v237, v54, vcc
	v_cmp_gt_i32_e32 vcc, v20, v251
	v_cndmask_b32_e64 v55, v237, v55, s[6:7]
	v_cmp_gt_i32_e64 s[6:7], v21, v56
	v_cndmask_b32_e32 v160, v54, v50, vcc
	v_cmp_ne_u32_e32 vcc, v24, v252
	v_cndmask_b32_e64 v161, v55, v51, s[6:7]
	v_mul_f32_e32 v50, v182, v58
	v_mul_f32_e32 v51, v182, v59
	v_add_u32_e32 v54, 0x61, v62
	v_mul_f32_e32 v46, v64, v46
	v_mul_f32_e32 v47, v64, v47
	v_cndmask_b32_e32 v50, v237, v50, vcc
	v_cmp_gt_i32_e32 vcc, v24, v252
	v_cmp_ne_u32_e64 s[6:7], v25, v54
	v_mul_f32_e32 v42, v64, v42
	v_mul_f32_e32 v43, v64, v43
	v_cndmask_b32_e32 v56, v50, v46, vcc
	v_cndmask_b32_e64 v51, v237, v51, s[6:7]
	v_cmp_gt_i32_e64 s[6:7], v25, v54
	v_add_u32_e32 v50, 0x71, v62
	v_cmp_ne_u32_e32 vcc, v28, v253
	v_cndmask_b32_e64 v57, v51, v47, s[6:7]
	v_mul_f32_e32 v46, v182, v52
	v_mul_f32_e32 v47, v182, v53
	v_cmp_ne_u32_e64 s[6:7], v29, v50
	v_cndmask_b32_e32 v46, v237, v46, vcc
	v_cmp_gt_i32_e32 vcc, v28, v253
	v_cndmask_b32_e64 v47, v237, v47, s[6:7]
	v_cmp_gt_i32_e64 s[6:7], v29, v50
	v_cndmask_b32_e32 v52, v46, v42, vcc
	v_mul_f32_e32 v34, v128, v34
	v_mul_f32_e32 v35, v129, v35
	v_cndmask_b32_e64 v53, v47, v43, s[6:7]
	v_mul_f32_e32 v62, v156, v44
	v_mul_f32_e32 v63, v157, v45
	v_mul_f32_e32 v58, v152, v48
	v_mul_f32_e32 v59, v153, v49
	v_mul_f32_e32 v54, v148, v162
	v_mul_f32_e32 v55, v149, v163
	v_mul_f32_e32 v50, v144, v166
	v_mul_f32_e32 v51, v145, v167
	v_mul_f32_e32 v46, v140, v170
	v_mul_f32_e32 v47, v141, v171
	v_mul_f32_e32 v42, v136, v38
	v_mul_f32_e32 v43, v137, v39
	v_mul_f32_e32 v38, v132, v184
	v_mul_f32_e32 v39, v133, v185
	v_mul_f32_e32 v60, v154, v52
	v_mul_f32_e32 v61, v155, v53
	v_mul_f32_e32 v56, v150, v56
	v_mul_f32_e32 v57, v151, v57
	v_mul_f32_e32 v52, v146, v160
	v_mul_f32_e32 v53, v147, v161
	v_mul_f32_e32 v48, v142, v158
	v_mul_f32_e32 v49, v143, v159
	v_mul_f32_e32 v44, v138, v40
	v_mul_f32_e32 v45, v139, v41
	v_mul_f32_e32 v40, v134, v36
	v_mul_f32_e32 v41, v135, v37
	v_mul_f32_e32 v36, v130, v32
	v_mul_f32_e32 v37, v131, v33
	v_mul_f32_e32 v32, v126, v226
	v_mul_f32_e32 v33, v127, v227
	s_mov_b64 s[6:7], 0
.LBB0_1170:
	s_andn2_b64 vcc, exec, s[6:7]
	s_cbranch_vccnz .LBB0_1172
	v_add_u32_e32 v60, 0x12200, v202
	ds_read_b128 v[32:35], v60
	ds_read_b128 v[36:39], v60 offset:64
	ds_read_b128 v[40:43], v60 offset:128
	ds_read_b128 v[44:47], v60 offset:192
	ds_read_b128 v[48:51], v60 offset:256
	ds_read_b128 v[52:55], v60 offset:320
	ds_read_b128 v[56:59], v60 offset:384
	ds_read_b128 v[60:63], v60 offset:448
	s_waitcnt lgkmcnt(7)
	v_mul_f32_e32 v34, v182, v34
	v_mul_f32_e32 v35, v182, v35
	s_waitcnt lgkmcnt(6)
	v_mul_f32_e32 v38, v182, v38
	v_mul_f32_e32 v39, v182, v39
	s_waitcnt lgkmcnt(5)
	v_mul_f32_e32 v42, v182, v42
	v_mul_f32_e32 v43, v182, v43
	s_waitcnt lgkmcnt(4)
	v_mul_f32_e32 v46, v182, v46
	v_mul_f32_e32 v47, v182, v47
	s_waitcnt lgkmcnt(3)
	v_mul_f32_e32 v50, v182, v50
	v_mul_f32_e32 v51, v182, v51
	s_waitcnt lgkmcnt(2)
	v_mul_f32_e32 v54, v182, v54
	v_mul_f32_e32 v55, v182, v55
	s_waitcnt lgkmcnt(1)
	v_mul_f32_e32 v58, v182, v58
	v_mul_f32_e32 v59, v182, v59
	s_waitcnt lgkmcnt(0)
	v_mul_f32_e32 v62, v182, v62
	v_mul_f32_e32 v63, v182, v63
	v_mul_f32_e32 v32, v182, v32
	v_mul_f32_e32 v33, v182, v33
	v_mul_f32_e32 v36, v182, v36
	v_mul_f32_e32 v37, v182, v37
	v_mul_f32_e32 v40, v182, v40
	v_mul_f32_e32 v41, v182, v41
	v_mul_f32_e32 v44, v182, v44
	v_mul_f32_e32 v45, v182, v45
	v_mul_f32_e32 v48, v182, v48
	v_mul_f32_e32 v49, v182, v49
	v_mul_f32_e32 v52, v182, v52
	v_mul_f32_e32 v53, v182, v53
	v_mul_f32_e32 v56, v182, v56
	v_mul_f32_e32 v57, v182, v57
	v_mul_f32_e32 v60, v182, v60
	v_mul_f32_e32 v61, v182, v61
	v_mul_f32_e32 v60, v154, v60
	v_mul_f32_e32 v61, v155, v61
	v_mul_f32_e32 v56, v150, v56
	v_mul_f32_e32 v57, v151, v57
	v_mul_f32_e32 v52, v146, v52
	v_mul_f32_e32 v53, v147, v53
	v_mul_f32_e32 v48, v142, v48
	v_mul_f32_e32 v49, v143, v49
	v_mul_f32_e32 v44, v138, v44
	v_mul_f32_e32 v45, v139, v45
	v_mul_f32_e32 v40, v134, v40
	v_mul_f32_e32 v41, v135, v41
	v_mul_f32_e32 v36, v130, v36
	v_mul_f32_e32 v37, v131, v37
	v_mul_f32_e32 v32, v126, v32
	v_mul_f32_e32 v33, v127, v33
	v_mul_f32_e32 v62, v156, v62
	v_mul_f32_e32 v63, v157, v63
	v_mul_f32_e32 v58, v152, v58
	v_mul_f32_e32 v59, v153, v59
	v_mul_f32_e32 v54, v148, v54
	v_mul_f32_e32 v55, v149, v55
	v_mul_f32_e32 v50, v144, v50
	v_mul_f32_e32 v51, v145, v51
	v_mul_f32_e32 v46, v140, v46
	v_mul_f32_e32 v47, v141, v47
	v_mul_f32_e32 v42, v136, v42
	v_mul_f32_e32 v43, v137, v43
	v_mul_f32_e32 v38, v132, v38
	v_mul_f32_e32 v39, v133, v39
	v_mul_f32_e32 v34, v128, v34
	v_mul_f32_e32 v35, v129, v35

.LBB0_1173:
	s_andn2_b64 vcc, exec, s[6:7]
	s_cbranch_vccnz .LBB0_1175
	v_add_u32_e32 v60, 0x12000, v202
	s_nop 1
	ds_read_b128 v[32:35], v60
	ds_read_b128 v[36:39], v60 offset:64
	ds_read_b128 v[40:43], v60 offset:128
	ds_read_b128 v[44:47], v60 offset:192
	ds_read_b128 v[48:51], v60 offset:256
	ds_read_b128 v[52:55], v60 offset:320
	ds_read_b128 v[56:59], v60 offset:384
	ds_read_b128 v[60:63], v60 offset:448
	s_waitcnt lgkmcnt(7)
	v_mul_f32_e32 v34, v64, v34
	v_mul_f32_e32 v35, v64, v35
	s_waitcnt lgkmcnt(6)
	v_mul_f32_e32 v38, v64, v38
	v_mul_f32_e32 v39, v64, v39
	s_waitcnt lgkmcnt(5)
	v_mul_f32_e32 v42, v64, v42
	v_mul_f32_e32 v43, v64, v43
	s_waitcnt lgkmcnt(4)
	v_mul_f32_e32 v46, v64, v46
	v_mul_f32_e32 v47, v64, v47
	s_waitcnt lgkmcnt(3)
	v_mul_f32_e32 v50, v64, v50
	v_mul_f32_e32 v51, v64, v51
	s_waitcnt lgkmcnt(2)
	v_mul_f32_e32 v54, v64, v54
	v_mul_f32_e32 v55, v64, v55
	s_waitcnt lgkmcnt(1)
	v_mul_f32_e32 v58, v64, v58
	v_mul_f32_e32 v59, v64, v59
	s_waitcnt lgkmcnt(0)
	v_mul_f32_e32 v62, v64, v62
	v_mul_f32_e32 v63, v64, v63
	v_mul_f32_e32 v32, v64, v32
	v_mul_f32_e32 v33, v64, v33
	v_mul_f32_e32 v36, v64, v36
	v_mul_f32_e32 v37, v64, v37
	v_mul_f32_e32 v40, v64, v40
	v_mul_f32_e32 v41, v64, v41
	v_mul_f32_e32 v44, v64, v44
	v_mul_f32_e32 v45, v64, v45
	v_mul_f32_e32 v48, v64, v48
	v_mul_f32_e32 v49, v64, v49
	v_mul_f32_e32 v52, v64, v52
	v_mul_f32_e32 v53, v64, v53
	v_mul_f32_e32 v56, v64, v56
	v_mul_f32_e32 v57, v64, v57
	v_mul_f32_e32 v60, v64, v60
	v_mul_f32_e32 v61, v64, v61
	v_mul_f32_e32 v60, v154, v60
	v_mul_f32_e32 v61, v155, v61
	v_mul_f32_e32 v56, v150, v56
	v_mul_f32_e32 v57, v151, v57
	v_mul_f32_e32 v52, v146, v52
	v_mul_f32_e32 v53, v147, v53
	v_mul_f32_e32 v48, v142, v48
	v_mul_f32_e32 v49, v143, v49
	v_mul_f32_e32 v44, v138, v44
	v_mul_f32_e32 v45, v139, v45
	v_mul_f32_e32 v40, v134, v40
	v_mul_f32_e32 v41, v135, v41
	v_mul_f32_e32 v36, v130, v36
	v_mul_f32_e32 v37, v131, v37
	v_mul_f32_e32 v32, v126, v32
	v_mul_f32_e32 v33, v127, v33
	v_mul_f32_e32 v62, v156, v62
	v_mul_f32_e32 v63, v157, v63
	v_mul_f32_e32 v58, v152, v58
	v_mul_f32_e32 v59, v153, v59
	v_mul_f32_e32 v54, v148, v54
	v_mul_f32_e32 v55, v149, v55
	v_mul_f32_e32 v50, v144, v50
	v_mul_f32_e32 v51, v145, v51
	v_mul_f32_e32 v46, v140, v46
	v_mul_f32_e32 v47, v141, v47
	v_mul_f32_e32 v42, v136, v42
	v_mul_f32_e32 v43, v137, v43
	v_mul_f32_e32 v38, v132, v38
	v_mul_f32_e32 v39, v133, v39
	v_mul_f32_e32 v34, v128, v34
	v_mul_f32_e32 v35, v129, v35

.LBB0_1186:
	ds_read_b128 v[32:35], v223 offset:41472
	ds_read_b128 v[36:39], v223 offset:41536
	s_mov_b64 s[6:7], -1
	s_and_b64 vcc, exec, s[10:11]
	s_cbranch_vccz .LBB0_1188
	ds_read_b128 v[40:43], v223 offset:36864
	ds_read_b128 v[44:47], v223 offset:36928
	s_mov_b64 s[6:7], 0
	s_waitcnt lgkmcnt(1)
	v_mfma_f32_16x16x32_bf16 v[40:43], v[40:43], v[66:69], 0
	s_waitcnt lgkmcnt(0)
	v_mfma_f32_16x16x32_bf16 v[40:43], v[44:47], v[70:73], v[40:43]
	ds_read_b128 v[44:47], v223 offset:39168
	ds_read_b128 v[48:51], v223 offset:39232
	ds_read_b128 v[52:55], v223 offset:43776
	ds_read_b128 v[56:59], v223 offset:43840
	s_waitcnt lgkmcnt(3)
	v_mfma_f32_16x16x32_bf16 v[44:47], v[44:47], v[66:69], 0
	s_nop 1
	v_mul_f32_e64 v40, v178, v40
	v_mul_f32_e64 v41, v179, v41
	v_mul_f32_e32 v42, v178, v42
	v_mul_f32_e32 v43, v179, v43
	v_cvt_pk_bf16_f32 v40, v40, v41
	s_waitcnt lgkmcnt(2)
	v_mfma_f32_16x16x32_bf16 v[44:47], v[48:51], v[70:73], v[44:47]
	v_cvt_pk_bf16_f32 v41, v42, v43
	v_mfma_f32_16x16x32_bf16 v[48:51], v[32:35], v[66:69], 0
	s_waitcnt lgkmcnt(1)
	v_mfma_f32_16x16x32_bf16 v[52:55], v[52:55], v[66:69], 0
	s_nop 3
	v_mul_f32_e64 v44, v178, v44
	v_mul_f32_e64 v45, v179, v45
	v_mul_f32_e32 v46, v178, v46
	v_mul_f32_e32 v47, v179, v47
	v_cvt_pk_bf16_f32 v42, v44, v45
	v_mfma_f32_16x16x32_bf16 v[48:51], v[36:39], v[70:73], v[48:51]
	v_cvt_pk_bf16_f32 v43, v46, v47
	s_waitcnt lgkmcnt(0)
	v_mfma_f32_16x16x32_bf16 v[52:55], v[56:59], v[70:73], v[52:55]
	s_nop 4
	v_mul_f32_e64 v48, v178, v48
	v_mul_f32_e64 v49, v179, v49
	v_mul_f32_e32 v50, v178, v50
	v_mul_f32_e32 v51, v179, v51
	v_mul_f32_e32 v52, v178, v52
	v_mul_f32_e32 v53, v179, v53
	v_mul_f32_e32 v54, v178, v54
	v_mul_f32_e32 v55, v179, v55
	v_cvt_pk_bf16_f32 v44, v48, v49
	v_cvt_pk_bf16_f32 v45, v50, v51
	v_cvt_pk_bf16_f32 v46, v52, v53
	v_cvt_pk_bf16_f32 v47, v54, v55
	ds_read_b64_tr_b16 v[50:51], v203 offset:57600
	ds_read_b64_tr_b16 v[48:49], v203 offset:55296
	ds_read_b64_tr_b16 v[52:53], v203 offset:55328
	ds_read_b64_tr_b16 v[54:55], v203 offset:57632
	ds_read_b64_tr_b16 v[56:57], v203 offset:55360
	ds_read_b64_tr_b16 v[58:59], v203 offset:57664
	ds_read_b64_tr_b16 v[60:61], v203 offset:55392
	ds_read_b64_tr_b16 v[62:63], v203 offset:57696
	s_waitcnt lgkmcnt(6)
	v_mfma_f32_16x16x32_bf16 v[48:51], v[48:51], v[40:43], v[126:129]
	s_waitcnt lgkmcnt(4)
	v_mfma_f32_16x16x32_bf16 v[52:55], v[52:55], v[40:43], v[130:133]
	s_waitcnt lgkmcnt(2)
	v_mfma_f32_16x16x32_bf16 v[56:59], v[56:59], v[40:43], v[134:137]
	s_waitcnt lgkmcnt(0)
	v_mfma_f32_16x16x32_bf16 v[40:43], v[60:63], v[40:43], v[138:141]
	ds_read_b64_tr_b16 v[60:61], v203 offset:59904
	ds_read_b64_tr_b16 v[62:63], v203 offset:62208
	s_waitcnt lgkmcnt(0)
	v_mfma_f32_16x16x32_bf16 v[118:121], v[60:63], v[44:47], v[48:51]
	s_nop 2
	ds_read_b64_tr_b16 v[48:49], v203 offset:59936
	ds_read_b64_tr_b16 v[50:51], v203 offset:62240
	s_waitcnt lgkmcnt(0)
	v_mfma_f32_16x16x32_bf16 v[122:125], v[48:51], v[44:47], v[52:55]
	ds_read_b64_tr_b16 v[48:49], v203 offset:59968
	ds_read_b64_tr_b16 v[50:51], v203 offset:62272
	s_waitcnt lgkmcnt(0)
	v_mfma_f32_16x16x32_bf16 v[114:117], v[48:51], v[44:47], v[56:59]
	ds_read_b64_tr_b16 v[48:49], v203 offset:60000
	ds_read_b64_tr_b16 v[50:51], v203 offset:62304
	s_waitcnt lgkmcnt(0)
	v_mfma_f32_16x16x32_bf16 v[110:113], v[48:51], v[44:47], v[40:43]
.LBB0_1188:
	s_andn2_b64 vcc, exec, s[6:7]
	s_cbranch_vccnz .LBB0_1154
	s_nop 0
	v_add_u32_e32 v40, 0xffffff80, v224
	v_cvt_f32_i32_e32 v40, v40
	s_waitcnt lgkmcnt(1)
	v_mfma_f32_16x16x32_bf16 v[32:35], v[32:35], v[66:69], 0
	s_add_i32 s10, s19, 0xff
	v_readfirstlane_b32 s9, v186
	v_mul_f32_e32 v48, v187, v40
	ds_read_b128 v[40:43], v223 offset:36864
	ds_read_b128 v[44:47], v223 offset:36928
	s_waitcnt lgkmcnt(2)
	v_mfma_f32_16x16x32_bf16 v[118:121], v[36:39], v[70:73], v[32:35]
	v_exp_f32_e32 v64, v48
	s_mov_b64 s[6:7], -1
	s_cmp_ge_i32 s10, s9
	s_waitcnt lgkmcnt(1)
	v_mfma_f32_16x16x32_bf16 v[40:43], v[40:43], v[66:69], 0
	s_waitcnt lgkmcnt(0)
	v_mfma_f32_16x16x32_bf16 v[110:113], v[44:47], v[70:73], v[40:43]
	s_nop 5
	ds_read_b128 v[40:43], v223 offset:39168
	ds_read_b128 v[44:47], v223 offset:39232
	ds_read_b128 v[32:35], v223 offset:43776
	ds_read_b128 v[36:39], v223 offset:43840
	s_waitcnt lgkmcnt(1)
	v_mfma_f32_16x16x32_bf16 v[32:35], v[32:35], v[66:69], 0
	s_waitcnt lgkmcnt(0)
	v_mfma_f32_16x16x32_bf16 v[122:125], v[36:39], v[70:73], v[32:35]
	s_nop 5
	ds_read_b128 v[32:35], v223 offset:46080
	ds_read_b128 v[36:39], v223 offset:46144
	s_waitcnt lgkmcnt(1)
	v_mfma_f32_16x16x32_bf16 v[32:35], v[32:35], v[66:69], 0
	s_waitcnt lgkmcnt(0)
	v_mfma_f32_16x16x32_bf16 v[142:145], v[36:39], v[70:73], v[32:35]
	s_nop 5
	ds_read_b128 v[32:35], v223 offset:48384
	ds_read_b128 v[36:39], v223 offset:48448
	s_waitcnt lgkmcnt(1)
	v_mfma_f32_16x16x32_bf16 v[32:35], v[32:35], v[66:69], 0
	s_waitcnt lgkmcnt(0)
	v_mfma_f32_16x16x32_bf16 v[146:149], v[36:39], v[70:73], v[32:35]
	s_nop 5
	ds_read_b128 v[32:35], v223 offset:50688
	ds_read_b128 v[36:39], v223 offset:50752
	s_waitcnt lgkmcnt(1)
	v_mfma_f32_16x16x32_bf16 v[32:35], v[32:35], v[66:69], 0
	s_waitcnt lgkmcnt(0)
	v_mfma_f32_16x16x32_bf16 v[150:153], v[36:39], v[70:73], v[32:35]
	s_nop 5
	ds_read_b128 v[32:35], v223 offset:52992
	ds_read_b128 v[36:39], v223 offset:53056
	v_mfma_f32_16x16x32_bf16 v[40:43], v[40:43], v[66:69], 0
	s_waitcnt lgkmcnt(1)
	v_mfma_f32_16x16x32_bf16 v[32:35], v[32:35], v[66:69], 0
	v_mfma_f32_16x16x32_bf16 v[114:117], v[44:47], v[70:73], v[40:43]
	s_waitcnt lgkmcnt(0)
	v_mfma_f32_16x16x32_bf16 v[154:157], v[36:39], v[70:73], v[32:35]
	s_cbranch_scc0 .LBB0_1195
	s_nop 3
	v_add_u32_e32 v32, s19, v220
	v_add_u32_e32 v32, 0x80, v32
	v_cvt_f32_i32_e32 v32, v32
	s_add_i32 s10, s19, 0x71
	s_cmp_gt_i32 s10, s9
	v_add_u32_e32 v171, 0x12200, v202
	v_mul_f32_e32 v32, v188, v32
	v_exp_f32_e32 v170, v32
	s_cbranch_scc1 .LBB0_1192
	ds_read_b128 v[32:35], v171
	ds_read_b128 v[36:39], v218
	ds_read_b128 v[240:243], v204
	ds_read_b128 v[166:169], v205
	v_add_u32_e32 v184, s19, v191
	v_add_u32_e32 v185, 0x80, v184
	v_or_b32_e32 v42, 2, v185
	s_waitcnt lgkmcnt(3)
	v_mul_f32_e32 v34, v170, v34
	v_mul_f32_e32 v35, v170, v35
	v_cmp_ne_u32_e32 vcc, v2, v42
	s_waitcnt lgkmcnt(1)
	v_mul_f32_e32 v40, v64, v242
	v_mul_f32_e32 v41, v64, v243
	ds_read_b128 v[242:245], v206
	ds_read_b128 v[60:63], v207
	v_cndmask_b32_e32 v34, v237, v34, vcc
	v_cmp_gt_i32_e32 vcc, v2, v42
	v_or_b32_e32 v42, 3, v185
	v_cmp_ne_u32_e64 s[6:7], v3, v42
	v_add_u32_e32 v225, 0x90, v184
	v_or_b32_e32 v44, 2, v225
	v_cndmask_b32_e64 v35, v237, v35, s[6:7]
	v_cmp_gt_i32_e64 s[6:7], v3, v42
	v_cndmask_b32_e32 v34, v34, v40, vcc
	v_cmp_ne_u32_e32 vcc, v6, v44
	v_cndmask_b32_e64 v35, v35, v41, s[6:7]
	s_waitcnt lgkmcnt(1)
	v_mul_f32_e32 v40, v170, v244
	v_mul_f32_e32 v41, v170, v245
	ds_read_b128 v[244:247], v208
	ds_read_b128 v[54:57], v209
	v_cndmask_b32_e32 v40, v237, v40, vcc
	v_cmp_gt_i32_e32 vcc, v6, v44
	v_or_b32_e32 v44, 3, v225
	v_cmp_ne_u32_e64 s[6:7], v7, v44
	v_add_u32_e32 v226, 0xa0, v184
	v_mul_f32_e32 v42, v64, v168
	v_mul_f32_e32 v43, v64, v169
	v_cndmask_b32_e64 v41, v237, v41, s[6:7]
	v_cmp_gt_i32_e64 s[6:7], v7, v44
	v_or_b32_e32 v44, 2, v226
	v_cndmask_b32_e32 v168, v40, v42, vcc
	v_cndmask_b32_e64 v169, v41, v43, s[6:7]
	s_waitcnt lgkmcnt(1)
	v_mul_f32_e32 v40, v170, v246
	v_mul_f32_e32 v41, v170, v247
	v_cmp_ne_u32_e32 vcc, v10, v44
	ds_read_b128 v[162:165], v210
	ds_read_b128 v[48:51], v211
	v_cndmask_b32_e32 v40, v237, v40, vcc
	v_cmp_gt_i32_e32 vcc, v10, v44
	v_or_b32_e32 v44, 3, v226
	v_mul_f32_e32 v42, v64, v62
	v_mul_f32_e32 v43, v64, v63
	v_cmp_ne_u32_e64 s[6:7], v11, v44
	v_add_u32_e32 v62, 0xb0, v184
	v_cndmask_b32_e32 v182, v40, v42, vcc
	v_cndmask_b32_e64 v41, v237, v41, s[6:7]
	v_cmp_gt_i32_e64 s[6:7], v11, v44
	v_or_b32_e32 v44, 2, v62
	v_cmp_ne_u32_e32 vcc, v14, v44
	v_cndmask_b32_e64 v183, v41, v43, s[6:7]
	s_waitcnt lgkmcnt(1)
	v_mul_f32_e32 v40, v170, v164
	v_mul_f32_e32 v41, v170, v165
	v_cndmask_b32_e32 v40, v237, v40, vcc
	v_cmp_gt_i32_e32 vcc, v14, v44
	v_or_b32_e32 v44, 3, v62
	v_cmp_ne_u32_e64 s[6:7], v15, v44
	v_mul_f32_e32 v42, v64, v56
	v_mul_f32_e32 v43, v64, v57
	v_add_u32_e32 v63, 0xc0, v184
	v_cndmask_b32_e64 v41, v237, v41, s[6:7]
	v_cmp_gt_i32_e64 s[6:7], v15, v44
	ds_read_b128 v[158:161], v212
	ds_read_b128 v[44:47], v213
	v_cndmask_b32_e64 v165, v41, v43, s[6:7]
	v_cndmask_b32_e32 v164, v40, v42, vcc
	v_or_b32_e32 v52, 2, v63
	s_waitcnt lgkmcnt(2)
	v_mul_f32_e32 v42, v64, v50
	v_mul_f32_e32 v43, v64, v51
	v_or_b32_e32 v50, 3, v63
	s_waitcnt lgkmcnt(1)
	v_mul_f32_e32 v40, v170, v160
	v_mul_f32_e32 v41, v170, v161
	v_cmp_ne_u32_e32 vcc, v18, v52
	v_cmp_ne_u32_e64 s[6:7], v19, v50
	v_add_u32_e32 v250, 0xd0, v184
	v_cndmask_b32_e32 v40, v237, v40, vcc
	v_cmp_gt_i32_e32 vcc, v18, v52
	v_cndmask_b32_e64 v41, v237, v41, s[6:7]
	v_cmp_gt_i32_e64 s[6:7], v19, v50
	v_cndmask_b32_e32 v160, v40, v42, vcc
	v_or_b32_e32 v52, 2, v250
	v_cndmask_b32_e64 v161, v41, v43, s[6:7]
	ds_read_b128 v[56:59], v214
	ds_read_b128 v[40:43], v215
	v_cmp_ne_u32_e32 vcc, v22, v52
	s_waitcnt lgkmcnt(2)
	v_mul_f32_e32 v46, v64, v46
	v_mul_f32_e32 v47, v64, v47
	v_add_u32_e32 v251, 0xe0, v184
	s_waitcnt lgkmcnt(1)
	v_mul_f32_e32 v50, v170, v58
	v_mul_f32_e32 v51, v170, v59
	v_cndmask_b32_e32 v50, v237, v50, vcc
	v_cmp_gt_i32_e32 vcc, v22, v52
	v_or_b32_e32 v52, 3, v250
	v_cmp_ne_u32_e64 s[6:7], v23, v52
	v_cndmask_b32_e32 v46, v50, v46, vcc
	v_or_b32_e32 v58, 2, v251
	v_cndmask_b32_e64 v51, v237, v51, s[6:7]
	v_cmp_gt_i32_e64 s[6:7], v23, v52
	v_cmp_ne_u32_e32 vcc, v26, v58
	v_add_u32_e32 v252, 0xf0, v184
	v_cndmask_b32_e64 v47, v51, v47, s[6:7]
	ds_read_b128 v[50:53], v216
	ds_read_b128 v[246:249], v217
	s_waitcnt lgkmcnt(2)
	v_mul_f32_e32 v42, v64, v42
	v_mul_f32_e32 v43, v64, v43
	v_mul_f32_e32 v38, v170, v38
	v_mul_f32_e32 v39, v170, v39
	v_mul_f32_e32 v32, v170, v32
	v_mul_f32_e32 v33, v170, v33
	s_waitcnt lgkmcnt(1)
	v_mul_f32_e32 v52, v170, v52
	v_mul_f32_e32 v53, v170, v53
	v_cndmask_b32_e32 v52, v237, v52, vcc
	v_cmp_gt_i32_e32 vcc, v26, v58
	v_or_b32_e32 v58, 3, v251
	v_cmp_ne_u32_e64 s[6:7], v27, v58
	v_cndmask_b32_e32 v42, v52, v42, vcc
	v_mul_f32_e32 v48, v64, v48
	v_mul_f32_e32 v49, v64, v49
	v_cndmask_b32_e64 v53, v237, v53, s[6:7]
	v_cmp_gt_i32_e64 s[6:7], v27, v58
	v_or_b32_e32 v58, 2, v252
	v_cmp_ne_u32_e32 vcc, v30, v58
	v_cndmask_b32_e64 v43, v53, v43, s[6:7]
	s_waitcnt lgkmcnt(0)
	v_mul_f32_e32 v52, v64, v248
	v_mul_f32_e32 v53, v64, v249
	v_cndmask_b32_e32 v38, v237, v38, vcc
	v_cmp_gt_i32_e32 vcc, v30, v58
	v_or_b32_e32 v58, 3, v252
	v_cmp_ne_u32_e64 s[6:7], v31, v58
	v_cndmask_b32_e32 v38, v38, v52, vcc
	v_cmp_ne_u32_e32 vcc, v0, v185
	v_cndmask_b32_e64 v39, v237, v39, s[6:7]
	v_cmp_gt_i32_e64 s[6:7], v31, v58
	v_add_u32_e32 v58, 0x81, v184
	v_cndmask_b32_e32 v32, v237, v32, vcc
	v_cndmask_b32_e64 v39, v39, v53, s[6:7]
	v_cmp_ne_u32_e64 s[6:7], v1, v58
	v_mul_f32_e32 v52, v64, v240
	v_mul_f32_e32 v53, v64, v241
	v_cmp_gt_i32_e32 vcc, v0, v185
	v_cndmask_b32_e64 v33, v237, v33, s[6:7]
	v_cmp_gt_i32_e64 s[6:7], v1, v58
	v_cndmask_b32_e32 v32, v32, v52, vcc
	v_mul_f32_e32 v58, v170, v242
	v_mul_f32_e32 v59, v170, v243
	v_cndmask_b32_e64 v33, v33, v53, s[6:7]
	v_mul_f32_e32 v52, v64, v166
	v_mul_f32_e32 v53, v64, v167
	v_add_u32_e32 v166, 0x91, v184
	v_cmp_ne_u32_e32 vcc, v4, v225
	v_cmp_ne_u32_e64 s[6:7], v5, v166
	v_mul_f32_e32 v44, v64, v44
	v_mul_f32_e32 v45, v64, v45
	v_cndmask_b32_e32 v58, v237, v58, vcc
	v_cmp_gt_i32_e32 vcc, v4, v225
	v_cndmask_b32_e64 v59, v237, v59, s[6:7]
	v_cmp_gt_i32_e64 s[6:7], v5, v166
	v_cndmask_b32_e32 v166, v58, v52, vcc
	v_cmp_ne_u32_e32 vcc, v8, v226
	v_cndmask_b32_e64 v167, v59, v53, s[6:7]
	v_mul_f32_e32 v52, v64, v60
	v_mul_f32_e32 v53, v64, v61
	v_add_u32_e32 v60, 0xa1, v184
	v_mul_f32_e32 v58, v170, v244
	v_mul_f32_e32 v59, v170, v245
	v_cmp_ne_u32_e64 s[6:7], v9, v60
	v_cndmask_b32_e32 v58, v237, v58, vcc
	v_cmp_gt_i32_e32 vcc, v8, v226
	v_cndmask_b32_e64 v59, v237, v59, s[6:7]
	v_cmp_gt_i32_e64 s[6:7], v9, v60
	v_cndmask_b32_e32 v226, v58, v52, vcc
	v_cmp_ne_u32_e32 vcc, v12, v62
	v_cndmask_b32_e64 v227, v59, v53, s[6:7]
	v_mul_f32_e32 v52, v64, v54
	v_mul_f32_e32 v53, v64, v55
	v_mul_f32_e32 v54, v170, v162
	v_mul_f32_e32 v55, v170, v163
	v_add_u32_e32 v58, 0xb1, v184
	v_cndmask_b32_e32 v54, v237, v54, vcc
	v_cmp_gt_i32_e32 vcc, v12, v62
	v_cmp_ne_u32_e64 s[6:7], v13, v58
	v_mul_f32_e32 v50, v170, v50
	v_mul_f32_e32 v51, v170, v51
	v_cndmask_b32_e32 v162, v54, v52, vcc
	v_cndmask_b32_e64 v55, v237, v55, s[6:7]
	v_cmp_gt_i32_e64 s[6:7], v13, v58
	v_add_u32_e32 v54, 0xc1, v184
	v_cmp_ne_u32_e32 vcc, v16, v63
	v_cndmask_b32_e64 v163, v55, v53, s[6:7]
	v_mul_f32_e32 v52, v170, v158
	v_mul_f32_e32 v53, v170, v159
	v_cmp_ne_u32_e64 s[6:7], v17, v54
	v_cndmask_b32_e32 v52, v237, v52, vcc
	v_cmp_gt_i32_e32 vcc, v16, v63
	v_cndmask_b32_e64 v53, v237, v53, s[6:7]
	v_cmp_gt_i32_e64 s[6:7], v17, v54
	v_cndmask_b32_e32 v48, v52, v48, vcc
	v_cmp_ne_u32_e32 vcc, v20, v250
	v_cndmask_b32_e64 v49, v53, v49, s[6:7]
	v_mul_f32_e32 v52, v170, v56
	v_mul_f32_e32 v53, v170, v57
	v_add_u32_e32 v54, 0xd1, v184
	v_cndmask_b32_e32 v52, v237, v52, vcc
	v_cmp_gt_i32_e32 vcc, v20, v250
	v_cmp_ne_u32_e64 s[6:7], v21, v54
	v_mul_f32_e32 v40, v64, v40
	v_mul_f32_e32 v41, v64, v41
	v_cndmask_b32_e32 v44, v52, v44, vcc
	v_cndmask_b32_e64 v53, v237, v53, s[6:7]
	v_cmp_gt_i32_e64 s[6:7], v21, v54
	v_add_u32_e32 v52, 0xe1, v184
	v_cmp_ne_u32_e32 vcc, v24, v251
	v_cndmask_b32_e64 v45, v53, v45, s[6:7]
	v_cmp_ne_u32_e64 s[6:7], v25, v52
	v_cndmask_b32_e32 v50, v237, v50, vcc
	v_cmp_gt_i32_e32 vcc, v24, v251
	v_cndmask_b32_e64 v51, v237, v51, s[6:7]
	v_cmp_gt_i32_e64 s[6:7], v25, v52
	v_add_u32_e32 v52, 0xf1, v184
	v_cndmask_b32_e32 v40, v50, v40, vcc
	v_cndmask_b32_e64 v41, v51, v41, s[6:7]
	v_mul_f32_e32 v36, v170, v36
	v_mul_f32_e32 v37, v170, v37
	v_cmp_ne_u32_e32 vcc, v28, v252
	v_cmp_ne_u32_e64 s[6:7], v29, v52
	v_mul_f32_e32 v50, v64, v246
	v_mul_f32_e32 v51, v64, v247
	v_cndmask_b32_e32 v36, v237, v36, vcc
	v_cmp_gt_i32_e32 vcc, v28, v252
	v_cndmask_b32_e64 v37, v237, v37, s[6:7]
	v_cmp_gt_i32_e64 s[6:7], v29, v52
	v_cndmask_b32_e32 v36, v36, v50, vcc
	v_mul_f32_e32 v62, v156, v38
	v_mul_f32_e32 v63, v157, v39
	v_cndmask_b32_e64 v37, v37, v51, s[6:7]
	v_mul_f32_e32 v58, v152, v42
	v_mul_f32_e32 v59, v153, v43
	v_mul_f32_e32 v54, v148, v46
	v_mul_f32_e32 v55, v149, v47
	v_mul_f32_e32 v50, v144, v160
	v_mul_f32_e32 v51, v145, v161
	v_mul_f32_e32 v46, v124, v164
	v_mul_f32_e32 v47, v125, v165
	v_mul_f32_e32 v42, v120, v182
	v_mul_f32_e32 v43, v121, v183
	v_mul_f32_e32 v38, v116, v168
	v_mul_f32_e32 v39, v117, v169
	v_mul_f32_e32 v34, v112, v34
	v_mul_f32_e32 v35, v113, v35
	v_mul_f32_e32 v60, v154, v36
	v_mul_f32_e32 v61, v155, v37
	v_mul_f32_e32 v56, v150, v40
	v_mul_f32_e32 v57, v151, v41
	v_mul_f32_e32 v52, v146, v44
	v_mul_f32_e32 v53, v147, v45
	v_mul_f32_e32 v48, v142, v48
	v_mul_f32_e32 v49, v143, v49
	v_mul_f32_e32 v44, v122, v162
	v_mul_f32_e32 v45, v123, v163
	v_mul_f32_e32 v40, v118, v226
	v_mul_f32_e32 v41, v119, v227
	v_mul_f32_e32 v36, v114, v166
	v_mul_f32_e32 v37, v115, v167
	v_mul_f32_e32 v32, v110, v32
	v_mul_f32_e32 v33, v111, v33
	s_mov_b64 s[6:7], 0
.LBB0_1192:
	s_andn2_b64 vcc, exec, s[6:7]
	s_cbranch_vccnz .LBB0_1194
	ds_read_b128 v[32:35], v171
	ds_read_b128 v[36:39], v171 offset:64
	ds_read_b128 v[40:43], v171 offset:128
	ds_read_b128 v[44:47], v171 offset:192
	ds_read_b128 v[48:51], v171 offset:256
	ds_read_b128 v[52:55], v171 offset:320
	ds_read_b128 v[56:59], v171 offset:384
	ds_read_b128 v[60:63], v171 offset:448
	s_waitcnt lgkmcnt(7)
	v_mul_f32_e32 v34, v170, v34
	v_mul_f32_e32 v35, v170, v35
	s_waitcnt lgkmcnt(6)
	v_mul_f32_e32 v38, v170, v38
	v_mul_f32_e32 v39, v170, v39
	s_waitcnt lgkmcnt(5)
	v_mul_f32_e32 v42, v170, v42
	v_mul_f32_e32 v43, v170, v43
	s_waitcnt lgkmcnt(4)
	v_mul_f32_e32 v46, v170, v46
	v_mul_f32_e32 v47, v170, v47
	s_waitcnt lgkmcnt(3)
	v_mul_f32_e32 v50, v170, v50
	v_mul_f32_e32 v51, v170, v51
	s_waitcnt lgkmcnt(2)
	v_mul_f32_e32 v54, v170, v54
	v_mul_f32_e32 v55, v170, v55
	s_waitcnt lgkmcnt(1)
	v_mul_f32_e32 v58, v170, v58
	v_mul_f32_e32 v59, v170, v59
	s_waitcnt lgkmcnt(0)
	v_mul_f32_e32 v62, v170, v62
	v_mul_f32_e32 v63, v170, v63
	v_mul_f32_e32 v32, v170, v32
	v_mul_f32_e32 v33, v170, v33
	v_mul_f32_e32 v36, v170, v36
	v_mul_f32_e32 v37, v170, v37
	v_mul_f32_e32 v40, v170, v40
	v_mul_f32_e32 v41, v170, v41
	v_mul_f32_e32 v44, v170, v44
	v_mul_f32_e32 v45, v170, v45
	v_mul_f32_e32 v48, v170, v48
	v_mul_f32_e32 v49, v170, v49
	v_mul_f32_e32 v52, v170, v52
	v_mul_f32_e32 v53, v170, v53
	v_mul_f32_e32 v56, v170, v56
	v_mul_f32_e32 v57, v170, v57
	v_mul_f32_e32 v60, v170, v60
	v_mul_f32_e32 v61, v170, v61
	v_mul_f32_e32 v60, v154, v60
	v_mul_f32_e32 v61, v155, v61
	v_mul_f32_e32 v56, v150, v56
	v_mul_f32_e32 v57, v151, v57
	v_mul_f32_e32 v52, v146, v52
	v_mul_f32_e32 v53, v147, v53
	v_mul_f32_e32 v48, v142, v48
	v_mul_f32_e32 v49, v143, v49
	v_mul_f32_e32 v44, v122, v44
	v_mul_f32_e32 v45, v123, v45
	v_mul_f32_e32 v40, v118, v40
	v_mul_f32_e32 v41, v119, v41
	v_mul_f32_e32 v36, v114, v36
	v_mul_f32_e32 v37, v115, v37
	v_mul_f32_e32 v32, v110, v32
	v_mul_f32_e32 v33, v111, v33
	v_mul_f32_e32 v62, v156, v62
	v_mul_f32_e32 v63, v157, v63
	v_mul_f32_e32 v58, v152, v58
	v_mul_f32_e32 v59, v153, v59
	v_mul_f32_e32 v54, v148, v54
	v_mul_f32_e32 v55, v149, v55
	v_mul_f32_e32 v50, v144, v50
	v_mul_f32_e32 v51, v145, v51
	v_mul_f32_e32 v46, v124, v46
	v_mul_f32_e32 v47, v125, v47
	v_mul_f32_e32 v42, v120, v42
	v_mul_f32_e32 v43, v121, v43
	v_mul_f32_e32 v38, v116, v38
	v_mul_f32_e32 v39, v117, v39
	v_mul_f32_e32 v34, v112, v34
	v_mul_f32_e32 v35, v113, v35

.LBB0_1195:
	s_andn2_b64 vcc, exec, s[6:7]
	s_cbranch_vccnz .LBB0_1153
	v_add_u32_e32 v60, 0x12000, v202
	s_nop 0
	ds_read_b128 v[32:35], v60
	ds_read_b128 v[36:39], v60 offset:64
	ds_read_b128 v[40:43], v60 offset:128
	ds_read_b128 v[44:47], v60 offset:192
	ds_read_b128 v[48:51], v60 offset:256
	ds_read_b128 v[52:55], v60 offset:320
	ds_read_b128 v[56:59], v60 offset:384
	ds_read_b128 v[60:63], v60 offset:448
	s_waitcnt lgkmcnt(7)
	v_mul_f32_e32 v34, v64, v34
	v_mul_f32_e32 v35, v64, v35
	s_waitcnt lgkmcnt(6)
	v_mul_f32_e32 v38, v64, v38
	v_mul_f32_e32 v39, v64, v39
	s_waitcnt lgkmcnt(5)
	v_mul_f32_e32 v42, v64, v42
	v_mul_f32_e32 v43, v64, v43
	s_waitcnt lgkmcnt(4)
	v_mul_f32_e32 v46, v64, v46
	v_mul_f32_e32 v47, v64, v47
	s_waitcnt lgkmcnt(3)
	v_mul_f32_e32 v50, v64, v50
	v_mul_f32_e32 v51, v64, v51
	s_waitcnt lgkmcnt(2)
	v_mul_f32_e32 v54, v64, v54
	v_mul_f32_e32 v55, v64, v55
	s_waitcnt lgkmcnt(1)
	v_mul_f32_e32 v58, v64, v58
	v_mul_f32_e32 v59, v64, v59
	s_waitcnt lgkmcnt(0)
	v_mul_f32_e32 v62, v64, v62
	v_mul_f32_e32 v63, v64, v63
	v_mul_f32_e32 v32, v64, v32
	v_mul_f32_e32 v33, v64, v33
	v_mul_f32_e32 v36, v64, v36
	v_mul_f32_e32 v37, v64, v37
	v_mul_f32_e32 v40, v64, v40
	v_mul_f32_e32 v41, v64, v41
	v_mul_f32_e32 v44, v64, v44
	v_mul_f32_e32 v45, v64, v45
	v_mul_f32_e32 v48, v64, v48
	v_mul_f32_e32 v49, v64, v49
	v_mul_f32_e32 v52, v64, v52
	v_mul_f32_e32 v53, v64, v53
	v_mul_f32_e32 v56, v64, v56
	v_mul_f32_e32 v57, v64, v57
	v_mul_f32_e32 v60, v64, v60
	v_mul_f32_e32 v61, v64, v61
	v_mul_f32_e32 v60, v154, v60
	v_mul_f32_e32 v61, v155, v61
	v_mul_f32_e32 v56, v150, v56
	v_mul_f32_e32 v57, v151, v57
	v_mul_f32_e32 v52, v146, v52
	v_mul_f32_e32 v53, v147, v53
	v_mul_f32_e32 v48, v142, v48
	v_mul_f32_e32 v49, v143, v49
	v_mul_f32_e32 v44, v122, v44
	v_mul_f32_e32 v45, v123, v45
	v_mul_f32_e32 v40, v118, v40
	v_mul_f32_e32 v41, v119, v41
	v_mul_f32_e32 v36, v114, v36
	v_mul_f32_e32 v37, v115, v37
	v_mul_f32_e32 v32, v110, v32
	v_mul_f32_e32 v33, v111, v33
	v_mul_f32_e32 v62, v156, v62
	v_mul_f32_e32 v63, v157, v63
	v_mul_f32_e32 v58, v152, v58
	v_mul_f32_e32 v59, v153, v59
	v_mul_f32_e32 v54, v148, v54
	v_mul_f32_e32 v55, v149, v55
	v_mul_f32_e32 v50, v144, v50
	v_mul_f32_e32 v51, v145, v51
	v_mul_f32_e32 v46, v124, v46
	v_mul_f32_e32 v47, v125, v47
	v_mul_f32_e32 v42, v120, v42
	v_mul_f32_e32 v43, v121, v43
	v_mul_f32_e32 v38, v116, v38
	v_mul_f32_e32 v39, v117, v39
	v_mul_f32_e32 v34, v112, v34
	v_mul_f32_e32 v35, v113, v35
	s_branch .LBB0_1153
.LBB0_1197:
	v_lshlrev_b32_e32 v64, 1, v191
	v_lshl_add_u64 v[0:1], v[174:175], 0, v[64:65]
	global_load_dwordx2 v[20:21], v[0:1], off offset:1536
	global_load_dwordx2 v[22:23], v[0:1], off offset:1568
	v_add_f32_e32 v4, v118, v119
	v_add_f32_e32 v5, v120, v121
	v_add_f32_e32 v6, v122, v123
	v_add_f32_e32 v7, v124, v125
	s_load_dwordx2 s[6:7], s[0:1], 0x78
	v_add_f32_e32 v4, v4, v5
	v_add_f32_e32 v5, v6, v7
	global_load_dwordx2 v[24:25], v[0:1], off offset:1600
	global_load_dwordx2 v[6:7], v[0:1], off offset:1632
	s_lshl_b32 s8, s45, 8
	v_lshlrev_b64 v[2:3], 11, v[172:173]
	v_add_f32_e32 v8, v114, v115
	v_add_f32_e32 v9, v116, v117
	s_mov_b32 s17, s97
	s_ashr_i32 s9, s8, 31
	v_lshl_add_u64 v[2:3], s[14:15], 0, v[2:3]
	v_add_f32_e32 v4, 0, v4
	v_add_f32_e32 v10, v110, v111
	v_add_f32_e32 v11, v112, v113
	v_add_f32_e32 v8, v8, v9
	s_lshl_b64 s[8:9], s[8:9], 2
	v_lshl_add_u64 v[0:1], v[2:3], 0, s[16:17]
	v_add_f32_e32 v2, v5, v4
	v_add_f32_e32 v9, v10, v11
	v_lshl_add_u64 v[26:27], v[0:1], 0, v[64:65]
	v_add_f32_e32 v0, v8, v2
	s_waitcnt lgkmcnt(0)
	s_add_u32 s6, s6, s8
	v_add_f32_e32 v0, v9, v0
	s_addc_u32 s7, s7, s9
	s_lshl_b32 s8, s18, 2
	v_mov_b32_e32 v1, v0
	s_add_u32 s6, s6, s8
	v_lshlrev_b32_e32 v28, 2, v191
	v_permlane16_swap_b32_e32 v0, v1
	s_addc_u32 s7, s7, 0
	v_add_f32_e32 v29, v0, v1
	global_load_dwordx4 v[8:11], v28, s[6:7]
	global_load_dwordx4 v[12:15], v28, s[6:7] offset:64
	global_load_dwordx4 v[16:19], v28, s[6:7] offset:128
	global_load_dwordx4 v[0:3], v28, s[6:7] offset:192
	v_mov_b32_e32 v30, v29
	s_nop 1
	v_permlane32_swap_b32_e32 v29, v30
	v_add_f32_e32 v28, v29, v30
	v_mul_f32_e32 v28, 0x3c800000, v28
	v_sub_f32_e32 v32, v118, v28
	v_sub_f32_e32 v33, v119, v28
	v_sub_f32_e32 v30, v120, v28
	v_sub_f32_e32 v31, v121, v28
	v_mul_f32_e32 v38, v33, v33
	v_fma_f32 v39, v33, v33, v38
	v_fma_f32 v38, v32, v32, v38
	v_mul_f32_e32 v40, v31, v31
	v_fma_f32 v38, v30, v30, v38
	v_fma_f32 v39, v31, v31, v39
	v_sub_f32_e32 v36, v122, v28
	v_sub_f32_e32 v37, v123, v28
	v_add_f32_e32 v38, v40, v38
	v_add_f32_e32 v39, v40, v39
	v_mul_f32_e32 v42, v37, v37
	v_fma_f32 v38, v36, v36, v38
	v_fma_f32 v39, v37, v37, v39
	v_sub_f32_e32 v34, v124, v28
	v_sub_f32_e32 v35, v125, v28
	v_add_f32_e32 v38, v42, v38
	v_add_f32_e32 v39, v42, v39
	v_fma_f32 v38, v34, v34, v38
	v_fma_f32 v39, v35, v35, v39
	s_mov_b32 s6, 0xf000000
	s_mov_b64 s[10:11], 0xf000000
	v_lshl_add_u64 v[4:5], v[26:27], 0, s[10:11]
	s_waitcnt vmcnt(7)
	v_lshlrev_b32_e32 v40, 16, v21
	v_and_b32_e32 v41, 0xffff0000, v21
	v_lshlrev_b32_e32 v42, 16, v20
	v_and_b32_e32 v43, 0xffff0000, v20
	v_mul_f32_e32 v29, 0xbfb8aa3b, v40
	s_waitcnt vmcnt(6)
	v_lshlrev_b32_e32 v20, 16, v23
	v_and_b32_e32 v21, 0xffff0000, v23
	v_lshlrev_b32_e32 v44, 16, v22
	v_and_b32_e32 v45, 0xffff0000, v22
	v_mul_f32_e32 v22, 0xbfb8aa3b, v42
	v_mul_f32_e32 v23, 0xbfb8aa3b, v43
	v_mul_f32_e32 v46, 0xbfb8aa3b, v41
	v_exp_f32_e32 v29, v29
	v_exp_f32_e32 v22, v22
	v_exp_f32_e32 v23, v23
	v_exp_f32_e32 v46, v46
	v_mul_f32_e32 v47, 0xbfb8aa3b, v44
	v_mul_f32_e32 v48, 0xbfb8aa3b, v45
	v_add_f32_e32 v29, 1.0, v29
	v_exp_f32_e32 v49, v47
	v_add_f32_e32 v22, 1.0, v22
	v_add_f32_e32 v23, 1.0, v23
	v_add_f32_e32 v47, 1.0, v46
	v_rcp_f32_e32 v46, v29
	v_exp_f32_e32 v29, v48
	v_rcp_f32_e32 v22, v22
	v_rcp_f32_e32 v23, v23
	v_rcp_f32_e32 v47, v47
	v_add_f32_e32 v29, 1.0, v29
	v_add_f32_e32 v48, 1.0, v49
	v_mul_f32_e32 v22, v22, v42
	v_mul_f32_e32 v23, v23, v43
	v_rcp_f32_e32 v43, v29
	v_mul_f32_e32 v29, 0xbfb8aa3b, v20
	v_mul_f32_e32 v40, v46, v40
	v_mul_f32_e32 v41, v47, v41
	v_exp_f32_e32 v29, v29
	v_mul_f32_e32 v46, 0xbfb8aa3b, v21
	v_rcp_f32_e32 v42, v48
	v_exp_f32_e32 v46, v46
	v_add_f32_e32 v29, 1.0, v29
	s_waitcnt vmcnt(5)
	v_lshlrev_b32_e32 v52, 16, v24
	v_mul_f32_e32 v42, v42, v44
	v_mul_f32_e32 v43, v43, v45
	v_rcp_f32_e32 v44, v29
	v_add_f32_e32 v29, 1.0, v46
	v_rcp_f32_e32 v45, v29
	v_and_b32_e32 v53, 0xffff0000, v24
	v_mul_f32_e32 v24, 0xbfb8aa3b, v52
	v_sub_f32_e32 v48, v114, v28
	v_sub_f32_e32 v49, v115, v28
	v_mul_f32_e32 v20, v44, v20
	v_mul_f32_e32 v21, v45, v21
	v_sub_f32_e32 v44, v116, v28
	v_sub_f32_e32 v45, v117, v28
	v_exp_f32_e32 v29, v24
	v_mul_f32_e32 v24, 0xbfb8aa3b, v53
	v_exp_f32_e32 v51, v24
	v_mul_f32_e32 v46, v35, v35
	v_add_f32_e32 v38, v46, v38
	v_add_f32_e32 v39, v46, v39
	v_fma_f32 v38, v48, v48, v38
	v_fma_f32 v39, v49, v49, v39
	v_mul_f32_e32 v50, v49, v49
	v_add_f32_e32 v29, 1.0, v29
	v_lshlrev_b32_e32 v46, 16, v25
	v_and_b32_e32 v47, 0xffff0000, v25
	v_add_f32_e32 v24, v50, v38
	v_add_f32_e32 v25, v50, v39
	v_rcp_f32_e32 v38, v29
	v_add_f32_e32 v29, 1.0, v51
	v_rcp_f32_e32 v39, v29
	v_mul_f32_e32 v29, 0xbfb8aa3b, v46
	v_exp_f32_e32 v29, v29
	v_mul_f32_e32 v50, 0xbfb8aa3b, v47
	v_exp_f32_e32 v51, v50
	s_waitcnt vmcnt(4)
	v_lshlrev_b32_e32 v54, 16, v6
	v_add_f32_e32 v29, 1.0, v29
	v_rcp_f32_e32 v50, v29
	v_add_f32_e32 v29, 1.0, v51
	v_mul_f32_e32 v38, v38, v52
	v_mul_f32_e32 v39, v39, v53
	v_rcp_f32_e32 v51, v29
	v_fma_f32 v24, v44, v44, v24
	v_fma_f32 v25, v45, v45, v25
	v_mul_f32_e32 v52, v45, v45
	v_and_b32_e32 v55, 0xffff0000, v6
	v_mul_f32_e32 v6, 0xbfb8aa3b, v54
	v_add_f32_e32 v24, v52, v24
	v_add_f32_e32 v25, v52, v25
	v_exp_f32_e32 v6, v6
	v_mul_f32_e32 v53, 0xbfb8aa3b, v55
	v_exp_f32_e32 v53, v53
	v_mul_f32_e32 v46, v50, v46
	v_mul_f32_e32 v47, v51, v47
	v_sub_f32_e32 v50, v112, v28
	v_sub_f32_e32 v51, v113, v28
	v_sub_f32_e32 v29, v111, v28
	v_sub_f32_e32 v28, v110, v28
	v_add_f32_e32 v6, 1.0, v6
	v_fma_f32 v24, v28, v28, v24
	v_fma_f32 v25, v29, v29, v25
	v_mul_f32_e32 v52, v29, v29
	v_add_f32_e32 v24, v52, v24
	v_add_f32_e32 v25, v52, v25
	v_rcp_f32_e32 v52, v6
	v_add_f32_e32 v6, 1.0, v53
	v_rcp_f32_e32 v53, v6
	v_fma_f32 v24, v50, v50, v24
	v_fma_f32 v25, v51, v51, v25
	v_mul_f32_e32 v6, v51, v51
	v_add_f32_e32 v24, v6, v24
	v_add_f32_e32 v25, v6, v25
	v_mov_b32_e32 v6, v24
	s_nop 1
	v_permlane16_swap_b32_e32 v24, v6
	v_add_f32_e32 v6, v24, v6
	v_mov_b32_e32 v24, v6
	s_nop 1
	v_permlane32_swap_b32_e32 v6, v24
	v_add_f32_e32 v6, v6, v24
	v_fmamk_f32 v6, v6, 0x3c800000, v229
	v_mul_f32_e32 v24, 0x4b800000, v6
	v_cmp_gt_f32_e32 vcc, s55, v6
	s_nop 1
	v_cndmask_b32_e32 v6, v6, v24, vcc
	v_rsq_f32_e32 v56, v6
	v_mul_f32_e32 v24, v52, v54
	v_mul_f32_e32 v25, v53, v55
	v_lshlrev_b32_e32 v6, 16, v7
	v_and_b32_e32 v7, 0xffff0000, v7
	v_mul_f32_e32 v52, 0x45800000, v56
	v_cndmask_b32_e32 v52, v56, v52, vcc
	v_mul_f32_e32 v32, v32, v52
	v_mul_f32_e32 v33, v33, v52
	s_waitcnt vmcnt(3)
	v_mul_f32_e32 v8, v8, v32
	v_mul_f32_e32 v9, v9, v33
	s_nop 0
	v_mul_f32_e32 v8, v22, v8
	v_mul_f32_e32 v9, v23, v9
	v_mul_f32_e32 v22, v30, v52
	v_mul_f32_e32 v23, v31, v52
	v_cvt_pk_bf16_f32 v8, v8, v9
	v_mul_f32_e32 v10, v10, v22
	v_mul_f32_e32 v11, v11, v23
	s_nop 0
	v_mul_f32_e32 v10, v40, v10
	v_mul_f32_e32 v11, v41, v11
	s_nop 0
	v_cvt_pk_bf16_f32 v9, v10, v11
	v_add_co_u32_e32 v10, vcc, s6, v26
	s_nop 1
	v_addc_co_u32_e32 v11, vcc, 0, v27, vcc
	global_store_dwordx2 v[10:11], v[8:9], off
	v_mul_f32_e32 v8, v36, v52
	v_mul_f32_e32 v9, v37, v52
	v_mul_f32_e32 v10, v34, v52
	v_mul_f32_e32 v11, v35, v52
	s_waitcnt vmcnt(3)
	v_mul_f32_e32 v8, v12, v8
	v_mul_f32_e32 v9, v13, v9
	v_mul_f32_e32 v10, v14, v10
	v_mul_f32_e32 v11, v15, v11
	v_mul_f32_e32 v8, v8, v42
	v_mul_f32_e32 v9, v9, v43
	v_mul_f32_e32 v10, v10, v20
	v_mul_f32_e32 v11, v11, v21
	v_cvt_pk_bf16_f32 v8, v8, v9
	v_cvt_pk_bf16_f32 v9, v10, v11
	global_store_dwordx2 v[4:5], v[8:9], off offset:32
	v_mul_f32_e32 v8, v48, v52
	v_mul_f32_e32 v9, v49, v52
	v_mul_f32_e32 v10, v44, v52
	v_mul_f32_e32 v11, v45, v52
	s_waitcnt vmcnt(3)
	v_mul_f32_e32 v8, v16, v8
	v_mul_f32_e32 v9, v17, v9
	v_mul_f32_e32 v10, v18, v10
	v_mul_f32_e32 v11, v19, v11
	v_mul_f32_e32 v8, v8, v38
	v_mul_f32_e32 v9, v9, v39
	v_mul_f32_e32 v10, v10, v46
	v_mul_f32_e32 v11, v11, v47
	v_cvt_pk_bf16_f32 v8, v8, v9
	v_cvt_pk_bf16_f32 v9, v10, v11
	v_mul_f32_e32 v10, 0xbfb8aa3b, v6
	v_mul_f32_e32 v11, 0xbfb8aa3b, v7
	v_exp_f32_e32 v10, v10
	v_exp_f32_e32 v11, v11
	global_store_dwordx2 v[4:5], v[8:9], off offset:64
	v_mul_f32_e32 v8, v28, v52
	v_mul_f32_e32 v9, v29, v52
	s_waitcnt vmcnt(3)
	v_mul_f32_e32 v0, v0, v8
	v_mul_f32_e32 v1, v1, v9
	v_add_f32_e32 v8, 1.0, v10
	v_add_f32_e32 v9, 1.0, v11
	v_rcp_f32_e32 v8, v8
	v_rcp_f32_e32 v9, v9
	v_mul_f32_e32 v10, v50, v52
	v_mul_f32_e32 v11, v51, v52
	v_mul_f32_e32 v0, v0, v24
	v_mul_f32_e32 v1, v1, v25
	v_mul_f32_e32 v2, v2, v10
	v_mul_f32_e32 v3, v3, v11
	v_mul_f32_e32 v6, v8, v6
	v_mul_f32_e32 v7, v9, v7
	v_cvt_pk_bf16_f32 v0, v0, v1
	v_mul_f32_e32 v2, v2, v6
	v_mul_f32_e32 v3, v3, v7
	s_nop 0
	v_cvt_pk_bf16_f32 v1, v2, v3
	global_store_dwordx2 v[4:5], v[0:1], off offset:96

.LBB0_1199:
	s_andn2_b64 vcc, exec, s[6:7]
	s_cbranch_vccnz .LBB0_1259
	v_mov_b32_e32 v9, v228
	s_load_dwordx2 s[6:7], s[0:1], 0x100
	s_add_i32 s10, s86, 0xfffffe70
	s_lshr_b32 s16, s10, 5
	s_lshl_b32 s14, s16, 10
	s_add_i32 s17, s14, 0x1000
	s_waitcnt lgkmcnt(0)
	s_add_u32 s8, s6, 0xae00000
	s_addc_u32 s9, s7, 0
	s_lshl_b32 s11, s86, 7
	s_and_b32 s11, s11, 0x380
	s_lshl_b32 s10, s10, 3
	v_and_b32_e32 v8, 15, v9
	v_ashrrev_i32_e32 v0, 2, v9
	s_and_b32 s15, s10, 0xc0
	s_or_b32 s10, s11, s17
	v_and_b32_e32 v0, -16, v0
	v_or_b32_e32 v1, s10, v8
	v_add_u32_e32 v180, v1, v0
	v_mov_b64_e32 v[0:1], s[8:9]
	v_mad_i64_i32 v[0:1], s[10:11], v180, s93, v[0:1]
	s_lshl_b32 s12, s15, 1
	s_mov_b32 s13, s97
	v_lshl_add_u64 v[0:1], v[0:1], 0, s[12:13]
	v_and_b32_e32 v64, 48, v9
	v_lshl_add_u64 v[0:1], v[0:1], 0, v[64:65]
	s_mov_b64 s[10:11], 0x1000
	v_lshl_add_u64 v[2:3], v[0:1], 0, s[10:11]
	v_add_co_u32_e32 v0, vcc, 0x1000, v0
	v_and_b32_e32 v10, 63, v9
	s_nop 0
	v_addc_co_u32_e32 v1, vcc, 0, v1, vcc
	global_load_dwordx4 v[4:7], v[0:1], off
	s_nop 0
	global_load_dwordx4 v[0:3], v[2:3], off offset:64
	v_cmp_gt_u32_e32 vcc, 32, v10
	v_mov_b32_e32 v209, 0
	v_mov_b32_e32 v182, 0
	v_mov_b32_e32 v183, 0
	s_and_saveexec_b64 s[10:11], vcc
	s_cbranch_execz .LBB0_1202
	s_load_dwordx2 s[18:19], s[0:1], 0xc0
	s_lshl_b32 s20, s45, 7
	s_ashr_i32 s21, s20, 31
	s_lshl_b64 s[20:21], s[20:21], 2
	v_lshlrev_b32_e32 v12, 2, v10
	s_waitcnt lgkmcnt(0)
	s_add_u32 s18, s18, s20
	s_addc_u32 s19, s19, s21
	global_load_dword v11, v12, s[18:19]
	global_load_dword v13, v12, s[18:19] offset:128
	global_load_dword v10, v12, s[18:19] offset:256
	s_nop 0
	global_load_dword v12, v12, s[18:19] offset:384
	s_waitcnt vmcnt(0)
	v_mul_f32_e32 v182, v10, v12
	v_mul_f32_e32 v183, v11, v13
.LBB0_1202:
	s_or_b64 exec, exec, s[10:11]
	v_lshlrev_b32_e32 v10, 3, v9
	v_and_b32_e32 v33, 56, v10
	v_add_u32_e32 v18, 0x200, v9
	v_lshlrev_b32_e32 v10, 1, v33
	v_mov_b32_e32 v11, v65
	v_ashrrev_i32_e32 v26, 3, v9
	v_ashrrev_i32_e32 v34, 3, v18
	v_lshl_add_u64 v[184:185], s[8:9], 0, v[10:11]
	v_add_u32_e32 v10, s17, v26
	v_add_u32_e32 v18, s17, v34
	v_mad_i64_i32 v[10:11], s[8:9], v10, s93, v[184:185]
	v_mad_i64_i32 v[18:19], s[8:9], v18, s93, v[184:185]
	s_waitcnt vmcnt(0)
	v_lshlrev_b32_e32 v28, 16, v4
	v_and_b32_e32 v29, 0xffff0000, v4
	s_mov_b32 s8, 0x3e8293ee
	s_bitset1_b32 s17, 7
	s_or_b32 s13, s15, 0x900
	s_or_b32 s18, s15, 0xa00
	v_mul_f32_e32 v28, s8, v28
	v_mul_f32_e32 v29, s8, v29
	v_lshlrev_b32_e32 v4, 16, v5
	v_and_b32_e32 v5, 0xffff0000, v5
	v_lshlrev_b32_e32 v30, 16, v6
	v_and_b32_e32 v31, 0xffff0000, v6
	v_lshlrev_b32_e32 v6, 16, v7
	v_and_b32_e32 v7, 0xffff0000, v7
	v_add_u32_e32 v27, s17, v26
	s_lshl_b32 s96, s13, 1
	s_lshl_b32 s20, s18, 1
	s_mov_b32 s21, s97
	v_mul_f32_e32 v4, s8, v4
	v_mul_f32_e32 v5, s8, v5
	v_mul_f32_e32 v30, s8, v30
	v_mul_f32_e32 v31, s8, v31
	v_mul_f32_e32 v6, s8, v6
	v_mul_f32_e32 v7, s8, v7
	v_cvt_pk_bf16_f32 v80, v28, v29
	v_mad_i64_i32 v[28:29], s[22:23], v27, s93, v[184:185]
	v_lshl_add_u64 v[12:13], v[10:11], 0, s[96:97]
	v_lshl_add_u64 v[14:15], v[10:11], 0, s[20:21]
	v_lshl_add_u64 v[20:21], v[18:19], 0, s[96:97]
	v_lshl_add_u64 v[22:23], v[18:19], 0, s[20:21]
	v_cvt_pk_bf16_f32 v81, v4, v5
	v_cvt_pk_bf16_f32 v82, v30, v31
	v_cvt_pk_bf16_f32 v83, v6, v7
	v_lshlrev_b32_e32 v4, 16, v0
	v_and_b32_e32 v5, 0xffff0000, v0
	v_lshlrev_b32_e32 v0, 16, v1
	v_and_b32_e32 v1, 0xffff0000, v1
	v_lshlrev_b32_e32 v6, 16, v2
	v_and_b32_e32 v7, 0xffff0000, v2
	v_lshlrev_b32_e32 v2, 16, v3
	v_and_b32_e32 v3, 0xffff0000, v3
	v_lshl_add_u64 v[30:31], v[28:29], 0, s[96:97]
	v_lshl_add_u64 v[28:29], v[28:29], 0, s[20:21]
	v_add_u32_e32 v27, s17, v34
	global_load_dwordx4 v[10:13], v[12:13], off
	s_nop 0
	global_load_dwordx4 v[14:17], v[14:15], off
	s_nop 0
	global_load_dwordx4 v[18:21], v[20:21], off
	s_nop 0
	global_load_dwordx4 v[22:25], v[22:23], off
	v_mul_f32_e32 v4, s8, v4
	v_mul_f32_e32 v5, s8, v5
	v_mul_f32_e32 v0, s8, v0
	v_mul_f32_e32 v1, s8, v1
	v_mul_f32_e32 v6, s8, v6
	v_mul_f32_e32 v7, s8, v7
	v_mul_f32_e32 v2, s8, v2
	v_mul_f32_e32 v3, s8, v3
	s_load_dwordx4 s[8:11], s[0:1], 0x38
	global_load_dwordx4 v[84:87], v[30:31], off
	global_load_dwordx4 v[88:91], v[28:29], off
	v_mad_i64_i32 v[28:29], s[22:23], v27, s93, v[184:185]
	s_add_i32 s17, s14, 0x1100
	v_lshl_add_u64 v[30:31], v[28:29], 0, s[96:97]
	v_lshl_add_u64 v[28:29], v[28:29], 0, s[20:21]
	v_add_u32_e32 v27, s17, v26
	global_load_dwordx4 v[96:99], v[30:31], off
	global_load_dwordx4 v[100:103], v[28:29], off
	v_mad_i64_i32 v[28:29], s[22:23], v27, s93, v[184:185]
	v_lshl_add_u64 v[30:31], v[28:29], 0, s[96:97]
	v_lshl_add_u64 v[28:29], v[28:29], 0, s[20:21]
	v_add_u32_e32 v27, s17, v34
	s_waitcnt lgkmcnt(0)
	s_barrier
	global_load_dwordx4 v[104:107], v[30:31], off
	global_load_dwordx4 v[108:111], v[28:29], off
	v_mad_i64_i32 v[28:29], s[22:23], v27, s93, v[184:185]
	v_lshl_add_u64 v[30:31], v[28:29], 0, s[96:97]
	v_lshl_add_u64 v[28:29], v[28:29], 0, s[20:21]
	global_load_dwordx4 v[112:115], v[30:31], off
	global_load_dwordx4 v[116:119], v[28:29], off
	s_lshl_b32 s16, s16, 2
	s_add_i32 s16, s45, s16
	s_ashr_i32 s17, s16, 31
	v_cvt_pk_bf16_f32 v94, v6, v7
	v_lshlrev_b32_e32 v6, 4, v9
	s_lshl_b64 s[16:17], s[16:17], 18
	s_lshl_b32 s15, s15, 2
	v_and_b32_e32 v191, 0x70, v6
	s_or_b32 s15, s16, s15
	v_cvt_pk_bf16_f32 v93, v0, v1
	v_cvt_pk_bf16_f32 v95, v2, v3
	v_add_u32_e32 v0, 0, v191
	v_mul_lo_u32 v1, v26, s94
	v_mul_lo_u32 v2, v34, s94
	s_add_u32 s8, s8, s15
	v_ashrrev_i32_e32 v27, 31, v26
	v_cvt_pk_bf16_f32 v92, v4, v5
	v_add_u32_e32 v199, v0, v1
	v_add_u32_e32 v200, v0, v2
	v_add_u32_e32 v201, 0, v1
	s_addc_u32 s9, s9, s17
	v_lshlrev_b64 v[0:1], 10, v[26:27]
	v_lshlrev_b32_e32 v4, 5, v9
	s_add_u32 s10, s10, s15
	v_lshl_add_u64 v[2:3], s[8:9], 0, v[0:1]
	v_and_b32_e32 v4, 0x80, v4
	v_mov_b32_e32 v5, v65
	s_addc_u32 s11, s11, s17
	v_lshl_add_u64 v[2:3], v[2:3], 0, v[4:5]
	v_and_b32_e32 v4, 48, v6
	v_bfe_u32 v32, v9, 4, 2
	v_lshl_add_u64 v[186:187], v[2:3], 0, v[4:5]
	v_lshl_add_u64 v[0:1], s[10:11], 0, v[0:1]
	v_lshlrev_b32_e32 v2, 2, v33
	v_mov_b32_e32 v3, v65
	v_lshl_add_u64 v[188:189], v[0:1], 0, v[2:3]
	v_lshlrev_b32_e32 v198, 2, v32
	v_lshrrev_b32_e32 v1, 2, v8
	v_or_b32_e32 v1, v198, v1
	v_lshlrev_b32_e32 v2, 3, v8
	v_and_b32_e32 v2, 24, v2
	v_mul_u32_u24_e32 v1, 0x90, v1
	v_add3_u32 v202, 0, v2, v1
	v_add_u32_e32 v1, s14, v34
	v_add_u32_e32 v0, 0, v64
	v_mul_u32_u24_e32 v3, 0x90, v8
	v_add_u32_e32 v204, 0x1200, v1
	v_add_u32_e32 v1, s14, v26
	v_mov_b32_e32 v64, v65
	s_waitcnt vmcnt(11)
	ds_write_b128 v199, v[10:13]
	s_waitcnt vmcnt(10)
	ds_write_b128 v199, v[14:17] offset:18432
	s_waitcnt vmcnt(9)
	ds_write_b128 v200, v[18:21]
	s_waitcnt vmcnt(8)
	ds_write_b128 v200, v[22:25] offset:18432
	v_add_u32_e32 v205, 0x1200, v1
	v_mov_b32_e32 v66, v65
	v_mov_b32_e32 v67, v65
	v_mov_b32_e32 v68, v65
	v_mov_b32_e32 v69, v65
	v_mov_b32_e32 v70, v65
	v_mov_b32_e32 v71, v65
	v_mov_b32_e32 v72, v65
	v_mov_b32_e32 v73, v65
	v_mov_b32_e32 v74, v65
	v_mov_b32_e32 v75, v65
	v_mov_b32_e32 v76, v65
	v_mov_b32_e32 v77, v65
	v_mov_b32_e32 v78, v65
	v_mov_b32_e32 v79, v65
	v_add_u32_e32 v206, v0, v3
	v_mov_b64_e32 v[16:17], v[64:65]
	v_mov_b64_e32 v[0:1], v[64:65]
	v_ashrrev_i32_e32 v181, 31, v180
	v_add_u32_e32 v203, 0xd800, v202
	s_mov_b32 s19, 0
	v_mov_b64_e32 v[18:19], v[66:67]
	v_mov_b64_e32 v[20:21], v[68:69]
	v_mov_b64_e32 v[22:23], v[70:71]
	v_mov_b64_e32 v[24:25], v[72:73]
	v_mov_b64_e32 v[26:27], v[74:75]
	v_mov_b64_e32 v[28:29], v[76:77]
	v_mov_b64_e32 v[30:31], v[78:79]
	v_mov_b64_e32 v[2:3], v[66:67]
	v_mov_b64_e32 v[4:5], v[68:69]
	v_mov_b64_e32 v[6:7], v[70:71]
	v_mov_b64_e32 v[8:9], v[72:73]
	v_mov_b64_e32 v[10:11], v[74:75]
	v_mov_b64_e32 v[12:13], v[76:77]
	v_mov_b64_e32 v[14:15], v[78:79]
	v_mov_b32_e32 v207, 0
	v_mov_b32_e32 v210, 0
	v_mov_b32_e32 v64, 0
	s_waitcnt lgkmcnt(0)
	s_barrier
	s_branch .LBB0_1205

.LBB0_1214:
	ds_read_b128 v[74:77], v206
	ds_read_b128 v[120:123], v206 offset:64
	ds_read_b128 v[124:127], v206 offset:2304
	ds_read_b128 v[128:131], v206 offset:2368
	ds_read_b128 v[132:135], v206 offset:4608
	ds_read_b128 v[136:139], v206 offset:4672
	ds_read_b128 v[140:143], v206 offset:6912
	ds_read_b128 v[144:147], v206 offset:6976
	v_xor_b32_e32 v70, 0x80000000, v64
	v_xor_b32_e32 v66, 0x80000000, v207
	v_mov_b32_e32 v71, v70
	v_mov_b32_e32 v72, v70
	v_mov_b32_e32 v73, v70
	v_mov_b32_e32 v67, v66
	v_mov_b32_e32 v68, v66
	v_mov_b32_e32 v69, v66
	s_mov_b64 s[8:9], -1
	s_and_b64 vcc, exec, s[10:11]
	s_cbranch_vccz .LBB0_1220
	s_waitcnt lgkmcnt(7)
	v_mfma_f32_16x16x32_bf16 v[176:179], v[74:77], v[80:83], v[70:73]
	v_mov_b32_e32 v79, v64
	v_mov_b32_e32 v208, v210
	s_waitcnt lgkmcnt(5)
	v_mfma_f32_16x16x32_bf16 v[172:175], v[124:127], v[80:83], v[70:73]
	s_waitcnt lgkmcnt(3)
	v_mfma_f32_16x16x32_bf16 v[168:171], v[132:135], v[80:83], v[70:73]
	s_nop 1
	v_max3_f32 v32, v178, v176, v177
	s_nop 2
	v_max3_f32 v32, v172, v179, v32
	v_max3_f32 v32, v174, v173, v32
	s_waitcnt lgkmcnt(1)
	v_mfma_f32_16x16x32_bf16 v[164:167], v[140:143], v[80:83], v[70:73]
	v_mfma_f32_16x16x32_bf16 v[148:151], v[120:123], v[92:95], v[66:69]
	v_max3_f32 v32, v168, v175, v32
	v_max3_f32 v32, v170, v169, v32
	s_nop 4
	v_max3_f32 v32, v164, v171, v32
	v_max3_f32 v32, v166, v165, v32
	v_mfma_f32_16x16x32_bf16 v[160:163], v[128:131], v[92:95], v[66:69]
	v_max_f32_e32 v33, v167, v167
	v_max_f32_e32 v32, v33, v32
	v_cmp_lt_f32_e32 vcc, s52, v32
	v_mfma_f32_16x16x32_bf16 v[156:159], v[136:139], v[92:95], v[66:69]
	v_mov_b64_e32 v[46:47], v[30:31]
	v_mov_b64_e32 v[44:45], v[28:29]
	v_mov_b64_e32 v[42:43], v[26:27]
	s_waitcnt lgkmcnt(0)
	v_mfma_f32_16x16x32_bf16 v[152:155], v[144:147], v[92:95], v[66:69]
	v_mov_b64_e32 v[40:41], v[24:25]
	v_mov_b64_e32 v[38:39], v[22:23]
	v_mov_b64_e32 v[36:37], v[20:21]
	v_mov_b64_e32 v[34:35], v[18:19]
	v_mov_b64_e32 v[32:33], v[16:17]
	s_cbranch_vccz .LBB0_1217
	v_max_f32_e32 v32, v177, v177
	v_max_f32_e32 v33, v176, v176
	v_max_f32_e32 v32, v33, v32
	v_max3_f32 v32, v32, v178, v179
	v_max3_f32 v32, v32, v172, v173
	v_max3_f32 v32, v32, v174, v175
	v_max3_f32 v32, v32, v168, v169
	v_max3_f32 v32, v32, v170, v171
	v_max3_f32 v32, v32, v164, v165
	v_max3_f32 v32, v32, v166, v167
	v_mov_b32_e32 v33, v32
	s_nop 1
	v_permlane16_swap_b32_e32 v32, v33
	v_max_f32_e32 v33, v33, v33
	v_max_f32_e32 v32, v32, v32
	v_max_f32_e32 v32, v32, v33
	v_mov_b32_e32 v33, v32
	s_nop 1
	v_permlane32_swap_b32_e32 v32, v33
	v_max_f32_e32 v33, v33, v33
	v_max_f32_e32 v32, v32, v32
	v_max_f32_e32 v32, v32, v33
	v_cmp_lt_f32_e32 vcc, s52, v32
	s_nop 1
	v_cndmask_b32_e32 v32, 0, v32, vcc
	v_exp_f32_e64 v48, -v32
	v_add_f32_e32 v79, v64, v32
	v_sub_f32_e32 v176, v176, v32
	v_sub_f32_e32 v177, v177, v32
	v_sub_f32_e32 v178, v178, v32
	v_sub_f32_e32 v179, v179, v32
	v_mul_f32_e32 v208, v210, v48
	v_sub_f32_e32 v172, v172, v32
	v_sub_f32_e32 v173, v173, v32
	v_sub_f32_e32 v174, v174, v32
	v_sub_f32_e32 v175, v175, v32
	v_sub_f32_e32 v168, v168, v32
	v_sub_f32_e32 v169, v169, v32
	v_sub_f32_e32 v170, v170, v32
	v_sub_f32_e32 v171, v171, v32
	v_sub_f32_e32 v164, v164, v32
	v_sub_f32_e32 v165, v165, v32
	v_sub_f32_e32 v166, v166, v32
	v_sub_f32_e32 v167, v167, v32
	v_mul_f32_e32 v46, v30, v48
	v_mul_f32_e32 v47, v31, v48
	v_mul_f32_e32 v44, v28, v48
	v_mul_f32_e32 v45, v29, v48
	v_mul_f32_e32 v42, v26, v48
	v_mul_f32_e32 v43, v27, v48
	v_mul_f32_e32 v40, v24, v48
	v_mul_f32_e32 v41, v25, v48
	v_mul_f32_e32 v38, v22, v48
	v_mul_f32_e32 v39, v23, v48
	v_mul_f32_e32 v36, v20, v48
	v_mul_f32_e32 v37, v21, v48
	v_mul_f32_e32 v34, v18, v48
	v_mul_f32_e32 v35, v19, v48
	v_mul_f32_e32 v32, v16, v48
	v_mul_f32_e32 v33, v17, v48
.LBB0_1217:
	v_max3_f32 v48, v150, v148, v149
	v_max3_f32 v48, v160, v151, v48
	v_max3_f32 v48, v162, v161, v48
	v_max3_f32 v48, v156, v163, v48
	v_max3_f32 v48, v158, v157, v48
	v_max3_f32 v48, v152, v159, v48
	v_max3_f32 v48, v154, v153, v48
	v_max_f32_e32 v49, v155, v155
	v_max_f32_e32 v48, v49, v48
	v_cmp_lt_f32_e32 vcc, s52, v48
	v_mov_b64_e32 v[62:63], v[14:15]
	v_mov_b32_e32 v78, v207
	v_mov_b32_e32 v212, v209
	v_mov_b64_e32 v[60:61], v[12:13]
	v_mov_b64_e32 v[58:59], v[10:11]
	v_mov_b64_e32 v[56:57], v[8:9]
	v_mov_b64_e32 v[54:55], v[6:7]
	v_mov_b64_e32 v[52:53], v[4:5]
	v_mov_b64_e32 v[50:51], v[2:3]
	v_mov_b64_e32 v[48:49], v[0:1]
	s_cbranch_vccz .LBB0_1219
	v_max_f32_e32 v48, v149, v149
	v_max_f32_e32 v49, v148, v148
	v_max_f32_e32 v48, v49, v48
	v_max3_f32 v48, v48, v150, v151
	v_max3_f32 v48, v48, v160, v161
	v_max3_f32 v48, v48, v162, v163
	v_max3_f32 v48, v48, v156, v157
	v_max3_f32 v48, v48, v158, v159
	v_max3_f32 v48, v48, v152, v153
	v_max3_f32 v48, v48, v154, v155
	v_mov_b32_e32 v49, v48
	s_nop 1
	v_permlane16_swap_b32_e32 v48, v49
	v_max_f32_e32 v49, v49, v49
	v_max_f32_e32 v48, v48, v48
	v_max_f32_e32 v48, v48, v49
	v_mov_b32_e32 v49, v48
	s_nop 1
	v_permlane32_swap_b32_e32 v48, v49
	v_max_f32_e32 v49, v49, v49
	v_max_f32_e32 v48, v48, v48
	v_max_f32_e32 v48, v48, v49
	v_cmp_lt_f32_e32 vcc, s52, v48
	s_nop 1
	v_cndmask_b32_e32 v48, 0, v48, vcc
	v_exp_f32_e64 v214, -v48
	v_add_f32_e32 v78, v207, v48
	v_sub_f32_e32 v148, v148, v48
	v_sub_f32_e32 v149, v149, v48
	v_sub_f32_e32 v150, v150, v48
	v_sub_f32_e32 v151, v151, v48
	v_mul_f32_e32 v212, v209, v214
	v_sub_f32_e32 v160, v160, v48
	v_sub_f32_e32 v161, v161, v48
	v_sub_f32_e32 v162, v162, v48
	v_sub_f32_e32 v163, v163, v48
	v_sub_f32_e32 v156, v156, v48
	v_sub_f32_e32 v157, v157, v48
	v_sub_f32_e32 v158, v158, v48
	v_sub_f32_e32 v159, v159, v48
	v_sub_f32_e32 v152, v152, v48
	v_sub_f32_e32 v153, v153, v48
	v_sub_f32_e32 v154, v154, v48
	v_sub_f32_e32 v155, v155, v48
	v_mul_f32_e32 v62, v14, v214
	v_mul_f32_e32 v63, v15, v214
	v_mul_f32_e32 v60, v12, v214
	v_mul_f32_e32 v61, v13, v214
	v_mul_f32_e32 v58, v10, v214
	v_mul_f32_e32 v59, v11, v214
	v_mul_f32_e32 v56, v8, v214
	v_mul_f32_e32 v57, v9, v214
	v_mul_f32_e32 v54, v6, v214
	v_mul_f32_e32 v55, v7, v214
	v_mul_f32_e32 v52, v4, v214
	v_mul_f32_e32 v53, v5, v214
	v_mul_f32_e32 v50, v2, v214
	v_mul_f32_e32 v51, v3, v214
	v_mul_f32_e32 v48, v0, v214
	v_mul_f32_e32 v49, v1, v214

.LBB0_1220:
	s_and_b64 vcc, exec, s[8:9]
	s_cbranch_vccz .LBB0_1231
	s_waitcnt lgkmcnt(7)
	v_mfma_f32_16x16x32_bf16 v[60:63], v[74:77], v[80:83], v[70:73]
	s_cmp_eq_u32 s19, 0
	s_cselect_b64 s[8:9], -1, 0
	s_waitcnt lgkmcnt(5)
	v_mfma_f32_16x16x32_bf16 v[56:59], v[124:127], v[80:83], v[70:73]
	s_waitcnt lgkmcnt(3)
	v_mfma_f32_16x16x32_bf16 v[52:55], v[132:135], v[80:83], v[70:73]
	v_mfma_f32_16x16x32_bf16 v[48:51], v[120:123], v[92:95], v[66:69]
	v_mfma_f32_16x16x32_bf16 v[44:47], v[128:131], v[92:95], v[66:69]
	s_waitcnt lgkmcnt(2)
	v_mfma_f32_16x16x32_bf16 v[36:39], v[136:139], v[92:95], v[66:69]
	s_waitcnt lgkmcnt(0)
	v_mfma_f32_16x16x32_bf16 v[32:35], v[144:147], v[92:95], v[66:69]
	s_nop 2
	v_max3_f32 v67, v62, v60, v61
	v_mfma_f32_16x16x32_bf16 v[40:43], v[140:143], v[80:83], v[70:73]
	v_max3_f32 v67, v56, v63, v67
	v_max3_f32 v67, v58, v57, v67
	v_max3_f32 v67, v52, v59, v67
	v_max3_f32 v67, v54, v53, v67
	s_nop 3
	v_max3_f32 v67, v40, v55, v67
	v_max3_f32 v67, v42, v41, v67
	v_max_f32_e32 v68, v43, v43
	v_max_f32_e32 v67, v68, v67
	v_cmp_lt_f32_e32 vcc, s52, v67
	s_or_b64 vcc, s[8:9], vcc
	s_cbranch_vccz .LBB0_1223
	v_max_f32_e32 v67, v61, v61
	v_max_f32_e32 v68, v60, v60
	v_max_f32_e32 v67, v68, v67
	v_max3_f32 v67, v67, v62, v63
	v_max3_f32 v67, v67, v56, v57
	v_max3_f32 v67, v67, v58, v59
	v_max3_f32 v67, v67, v52, v53
	v_max3_f32 v67, v67, v54, v55
	v_max3_f32 v67, v67, v40, v41
	v_max3_f32 v67, v67, v42, v43
	v_mov_b32_e32 v68, v67
	s_nop 1
	v_permlane16_swap_b32_e32 v67, v68
	v_max_f32_e32 v68, v68, v68
	v_max_f32_e32 v67, v67, v67
	v_max_f32_e32 v67, v67, v68
	v_mov_b32_e32 v68, v67
	s_nop 1
	v_permlane32_swap_b32_e32 v67, v68
	v_max_f32_e32 v68, v68, v68
	v_max_f32_e32 v67, v67, v67
	v_max_f32_e32 v67, v67, v68
	v_cmp_lt_f32_e32 vcc, s52, v67
	s_or_b64 vcc, s[8:9], vcc
	s_nop 0
	v_cndmask_b32_e32 v68, 0, v67, vcc
	v_exp_f32_e64 v70, -v68
	v_add_f32_e32 v79, v64, v68
	v_sub_f32_e32 v60, v60, v68
	v_sub_f32_e32 v61, v61, v68
	v_sub_f32_e32 v62, v62, v68
	v_sub_f32_e32 v63, v63, v68
	v_mul_f32_e32 v210, v210, v70
	v_sub_f32_e32 v56, v56, v68
	v_sub_f32_e32 v57, v57, v68
	v_sub_f32_e32 v58, v58, v68
	v_sub_f32_e32 v59, v59, v68
	v_sub_f32_e32 v52, v52, v68
	v_sub_f32_e32 v53, v53, v68
	v_sub_f32_e32 v54, v54, v68
	v_sub_f32_e32 v55, v55, v68
	v_sub_f32_e32 v40, v40, v68
	v_sub_f32_e32 v41, v41, v68
	v_sub_f32_e32 v42, v42, v68
	v_sub_f32_e32 v43, v43, v68
	v_mul_f32_e32 v30, v30, v70
	v_mul_f32_e32 v31, v31, v70
	v_mul_f32_e32 v28, v28, v70
	v_mul_f32_e32 v29, v29, v70
	v_mul_f32_e32 v26, v26, v70
	v_mul_f32_e32 v27, v27, v70
	v_mul_f32_e32 v24, v24, v70
	v_mul_f32_e32 v25, v25, v70
	v_mul_f32_e32 v22, v22, v70
	v_mul_f32_e32 v23, v23, v70
	v_mul_f32_e32 v20, v20, v70
	v_mul_f32_e32 v21, v21, v70
	v_mul_f32_e32 v18, v18, v70
	v_mul_f32_e32 v19, v19, v70
	v_mul_f32_e32 v16, v16, v70
	v_mul_f32_e32 v17, v17, v70
	s_branch .LBB0_1224

.LBB0_1224:
	v_max3_f32 v64, v50, v48, v49
	v_max3_f32 v64, v44, v51, v64
	v_max3_f32 v64, v46, v45, v64
	v_max3_f32 v64, v36, v47, v64
	v_max3_f32 v64, v38, v37, v64
	v_max3_f32 v64, v32, v39, v64
	v_max3_f32 v64, v34, v33, v64
	v_max_f32_e32 v67, v35, v35
	v_max_f32_e32 v64, v67, v64
	v_cmp_lt_f32_e32 vcc, s52, v64
	s_or_b64 s[16:17], s[8:9], vcc
	v_cndmask_b32_e64 v64, 0, 1, s[16:17]
	v_cmp_ne_u32_e32 vcc, 0, v64
	s_cbranch_vccz .LBB0_1226
	v_max_f32_e32 v64, v49, v49
	v_max_f32_e32 v66, v48, v48
	v_max_f32_e32 v64, v66, v64
	v_max3_f32 v64, v64, v50, v51
	v_max3_f32 v64, v64, v44, v45
	v_max3_f32 v64, v64, v46, v47
	v_max3_f32 v64, v64, v36, v37
	v_max3_f32 v64, v64, v38, v39
	v_max3_f32 v64, v64, v32, v33
	v_max3_f32 v64, v64, v34, v35
	v_mov_b32_e32 v66, v64
	s_nop 1
	v_permlane16_swap_b32_e32 v64, v66
	v_max_f32_e32 v66, v66, v66
	v_max_f32_e32 v64, v64, v64
	v_max_f32_e32 v64, v64, v66
	v_mov_b32_e32 v66, v64
	s_nop 1
	v_permlane32_swap_b32_e32 v64, v66
	v_max_f32_e32 v66, v66, v66
	v_max_f32_e32 v64, v64, v64
	v_max_f32_e32 v64, v64, v66
	v_cmp_lt_f32_e32 vcc, s52, v64
	s_or_b64 vcc, s[8:9], vcc
	s_nop 0
	v_cndmask_b32_e32 v64, 0, v64, vcc
	v_exp_f32_e64 v66, -v64
	v_add_f32_e32 v207, v207, v64
	v_sub_f32_e32 v48, v48, v64
	v_sub_f32_e32 v49, v49, v64
	v_sub_f32_e32 v50, v50, v64
	v_sub_f32_e32 v51, v51, v64
	v_mul_f32_e32 v209, v209, v66
	v_sub_f32_e32 v44, v44, v64
	v_sub_f32_e32 v45, v45, v64
	v_sub_f32_e32 v46, v46, v64
	v_sub_f32_e32 v47, v47, v64
	v_sub_f32_e32 v36, v36, v64
	v_sub_f32_e32 v37, v37, v64
	v_sub_f32_e32 v38, v38, v64
	v_sub_f32_e32 v39, v39, v64
	v_sub_f32_e32 v32, v32, v64
	v_sub_f32_e32 v33, v33, v64
	v_sub_f32_e32 v34, v34, v64
	v_sub_f32_e32 v35, v35, v64
	v_mul_f32_e32 v14, v14, v66
	v_mul_f32_e32 v15, v15, v66
	v_mul_f32_e32 v12, v12, v66
	v_mul_f32_e32 v13, v13, v66
	v_mul_f32_e32 v10, v10, v66
	v_mul_f32_e32 v11, v11, v66
	v_mul_f32_e32 v8, v8, v66
	v_mul_f32_e32 v9, v9, v66
	v_mul_f32_e32 v6, v6, v66
	v_mul_f32_e32 v7, v7, v66
	v_mul_f32_e32 v4, v4, v66
	v_mul_f32_e32 v5, v5, v66
	v_mul_f32_e32 v2, v2, v66
	v_mul_f32_e32 v3, v3, v66
	v_mul_f32_e32 v0, v0, v66
	v_mul_f32_e32 v1, v1, v66
	v_xor_b32_e32 v66, 0x80000000, v207
.LBB0_1226:
	v_exp_f32_e32 v70, v48
	v_exp_f32_e32 v71, v49
	v_exp_f32_e32 v72, v50
	v_exp_f32_e32 v73, v51
	v_exp_f32_e32 v74, v44
	v_exp_f32_e32 v75, v45
	v_exp_f32_e32 v76, v46
	v_exp_f32_e32 v77, v47
	v_exp_f32_e32 v64, v60
	v_exp_f32_e32 v67, v61
	v_exp_f32_e32 v68, v62
	v_exp_f32_e32 v127, v63
	v_exp_f32_e32 v132, v56
	v_exp_f32_e32 v133, v57
	v_exp_f32_e32 v134, v58
	v_exp_f32_e32 v135, v59
	ds_read_b64_tr_b16 v[50:51], v202 offset:20736
	ds_read_b64_tr_b16 v[48:49], v202 offset:18432
	ds_read_b64_tr_b16 v[56:57], v202 offset:18464
	ds_read_b64_tr_b16 v[60:61], v202 offset:18496
	ds_read_b64_tr_b16 v[128:129], v202 offset:18528
	ds_read_b64_tr_b16 v[58:59], v202 offset:20768
	ds_read_b64_tr_b16 v[62:63], v202 offset:20800
	ds_read_b64_tr_b16 v[130:131], v202 offset:20832
	v_exp_f32_e32 v136, v52
	v_exp_f32_e32 v137, v53
	v_exp_f32_e32 v138, v54
	v_exp_f32_e32 v139, v55
	v_cvt_pk_bf16_f32 v52, v70, v71
	v_cvt_pk_bf16_f32 v53, v72, v73
	v_cvt_pk_bf16_f32 v54, v74, v75
	v_cvt_pk_bf16_f32 v55, v76, v77
	v_exp_f32_e32 v140, v40
	v_cvt_pk_bf16_f32 v44, v64, v67
	v_cvt_pk_bf16_f32 v45, v68, v127
	v_cvt_pk_bf16_f32 v46, v132, v133
	v_cvt_pk_bf16_f32 v47, v134, v135
	v_exp_f32_e32 v141, v41
	v_exp_f32_e32 v142, v42
	v_exp_f32_e32 v143, v43
	v_exp_f32_e32 v78, v36
	v_exp_f32_e32 v120, v37
	v_exp_f32_e32 v121, v38
	v_exp_f32_e32 v122, v39
	v_exp_f32_e32 v123, v32
	v_exp_f32_e32 v124, v33
	v_exp_f32_e32 v125, v34
	v_exp_f32_e32 v126, v35
	s_waitcnt lgkmcnt(1)
	v_mfma_f32_16x16x32_bf16 v[40:43], v[60:63], v[52:55], v[8:11]
	s_nop 2
	ds_read_b64_tr_b16 v[8:9], v202 offset:23040
	ds_read_b64_tr_b16 v[10:11], v202 offset:25344
	v_cvt_pk_bf16_f32 v32, v136, v137
	v_cvt_pk_bf16_f32 v33, v138, v139
	v_mfma_f32_16x16x32_bf16 v[0:3], v[48:51], v[52:55], v[0:3]
	v_cvt_pk_bf16_f32 v34, v140, v141
	v_cvt_pk_bf16_f32 v35, v142, v143
	v_mov_b32_e32 v69, v66
	v_mfma_f32_16x16x32_bf16 v[20:23], v[56:59], v[44:47], v[20:23]
	v_mfma_f32_16x16x32_bf16 v[4:7], v[56:59], v[52:55], v[4:7]
	v_mfma_f32_16x16x32_bf16 v[36:39], v[60:63], v[44:47], v[24:27]
	s_waitcnt lgkmcnt(2)
	v_mfma_f32_16x16x32_bf16 v[52:55], v[128:131], v[52:55], v[12:15]
	s_nop 2
	ds_read_b64_tr_b16 v[12:13], v202 offset:23072
	ds_read_b64_tr_b16 v[56:57], v202 offset:23104
	ds_read_b64_tr_b16 v[60:61], v202 offset:23136
	ds_read_b64_tr_b16 v[14:15], v202 offset:25376
	ds_read_b64_tr_b16 v[58:59], v202 offset:25408
	ds_read_b64_tr_b16 v[62:63], v202 offset:25440
	v_mfma_f32_16x16x32_bf16 v[16:19], v[48:51], v[44:47], v[16:19]
	v_cvt_pk_bf16_f32 v48, v78, v120
	v_cvt_pk_bf16_f32 v49, v121, v122
	v_cvt_pk_bf16_f32 v50, v123, v124
	v_mfma_f32_16x16x32_bf16 v[44:47], v[128:131], v[44:47], v[28:31]
	v_cvt_pk_bf16_f32 v51, v125, v126
	ds_read_b128 v[128:131], v206 offset:16128
	s_waitcnt lgkmcnt(7)
	v_mfma_f32_16x16x32_bf16 v[24:27], v[8:11], v[48:51], v[0:3]
	s_nop 2
	v_add_f32_e32 v0, 0, v64
	v_mfma_f32_16x16x32_bf16 v[16:19], v[8:11], v[32:35], v[16:19]
	s_waitcnt lgkmcnt(3)
	v_mfma_f32_16x16x32_bf16 v[20:23], v[12:15], v[32:35], v[20:23]
	v_mfma_f32_16x16x32_bf16 v[28:31], v[12:15], v[48:51], v[4:7]
	s_waitcnt lgkmcnt(2)
	v_mfma_f32_16x16x32_bf16 v[8:11], v[56:59], v[32:35], v[36:39]
	s_nop 0
	v_add_f32_e32 v4, v67, v0
	v_mov_b32_e32 v67, v66
	s_waitcnt lgkmcnt(1)
	v_mfma_f32_16x16x32_bf16 v[0:3], v[60:63], v[32:35], v[44:47]
	ds_read_b128 v[32:35], v206 offset:9216
	ds_read_b128 v[36:39], v206 offset:9280
	v_mfma_f32_16x16x32_bf16 v[12:15], v[56:59], v[48:51], v[40:43]
	v_add_f32_e32 v56, v68, v4
	v_mov_b32_e32 v68, v66
	v_mfma_f32_16x16x32_bf16 v[4:7], v[60:63], v[48:51], v[52:55]
	ds_read_b128 v[48:51], v206 offset:11520
	v_xor_b32_e32 v40, 0x80000000, v79
	v_mov_b32_e32 v41, v40
	s_waitcnt lgkmcnt(1)
	v_mfma_f32_16x16x32_bf16 v[44:47], v[36:39], v[92:95], v[66:69]
	v_add_f32_e32 v36, v127, v56
	v_mov_b32_e32 v42, v40
	v_mov_b32_e32 v43, v40
	v_add_f32_e32 v52, v132, v36
	ds_read_b128 v[36:39], v206 offset:13824
	v_mfma_f32_16x16x32_bf16 v[60:63], v[32:35], v[80:83], v[40:43]
	ds_read_b128 v[32:35], v206 offset:11584
	s_waitcnt lgkmcnt(2)
	v_mfma_f32_16x16x32_bf16 v[56:59], v[48:51], v[80:83], v[40:43]
	v_add_f32_e32 v48, v133, v52
	v_add_f32_e32 v52, v134, v48
	ds_read_b128 v[48:51], v206 offset:13888
	v_add_f32_e32 v52, v135, v52
	ds_read_b128 v[132:135], v206 offset:16192
	v_add_f32_e32 v64, v136, v52
	s_waitcnt lgkmcnt(3)
	v_mfma_f32_16x16x32_bf16 v[52:55], v[36:39], v[80:83], v[40:43]
	v_add_f32_e32 v36, v137, v64
	v_add_f32_e32 v64, v138, v36
	s_waitcnt lgkmcnt(1)
	v_mfma_f32_16x16x32_bf16 v[36:39], v[48:51], v[92:95], v[66:69]
	v_add_f32_e32 v48, v139, v64
	v_add_f32_e32 v48, v140, v48
	v_add_f32_e32 v64, v141, v48
	v_mfma_f32_16x16x32_bf16 v[48:51], v[128:131], v[80:83], v[40:43]
	s_nop 2
	v_add_f32_e32 v40, v142, v64
	v_add_f32_e32 v40, v143, v40
	v_mfma_f32_16x16x32_bf16 v[32:35], v[32:35], v[92:95], v[66:69]
	v_add_f32_e32 v64, v210, v40
	s_waitcnt lgkmcnt(0)
	v_mfma_f32_16x16x32_bf16 v[40:43], v[132:135], v[92:95], v[66:69]
	s_nop 2
	v_max3_f32 v66, v62, v60, v61
	v_max3_f32 v66, v63, v66, v56
	v_max3_f32 v66, v58, v57, v66
	v_max3_f32 v66, v52, v59, v66
	v_max3_f32 v66, v54, v53, v66
	v_max3_f32 v66, v48, v55, v66
	v_max3_f32 v66, v50, v49, v66
	v_max_f32_e32 v67, v51, v51
	v_max_f32_e32 v66, v67, v66
	v_cmp_lt_f32_e32 vcc, s52, v66
	s_cbranch_vccz .LBB0_1228
	v_max_f32_e32 v66, v61, v61
	v_max_f32_e32 v67, v60, v60
	v_max_f32_e32 v66, v67, v66
	v_max3_f32 v66, v66, v62, v63
	v_max3_f32 v66, v66, v56, v57
	v_max3_f32 v66, v66, v58, v59
	v_max3_f32 v66, v66, v52, v53
	v_max3_f32 v66, v66, v54, v55
	v_max3_f32 v66, v66, v48, v49
	v_max3_f32 v66, v66, v50, v51
	v_mov_b32_e32 v67, v66
	s_nop 1
	v_permlane16_swap_b32_e32 v66, v67
	v_max_f32_e32 v67, v67, v67
	v_max_f32_e32 v66, v66, v66
	v_max_f32_e32 v66, v66, v67
	v_mov_b32_e32 v67, v66
	s_nop 1
	v_permlane32_swap_b32_e32 v66, v67
	v_max_f32_e32 v67, v67, v67
	v_max_f32_e32 v66, v66, v66
	v_max_f32_e32 v66, v66, v67
	v_cmp_lt_f32_e32 vcc, s52, v66
	s_nop 1
	v_cndmask_b32_e32 v66, 0, v66, vcc
	v_exp_f32_e64 v68, -v66
	v_add_f32_e32 v79, v79, v66
	v_sub_f32_e32 v60, v60, v66
	v_sub_f32_e32 v61, v61, v66
	v_sub_f32_e32 v62, v62, v66
	v_sub_f32_e32 v63, v63, v66
	v_mul_f32_e32 v64, v64, v68
	v_sub_f32_e32 v56, v56, v66
	v_sub_f32_e32 v57, v57, v66
	v_sub_f32_e32 v58, v58, v66
	v_sub_f32_e32 v59, v59, v66
	v_sub_f32_e32 v52, v52, v66
	v_sub_f32_e32 v53, v53, v66
	v_sub_f32_e32 v54, v54, v66
	v_sub_f32_e32 v55, v55, v66
	v_sub_f32_e32 v48, v48, v66
	v_sub_f32_e32 v49, v49, v66
	v_sub_f32_e32 v50, v50, v66
	v_sub_f32_e32 v51, v51, v66
	v_mul_f32_e32 v2, v2, v68
	v_mul_f32_e32 v3, v3, v68
	v_mul_f32_e32 v0, v0, v68
	v_mul_f32_e32 v1, v1, v68
	v_mul_f32_e32 v10, v10, v68
	v_mul_f32_e32 v11, v11, v68
	v_mul_f32_e32 v8, v8, v68
	v_mul_f32_e32 v9, v9, v68
	v_mul_f32_e32 v22, v22, v68
	v_mul_f32_e32 v23, v23, v68
	v_mul_f32_e32 v20, v20, v68
	v_mul_f32_e32 v21, v21, v68
	v_mul_f32_e32 v18, v18, v68
	v_mul_f32_e32 v19, v19, v68
	v_mul_f32_e32 v16, v16, v68
	v_mul_f32_e32 v17, v17, v68
.LBB0_1228:
	v_add_f32_e32 v66, 0, v70
	v_add_f32_e32 v66, v71, v66
	v_add_f32_e32 v66, v72, v66
	v_add_f32_e32 v66, v73, v66
	v_add_f32_e32 v66, v74, v66
	v_add_f32_e32 v66, v75, v66
	v_add_f32_e32 v66, v76, v66
	v_add_f32_e32 v66, v77, v66
	v_add_f32_e32 v66, v78, v66
	v_max3_f32 v67, v46, v44, v45
	v_add_f32_e32 v66, v120, v66
	v_max3_f32 v67, v47, v67, v32
	v_add_f32_e32 v66, v121, v66
	v_max3_f32 v67, v34, v33, v67
	v_add_f32_e32 v66, v122, v66
	v_max3_f32 v67, v36, v35, v67
	v_add_f32_e32 v66, v123, v66
	v_max3_f32 v67, v38, v37, v67
	v_add_f32_e32 v66, v124, v66
	v_max3_f32 v67, v40, v39, v67
	v_add_f32_e32 v66, v125, v66
	v_max3_f32 v67, v42, v41, v67
	v_max_f32_e32 v68, v43, v43
	v_add_f32_e32 v66, v126, v66
	v_max_f32_e32 v67, v68, v67
	v_add_f32_e32 v66, v209, v66
	v_cmp_lt_f32_e32 vcc, s52, v67
	s_cbranch_vccz .LBB0_1230
	v_max_f32_e32 v67, v45, v45
	v_max_f32_e32 v68, v44, v44
	v_max_f32_e32 v67, v68, v67
	v_max3_f32 v67, v67, v46, v47
	v_max3_f32 v67, v67, v32, v33
	v_max3_f32 v67, v67, v34, v35
	v_max3_f32 v67, v67, v36, v37
	v_max3_f32 v67, v67, v38, v39
	v_max3_f32 v67, v67, v40, v41
	v_max3_f32 v67, v67, v42, v43
	v_mov_b32_e32 v68, v67
	s_nop 1
	v_permlane16_swap_b32_e32 v67, v68
	v_max_f32_e32 v68, v68, v68
	v_max_f32_e32 v67, v67, v67
	v_max_f32_e32 v67, v67, v68
	v_mov_b32_e32 v68, v67
	s_nop 1
	v_permlane32_swap_b32_e32 v67, v68
	v_max_f32_e32 v68, v68, v68
	v_max_f32_e32 v67, v67, v67
	v_max_f32_e32 v67, v67, v68
	v_cmp_lt_f32_e32 vcc, s52, v67
	s_nop 1
	v_cndmask_b32_e32 v68, 0, v67, vcc
	v_exp_f32_e64 v70, -v68
	v_add_f32_e32 v207, v207, v68
	v_sub_f32_e32 v44, v44, v68
	v_sub_f32_e32 v45, v45, v68
	v_sub_f32_e32 v46, v46, v68
	v_sub_f32_e32 v47, v47, v68
	v_mul_f32_e32 v66, v66, v70
	v_sub_f32_e32 v32, v32, v68
	v_sub_f32_e32 v33, v33, v68
	v_sub_f32_e32 v34, v34, v68
	v_sub_f32_e32 v35, v35, v68
	v_sub_f32_e32 v36, v36, v68
	v_sub_f32_e32 v37, v37, v68
	v_sub_f32_e32 v38, v38, v68
	v_sub_f32_e32 v39, v39, v68
	v_sub_f32_e32 v40, v40, v68
	v_sub_f32_e32 v41, v41, v68
	v_sub_f32_e32 v42, v42, v68
	v_sub_f32_e32 v43, v43, v68
	v_mul_f32_e32 v6, v6, v70
	v_mul_f32_e32 v7, v7, v70
	v_mul_f32_e32 v4, v4, v70
	v_mul_f32_e32 v5, v5, v70
	v_mul_f32_e32 v14, v14, v70
	v_mul_f32_e32 v15, v15, v70
	v_mul_f32_e32 v12, v12, v70
	v_mul_f32_e32 v13, v13, v70
	v_mul_f32_e32 v30, v30, v70
	v_mul_f32_e32 v31, v31, v70
	v_mul_f32_e32 v28, v28, v70
	v_mul_f32_e32 v29, v29, v70
	v_mul_f32_e32 v26, v26, v70
	v_mul_f32_e32 v27, v27, v70
	v_mul_f32_e32 v24, v24, v70
	v_mul_f32_e32 v25, v25, v70

.LBB0_1241:
	ds_read_b128 v[74:77], v206 offset:36864
	ds_read_b128 v[120:123], v206 offset:36928
	ds_read_b128 v[124:127], v206 offset:39168
	ds_read_b128 v[128:131], v206 offset:39232
	ds_read_b128 v[132:135], v206 offset:41472
	ds_read_b128 v[136:139], v206 offset:41536
	ds_read_b128 v[140:143], v206 offset:43776
	ds_read_b128 v[144:147], v206 offset:43840
	v_xor_b32_e32 v70, 0x80000000, v79
	v_xor_b32_e32 v66, 0x80000000, v78
	v_mov_b32_e32 v71, v70
	v_mov_b32_e32 v72, v70
	v_mov_b32_e32 v73, v70
	v_mov_b32_e32 v67, v66
	v_mov_b32_e32 v68, v66
	v_mov_b32_e32 v69, v66
	s_mov_b64 s[14:15], -1
	s_and_b64 vcc, exec, s[10:11]
	s_cbranch_vccz .LBB0_1248
	s_waitcnt lgkmcnt(7)
	v_mfma_f32_16x16x32_bf16 v[176:179], v[74:77], v[80:83], v[70:73]
	v_mov_b32_e32 v64, v79
	v_mov_b32_e32 v210, v211
	s_waitcnt lgkmcnt(5)
	v_mfma_f32_16x16x32_bf16 v[168:171], v[124:127], v[80:83], v[70:73]
	s_waitcnt lgkmcnt(3)
	v_mfma_f32_16x16x32_bf16 v[172:175], v[132:135], v[80:83], v[70:73]
	s_nop 1
	v_max3_f32 v0, v178, v176, v177
	s_nop 2
	v_max3_f32 v0, v168, v179, v0
	v_max3_f32 v0, v170, v169, v0
	s_waitcnt lgkmcnt(1)
	v_mfma_f32_16x16x32_bf16 v[164:167], v[140:143], v[80:83], v[70:73]
	v_mfma_f32_16x16x32_bf16 v[160:163], v[120:123], v[92:95], v[66:69]
	v_max3_f32 v0, v172, v171, v0
	v_max3_f32 v0, v174, v173, v0
	s_nop 4
	v_max3_f32 v0, v164, v175, v0
	v_max3_f32 v0, v166, v165, v0
	v_mfma_f32_16x16x32_bf16 v[156:159], v[128:131], v[92:95], v[66:69]
	v_max_f32_e32 v1, v167, v167
	v_max_f32_e32 v0, v1, v0
	v_cmp_lt_f32_e32 vcc, s52, v0
	v_mfma_f32_16x16x32_bf16 v[152:155], v[136:139], v[92:95], v[66:69]
	v_mov_b64_e32 v[0:1], v[32:33]
	v_mov_b64_e32 v[2:3], v[34:35]
	v_mov_b64_e32 v[4:5], v[36:37]
	s_waitcnt lgkmcnt(0)
	v_mfma_f32_16x16x32_bf16 v[148:151], v[144:147], v[92:95], v[66:69]
	v_mov_b64_e32 v[6:7], v[38:39]
	v_mov_b64_e32 v[8:9], v[40:41]
	v_mov_b64_e32 v[10:11], v[42:43]
	v_mov_b64_e32 v[12:13], v[44:45]
	v_mov_b64_e32 v[14:15], v[46:47]
	s_cbranch_vccz .LBB0_1244
	v_max_f32_e32 v0, v177, v177
	v_max_f32_e32 v1, v176, v176
	v_max_f32_e32 v0, v1, v0
	v_max3_f32 v0, v0, v178, v179
	v_max3_f32 v0, v0, v168, v169
	v_max3_f32 v0, v0, v170, v171
	v_max3_f32 v0, v0, v172, v173
	v_max3_f32 v0, v0, v174, v175
	v_max3_f32 v0, v0, v164, v165
	v_max3_f32 v0, v0, v166, v167
	v_mov_b32_e32 v1, v0
	s_nop 1
	v_permlane16_swap_b32_e32 v0, v1
	v_max_f32_e32 v1, v1, v1
	v_max_f32_e32 v0, v0, v0
	v_max_f32_e32 v0, v0, v1
	v_mov_b32_e32 v1, v0
	s_nop 1
	v_permlane32_swap_b32_e32 v0, v1
	v_max_f32_e32 v1, v1, v1
	v_max_f32_e32 v0, v0, v0
	v_max_f32_e32 v0, v0, v1
	v_cmp_lt_f32_e32 vcc, s52, v0
	s_nop 1
	v_cndmask_b32_e32 v0, 0, v0, vcc
	v_exp_f32_e64 v16, -v0
	v_add_f32_e32 v64, v79, v0
	v_sub_f32_e32 v176, v176, v0
	v_sub_f32_e32 v177, v177, v0
	v_sub_f32_e32 v178, v178, v0
	v_sub_f32_e32 v179, v179, v0
	v_mul_f32_e32 v210, v211, v16
	v_sub_f32_e32 v168, v168, v0
	v_sub_f32_e32 v169, v169, v0
	v_sub_f32_e32 v170, v170, v0
	v_sub_f32_e32 v171, v171, v0
	v_sub_f32_e32 v172, v172, v0
	v_sub_f32_e32 v173, v173, v0
	v_sub_f32_e32 v174, v174, v0
	v_sub_f32_e32 v175, v175, v0
	v_sub_f32_e32 v164, v164, v0
	v_sub_f32_e32 v165, v165, v0
	v_sub_f32_e32 v166, v166, v0
	v_sub_f32_e32 v167, v167, v0
	v_mul_f32_e32 v14, v46, v16
	v_mul_f32_e32 v15, v47, v16
	v_mul_f32_e32 v12, v44, v16
	v_mul_f32_e32 v13, v45, v16
	v_mul_f32_e32 v10, v42, v16
	v_mul_f32_e32 v11, v43, v16
	v_mul_f32_e32 v8, v40, v16
	v_mul_f32_e32 v9, v41, v16
	v_mul_f32_e32 v6, v38, v16
	v_mul_f32_e32 v7, v39, v16
	v_mul_f32_e32 v4, v36, v16
	v_mul_f32_e32 v5, v37, v16
	v_mul_f32_e32 v2, v34, v16
	v_mul_f32_e32 v3, v35, v16
	v_mul_f32_e32 v0, v32, v16
	v_mul_f32_e32 v1, v33, v16
.LBB0_1244:
	v_max3_f32 v16, v162, v160, v161
	v_max3_f32 v16, v156, v163, v16
	v_max3_f32 v16, v158, v157, v16
	v_max3_f32 v16, v152, v159, v16
	v_max3_f32 v16, v154, v153, v16
	v_max3_f32 v16, v148, v155, v16
	v_max3_f32 v16, v150, v149, v16
	v_max_f32_e32 v17, v151, v151
	v_max_f32_e32 v16, v17, v16
	v_cmp_lt_f32_e32 vcc, s52, v16
	s_cbranch_vccz .LBB0_1246
	v_max_f32_e32 v16, v161, v161
	v_max_f32_e32 v17, v160, v160
	v_max_f32_e32 v16, v17, v16
	v_max3_f32 v16, v16, v162, v163
	v_max3_f32 v16, v16, v156, v157
	v_max3_f32 v16, v16, v158, v159
	v_max3_f32 v16, v16, v152, v153
	v_max3_f32 v16, v16, v154, v155
	v_max3_f32 v16, v16, v148, v149
	v_max3_f32 v16, v16, v150, v151
	v_mov_b32_e32 v17, v16
	s_nop 1
	v_permlane16_swap_b32_e32 v16, v17
	v_max_f32_e32 v17, v17, v17
	v_max_f32_e32 v16, v16, v16
	v_max_f32_e32 v16, v16, v17
	v_mov_b32_e32 v17, v16
	s_nop 1
	v_permlane32_swap_b32_e32 v16, v17
	v_max_f32_e32 v17, v17, v17
	v_max_f32_e32 v16, v16, v16
	v_max_f32_e32 v16, v16, v17
	v_cmp_lt_f32_e32 vcc, s52, v16
	s_nop 1
	v_cndmask_b32_e32 v16, 0, v16, vcc
	v_exp_f32_e64 v28, -v16
	v_add_f32_e32 v207, v78, v16
	v_sub_f32_e32 v160, v160, v16
	v_sub_f32_e32 v161, v161, v16
	v_sub_f32_e32 v162, v162, v16
	v_sub_f32_e32 v163, v163, v16
	v_mul_f32_e32 v209, v208, v28
	v_sub_f32_e32 v156, v156, v16
	v_sub_f32_e32 v157, v157, v16
	v_sub_f32_e32 v158, v158, v16
	v_sub_f32_e32 v159, v159, v16
	v_sub_f32_e32 v152, v152, v16
	v_sub_f32_e32 v153, v153, v16
	v_sub_f32_e32 v154, v154, v16
	v_sub_f32_e32 v155, v155, v16
	v_sub_f32_e32 v148, v148, v16
	v_sub_f32_e32 v149, v149, v16
	v_sub_f32_e32 v150, v150, v16
	v_sub_f32_e32 v151, v151, v16
	v_mul_f32_e32 v26, v58, v28
	v_mul_f32_e32 v27, v59, v28
	v_mul_f32_e32 v24, v56, v28
	v_mul_f32_e32 v25, v57, v28
	v_mul_f32_e32 v22, v54, v28
	v_mul_f32_e32 v23, v55, v28
	v_mul_f32_e32 v20, v52, v28
	v_mul_f32_e32 v21, v53, v28
	v_mul_f32_e32 v18, v50, v28
	v_mul_f32_e32 v19, v51, v28
	v_mul_f32_e32 v16, v48, v28
	v_mul_f32_e32 v17, v49, v28
	v_mul_f32_e32 v30, v62, v28
	v_mul_f32_e32 v31, v63, v28
	v_mul_f32_e32 v29, v61, v28
	v_mul_f32_e32 v28, v60, v28
	s_branch .LBB0_1247

.LBB0_1248:
	s_and_b64 vcc, exec, s[14:15]
	s_cbranch_vccz .LBB0_1204
	s_waitcnt lgkmcnt(7)
	v_mfma_f32_16x16x32_bf16 v[28:31], v[74:77], v[80:83], v[70:73]
	s_waitcnt lgkmcnt(5)
	v_mfma_f32_16x16x32_bf16 v[24:27], v[124:127], v[80:83], v[70:73]
	s_waitcnt lgkmcnt(3)
	v_mfma_f32_16x16x32_bf16 v[20:23], v[132:135], v[80:83], v[70:73]
	s_nop 3
	v_max3_f32 v64, v30, v28, v29
	s_nop 0
	v_max3_f32 v64, v24, v31, v64
	v_max3_f32 v64, v26, v25, v64
	s_waitcnt lgkmcnt(1)
	v_mfma_f32_16x16x32_bf16 v[16:19], v[140:143], v[80:83], v[70:73]
	v_mfma_f32_16x16x32_bf16 v[12:15], v[120:123], v[92:95], v[66:69]
	v_max3_f32 v64, v20, v27, v64
	v_max3_f32 v64, v22, v21, v64
	s_nop 4
	v_max3_f32 v64, v16, v23, v64
	v_mfma_f32_16x16x32_bf16 v[8:11], v[128:131], v[92:95], v[66:69]
	v_max3_f32 v64, v18, v17, v64
	v_mfma_f32_16x16x32_bf16 v[4:7], v[136:139], v[92:95], v[66:69]
	s_waitcnt lgkmcnt(0)
	v_mfma_f32_16x16x32_bf16 v[0:3], v[144:147], v[92:95], v[66:69]
	s_nop 2
	v_max_f32_e32 v67, v19, v19
	v_max_f32_e32 v64, v67, v64
	v_cmp_lt_f32_e32 vcc, s52, v64
	s_cbranch_vccz .LBB0_1251
	v_max_f32_e32 v64, v29, v29
	v_max_f32_e32 v67, v28, v28
	v_max_f32_e32 v64, v67, v64
	v_max3_f32 v64, v64, v30, v31
	v_max3_f32 v64, v64, v24, v25
	v_max3_f32 v64, v64, v26, v27
	v_max3_f32 v64, v64, v20, v21
	v_max3_f32 v64, v64, v22, v23
	v_max3_f32 v64, v64, v16, v17
	v_max3_f32 v64, v64, v18, v19
	v_mov_b32_e32 v67, v64
	s_nop 1
	v_permlane16_swap_b32_e32 v64, v67
	v_max_f32_e32 v67, v67, v67
	v_max_f32_e32 v64, v64, v64
	v_max_f32_e32 v64, v64, v67
	v_mov_b32_e32 v67, v64
	s_nop 1
	v_permlane32_swap_b32_e32 v64, v67
	v_max_f32_e32 v67, v67, v67
	v_max_f32_e32 v64, v64, v64
	v_max_f32_e32 v64, v64, v67
	v_cmp_lt_f32_e32 vcc, s52, v64
	s_nop 1
	v_cndmask_b32_e32 v68, 0, v64, vcc
	v_exp_f32_e64 v70, -v68
	v_add_f32_e32 v64, v79, v68
	v_sub_f32_e32 v28, v28, v68
	v_sub_f32_e32 v29, v29, v68
	v_sub_f32_e32 v30, v30, v68
	v_sub_f32_e32 v31, v31, v68
	v_mul_f32_e32 v211, v211, v70
	v_sub_f32_e32 v24, v24, v68
	v_sub_f32_e32 v25, v25, v68
	v_sub_f32_e32 v26, v26, v68
	v_sub_f32_e32 v27, v27, v68
	v_sub_f32_e32 v20, v20, v68
	v_sub_f32_e32 v21, v21, v68
	v_sub_f32_e32 v22, v22, v68
	v_sub_f32_e32 v23, v23, v68
	v_sub_f32_e32 v16, v16, v68
	v_sub_f32_e32 v17, v17, v68
	v_sub_f32_e32 v18, v18, v68
	v_sub_f32_e32 v19, v19, v68
	v_mul_f32_e32 v46, v46, v70
	v_mul_f32_e32 v47, v47, v70
	v_mul_f32_e32 v44, v44, v70
	v_mul_f32_e32 v45, v45, v70
	v_mul_f32_e32 v42, v42, v70
	v_mul_f32_e32 v43, v43, v70
	v_mul_f32_e32 v40, v40, v70
	v_mul_f32_e32 v41, v41, v70
	v_mul_f32_e32 v38, v38, v70
	v_mul_f32_e32 v39, v39, v70
	v_mul_f32_e32 v36, v36, v70
	v_mul_f32_e32 v37, v37, v70
	v_mul_f32_e32 v34, v34, v70
	v_mul_f32_e32 v35, v35, v70
	v_mul_f32_e32 v32, v32, v70
	v_mul_f32_e32 v33, v33, v70
	s_branch .LBB0_1252

.LBB0_1252:
	v_max3_f32 v67, v14, v12, v13
	v_max3_f32 v67, v8, v15, v67
	v_max3_f32 v67, v10, v9, v67
	v_max3_f32 v67, v4, v11, v67
	v_max3_f32 v67, v6, v5, v67
	v_max3_f32 v67, v0, v7, v67
	v_max3_f32 v67, v2, v1, v67
	v_max_f32_e32 v68, v3, v3
	v_max_f32_e32 v67, v68, v67
	v_cmp_lt_f32_e32 vcc, s52, v67
	s_cbranch_vccz .LBB0_1254
	v_max_f32_e32 v66, v13, v13
	v_max_f32_e32 v67, v12, v12
	v_max_f32_e32 v66, v67, v66
	v_max3_f32 v66, v66, v14, v15
	v_max3_f32 v66, v66, v8, v9
	v_max3_f32 v66, v66, v10, v11
	v_max3_f32 v66, v66, v4, v5
	v_max3_f32 v66, v66, v6, v7
	v_max3_f32 v66, v66, v0, v1
	v_max3_f32 v66, v66, v2, v3
	v_mov_b32_e32 v67, v66
	s_nop 1
	v_permlane16_swap_b32_e32 v66, v67
	v_max_f32_e32 v67, v67, v67
	v_max_f32_e32 v66, v66, v66
	v_max_f32_e32 v66, v66, v67
	v_mov_b32_e32 v67, v66
	s_nop 1
	v_permlane32_swap_b32_e32 v66, v67
	v_max_f32_e32 v67, v67, v67
	v_max_f32_e32 v66, v66, v66
	v_max_f32_e32 v66, v66, v67
	v_cmp_lt_f32_e32 vcc, s52, v66
	s_nop 1
	v_cndmask_b32_e32 v66, 0, v66, vcc
	v_exp_f32_e64 v68, -v66
	v_add_f32_e32 v78, v78, v66
	v_sub_f32_e32 v12, v12, v66
	v_sub_f32_e32 v13, v13, v66
	v_sub_f32_e32 v14, v14, v66
	v_sub_f32_e32 v15, v15, v66
	v_mul_f32_e32 v208, v208, v68
	v_sub_f32_e32 v8, v8, v66
	v_sub_f32_e32 v9, v9, v66
	v_sub_f32_e32 v10, v10, v66
	v_sub_f32_e32 v11, v11, v66
	v_sub_f32_e32 v4, v4, v66
	v_sub_f32_e32 v5, v5, v66
	v_sub_f32_e32 v6, v6, v66
	v_sub_f32_e32 v7, v7, v66
	v_sub_f32_e32 v0, v0, v66
	v_sub_f32_e32 v1, v1, v66
	v_sub_f32_e32 v2, v2, v66
	v_sub_f32_e32 v3, v3, v66
	v_mul_f32_e32 v58, v58, v68
	v_mul_f32_e32 v59, v59, v68
	v_mul_f32_e32 v56, v56, v68
	v_mul_f32_e32 v57, v57, v68
	v_mul_f32_e32 v54, v54, v68
	v_mul_f32_e32 v55, v55, v68
	v_mul_f32_e32 v52, v52, v68
	v_mul_f32_e32 v53, v53, v68
	v_mul_f32_e32 v50, v50, v68
	v_mul_f32_e32 v51, v51, v68
	v_mul_f32_e32 v48, v48, v68
	v_mul_f32_e32 v49, v49, v68
	v_mul_f32_e32 v62, v62, v68
	v_mul_f32_e32 v63, v63, v68
	v_mul_f32_e32 v60, v60, v68
	v_mul_f32_e32 v61, v61, v68
	v_xor_b32_e32 v66, 0x80000000, v78
.LBB0_1254:
	v_exp_f32_e32 v28, v28
	v_exp_f32_e32 v29, v29
	v_exp_f32_e32 v30, v30
	v_exp_f32_e32 v31, v31
	v_add_f32_e32 v67, 0, v28
	v_exp_f32_e32 v24, v24
	v_add_f32_e32 v67, v29, v67
	v_exp_f32_e32 v25, v25
	v_add_f32_e32 v67, v30, v67
	v_exp_f32_e32 v26, v26
	v_add_f32_e32 v67, v31, v67
	v_exp_f32_e32 v27, v27
	v_add_f32_e32 v67, v24, v67
	v_exp_f32_e32 v20, v20
	v_add_f32_e32 v67, v25, v67
	v_exp_f32_e32 v21, v21
	v_add_f32_e32 v67, v26, v67
	v_exp_f32_e32 v22, v22
	v_add_f32_e32 v67, v27, v67
	v_exp_f32_e32 v23, v23
	v_add_f32_e32 v67, v20, v67
	v_exp_f32_e32 v16, v16
	v_add_f32_e32 v67, v21, v67
	v_exp_f32_e32 v17, v17
	v_add_f32_e32 v67, v22, v67
	v_exp_f32_e32 v18, v18
	v_add_f32_e32 v67, v23, v67
	v_exp_f32_e32 v19, v19
	v_add_f32_e32 v67, v16, v67
	v_add_f32_e32 v67, v17, v67
	v_add_f32_e32 v67, v18, v67
	v_add_f32_e32 v67, v19, v67
	v_exp_f32_e32 v75, v12
	v_exp_f32_e32 v76, v13
	v_exp_f32_e32 v77, v14
	v_exp_f32_e32 v79, v15
	v_exp_f32_e32 v130, v2
	v_exp_f32_e32 v131, v3
	v_cvt_pk_bf16_f32 v2, v16, v17
	v_cvt_pk_bf16_f32 v3, v18, v19
	ds_read_b64_tr_b16 v[14:15], v202 offset:57600
	ds_read_b64_tr_b16 v[12:13], v202 offset:55296
	ds_read_b64_tr_b16 v[16:17], v202 offset:55328
	ds_read_b64_tr_b16 v[18:19], v202 offset:57632
	v_exp_f32_e32 v120, v8
	v_exp_f32_e32 v121, v9
	v_exp_f32_e32 v122, v10
	v_exp_f32_e32 v123, v11
	v_exp_f32_e32 v124, v4
	v_exp_f32_e32 v125, v5
	v_exp_f32_e32 v126, v6
	v_exp_f32_e32 v127, v7
	v_cvt_pk_bf16_f32 v4, v28, v29
	v_cvt_pk_bf16_f32 v5, v30, v31
	v_cvt_pk_bf16_f32 v6, v24, v25
	v_cvt_pk_bf16_f32 v7, v26, v27
	v_cvt_pk_bf16_f32 v8, v75, v76
	v_cvt_pk_bf16_f32 v9, v77, v79
	v_cvt_pk_bf16_f32 v10, v120, v121
	v_cvt_pk_bf16_f32 v11, v122, v123
	v_exp_f32_e32 v128, v0
	v_exp_f32_e32 v129, v1
	v_cvt_pk_bf16_f32 v0, v20, v21
	v_cvt_pk_bf16_f32 v1, v22, v23
	s_waitcnt lgkmcnt(2)
	v_mfma_f32_16x16x32_bf16 v[20:23], v[12:15], v[4:7], v[32:35]
	v_cvt_pk_bf16_f32 v70, v124, v125
	v_cvt_pk_bf16_f32 v71, v126, v127
	v_cvt_pk_bf16_f32 v72, v128, v129
	s_waitcnt lgkmcnt(0)
	v_mfma_f32_16x16x32_bf16 v[24:27], v[16:19], v[4:7], v[36:39]
	v_cvt_pk_bf16_f32 v73, v130, v131
	v_add_f32_e32 v74, v211, v67
	v_mov_b32_e32 v67, v66
	v_mfma_f32_16x16x32_bf16 v[32:35], v[16:19], v[8:11], v[52:55]
	ds_read_b64_tr_b16 v[16:17], v202 offset:55360
	ds_read_b64_tr_b16 v[18:19], v202 offset:57664
	v_mov_b32_e32 v68, v66
	v_mov_b32_e32 v69, v66
	s_waitcnt lgkmcnt(0)
	v_mfma_f32_16x16x32_bf16 v[36:39], v[16:19], v[4:7], v[40:43]
	v_mfma_f32_16x16x32_bf16 v[40:43], v[16:19], v[8:11], v[56:59]
	ds_read_b64_tr_b16 v[16:17], v202 offset:55392
	ds_read_b64_tr_b16 v[18:19], v202 offset:57696
	v_mfma_f32_16x16x32_bf16 v[12:15], v[12:15], v[8:11], v[48:51]
	s_waitcnt lgkmcnt(0)
	v_mfma_f32_16x16x32_bf16 v[4:7], v[16:19], v[4:7], v[44:47]
	v_mfma_f32_16x16x32_bf16 v[44:47], v[16:19], v[8:11], v[60:63]
	ds_read_b64_tr_b16 v[8:9], v202 offset:59904
	ds_read_b64_tr_b16 v[10:11], v202 offset:62208
	s_waitcnt lgkmcnt(0)
	v_mfma_f32_16x16x32_bf16 v[20:23], v[8:11], v[0:3], v[20:23]
	v_mfma_f32_16x16x32_bf16 v[16:19], v[8:11], v[70:73], v[12:15]
	ds_read_b64_tr_b16 v[8:9], v202 offset:59936
	ds_read_b64_tr_b16 v[10:11], v202 offset:62240
	s_waitcnt lgkmcnt(0)
	v_mfma_f32_16x16x32_bf16 v[28:31], v[8:11], v[0:3], v[24:27]
	v_mfma_f32_16x16x32_bf16 v[24:27], v[8:11], v[70:73], v[32:35]
	ds_read_b64_tr_b16 v[8:9], v202 offset:59968
	ds_read_b64_tr_b16 v[10:11], v202 offset:62272
	s_nop 0
	ds_read_b64_tr_b16 v[32:33], v202 offset:60000
	ds_read_b64_tr_b16 v[34:35], v202 offset:62304
	s_waitcnt lgkmcnt(2)
	v_mfma_f32_16x16x32_bf16 v[12:15], v[8:11], v[0:3], v[36:39]
	s_waitcnt lgkmcnt(0)
	v_mfma_f32_16x16x32_bf16 v[4:7], v[32:35], v[0:3], v[4:7]
	v_mfma_f32_16x16x32_bf16 v[0:3], v[32:35], v[70:73], v[44:47]
	ds_read_b128 v[32:35], v206 offset:46080
	ds_read_b128 v[36:39], v206 offset:46144
	s_nop 0
	v_xor_b32_e32 v44, 0x80000000, v64
	v_mov_b32_e32 v45, v44
	v_mov_b32_e32 v46, v44
	v_mov_b32_e32 v47, v44
	v_mfma_f32_16x16x32_bf16 v[8:11], v[8:11], v[70:73], v[40:43]
	s_waitcnt lgkmcnt(1)
	v_mfma_f32_16x16x32_bf16 v[48:51], v[32:35], v[80:83], v[44:47]
	s_waitcnt lgkmcnt(0)
	v_mfma_f32_16x16x32_bf16 v[32:35], v[36:39], v[92:95], v[66:69]
	ds_read_b128 v[36:39], v206 offset:48384
	ds_read_b128 v[40:43], v206 offset:48448
	s_waitcnt lgkmcnt(1)
	v_mfma_f32_16x16x32_bf16 v[52:55], v[36:39], v[80:83], v[44:47]
	s_waitcnt lgkmcnt(0)
	v_mfma_f32_16x16x32_bf16 v[36:39], v[40:43], v[92:95], v[66:69]
	ds_read_b128 v[40:43], v206 offset:50688
	ds_read_b128 v[60:63], v206 offset:50752
	s_waitcnt lgkmcnt(1)
	v_mfma_f32_16x16x32_bf16 v[56:59], v[40:43], v[80:83], v[44:47]
	s_waitcnt lgkmcnt(0)
	v_mfma_f32_16x16x32_bf16 v[40:43], v[60:63], v[92:95], v[66:69]
	ds_read_b128 v[60:63], v206 offset:52992
	ds_read_b128 v[70:73], v206 offset:53056
	s_waitcnt lgkmcnt(1)
	v_mfma_f32_16x16x32_bf16 v[60:63], v[60:63], v[80:83], v[44:47]
	s_waitcnt lgkmcnt(0)
	v_mfma_f32_16x16x32_bf16 v[44:47], v[70:73], v[92:95], v[66:69]
	s_nop 2
	v_max3_f32 v66, v50, v48, v49
	v_max3_f32 v66, v51, v66, v52
	v_max3_f32 v66, v54, v53, v66
	v_max3_f32 v66, v56, v55, v66
	v_max3_f32 v66, v58, v57, v66
	v_max3_f32 v66, v60, v59, v66
	v_max3_f32 v66, v62, v61, v66
	v_max_f32_e32 v67, v63, v63
	v_max_f32_e32 v66, v67, v66
	v_cmp_lt_f32_e32 vcc, s52, v66
	s_cbranch_vccz .LBB0_1256
	v_max_f32_e32 v66, v49, v49
	v_max_f32_e32 v67, v48, v48
	v_max_f32_e32 v66, v67, v66
	v_max3_f32 v66, v66, v50, v51
	v_max3_f32 v66, v66, v52, v53
	v_max3_f32 v66, v66, v54, v55
	v_max3_f32 v66, v66, v56, v57
	v_max3_f32 v66, v66, v58, v59
	v_max3_f32 v66, v66, v60, v61
	v_max3_f32 v66, v66, v62, v63
	v_mov_b32_e32 v67, v66
	s_nop 1
	v_permlane16_swap_b32_e32 v66, v67
	v_max_f32_e32 v67, v67, v67
	v_max_f32_e32 v66, v66, v66
	v_max_f32_e32 v66, v66, v67
	v_mov_b32_e32 v67, v66
	s_nop 1
	v_permlane32_swap_b32_e32 v66, v67
	v_max_f32_e32 v67, v67, v67
	v_max_f32_e32 v66, v66, v66
	v_max_f32_e32 v66, v66, v67
	v_cmp_lt_f32_e32 vcc, s52, v66
	s_nop 1
	v_cndmask_b32_e32 v66, 0, v66, vcc
	v_exp_f32_e64 v68, -v66
	v_add_f32_e32 v64, v64, v66
	v_sub_f32_e32 v48, v48, v66
	v_sub_f32_e32 v49, v49, v66
	v_sub_f32_e32 v50, v50, v66
	v_sub_f32_e32 v51, v51, v66
	v_mul_f32_e32 v74, v74, v68
	v_sub_f32_e32 v52, v52, v66
	v_sub_f32_e32 v53, v53, v66
	v_sub_f32_e32 v54, v54, v66
	v_sub_f32_e32 v55, v55, v66
	v_sub_f32_e32 v56, v56, v66
	v_sub_f32_e32 v57, v57, v66
	v_sub_f32_e32 v58, v58, v66
	v_sub_f32_e32 v59, v59, v66
	v_sub_f32_e32 v60, v60, v66
	v_sub_f32_e32 v61, v61, v66
	v_sub_f32_e32 v62, v62, v66
	v_sub_f32_e32 v63, v63, v66
	v_mul_f32_e32 v6, v6, v68
	v_mul_f32_e32 v7, v7, v68
	v_mul_f32_e32 v4, v4, v68
	v_mul_f32_e32 v5, v5, v68
	v_mul_f32_e32 v14, v14, v68
	v_mul_f32_e32 v15, v15, v68
	v_mul_f32_e32 v12, v12, v68
	v_mul_f32_e32 v13, v13, v68
	v_mul_f32_e32 v30, v30, v68
	v_mul_f32_e32 v31, v31, v68
	v_mul_f32_e32 v28, v28, v68
	v_mul_f32_e32 v29, v29, v68
	v_mul_f32_e32 v22, v22, v68
	v_mul_f32_e32 v23, v23, v68
	v_mul_f32_e32 v20, v20, v68
	v_mul_f32_e32 v21, v21, v68
.LBB0_1256:
	v_add_f32_e32 v66, 0, v75
	v_add_f32_e32 v66, v76, v66
	v_add_f32_e32 v66, v77, v66
	v_add_f32_e32 v66, v79, v66
	v_add_f32_e32 v66, v120, v66
	v_add_f32_e32 v66, v121, v66
	v_add_f32_e32 v66, v122, v66
	v_add_f32_e32 v66, v123, v66
	v_add_f32_e32 v66, v124, v66
	v_max3_f32 v67, v34, v32, v33
	v_add_f32_e32 v66, v125, v66
	v_max3_f32 v67, v35, v67, v36
	v_add_f32_e32 v66, v126, v66
	v_max3_f32 v67, v38, v37, v67
	v_add_f32_e32 v66, v127, v66
	v_max3_f32 v67, v40, v39, v67
	v_add_f32_e32 v66, v128, v66
	v_max3_f32 v67, v42, v41, v67
	v_add_f32_e32 v66, v129, v66
	v_max3_f32 v67, v44, v43, v67
	v_add_f32_e32 v66, v130, v66
	v_max3_f32 v67, v46, v45, v67
	v_max_f32_e32 v68, v47, v47
	v_add_f32_e32 v66, v131, v66
	v_max_f32_e32 v67, v68, v67
	v_add_f32_e32 v66, v208, v66
	v_cmp_lt_f32_e32 vcc, s52, v67
	s_cbranch_vccz .LBB0_1203
	v_max_f32_e32 v67, v33, v33
	v_max_f32_e32 v68, v32, v32
	v_max_f32_e32 v67, v68, v67
	v_max3_f32 v67, v67, v34, v35
	v_max3_f32 v67, v67, v36, v37
	v_max3_f32 v67, v67, v38, v39
	v_max3_f32 v67, v67, v40, v41
	v_max3_f32 v67, v67, v42, v43
	v_max3_f32 v67, v67, v44, v45
	v_max3_f32 v67, v67, v46, v47
	v_mov_b32_e32 v68, v67
	s_nop 1
	v_permlane16_swap_b32_e32 v67, v68
	v_max_f32_e32 v68, v68, v68
	v_max_f32_e32 v67, v67, v67
	v_max_f32_e32 v67, v67, v68
	v_mov_b32_e32 v68, v67
	s_nop 1
	v_permlane32_swap_b32_e32 v67, v68
	v_max_f32_e32 v68, v68, v68
	v_max_f32_e32 v67, v67, v67
	v_max_f32_e32 v67, v67, v68
	v_cmp_lt_f32_e32 vcc, s52, v67
	s_nop 1
	v_cndmask_b32_e32 v68, 0, v67, vcc
	v_exp_f32_e64 v70, -v68
	v_add_f32_e32 v78, v78, v68
	v_sub_f32_e32 v32, v32, v68
	v_sub_f32_e32 v33, v33, v68
	v_sub_f32_e32 v34, v34, v68
	v_sub_f32_e32 v35, v35, v68
	v_mul_f32_e32 v66, v66, v70
	v_sub_f32_e32 v36, v36, v68
	v_sub_f32_e32 v37, v37, v68
	v_sub_f32_e32 v38, v38, v68
	v_sub_f32_e32 v39, v39, v68
	v_sub_f32_e32 v40, v40, v68
	v_sub_f32_e32 v41, v41, v68
	v_sub_f32_e32 v42, v42, v68
	v_sub_f32_e32 v43, v43, v68
	v_sub_f32_e32 v44, v44, v68
	v_sub_f32_e32 v45, v45, v68
	v_sub_f32_e32 v46, v46, v68
	v_sub_f32_e32 v47, v47, v68
	v_mul_f32_e32 v2, v2, v70
	v_mul_f32_e32 v3, v3, v70
	v_mul_f32_e32 v0, v0, v70
	v_mul_f32_e32 v1, v1, v70
	v_mul_f32_e32 v10, v10, v70
	v_mul_f32_e32 v11, v11, v70
	v_mul_f32_e32 v8, v8, v70
	v_mul_f32_e32 v9, v9, v70
	v_mul_f32_e32 v26, v26, v70
	v_mul_f32_e32 v27, v27, v70
	v_mul_f32_e32 v24, v24, v70
	v_mul_f32_e32 v25, v25, v70
	v_mul_f32_e32 v18, v18, v70
	v_mul_f32_e32 v19, v19, v70
	v_mul_f32_e32 v16, v16, v70
	v_mul_f32_e32 v17, v17, v70
	s_branch .LBB0_1203
.LBB0_1258:
	v_mov_b32_e32 v32, v210
	s_nop 1
	v_permlane16_swap_b32_e32 v210, v32
	v_add_f32_e32 v32, v210, v32
	v_mov_b32_e32 v33, v32
	s_nop 1
	v_permlane32_swap_b32_e32 v32, v33
	v_add_f32_e32 v42, v32, v33
	v_mov_b32_e32 v32, v209
	s_nop 1
	v_permlane16_swap_b32_e32 v209, v32
	v_add_f32_e32 v36, v209, v32
	s_nop 0
	v_add_f32_dpp v32, v183, v183 quad_perm:[1,0,3,2] row_mask:0xf bank_mask:0xf bound_ctrl:1
	v_cvt_f32_i32_e32 v35, s45
	s_load_dwordx2 s[8:9], s[0:1], 0xc8
	v_add_f32_dpp v32, v32, v32 quad_perm:[2,3,0,1] row_mask:0xf bank_mask:0xf bound_ctrl:1
	s_lshl_b32 s10, s45, 6
	s_ashr_i32 s11, s10, 31
	v_add_f32_dpp v32, v32, v32 row_half_mirror row_mask:0xf bank_mask:0xf bound_ctrl:1
	s_lshl_b64 s[10:11], s[10:11], 2
	s_waitcnt lgkmcnt(0)
	s_add_u32 s8, s8, s10
	v_add_f32_dpp v32, v32, v32 row_mirror row_mask:0xf bank_mask:0xf bound_ctrl:1
	v_mov_b32_e32 v33, v32
	s_nop 1
	v_permlane16_swap_b32_e32 v32, v33
	v_add_f32_e32 v32, v32, v33
	v_mov_b32_e32 v33, v32
	s_nop 1
	v_permlane32_swap_b32_e32 v32, v33
	v_add_f32_e32 v32, v32, v33
	s_nop 0
	v_add_f32_dpp v33, v182, v182 quad_perm:[1,0,3,2] row_mask:0xf bank_mask:0xf bound_ctrl:1
	v_mul_f32_e32 v40, 0x3fb8aa3b, v32
	s_addc_u32 s9, s9, s11
	v_add_f32_dpp v33, v33, v33 quad_perm:[2,3,0,1] row_mask:0xf bank_mask:0xf bound_ctrl:1
	v_lshlrev_b32_e32 v44, 2, v198
	v_exp_f32_e32 v191, v40
	v_add_f32_dpp v33, v33, v33 row_half_mirror row_mask:0xf bank_mask:0xf bound_ctrl:1
	v_mov_b32_e32 v38, v36
	s_nop 1
	v_permlane32_swap_b32_e32 v36, v38
	v_add_f32_dpp v33, v33, v33 row_mirror row_mask:0xf bank_mask:0xf bound_ctrl:1
	v_mov_b32_e32 v34, v33
	s_nop 1
	v_permlane16_swap_b32_e32 v33, v34
	v_add_f32_e32 v33, v33, v34
	v_mov_b32_e32 v34, v33
	s_nop 1
	v_permlane32_swap_b32_e32 v33, v34
	v_add_f32_e32 v37, v33, v34
	v_mul_f32_e32 v33, 0xbe99999a, v35
	v_mul_f32_e32 v33, 0x3fb8aa3b, v33
	v_exp_f32_e32 v39, v33
	v_mul_f32_e32 v37, 0x3fb8aa3b, v37
	global_load_dwordx4 v[32:35], v44, s[8:9]
	v_exp_f32_e32 v37, v37
	v_add_f32_e32 v38, v36, v38
	v_mul_f32_e32 v36, 0x3f19999a, v39
	v_rcp_f32_e32 v43, v38
	v_sub_f32_e32 v40, v190, v36
	v_sub_f32_e32 v41, v191, v37
	global_load_dwordx4 v[36:39], v44, s[8:9] offset:64
	v_add_f32_e32 v41, v40, v41
	v_rcp_f32_e32 v48, v42
	v_mul_f32_e32 v50, v43, v41
	v_sub_f32_e32 v49, 1.0, v40
	global_load_dwordx4 v[40:43], v44, s[8:9] offset:128
	s_nop 0
	global_load_dwordx4 v[44:47], v44, s[8:9] offset:192
	v_mul_f32_e32 v0, v0, v50
	v_mul_f32_e32 v1, v1, v50
	v_mul_f32_e32 v2, v2, v50
	v_mul_f32_e32 v3, v3, v50
	v_fma_f32 v0, v16, v48, -v0
	v_fma_f32 v1, v17, v48, -v1
	v_fma_f32 v2, v18, v48, -v2
	v_fma_f32 v3, v19, v48, -v3
	v_mul_f32_e32 v16, v1, v1
	v_fma_f32 v17, v1, v1, v16
	v_fma_f32 v16, v0, v0, v16
	v_mul_f32_e32 v18, v3, v3
	v_fma_f32 v16, v2, v2, v16
	v_fma_f32 v17, v3, v3, v17
	v_mul_f32_e32 v4, v4, v50
	v_mul_f32_e32 v5, v5, v50
	v_add_f32_e32 v16, v18, v16
	v_add_f32_e32 v17, v18, v17
	v_fma_f32 v4, v20, v48, -v4
	v_fma_f32 v5, v21, v48, -v5
	v_mul_f32_e32 v6, v6, v50
	v_mul_f32_e32 v7, v7, v50
	v_fma_f32 v16, v4, v4, v16
	v_fma_f32 v17, v5, v5, v17
	v_mul_f32_e32 v18, v5, v5
	v_fma_f32 v6, v22, v48, -v6
	v_fma_f32 v7, v23, v48, -v7
	v_add_f32_e32 v16, v18, v16
	v_add_f32_e32 v17, v18, v17
	v_fma_f32 v16, v6, v6, v16
	v_fma_f32 v17, v7, v7, v17
	v_mul_f32_e32 v18, v7, v7
	v_mul_f32_e32 v8, v8, v50
	v_mul_f32_e32 v9, v9, v50
	v_add_f32_e32 v16, v18, v16
	v_add_f32_e32 v17, v18, v17
	v_fma_f32 v8, v24, v48, -v8
	v_fma_f32 v9, v25, v48, -v9
	v_mul_f32_e32 v10, v10, v50
	v_mul_f32_e32 v11, v11, v50
	v_fma_f32 v16, v8, v8, v16
	v_fma_f32 v17, v9, v9, v17
	v_mul_f32_e32 v18, v9, v9
	v_fma_f32 v10, v26, v48, -v10
	v_fma_f32 v11, v27, v48, -v11
	v_add_f32_e32 v16, v18, v16
	v_add_f32_e32 v17, v18, v17
	v_fma_f32 v16, v10, v10, v16
	v_fma_f32 v17, v11, v11, v17
	v_mul_f32_e32 v18, v11, v11
	v_mul_f32_e32 v12, v12, v50
	v_mul_f32_e32 v13, v13, v50
	v_add_f32_e32 v16, v18, v16
	v_add_f32_e32 v17, v18, v17
	v_fma_f32 v12, v28, v48, -v12
	v_fma_f32 v13, v29, v48, -v13
	v_mul_f32_e32 v14, v14, v50
	v_mul_f32_e32 v15, v15, v50
	v_fma_f32 v16, v12, v12, v16
	v_fma_f32 v17, v13, v13, v17
	v_mul_f32_e32 v18, v13, v13
	v_fma_f32 v14, v30, v48, -v14
	v_fma_f32 v15, v31, v48, -v15
	v_add_f32_e32 v16, v18, v16
	v_add_f32_e32 v17, v18, v17
	v_fma_f32 v16, v14, v14, v16
	v_fma_f32 v17, v15, v15, v17
	v_mul_f32_e32 v18, v15, v15
	v_add_f32_e32 v16, v18, v16
	v_add_f32_e32 v17, v18, v17
	v_mov_b32_e32 v17, v16
	s_nop 1
	v_permlane16_swap_b32_e32 v16, v17
	v_add_f32_e32 v16, v16, v17
	v_mov_b32_e32 v17, v16
	s_nop 1
	v_permlane32_swap_b32_e32 v16, v17
	v_add_f32_e32 v16, v16, v17
	v_fmamk_f32 v16, v16, 0x3c800000, v229
	v_mul_f32_e32 v17, 0x4b800000, v16
	v_cmp_gt_f32_e32 vcc, s55, v16
	v_lshlrev_b64 v[52:53], 11, v[180:181]
	v_lshl_add_u64 v[52:53], s[6:7], 0, v[52:53]
	v_cndmask_b32_e32 v16, v16, v17, vcc
	v_rsq_f32_e32 v20, v16
	s_mov_b32 s13, s97
	v_lshl_add_u64 v[52:53], v[52:53], 0, s[12:13]
	v_lshlrev_b32_e32 v64, 1, v198
	v_mul_f32_e32 v21, 0x45800000, v20
	v_cndmask_b32_e32 v20, v20, v21, vcc
	v_mul_f32_e32 v20, v49, v20
	v_lshl_add_u64 v[16:17], v[52:53], 0, v[64:65]
	s_mov_b64 s[6:7], 0xf000600
	v_mul_f32_e32 v0, v0, v20
	v_mul_f32_e32 v1, v1, v20
	v_mul_f32_e32 v2, v2, v20
	v_mul_f32_e32 v3, v3, v20
	v_lshl_add_u64 v[18:19], v[16:17], 0, s[6:7]
	s_mov_b32 s6, 0xf000000
	s_waitcnt vmcnt(3)
	v_mul_f32_e32 v0, v32, v0
	v_mul_f32_e32 v1, v33, v1
	v_mul_f32_e32 v2, v34, v2
	v_mul_f32_e32 v3, v35, v3
	v_cvt_pk_bf16_f32 v0, v0, v1
	v_cvt_pk_bf16_f32 v1, v2, v3
	v_add_co_u32_e32 v2, vcc, s6, v16
	s_nop 1
	v_addc_co_u32_e32 v3, vcc, 0, v17, vcc
	global_store_dwordx2 v[2:3], v[0:1], off offset:1536
	v_mul_f32_e32 v0, v4, v20
	v_mul_f32_e32 v1, v5, v20
	v_mul_f32_e32 v2, v6, v20
	v_mul_f32_e32 v3, v7, v20
	s_waitcnt vmcnt(3)
	v_mul_f32_e32 v0, v36, v0
	v_mul_f32_e32 v1, v37, v1
	v_mul_f32_e32 v2, v38, v2
	v_mul_f32_e32 v3, v39, v3
	v_cvt_pk_bf16_f32 v0, v0, v1
	v_cvt_pk_bf16_f32 v1, v2, v3
	global_store_dwordx2 v[18:19], v[0:1], off offset:32
	v_mul_f32_e32 v0, v8, v20
	v_mul_f32_e32 v1, v9, v20
	v_mul_f32_e32 v2, v10, v20
	v_mul_f32_e32 v3, v11, v20
	s_waitcnt vmcnt(3)
	v_mul_f32_e32 v0, v40, v0
	v_mul_f32_e32 v1, v41, v1
	v_mul_f32_e32 v2, v42, v2
	v_mul_f32_e32 v3, v43, v3
	v_cvt_pk_bf16_f32 v0, v0, v1
	v_cvt_pk_bf16_f32 v1, v2, v3
	global_store_dwordx2 v[18:19], v[0:1], off offset:64
	v_mul_f32_e32 v0, v12, v20
	v_mul_f32_e32 v1, v13, v20
	v_mul_f32_e32 v2, v14, v20
	v_mul_f32_e32 v3, v15, v20
	s_waitcnt vmcnt(3)
	v_mul_f32_e32 v0, v44, v0
	v_mul_f32_e32 v1, v45, v1
	v_mul_f32_e32 v2, v46, v2
	v_mul_f32_e32 v3, v47, v3
	v_cvt_pk_bf16_f32 v0, v0, v1
	v_cvt_pk_bf16_f32 v1, v2, v3
	global_store_dwordx2 v[18:19], v[0:1], off offset:96
